# hand-written token-parallel rg_item (phases 5,7) + spread ctx gla items over WGs
# speedup vs baseline: 1.0171x; 1.0171x over previous
; #define LAS __attribute__((address_space(3)))
; template <bool FINAL>
; __device__ __forceinline__ void rg_item(PREF p, int l, int item, LAS unsigned char* wl, int lane) {
;     ...
;     const int h = item & 7, rest = item >> 3;
;     const int ci = rest < 512 ? 4 + (rest & 255) : ((rest - 512) & 3), b = rest < 512 ? (rest >> 8) : ((rest - 512) >> 2);
;     const int seq_row0 = ci < 4 ? TL + b * 256 : b * 16384;
;     const int t0 = ci < 4 ? ci * 64 : (ci - 4) * 64;
;     const int seqlen = ci < 4 ? 256 : 16384;
;     const int ch = h * 64 + lane;
;     LAS bf16_t* sXc = (LAS bf16_t*)wl;
;     LAS float* stg = (LAS float*)(wl + 9216);
;     {
;         const float cw0 = p.conv_w[(l * 4 + 0) * 512 + ch], cw1 = p.conv_w[(l * 4 + 1) * 512 + ch], cw2 = p.conv_w[(l * 4 + 2) * 512 + ch], cw3 = p.conv_w[(l * 4 + 3) * 512 + ch];
;         const float cb = p.conv_b[l * 512 + ch];
;         float xv[67]; unsigned xr_[67];
; #pragma unroll
;         for (int i = 0; i < 67; ++i) { const int t = t0 - 2 + i; const int tc = t < 0 ? 0 : (t >= seqlen ? seqlen - 1 : t);
;             xr_[i] = P[(size_t)(seq_row0 + tc) * PW + ch]; }
.LBB0_77:
	v_readlane_b32 s2, v253, 55
	v_readlane_b32 s3, v253, 56
	v_readlane_b32 s47, v254, 5
	v_readlane_b32 s44, v255, 6
	s_nop 3
	s_load_dwordx2 s[0:1], s[2:3], 0xc0
	s_load_dwordx4 s[72:75], s[2:3], 0x58
	s_load_dwordx2 s[76:77], s[2:3], 0x68
	s_load_dwordx2 s[78:79], s[2:3], 0x78
	s_load_dwordx2 s[80:81], s[2:3], 0x88
	v_mbcnt_lo_u32_b32 v233, -1, 0
	v_mbcnt_hi_u32_b32 v233, -1, v233
	s_and_b32 s7, s12, 7
	s_lshr_b32 s6, s12, 3
	s_and_b32 s8, s6, 0xff
	s_lshr_b32 s9, s6, 8
	s_lshl_b32 s10, s8, 6
	s_lshl_b32 s11, s9, 14
	s_add_i32 s8, s8, 4
	s_mov_b32 s14, 0x4000
	s_cmpk_lt_u32 s6, 0x200
	s_cbranch_scc1 .Lrg7_dec
	s_sub_i32 s15, s6, 0x200
	s_and_b32 s8, s15, 3
	s_lshr_b32 s9, s15, 2
	s_lshl_b32 s10, s8, 6
	s_lshl_b32 s11, s9, 8
	s_add_i32 s11, s11, 0x8000
	s_movk_i32 s14, 0x100
.Lrg7_dec:
	s_add_i32 s15, s11, s10
	s_mul_i32 s36, s9, 0x104
	s_add_i32 s36, s36, s8
	s_lshl_b32 s36, s36, 12
	s_cmp_eq_u32 s10, 0
	s_cselect_b32 s37, 0, -1
	s_add_i32 s38, s10, 64
	s_cmp_eq_u32 s38, s14
	s_cselect_b32 s38, 0, -1
	s_bfe_u32 s44, s44, 0x30006
	s_mul_i32 s44, s44, 0x4800
	v_lshl_or_b32 v234, s7, 6, v233
	v_lshlrev_b32_e32 v235, 2, v234
	v_lshlrev_b32_e32 v234, 1, v234
	v_and_b32_e32 v236, 15, v233
	v_lshrrev_b32_e32 v241, 4, v233
	s_movk_i32 s39, 0x90
	v_mul_u32_u24_e32 v237, 0x90, v236
	v_lshl_add_u32 v237, v241, 4, v237
	v_lshlrev_b32_e32 v238, 7, v236
	v_lshl_add_u32 v238, v241, 4, v238
	v_lshlrev_b32_e32 v239, 10, v241
	v_lshl_add_u32 v239, v236, 2, v239
	v_mov_b32_e32 v241, v238
	v_add_u32_e32 v236, s44, v237
	s_add_i32 s39, s44, 0x2400
	v_add_u32_e32 v237, s39, v239
	v_add_u32_e32 v238, 0x1000, v237
	v_lshl_add_u32 v239, v233, 2, s44
	v_lshl_add_u32 v240, v233, 1, s44
	s_add_i32 s39, s15, -2
	s_mul_hi_i32 s83, s39, 0x1600
	s_mul_i32 s82, s39, 0x1600
	s_waitcnt lgkmcnt(0)
	s_add_u32 s82, s82, s0
	s_addc_u32 s83, s83, s1
	s_add_u32 s82, s82, 0xbc00000
	s_addc_u32 s83, s83, 0
	global_load_ushort v158, v234, s[82:83]
	s_add_u32 s82, s82, 0x1600
	s_addc_u32 s83, s83, 0
	global_load_ushort v159, v234, s[82:83]
	s_add_u32 s82, s82, 0x1600
	s_addc_u32 s83, s83, 0
	global_load_ushort v160, v234, s[82:83]
	s_add_u32 s82, s82, 0x1600
	s_addc_u32 s83, s83, 0
	global_load_ushort v161, v234, s[82:83]
	s_add_u32 s82, s82, 0x1600
	s_addc_u32 s83, s83, 0
	global_load_ushort v162, v234, s[82:83]
	s_add_u32 s82, s82, 0x1600
	s_addc_u32 s83, s83, 0
	global_load_ushort v163, v234, s[82:83]
	s_add_u32 s82, s82, 0x1600
	s_addc_u32 s83, s83, 0
	global_load_ushort v164, v234, s[82:83]
	s_add_u32 s82, s82, 0x1600
	s_addc_u32 s83, s83, 0
	global_load_ushort v165, v234, s[82:83]
	s_add_u32 s82, s82, 0x1600
	s_addc_u32 s83, s83, 0
	global_load_ushort v166, v234, s[82:83]
	s_add_u32 s82, s82, 0x1600
	s_addc_u32 s83, s83, 0
	global_load_ushort v167, v234, s[82:83]
	s_add_u32 s82, s82, 0x1600
	s_addc_u32 s83, s83, 0
	global_load_ushort v168, v234, s[82:83]
	s_add_u32 s82, s82, 0x1600
	s_addc_u32 s83, s83, 0
	global_load_ushort v169, v234, s[82:83]
	s_add_u32 s82, s82, 0x1600
	s_addc_u32 s83, s83, 0
	global_load_ushort v170, v234, s[82:83]
	s_add_u32 s82, s82, 0x1600
	s_addc_u32 s83, s83, 0
	global_load_ushort v171, v234, s[82:83]
	s_add_u32 s82, s82, 0x1600
	s_addc_u32 s83, s83, 0
	global_load_ushort v172, v234, s[82:83]
	s_add_u32 s82, s82, 0x1600
	s_addc_u32 s83, s83, 0
	global_load_ushort v173, v234, s[82:83]
	s_add_u32 s82, s82, 0x1600
	s_addc_u32 s83, s83, 0
	global_load_ushort v174, v234, s[82:83]
	s_add_u32 s82, s82, 0x1600
	s_addc_u32 s83, s83, 0
	global_load_ushort v175, v234, s[82:83]
	s_add_u32 s82, s82, 0x1600
	s_addc_u32 s83, s83, 0
	global_load_ushort v176, v234, s[82:83]
	s_add_u32 s82, s82, 0x1600
	s_addc_u32 s83, s83, 0
	global_load_ushort v177, v234, s[82:83]
	s_add_u32 s82, s82, 0x1600
	s_addc_u32 s83, s83, 0
	global_load_ushort v178, v234, s[82:83]
	s_add_u32 s82, s82, 0x1600
	s_addc_u32 s83, s83, 0
	global_load_ushort v179, v234, s[82:83]
	s_add_u32 s82, s82, 0x1600
	s_addc_u32 s83, s83, 0
	global_load_ushort v180, v234, s[82:83]
	s_add_u32 s82, s82, 0x1600
	s_addc_u32 s83, s83, 0
	global_load_ushort v181, v234, s[82:83]
	s_add_u32 s82, s82, 0x1600
	s_addc_u32 s83, s83, 0
	global_load_ushort v182, v234, s[82:83]
	s_add_u32 s82, s82, 0x1600
	s_addc_u32 s83, s83, 0
	global_load_ushort v183, v234, s[82:83]
	s_add_u32 s82, s82, 0x1600
	s_addc_u32 s83, s83, 0
	global_load_ushort v184, v234, s[82:83]
	s_add_u32 s82, s82, 0x1600
	s_addc_u32 s83, s83, 0
	global_load_ushort v185, v234, s[82:83]
	s_add_u32 s82, s82, 0x1600
	s_addc_u32 s83, s83, 0
	global_load_ushort v186, v234, s[82:83]
	s_add_u32 s82, s82, 0x1600
	s_addc_u32 s83, s83, 0
	global_load_ushort v187, v234, s[82:83]
	s_add_u32 s82, s82, 0x1600
	s_addc_u32 s83, s83, 0
	global_load_ushort v188, v234, s[82:83]
	s_add_u32 s82, s82, 0x1600
	s_addc_u32 s83, s83, 0
	global_load_ushort v189, v234, s[82:83]
	s_add_u32 s82, s82, 0x1600
	s_addc_u32 s83, s83, 0
	global_load_ushort v190, v234, s[82:83]
	s_add_u32 s82, s82, 0x1600
	s_addc_u32 s83, s83, 0
	global_load_ushort v191, v234, s[82:83]
	s_add_u32 s82, s82, 0x1600
	s_addc_u32 s83, s83, 0
	global_load_ushort v192, v234, s[82:83]
	s_add_u32 s82, s82, 0x1600
	s_addc_u32 s83, s83, 0
	global_load_ushort v193, v234, s[82:83]
	s_add_u32 s82, s82, 0x1600
	s_addc_u32 s83, s83, 0
	global_load_ushort v194, v234, s[82:83]
	s_add_u32 s82, s82, 0x1600
	s_addc_u32 s83, s83, 0
	global_load_ushort v195, v234, s[82:83]
	s_add_u32 s82, s82, 0x1600
	s_addc_u32 s83, s83, 0
	global_load_ushort v196, v234, s[82:83]
	s_add_u32 s82, s82, 0x1600
	s_addc_u32 s83, s83, 0
	global_load_ushort v197, v234, s[82:83]
	s_add_u32 s82, s82, 0x1600
	s_addc_u32 s83, s83, 0
; __device__ __forceinline__ float rcpf_(float x) { return __builtin_amdgcn_rcpf(x); }
; template <bool FINAL, int D>
; __device__ __forceinline__ void rg_dir(PREF p, int l, int h, int ch, int sidx, int rowbase  , LAS bf16_t* sXc, LAS float* stg, int lane) {
;     ...
;     const bf16_t* wr_ = WgT + (size_t)(((l * 2 + D) * 2 + 0) * 8 + h) * 4096; const bf16_t* wi_ = WgT + (size_t)(((l * 2 + D) * 2 + 1) * 8 + h) * 4096;
;     const float ba = p.rg_ba[(l * 2 + D) * 512 + ch], bi = p.rg_bi[(l * 2 + D) * 512 + ch], lam = p.rg_lam[(l * 2 + D) * 512 + ch];
;     const float e_ = __expf(-lam), u_ = 1.f + e_;
;     const float l1p = (u_ == 1.f) ? e_ : __logf(u_) * e_ * rcpf_(u_ - 1.f);
;     const float sp8 = -8.f * 1.4426950408889634f * l1p;
;     float hc = FINAL ? RGC[sidx] : 0.f, Ap = 1.f;
;     bf16x8 Br[4][2], Bi[4][2];
; #pragma unroll
;     for (int nt = 0; nt < 4; ++nt) { const int o0 = (nt * 16 + (lane & 15)) * 64 + (lane >> 4) * 8;
;         Br[nt][0] = *(const bf16x8*)(wr_ + o0); Br[nt][1] = *(const bf16x8*)(wr_ + o0 + 32); Bi[nt][0] = *(const bf16x8*)(wi_ + o0); Bi[nt][1] = *(const bf16x8*)(wi_ + o0 + 32); }
; template <bool FINAL>
; __device__ __forceinline__ void rg_item(PREF p, int l, int item, LAS unsigned char* wl, int lane) {
;     ...
;         const float cw0 = p.conv_w[(l * 4 + 0) * 512 + ch], cw1 = p.conv_w[(l * 4 + 1) * 512 + ch], cw2 = p.conv_w[(l * 4 + 2) * 512 + ch], cw3 = p.conv_w[(l * 4 + 3) * 512 + ch];
;         const float cb = p.conv_b[l * 512 + ch];
;         float xv[67]; unsigned xr_[67];
; #pragma unroll
;         for (int i = 0; i < 67; ++i) { const int t = t0 - 2 + i; const int tc = t < 0 ? 0 : (t >= seqlen ? seqlen - 1 : t);
;             xr_[i] = P[(size_t)(seq_row0 + tc) * PW + ch]; }
	global_load_ushort v198, v234, s[82:83]
	s_add_u32 s82, s82, 0x1600
	s_addc_u32 s83, s83, 0
	global_load_ushort v199, v234, s[82:83]
	s_add_u32 s82, s82, 0x1600
	s_addc_u32 s83, s83, 0
	global_load_ushort v200, v234, s[82:83]
	s_add_u32 s82, s82, 0x1600
	s_addc_u32 s83, s83, 0
	global_load_ushort v201, v234, s[82:83]
	s_add_u32 s82, s82, 0x1600
	s_addc_u32 s83, s83, 0
	global_load_ushort v202, v234, s[82:83]
	s_add_u32 s82, s82, 0x1600
	s_addc_u32 s83, s83, 0
	global_load_ushort v203, v234, s[82:83]
	s_add_u32 s82, s82, 0x1600
	s_addc_u32 s83, s83, 0
	global_load_ushort v204, v234, s[82:83]
	s_add_u32 s82, s82, 0x1600
	s_addc_u32 s83, s83, 0
	global_load_ushort v205, v234, s[82:83]
	s_add_u32 s82, s82, 0x1600
	s_addc_u32 s83, s83, 0
	global_load_ushort v206, v234, s[82:83]
	s_add_u32 s82, s82, 0x1600
	s_addc_u32 s83, s83, 0
	global_load_ushort v207, v234, s[82:83]
	s_add_u32 s82, s82, 0x1600
	s_addc_u32 s83, s83, 0
	global_load_ushort v208, v234, s[82:83]
	s_add_u32 s82, s82, 0x1600
	s_addc_u32 s83, s83, 0
	global_load_ushort v209, v234, s[82:83]
	s_add_u32 s82, s82, 0x1600
	s_addc_u32 s83, s83, 0
	global_load_ushort v210, v234, s[82:83]
	s_add_u32 s82, s82, 0x1600
	s_addc_u32 s83, s83, 0
	global_load_ushort v211, v234, s[82:83]
	s_add_u32 s82, s82, 0x1600
	s_addc_u32 s83, s83, 0
	global_load_ushort v212, v234, s[82:83]
	s_add_u32 s82, s82, 0x1600
	s_addc_u32 s83, s83, 0
	global_load_ushort v213, v234, s[82:83]
	s_add_u32 s82, s82, 0x1600
	s_addc_u32 s83, s83, 0
	global_load_ushort v214, v234, s[82:83]
	s_add_u32 s82, s82, 0x1600
	s_addc_u32 s83, s83, 0
	global_load_ushort v215, v234, s[82:83]
	s_add_u32 s82, s82, 0x1600
	s_addc_u32 s83, s83, 0
	global_load_ushort v216, v234, s[82:83]
	s_add_u32 s82, s82, 0x1600
	s_addc_u32 s83, s83, 0
	global_load_ushort v217, v234, s[82:83]
	s_add_u32 s82, s82, 0x1600
	s_addc_u32 s83, s83, 0
	global_load_ushort v218, v234, s[82:83]
	s_add_u32 s82, s82, 0x1600
	s_addc_u32 s83, s83, 0
	global_load_ushort v219, v234, s[82:83]
	s_add_u32 s82, s82, 0x1600
	s_addc_u32 s83, s83, 0
	global_load_ushort v222, v234, s[82:83]
	s_add_u32 s82, s82, 0x1600
	s_addc_u32 s83, s83, 0
	global_load_ushort v223, v234, s[82:83]
	s_add_u32 s82, s82, 0x1600
	s_addc_u32 s83, s83, 0
	global_load_ushort v140, v234, s[82:83]
	s_add_u32 s82, s82, 0x1600
	s_addc_u32 s83, s83, 0
	global_load_ushort v141, v234, s[82:83]
	s_add_u32 s82, s82, 0x1600
	s_addc_u32 s83, s83, 0
	global_load_ushort v232, v234, s[82:83]
	s_lshl_b32 s39, s47, 13
	s_add_u32 s72, s72, s39
	s_addc_u32 s73, s73, 0
	global_load_dword v40, v235, s[72:73]
	global_load_dword v41, v235, s[72:73] offset:2048
	s_add_u32 s72, s72, 0x1000
	s_addc_u32 s73, s73, 0
	global_load_dword v42, v235, s[72:73]
	global_load_dword v43, v235, s[72:73] offset:2048
	s_lshl_b32 s39, s47, 11
	s_add_u32 s74, s74, s39
	s_addc_u32 s75, s75, 0
	global_load_dword v44, v235, s[74:75]
	s_lshl_b32 s39, s47, 12
	s_add_u32 s76, s76, s39
	s_addc_u32 s77, s77, 0
	s_add_u32 s78, s78, s39
	s_addc_u32 s79, s79, 0
	s_add_u32 s80, s80, s39
	s_addc_u32 s81, s81, 0
	s_add_u32 s96, s0, 0xa00000
	s_addc_u32 s97, s1, 0
	s_add_u32 s96, s96, s36
	s_addc_u32 s97, s97, 0
	s_lshl_b32 s39, s47, 5
	s_add_i32 s39, s39, s7
	s_lshl_b32 s39, s39, 13
	s_add_u32 s92, s0, 0x300000
	s_addc_u32 s93, s1, 0
	s_add_u32 s92, s92, s39
	s_addc_u32 s93, s93, 0
	global_load_dword v45, v235, s[76:77]
	global_load_dword v46, v235, s[78:79]
	global_load_dword v47, v235, s[80:81]
	global_load_dword v250, v235, s[96:97]
	s_add_u32 s90, s92, 0x0
	s_addc_u32 s91, s93, 0
	global_load_dwordx4 v[80:83], v241, s[90:91]
	global_load_dwordx4 v[84:87], v241, s[90:91] offset:64
	global_load_dwordx4 v[88:91], v241, s[90:91] offset:2048
	global_load_dwordx4 v[92:95], v241, s[90:91] offset:2112
	s_add_u32 s90, s92, 0x1000
	s_addc_u32 s91, s93, 0
	global_load_dwordx4 v[96:99], v241, s[90:91]
	global_load_dwordx4 v[100:103], v241, s[90:91] offset:64
	global_load_dwordx4 v[104:107], v241, s[90:91] offset:2048
	global_load_dwordx4 v[108:111], v241, s[90:91] offset:2112
	s_add_u32 s90, s92, 0x10000
	s_addc_u32 s91, s93, 0
	global_load_dwordx4 v[112:115], v241, s[90:91]
	global_load_dwordx4 v[116:119], v241, s[90:91] offset:64
	global_load_dwordx4 v[120:123], v241, s[90:91] offset:2048
	global_load_dwordx4 v[124:127], v241, s[90:91] offset:2112
	s_add_u32 s90, s92, 0x11000
	s_addc_u32 s91, s93, 0
	global_load_dwordx4 v[128:131], v241, s[90:91]
	global_load_dwordx4 v[132:135], v241, s[90:91] offset:64
	global_load_dwordx4 v[136:139], v241, s[90:91] offset:2048
	global_load_dwordx4 v[228:231], v241, s[90:91] offset:2112
	s_waitcnt vmcnt(20)
; __device__ __forceinline__ unsigned f2bf(float f) { unsigned r; asm("v_cvt_pk_bf16_f32 %0, %1, %1" : "=v"(r) : "v"(f)); return r & 0xffffu; }
; template <bool FINAL>
; __device__ __forceinline__ void rg_item(PREF p, int l, int item, LAS unsigned char* wl, int lane) {
;     ...
;         for (int i = 0; i < 67; ++i) { const int t = t0 - 2 + i; const int tc = t < 0 ? 0 : (t >= seqlen ? seqlen - 1 : t); xv[i] = (t == tc) ? bf2f(xr_[i]) : 0.f; }
; #pragma unroll
;         for (int tt = 0; tt < 64; ++tt) { const float xc = xv[tt] * cw0 + xv[tt + 1] * cw1 + xv[tt + 2] * cw2 + xv[tt + 3] * cw3 + cb; sXc[tt * 72 + lane] = (bf16_t)f2bf(xc); }
	v_lshlrev_b32_e32 v158, 16, v158
	v_lshlrev_b32_e32 v159, 16, v159
	v_lshlrev_b32_e32 v160, 16, v160
	v_lshlrev_b32_e32 v161, 16, v161
	v_lshlrev_b32_e32 v162, 16, v162
	v_lshlrev_b32_e32 v163, 16, v163
	v_lshlrev_b32_e32 v164, 16, v164
	v_lshlrev_b32_e32 v165, 16, v165
	v_lshlrev_b32_e32 v166, 16, v166
	v_lshlrev_b32_e32 v167, 16, v167
	v_lshlrev_b32_e32 v168, 16, v168
	v_lshlrev_b32_e32 v169, 16, v169
	v_lshlrev_b32_e32 v170, 16, v170
	v_lshlrev_b32_e32 v171, 16, v171
	v_lshlrev_b32_e32 v172, 16, v172
	v_lshlrev_b32_e32 v173, 16, v173
	v_lshlrev_b32_e32 v174, 16, v174
	v_lshlrev_b32_e32 v175, 16, v175
	v_lshlrev_b32_e32 v176, 16, v176
	v_lshlrev_b32_e32 v177, 16, v177
	v_lshlrev_b32_e32 v178, 16, v178
	v_lshlrev_b32_e32 v179, 16, v179
	v_lshlrev_b32_e32 v180, 16, v180
	v_lshlrev_b32_e32 v181, 16, v181
	v_lshlrev_b32_e32 v182, 16, v182
	v_lshlrev_b32_e32 v183, 16, v183
	v_lshlrev_b32_e32 v184, 16, v184
	v_lshlrev_b32_e32 v185, 16, v185
	v_lshlrev_b32_e32 v186, 16, v186
	v_lshlrev_b32_e32 v187, 16, v187
	v_lshlrev_b32_e32 v188, 16, v188
	v_lshlrev_b32_e32 v189, 16, v189
	v_lshlrev_b32_e32 v190, 16, v190
	v_lshlrev_b32_e32 v191, 16, v191
	v_lshlrev_b32_e32 v192, 16, v192
	v_lshlrev_b32_e32 v193, 16, v193
	v_lshlrev_b32_e32 v194, 16, v194
	v_lshlrev_b32_e32 v195, 16, v195
	v_lshlrev_b32_e32 v196, 16, v196
	v_lshlrev_b32_e32 v197, 16, v197
	v_lshlrev_b32_e32 v198, 16, v198
	v_lshlrev_b32_e32 v199, 16, v199
	v_lshlrev_b32_e32 v200, 16, v200
	v_lshlrev_b32_e32 v201, 16, v201
	v_lshlrev_b32_e32 v202, 16, v202
	v_lshlrev_b32_e32 v203, 16, v203
	v_lshlrev_b32_e32 v204, 16, v204
	v_lshlrev_b32_e32 v205, 16, v205
	v_lshlrev_b32_e32 v206, 16, v206
	v_lshlrev_b32_e32 v207, 16, v207
	v_lshlrev_b32_e32 v208, 16, v208
	v_lshlrev_b32_e32 v209, 16, v209
	v_lshlrev_b32_e32 v210, 16, v210
	v_lshlrev_b32_e32 v211, 16, v211
	v_lshlrev_b32_e32 v212, 16, v212
	v_lshlrev_b32_e32 v213, 16, v213
	v_lshlrev_b32_e32 v214, 16, v214
	v_lshlrev_b32_e32 v215, 16, v215
	v_lshlrev_b32_e32 v216, 16, v216
	v_lshlrev_b32_e32 v217, 16, v217
	v_lshlrev_b32_e32 v218, 16, v218
	v_lshlrev_b32_e32 v219, 16, v219
	v_lshlrev_b32_e32 v222, 16, v222
	v_lshlrev_b32_e32 v223, 16, v223
	v_lshlrev_b32_e32 v140, 16, v140
	v_lshlrev_b32_e32 v141, 16, v141
	v_lshlrev_b32_e32 v232, 16, v232
	v_and_b32_e32 v158, s37, v158
	v_and_b32_e32 v159, s37, v159
	v_and_b32_e32 v232, s38, v232
	v_mul_f32_e32 v32, v41, v159
	v_mul_f32_e32 v33, v41, v160
	v_mul_f32_e32 v34, v41, v161
	v_mul_f32_e32 v35, v41, v162
	v_mul_f32_e32 v36, v41, v163
	v_mul_f32_e32 v37, v41, v164
	v_mul_f32_e32 v38, v41, v165
	v_mul_f32_e32 v39, v41, v166
	v_fmac_f32_e32 v32, v40, v158
	v_fmac_f32_e32 v33, v40, v159
	v_fmac_f32_e32 v34, v40, v160
	v_fmac_f32_e32 v35, v40, v161
	v_fmac_f32_e32 v36, v40, v162
	v_fmac_f32_e32 v37, v40, v163
	v_fmac_f32_e32 v38, v40, v164
	v_fmac_f32_e32 v39, v40, v165
	v_fmac_f32_e32 v32, v42, v160
	v_fmac_f32_e32 v33, v42, v161
	v_fmac_f32_e32 v34, v42, v162
	v_fmac_f32_e32 v35, v42, v163
	v_fmac_f32_e32 v36, v42, v164
	v_fmac_f32_e32 v37, v42, v165
	v_fmac_f32_e32 v38, v42, v166
	v_fmac_f32_e32 v39, v42, v167
	v_fmac_f32_e32 v32, v43, v161
	v_fmac_f32_e32 v33, v43, v162
	v_fmac_f32_e32 v34, v43, v163
	v_fmac_f32_e32 v35, v43, v164
	v_fmac_f32_e32 v36, v43, v165
	v_fmac_f32_e32 v37, v43, v166
	v_fmac_f32_e32 v38, v43, v167
	v_fmac_f32_e32 v39, v43, v168
	v_add_f32_e32 v32, v44, v32
	v_add_f32_e32 v33, v44, v33
	v_add_f32_e32 v34, v44, v34
	v_add_f32_e32 v35, v44, v35
	v_add_f32_e32 v36, v44, v36
	v_add_f32_e32 v37, v44, v37
	v_add_f32_e32 v38, v44, v38
	v_add_f32_e32 v39, v44, v39
	v_cvt_pk_bf16_f32 v32, v32, v33
	v_cvt_pk_bf16_f32 v34, v34, v35
	v_cvt_pk_bf16_f32 v36, v36, v37
	v_cvt_pk_bf16_f32 v38, v38, v39
	ds_write_b16 v240, v32 offset:0
	ds_write_b16_d16_hi v240, v32 offset:144
	ds_write_b16 v240, v34 offset:288
	ds_write_b16_d16_hi v240, v34 offset:432
	ds_write_b16 v240, v36 offset:576
	ds_write_b16_d16_hi v240, v36 offset:720
	ds_write_b16 v240, v38 offset:864
	ds_write_b16_d16_hi v240, v38 offset:1008
	v_mul_f32_e32 v32, v41, v167
	v_mul_f32_e32 v33, v41, v168
	v_mul_f32_e32 v34, v41, v169
	v_mul_f32_e32 v35, v41, v170
	v_mul_f32_e32 v36, v41, v171
	v_mul_f32_e32 v37, v41, v172
	v_mul_f32_e32 v38, v41, v173
	v_mul_f32_e32 v39, v41, v174
	v_fmac_f32_e32 v32, v40, v166
	v_fmac_f32_e32 v33, v40, v167
	v_fmac_f32_e32 v34, v40, v168
	v_fmac_f32_e32 v35, v40, v169
	v_fmac_f32_e32 v36, v40, v170
	v_fmac_f32_e32 v37, v40, v171
	v_fmac_f32_e32 v38, v40, v172
	v_fmac_f32_e32 v39, v40, v173
	v_fmac_f32_e32 v32, v42, v168
	v_fmac_f32_e32 v33, v42, v169
	v_fmac_f32_e32 v34, v42, v170
	v_fmac_f32_e32 v35, v42, v171
	v_fmac_f32_e32 v36, v42, v172
	v_fmac_f32_e32 v37, v42, v173
	v_fmac_f32_e32 v38, v42, v174
	v_fmac_f32_e32 v39, v42, v175
	v_fmac_f32_e32 v32, v43, v169
	v_fmac_f32_e32 v33, v43, v170
	v_fmac_f32_e32 v34, v43, v171
	v_fmac_f32_e32 v35, v43, v172
	v_fmac_f32_e32 v36, v43, v173
	v_fmac_f32_e32 v37, v43, v174
	v_fmac_f32_e32 v38, v43, v175
	v_fmac_f32_e32 v39, v43, v176
	v_add_f32_e32 v32, v44, v32
	v_add_f32_e32 v33, v44, v33
	v_add_f32_e32 v34, v44, v34
	v_add_f32_e32 v35, v44, v35
	v_add_f32_e32 v36, v44, v36
	v_add_f32_e32 v37, v44, v37
	v_add_f32_e32 v38, v44, v38
	v_add_f32_e32 v39, v44, v39
	v_cvt_pk_bf16_f32 v32, v32, v33
	v_cvt_pk_bf16_f32 v34, v34, v35
	v_cvt_pk_bf16_f32 v36, v36, v37
	v_cvt_pk_bf16_f32 v38, v38, v39
	ds_write_b16 v240, v32 offset:1152
	ds_write_b16_d16_hi v240, v32 offset:1296
	ds_write_b16 v240, v34 offset:1440
	ds_write_b16_d16_hi v240, v34 offset:1584
	ds_write_b16 v240, v36 offset:1728
	ds_write_b16_d16_hi v240, v36 offset:1872
	ds_write_b16 v240, v38 offset:2016
; __device__ __forceinline__ unsigned f2bf(float f) { unsigned r; asm("v_cvt_pk_bf16_f32 %0, %1, %1" : "=v"(r) : "v"(f)); return r & 0xffffu; }
; template <bool FINAL>
; __device__ __forceinline__ void rg_item(PREF p, int l, int item, LAS unsigned char* wl, int lane) {
;     ...
;         for (int i = 0; i < 67; ++i) { const int t = t0 - 2 + i; const int tc = t < 0 ? 0 : (t >= seqlen ? seqlen - 1 : t); xv[i] = (t == tc) ? bf2f(xr_[i]) : 0.f; }
; #pragma unroll
;         for (int tt = 0; tt < 64; ++tt) { const float xc = xv[tt] * cw0 + xv[tt + 1] * cw1 + xv[tt + 2] * cw2 + xv[tt + 3] * cw3 + cb; sXc[tt * 72 + lane] = (bf16_t)f2bf(xc); }
	ds_write_b16_d16_hi v240, v38 offset:2160
	v_mul_f32_e32 v32, v41, v175
	v_mul_f32_e32 v33, v41, v176
	v_mul_f32_e32 v34, v41, v177
	v_mul_f32_e32 v35, v41, v178
	v_mul_f32_e32 v36, v41, v179
	v_mul_f32_e32 v37, v41, v180
	v_mul_f32_e32 v38, v41, v181
	v_mul_f32_e32 v39, v41, v182
	v_fmac_f32_e32 v32, v40, v174
	v_fmac_f32_e32 v33, v40, v175
	v_fmac_f32_e32 v34, v40, v176
	v_fmac_f32_e32 v35, v40, v177
	v_fmac_f32_e32 v36, v40, v178
	v_fmac_f32_e32 v37, v40, v179
	v_fmac_f32_e32 v38, v40, v180
	v_fmac_f32_e32 v39, v40, v181
	v_fmac_f32_e32 v32, v42, v176
	v_fmac_f32_e32 v33, v42, v177
	v_fmac_f32_e32 v34, v42, v178
	v_fmac_f32_e32 v35, v42, v179
	v_fmac_f32_e32 v36, v42, v180
	v_fmac_f32_e32 v37, v42, v181
	v_fmac_f32_e32 v38, v42, v182
	v_fmac_f32_e32 v39, v42, v183
	v_fmac_f32_e32 v32, v43, v177
	v_fmac_f32_e32 v33, v43, v178
	v_fmac_f32_e32 v34, v43, v179
	v_fmac_f32_e32 v35, v43, v180
	v_fmac_f32_e32 v36, v43, v181
	v_fmac_f32_e32 v37, v43, v182
	v_fmac_f32_e32 v38, v43, v183
	v_fmac_f32_e32 v39, v43, v184
	v_add_f32_e32 v32, v44, v32
	v_add_f32_e32 v33, v44, v33
	v_add_f32_e32 v34, v44, v34
	v_add_f32_e32 v35, v44, v35
	v_add_f32_e32 v36, v44, v36
	v_add_f32_e32 v37, v44, v37
	v_add_f32_e32 v38, v44, v38
	v_add_f32_e32 v39, v44, v39
	v_cvt_pk_bf16_f32 v32, v32, v33
	v_cvt_pk_bf16_f32 v34, v34, v35
	v_cvt_pk_bf16_f32 v36, v36, v37
	v_cvt_pk_bf16_f32 v38, v38, v39
	ds_write_b16 v240, v32 offset:2304
	ds_write_b16_d16_hi v240, v32 offset:2448
	ds_write_b16 v240, v34 offset:2592
	ds_write_b16_d16_hi v240, v34 offset:2736
	ds_write_b16 v240, v36 offset:2880
	ds_write_b16_d16_hi v240, v36 offset:3024
	ds_write_b16 v240, v38 offset:3168
	ds_write_b16_d16_hi v240, v38 offset:3312
	v_mul_f32_e32 v32, v41, v183
	v_mul_f32_e32 v33, v41, v184
	v_mul_f32_e32 v34, v41, v185
	v_mul_f32_e32 v35, v41, v186
	v_mul_f32_e32 v36, v41, v187
	v_mul_f32_e32 v37, v41, v188
	v_mul_f32_e32 v38, v41, v189
	v_mul_f32_e32 v39, v41, v190
	v_fmac_f32_e32 v32, v40, v182
	v_fmac_f32_e32 v33, v40, v183
	v_fmac_f32_e32 v34, v40, v184
	v_fmac_f32_e32 v35, v40, v185
	v_fmac_f32_e32 v36, v40, v186
	v_fmac_f32_e32 v37, v40, v187
	v_fmac_f32_e32 v38, v40, v188
	v_fmac_f32_e32 v39, v40, v189
	v_fmac_f32_e32 v32, v42, v184
	v_fmac_f32_e32 v33, v42, v185
	v_fmac_f32_e32 v34, v42, v186
	v_fmac_f32_e32 v35, v42, v187
	v_fmac_f32_e32 v36, v42, v188
	v_fmac_f32_e32 v37, v42, v189
	v_fmac_f32_e32 v38, v42, v190
	v_fmac_f32_e32 v39, v42, v191
	v_fmac_f32_e32 v32, v43, v185
	v_fmac_f32_e32 v33, v43, v186
	v_fmac_f32_e32 v34, v43, v187
	v_fmac_f32_e32 v35, v43, v188
	v_fmac_f32_e32 v36, v43, v189
	v_fmac_f32_e32 v37, v43, v190
	v_fmac_f32_e32 v38, v43, v191
	v_fmac_f32_e32 v39, v43, v192
	v_add_f32_e32 v32, v44, v32
	v_add_f32_e32 v33, v44, v33
	v_add_f32_e32 v34, v44, v34
	v_add_f32_e32 v35, v44, v35
	v_add_f32_e32 v36, v44, v36
	v_add_f32_e32 v37, v44, v37
	v_add_f32_e32 v38, v44, v38
	v_add_f32_e32 v39, v44, v39
	v_cvt_pk_bf16_f32 v32, v32, v33
	v_cvt_pk_bf16_f32 v34, v34, v35
	v_cvt_pk_bf16_f32 v36, v36, v37
	v_cvt_pk_bf16_f32 v38, v38, v39
	ds_write_b16 v240, v32 offset:3456
	ds_write_b16_d16_hi v240, v32 offset:3600
	ds_write_b16 v240, v34 offset:3744
	ds_write_b16_d16_hi v240, v34 offset:3888
	ds_write_b16 v240, v36 offset:4032
	ds_write_b16_d16_hi v240, v36 offset:4176
	ds_write_b16 v240, v38 offset:4320
	ds_write_b16_d16_hi v240, v38 offset:4464
	v_mul_f32_e32 v32, v41, v191
	v_mul_f32_e32 v33, v41, v192
	v_mul_f32_e32 v34, v41, v193
	v_mul_f32_e32 v35, v41, v194
	v_mul_f32_e32 v36, v41, v195
	v_mul_f32_e32 v37, v41, v196
	v_mul_f32_e32 v38, v41, v197
	v_mul_f32_e32 v39, v41, v198
	v_fmac_f32_e32 v32, v40, v190
	v_fmac_f32_e32 v33, v40, v191
	v_fmac_f32_e32 v34, v40, v192
	v_fmac_f32_e32 v35, v40, v193
	v_fmac_f32_e32 v36, v40, v194
	v_fmac_f32_e32 v37, v40, v195
	v_fmac_f32_e32 v38, v40, v196
	v_fmac_f32_e32 v39, v40, v197
	v_fmac_f32_e32 v32, v42, v192
	v_fmac_f32_e32 v33, v42, v193
	v_fmac_f32_e32 v34, v42, v194
	v_fmac_f32_e32 v35, v42, v195
	v_fmac_f32_e32 v36, v42, v196
	v_fmac_f32_e32 v37, v42, v197
	v_fmac_f32_e32 v38, v42, v198
	v_fmac_f32_e32 v39, v42, v199
	v_fmac_f32_e32 v32, v43, v193
	v_fmac_f32_e32 v33, v43, v194
	v_fmac_f32_e32 v34, v43, v195
	v_fmac_f32_e32 v35, v43, v196
	v_fmac_f32_e32 v36, v43, v197
	v_fmac_f32_e32 v37, v43, v198
	v_fmac_f32_e32 v38, v43, v199
	v_fmac_f32_e32 v39, v43, v200
	v_add_f32_e32 v32, v44, v32
	v_add_f32_e32 v33, v44, v33
	v_add_f32_e32 v34, v44, v34
	v_add_f32_e32 v35, v44, v35
	v_add_f32_e32 v36, v44, v36
	v_add_f32_e32 v37, v44, v37
	v_add_f32_e32 v38, v44, v38
	v_add_f32_e32 v39, v44, v39
	v_cvt_pk_bf16_f32 v32, v32, v33
	v_cvt_pk_bf16_f32 v34, v34, v35
	v_cvt_pk_bf16_f32 v36, v36, v37
	v_cvt_pk_bf16_f32 v38, v38, v39
	ds_write_b16 v240, v32 offset:4608
	ds_write_b16_d16_hi v240, v32 offset:4752
	ds_write_b16 v240, v34 offset:4896
	ds_write_b16_d16_hi v240, v34 offset:5040
	ds_write_b16 v240, v36 offset:5184
	ds_write_b16_d16_hi v240, v36 offset:5328
	ds_write_b16 v240, v38 offset:5472
	ds_write_b16_d16_hi v240, v38 offset:5616
	v_mul_f32_e32 v32, v41, v199
	v_mul_f32_e32 v33, v41, v200
	v_mul_f32_e32 v34, v41, v201
	v_mul_f32_e32 v35, v41, v202
	v_mul_f32_e32 v36, v41, v203
	v_mul_f32_e32 v37, v41, v204
	v_mul_f32_e32 v38, v41, v205
	v_mul_f32_e32 v39, v41, v206
	v_fmac_f32_e32 v32, v40, v198
	v_fmac_f32_e32 v33, v40, v199
	v_fmac_f32_e32 v34, v40, v200
	v_fmac_f32_e32 v35, v40, v201
	v_fmac_f32_e32 v36, v40, v202
	v_fmac_f32_e32 v37, v40, v203
	v_fmac_f32_e32 v38, v40, v204
	v_fmac_f32_e32 v39, v40, v205
	v_fmac_f32_e32 v32, v42, v200
	v_fmac_f32_e32 v33, v42, v201
	v_fmac_f32_e32 v34, v42, v202
	v_fmac_f32_e32 v35, v42, v203
; __device__ __forceinline__ unsigned f2bf(float f) { unsigned r; asm("v_cvt_pk_bf16_f32 %0, %1, %1" : "=v"(r) : "v"(f)); return r & 0xffffu; }
; __device__ __forceinline__ float rcpf_(float x) { return __builtin_amdgcn_rcpf(x); }
; template <bool FINAL, int D>
; __device__ __forceinline__ void rg_dir(PREF p, int l, int h, int ch, int sidx, int rowbase  , LAS bf16_t* sXc, LAS float* stg, int lane) {
;     ...
;     const float ba = p.rg_ba[(l * 2 + D) * 512 + ch], bi = p.rg_bi[(l * 2 + D) * 512 + ch], lam = p.rg_lam[(l * 2 + D) * 512 + ch];
;     const float e_ = __expf(-lam), u_ = 1.f + e_;
;     const float l1p = (u_ == 1.f) ? e_ : __logf(u_) * e_ * rcpf_(u_ - 1.f);
;     const float sp8 = -8.f * 1.4426950408889634f * l1p;
;     float hc = FINAL ? RGC[sidx] : 0.f, Ap = 1.f;
; template <bool FINAL>
; __device__ __forceinline__ void rg_item(PREF p, int l, int item, LAS unsigned char* wl, int lane) {
;     ...
;         for (int i = 0; i < 67; ++i) { const int t = t0 - 2 + i; const int tc = t < 0 ? 0 : (t >= seqlen ? seqlen - 1 : t); xv[i] = (t == tc) ? bf2f(xr_[i]) : 0.f; }
; #pragma unroll
;         for (int tt = 0; tt < 64; ++tt) { const float xc = xv[tt] * cw0 + xv[tt + 1] * cw1 + xv[tt + 2] * cw2 + xv[tt + 3] * cw3 + cb; sXc[tt * 72 + lane] = (bf16_t)f2bf(xc); }
	v_fmac_f32_e32 v36, v42, v204
	v_fmac_f32_e32 v37, v42, v205
	v_fmac_f32_e32 v38, v42, v206
	v_fmac_f32_e32 v39, v42, v207
	v_fmac_f32_e32 v32, v43, v201
	v_fmac_f32_e32 v33, v43, v202
	v_fmac_f32_e32 v34, v43, v203
	v_fmac_f32_e32 v35, v43, v204
	v_fmac_f32_e32 v36, v43, v205
	v_fmac_f32_e32 v37, v43, v206
	v_fmac_f32_e32 v38, v43, v207
	v_fmac_f32_e32 v39, v43, v208
	v_add_f32_e32 v32, v44, v32
	v_add_f32_e32 v33, v44, v33
	v_add_f32_e32 v34, v44, v34
	v_add_f32_e32 v35, v44, v35
	v_add_f32_e32 v36, v44, v36
	v_add_f32_e32 v37, v44, v37
	v_add_f32_e32 v38, v44, v38
	v_add_f32_e32 v39, v44, v39
	v_cvt_pk_bf16_f32 v32, v32, v33
	v_cvt_pk_bf16_f32 v34, v34, v35
	v_cvt_pk_bf16_f32 v36, v36, v37
	v_cvt_pk_bf16_f32 v38, v38, v39
	ds_write_b16 v240, v32 offset:5760
	ds_write_b16_d16_hi v240, v32 offset:5904
	ds_write_b16 v240, v34 offset:6048
	ds_write_b16_d16_hi v240, v34 offset:6192
	ds_write_b16 v240, v36 offset:6336
	ds_write_b16_d16_hi v240, v36 offset:6480
	ds_write_b16 v240, v38 offset:6624
	ds_write_b16_d16_hi v240, v38 offset:6768
	v_mul_f32_e32 v32, v41, v207
	v_mul_f32_e32 v33, v41, v208
	v_mul_f32_e32 v34, v41, v209
	v_mul_f32_e32 v35, v41, v210
	v_mul_f32_e32 v36, v41, v211
	v_mul_f32_e32 v37, v41, v212
	v_mul_f32_e32 v38, v41, v213
	v_mul_f32_e32 v39, v41, v214
	v_fmac_f32_e32 v32, v40, v206
	v_fmac_f32_e32 v33, v40, v207
	v_fmac_f32_e32 v34, v40, v208
	v_fmac_f32_e32 v35, v40, v209
	v_fmac_f32_e32 v36, v40, v210
	v_fmac_f32_e32 v37, v40, v211
	v_fmac_f32_e32 v38, v40, v212
	v_fmac_f32_e32 v39, v40, v213
	v_fmac_f32_e32 v32, v42, v208
	v_fmac_f32_e32 v33, v42, v209
	v_fmac_f32_e32 v34, v42, v210
	v_fmac_f32_e32 v35, v42, v211
	v_fmac_f32_e32 v36, v42, v212
	v_fmac_f32_e32 v37, v42, v213
	v_fmac_f32_e32 v38, v42, v214
	v_fmac_f32_e32 v39, v42, v215
	v_fmac_f32_e32 v32, v43, v209
	v_fmac_f32_e32 v33, v43, v210
	v_fmac_f32_e32 v34, v43, v211
	v_fmac_f32_e32 v35, v43, v212
	v_fmac_f32_e32 v36, v43, v213
	v_fmac_f32_e32 v37, v43, v214
	v_fmac_f32_e32 v38, v43, v215
	v_fmac_f32_e32 v39, v43, v216
	v_add_f32_e32 v32, v44, v32
	v_add_f32_e32 v33, v44, v33
	v_add_f32_e32 v34, v44, v34
	v_add_f32_e32 v35, v44, v35
	v_add_f32_e32 v36, v44, v36
	v_add_f32_e32 v37, v44, v37
	v_add_f32_e32 v38, v44, v38
	v_add_f32_e32 v39, v44, v39
	v_cvt_pk_bf16_f32 v32, v32, v33
	v_cvt_pk_bf16_f32 v34, v34, v35
	v_cvt_pk_bf16_f32 v36, v36, v37
	v_cvt_pk_bf16_f32 v38, v38, v39
	ds_write_b16 v240, v32 offset:6912
	ds_write_b16_d16_hi v240, v32 offset:7056
	ds_write_b16 v240, v34 offset:7200
	ds_write_b16_d16_hi v240, v34 offset:7344
	ds_write_b16 v240, v36 offset:7488
	ds_write_b16_d16_hi v240, v36 offset:7632
	ds_write_b16 v240, v38 offset:7776
	ds_write_b16_d16_hi v240, v38 offset:7920
	v_mul_f32_e32 v32, v41, v215
	v_mul_f32_e32 v33, v41, v216
	v_mul_f32_e32 v34, v41, v217
	v_mul_f32_e32 v35, v41, v218
	v_mul_f32_e32 v36, v41, v219
	v_mul_f32_e32 v37, v41, v222
	v_mul_f32_e32 v38, v41, v223
	v_mul_f32_e32 v39, v41, v140
	v_fmac_f32_e32 v32, v40, v214
	v_fmac_f32_e32 v33, v40, v215
	v_fmac_f32_e32 v34, v40, v216
	v_fmac_f32_e32 v35, v40, v217
	v_fmac_f32_e32 v36, v40, v218
	v_fmac_f32_e32 v37, v40, v219
	v_fmac_f32_e32 v38, v40, v222
	v_fmac_f32_e32 v39, v40, v223
	v_fmac_f32_e32 v32, v42, v216
	v_fmac_f32_e32 v33, v42, v217
	v_fmac_f32_e32 v34, v42, v218
	v_fmac_f32_e32 v35, v42, v219
	v_fmac_f32_e32 v36, v42, v222
	v_fmac_f32_e32 v37, v42, v223
	v_fmac_f32_e32 v38, v42, v140
	v_fmac_f32_e32 v39, v42, v141
	v_fmac_f32_e32 v32, v43, v217
	v_fmac_f32_e32 v33, v43, v218
	v_fmac_f32_e32 v34, v43, v219
	v_fmac_f32_e32 v35, v43, v222
	v_fmac_f32_e32 v36, v43, v223
	v_fmac_f32_e32 v37, v43, v140
	v_fmac_f32_e32 v38, v43, v141
	v_fmac_f32_e32 v39, v43, v232
	v_add_f32_e32 v32, v44, v32
	v_add_f32_e32 v33, v44, v33
	v_add_f32_e32 v34, v44, v34
	v_add_f32_e32 v35, v44, v35
	v_add_f32_e32 v36, v44, v36
	v_add_f32_e32 v37, v44, v37
	v_add_f32_e32 v38, v44, v38
	v_add_f32_e32 v39, v44, v39
	v_cvt_pk_bf16_f32 v32, v32, v33
	v_cvt_pk_bf16_f32 v34, v34, v35
	v_cvt_pk_bf16_f32 v36, v36, v37
	v_cvt_pk_bf16_f32 v38, v38, v39
	ds_write_b16 v240, v32 offset:8064
	ds_write_b16_d16_hi v240, v32 offset:8208
	ds_write_b16 v240, v34 offset:8352
	ds_write_b16_d16_hi v240, v34 offset:8496
	ds_write_b16 v240, v36 offset:8640
	ds_write_b16_d16_hi v240, v36 offset:8784
	ds_write_b16 v240, v38 offset:8928
	ds_write_b16_d16_hi v240, v38 offset:9072
	v_mov_b32_e32 v248, 0xbfb8aa3b
	v_mov_b32_e32 v249, 0xbfb8aa3b
	v_mov_b32_e32 v140, 0x3d372713
	v_mov_b32_e32 v141, 0x3d372713
	s_waitcnt vmcnt(16)
	s_mov_b32 s8, 0x800000
	s_mov_b32 s9, 0x3f317217
	s_mov_b32 s14, 0x7f800000
	v_mul_f32_e32 v32, 0xbfb8aa3b, v45
	v_exp_f32_e32 v32, v32
	s_nop 0
	v_add_f32_e32 v33, 1.0, v32
	v_cmp_gt_f32_e32 vcc, s8, v33
	s_nop 1
	v_cndmask_b32_e64 v34, 0, 32, vcc
	v_ldexp_f32 v34, v33, v34
	v_log_f32_e32 v34, v34
	v_cndmask_b32_e32 v36, 0, v226, vcc
	v_cmp_eq_f32_e32 vcc, 1.0, v33
	v_mul_f32_e32 v35, 0x3f317217, v34
	v_fma_f32 v35, v34, s9, -v35
	v_fmac_f32_e32 v35, 0x3377d1cf, v34
	v_fmac_f32_e32 v35, 0x3f317217, v34
	v_cmp_lt_f32_e64 s[10:11], |v34|, s14
	s_nop 1
	v_cndmask_b32_e64 v34, v34, v35, s[10:11]
	v_add_f32_e32 v35, -1.0, v33
	v_rcp_f32_e32 v35, v35
	v_sub_f32_e32 v34, v34, v36
	v_mul_f32_e32 v34, v32, v34
	v_mul_f32_e32 v34, v34, v35
	v_cndmask_b32_e32 v32, v34, v32, vcc
	v_mul_f32_e32 v246, 0xc138aa3b, v32
	v_mov_b32_e32 v247, v246
	v_mov_b32_e32 v242, v46
	v_mov_b32_e32 v243, v46
	v_mov_b32_e32 v244, v47
	v_mov_b32_e32 v245, v47
	s_waitcnt vmcnt(0)
; #define LAS __attribute__((address_space(3)))
; #define WAVE_SYNC() asm volatile("s_waitcnt lgkmcnt(0)" ::: "memory")
; __device__ __forceinline__ f32x4 mfma16(bf16x8 a, bf16x8 b, f32x4 c) { return __builtin_amdgcn_mfma_f32_16x16x32_bf16(a, b, c, 0, 0, 0); }
; template <bool FINAL, int D>
; __device__ __forceinline__ void rg_dir(PREF p, int l, int h, int ch, int sidx, int rowbase  , LAS bf16_t* sXc, LAS float* stg, int lane) {
;     ...
;             for (int ti = 0; ti < 16; ++ti) { const size_t row = (size_t)(rowbase + mt * 16 + 15 - ti); grv[ti] = __builtin_bit_cast(float, (unsigned)P[row * PW + 512 + ch]); hfv[ti] = __builtin_bit_cast(float, (unsigned)TMP[row * 512 + ch]); }
;     ...
;         const bf16x8 A0 = *(const LAS bf16x8*)(sXc + (mt * 16 + (lane & 15)) * 72 + (lane >> 4) * 8), A1 = *(const LAS bf16x8*)(sXc + (mt * 16 + (lane & 15)) * 72 + 32 + (lane >> 4) * 8);
;         f32x4 ar[4], ai[4];
; #pragma unroll
;         for (int nt = 0; nt < 4; ++nt) { const f32x4 z = {0.f, 0.f, 0.f, 0.f};
;             ar[nt] = mfma16(A0, Br[nt][0], z); ar[nt] = mfma16(A1, Br[nt][1], ar[nt]); ai[nt] = mfma16(A0, Bi[nt][0], z); ai[nt] = mfma16(A1, Bi[nt][1], ai[nt]); }
;         WAVE_SYNC();
; #pragma unroll
;         for (int nt = 0; nt < 4; ++nt)
; #pragma unroll
;             for (int j = 0; j < 4; ++j) { const int o = ((lane >> 4) * 4 + j) * 64 + nt * 16 + (lane & 15); stg[o] = ar[nt][j]; stg[1024 + o] = ai[nt][j]; }
;         WAVE_SYNC();
;         float av[16], iv[16];
; #pragma unroll
;         for (int ti = 0; ti < 16; ++ti) { const int tk = D ? 15 - ti : ti;
;             const float zr = stg[tk * 64 + lane] + ba, zi = stg[1024 + tk * 64 + lane] + bi;
	s_add_i32 s39, s15, 48
	s_mul_hi_u32 s83, s39, 0x1600
	s_mul_i32 s82, s39, 0x1600
	s_add_u32 s82, s82, s0
	s_addc_u32 s83, s83, s1
	s_add_u32 s82, s82, 0xbc00400
	s_addc_u32 s83, s83, 0
	global_load_ushort v190, v234, s[82:83]
	s_add_u32 s82, s82, 0x1600
	s_addc_u32 s83, s83, 0
	global_load_ushort v191, v234, s[82:83]
	s_add_u32 s82, s82, 0x1600
	s_addc_u32 s83, s83, 0
	global_load_ushort v192, v234, s[82:83]
	s_add_u32 s82, s82, 0x1600
	s_addc_u32 s83, s83, 0
	global_load_ushort v193, v234, s[82:83]
	s_add_u32 s82, s82, 0x1600
	s_addc_u32 s83, s83, 0
	global_load_ushort v194, v234, s[82:83]
	s_add_u32 s82, s82, 0x1600
	s_addc_u32 s83, s83, 0
	global_load_ushort v195, v234, s[82:83]
	s_add_u32 s82, s82, 0x1600
	s_addc_u32 s83, s83, 0
	global_load_ushort v196, v234, s[82:83]
	s_add_u32 s82, s82, 0x1600
	s_addc_u32 s83, s83, 0
	global_load_ushort v197, v234, s[82:83]
	s_add_u32 s82, s82, 0x1600
	s_addc_u32 s83, s83, 0
	global_load_ushort v198, v234, s[82:83]
	s_add_u32 s82, s82, 0x1600
	s_addc_u32 s83, s83, 0
	global_load_ushort v199, v234, s[82:83]
	s_add_u32 s82, s82, 0x1600
	s_addc_u32 s83, s83, 0
	global_load_ushort v200, v234, s[82:83]
	s_add_u32 s82, s82, 0x1600
	s_addc_u32 s83, s83, 0
	global_load_ushort v201, v234, s[82:83]
	s_add_u32 s82, s82, 0x1600
	s_addc_u32 s83, s83, 0
	global_load_ushort v202, v234, s[82:83]
	s_add_u32 s82, s82, 0x1600
	s_addc_u32 s83, s83, 0
	global_load_ushort v203, v234, s[82:83]
	s_add_u32 s82, s82, 0x1600
	s_addc_u32 s83, s83, 0
	global_load_ushort v204, v234, s[82:83]
	s_add_u32 s82, s82, 0x1600
	s_addc_u32 s83, s83, 0
	global_load_ushort v205, v234, s[82:83]
	ds_read_b128 v[32:35], v236 offset:0
	ds_read_b128 v[36:39], v236 offset:64
	s_waitcnt lgkmcnt(0)
	v_mfma_f32_16x16x32_bf16 v[0:3], v[32:35], v[80:83], 0
	v_mfma_f32_16x16x32_bf16 v[4:7], v[32:35], v[88:91], 0
	v_mfma_f32_16x16x32_bf16 v[8:11], v[32:35], v[96:99], 0
	v_mfma_f32_16x16x32_bf16 v[12:15], v[32:35], v[104:107], 0
	v_mfma_f32_16x16x32_bf16 v[16:19], v[32:35], v[112:115], 0
	v_mfma_f32_16x16x32_bf16 v[20:23], v[32:35], v[120:123], 0
	v_mfma_f32_16x16x32_bf16 v[24:27], v[32:35], v[128:131], 0
	v_mfma_f32_16x16x32_bf16 v[28:31], v[32:35], v[136:139], 0
	v_mfma_f32_16x16x32_bf16 v[0:3], v[36:39], v[84:87], v[0:3]
	v_mfma_f32_16x16x32_bf16 v[4:7], v[36:39], v[92:95], v[4:7]
	v_mfma_f32_16x16x32_bf16 v[8:11], v[36:39], v[100:103], v[8:11]
	v_mfma_f32_16x16x32_bf16 v[12:15], v[36:39], v[108:111], v[12:15]
	v_mfma_f32_16x16x32_bf16 v[16:19], v[36:39], v[116:119], v[16:19]
	v_mfma_f32_16x16x32_bf16 v[20:23], v[36:39], v[124:127], v[20:23]
	v_mfma_f32_16x16x32_bf16 v[24:27], v[36:39], v[132:135], v[24:27]
	v_mfma_f32_16x16x32_bf16 v[28:31], v[36:39], v[228:231], v[28:31]
	s_nop 3
	ds_write2_b32 v237, v0, v4 offset0:0 offset1:16
	ds_write2_b32 v237, v8, v12 offset0:32 offset1:48
	ds_write2_b32 v237, v1, v5 offset0:64 offset1:80
	ds_write2_b32 v237, v9, v13 offset0:96 offset1:112
	ds_write2_b32 v237, v2, v6 offset0:128 offset1:144
	ds_write2_b32 v237, v10, v14 offset0:160 offset1:176
	ds_write2_b32 v237, v3, v7 offset0:192 offset1:208
	ds_write2_b32 v237, v11, v15 offset0:224 offset1:240
	ds_write2_b32 v238, v16, v20 offset0:0 offset1:16
	ds_write2_b32 v238, v24, v28 offset0:32 offset1:48
	ds_write2_b32 v238, v17, v21 offset0:64 offset1:80
	ds_write2_b32 v238, v25, v29 offset0:96 offset1:112
	ds_write2_b32 v238, v18, v22 offset0:128 offset1:144
	ds_write2_b32 v238, v26, v30 offset0:160 offset1:176
	ds_write2_b32 v238, v19, v23 offset0:192 offset1:208
	ds_write2_b32 v238, v27, v31 offset0:224 offset1:240
	s_waitcnt lgkmcnt(0)
	ds_read2st64_b32 v[0:1], v239 offset0:36 offset1:37
	ds_read2st64_b32 v[2:3], v239 offset0:38 offset1:39
	ds_read2st64_b32 v[4:5], v239 offset0:40 offset1:41
	ds_read2st64_b32 v[6:7], v239 offset0:42 offset1:43
	ds_read2st64_b32 v[8:9], v239 offset0:44 offset1:45
	ds_read2st64_b32 v[10:11], v239 offset0:46 offset1:47
	ds_read2st64_b32 v[12:13], v239 offset0:48 offset1:49
	ds_read2st64_b32 v[14:15], v239 offset0:50 offset1:51
	ds_read2st64_b32 v[16:17], v239 offset0:52 offset1:53
	ds_read2st64_b32 v[18:19], v239 offset0:54 offset1:55
	ds_read2st64_b32 v[20:21], v239 offset0:56 offset1:57
	ds_read2st64_b32 v[22:23], v239 offset0:58 offset1:59
	ds_read2st64_b32 v[24:25], v239 offset0:60 offset1:61
	ds_read2st64_b32 v[26:27], v239 offset0:62 offset1:63
	ds_read2st64_b32 v[28:29], v239 offset0:64 offset1:65
	ds_read2st64_b32 v[30:31], v239 offset0:66 offset1:67
	ds_read_u16 v48, v240 offset:0
	ds_read_u16 v49, v240 offset:144
	ds_read_u16 v50, v240 offset:288
	ds_read_u16 v51, v240 offset:432
	ds_read_u16 v52, v240 offset:576
	ds_read_u16 v53, v240 offset:720
	ds_read_u16 v54, v240 offset:864
	ds_read_u16 v55, v240 offset:1008
	ds_read_u16 v56, v240 offset:1152
	ds_read_u16 v57, v240 offset:1296
	ds_read_u16 v58, v240 offset:1440
	ds_read_u16 v59, v240 offset:1584
	ds_read_u16 v60, v240 offset:1728
	ds_read_u16 v61, v240 offset:1872
	ds_read_u16 v62, v240 offset:2016
	ds_read_u16 v63, v240 offset:2160
	s_waitcnt lgkmcnt(0)
; __device__ __forceinline__ float sigmoid_f(float x) { return rcpf_(1.f + __expf(-x)); }
; template <bool FINAL, int D>
; __device__ __forceinline__ void rg_dir(PREF p, int l, int h, int ch, int sidx, int rowbase  , LAS bf16_t* sXc, LAS float* stg, int lane) {
;     ...
;         for (int ti = 0; ti < 16; ++ti) { const int tk = D ? 15 - ti : ti;
;             const float zr = stg[tk * 64 + lane] + ba, zi = stg[1024 + tk * 64 + lane] + bi;
;             const float r = sigmoid_f(zr), ig = sigmoid_f(zi);
;             const float a = __builtin_amdgcn_exp2f(r * sp8);
;             const float xc = bf2f(sXc[(mt * 16 + tk) * 72 + lane]);
;             av[ti] = a; iv[ti] = __builtin_amdgcn_sqrtf(fmaxf(1.f - a * a, 0.f)) * ig * xc;
	v_pk_add_f32 v[0:1], v[242:243], v[0:1]
	v_pk_add_f32 v[2:3], v[242:243], v[2:3]
	v_pk_add_f32 v[4:5], v[242:243], v[4:5]
	v_pk_add_f32 v[6:7], v[242:243], v[6:7]
	v_pk_add_f32 v[8:9], v[242:243], v[8:9]
	v_pk_add_f32 v[10:11], v[242:243], v[10:11]
	v_pk_add_f32 v[12:13], v[242:243], v[12:13]
	v_pk_add_f32 v[14:15], v[242:243], v[14:15]
	v_pk_add_f32 v[16:17], v[244:245], v[16:17]
	v_pk_add_f32 v[18:19], v[244:245], v[18:19]
	v_pk_add_f32 v[20:21], v[244:245], v[20:21]
	v_pk_add_f32 v[22:23], v[244:245], v[22:23]
	v_pk_add_f32 v[24:25], v[244:245], v[24:25]
	v_pk_add_f32 v[26:27], v[244:245], v[26:27]
	v_pk_add_f32 v[28:29], v[244:245], v[28:29]
	v_pk_add_f32 v[30:31], v[244:245], v[30:31]
	v_pk_mul_f32 v[0:1], v[248:249], v[0:1]
	v_pk_mul_f32 v[2:3], v[248:249], v[2:3]
	v_pk_mul_f32 v[4:5], v[248:249], v[4:5]
	v_pk_mul_f32 v[6:7], v[248:249], v[6:7]
	v_pk_mul_f32 v[8:9], v[248:249], v[8:9]
	v_pk_mul_f32 v[10:11], v[248:249], v[10:11]
	v_pk_mul_f32 v[12:13], v[248:249], v[12:13]
	v_pk_mul_f32 v[14:15], v[248:249], v[14:15]
	v_pk_mul_f32 v[16:17], v[248:249], v[16:17]
	v_pk_mul_f32 v[18:19], v[248:249], v[18:19]
	v_pk_mul_f32 v[20:21], v[248:249], v[20:21]
	v_pk_mul_f32 v[22:23], v[248:249], v[22:23]
	v_pk_mul_f32 v[24:25], v[248:249], v[24:25]
	v_pk_mul_f32 v[26:27], v[248:249], v[26:27]
	v_pk_mul_f32 v[28:29], v[248:249], v[28:29]
	v_pk_mul_f32 v[30:31], v[248:249], v[30:31]
	v_exp_f32_e32 v0, v0
	v_exp_f32_e32 v1, v1
	v_exp_f32_e32 v2, v2
	v_exp_f32_e32 v3, v3
	v_exp_f32_e32 v4, v4
	v_exp_f32_e32 v5, v5
	v_exp_f32_e32 v6, v6
	v_exp_f32_e32 v7, v7
	v_exp_f32_e32 v8, v8
	v_exp_f32_e32 v9, v9
	v_exp_f32_e32 v10, v10
	v_exp_f32_e32 v11, v11
	v_exp_f32_e32 v12, v12
	v_exp_f32_e32 v13, v13
	v_exp_f32_e32 v14, v14
	v_exp_f32_e32 v15, v15
	v_exp_f32_e32 v16, v16
	v_exp_f32_e32 v17, v17
	v_exp_f32_e32 v18, v18
	v_exp_f32_e32 v19, v19
	v_exp_f32_e32 v20, v20
	v_exp_f32_e32 v21, v21
	v_exp_f32_e32 v22, v22
	v_exp_f32_e32 v23, v23
	v_exp_f32_e32 v24, v24
	v_exp_f32_e32 v25, v25
	v_exp_f32_e32 v26, v26
	v_exp_f32_e32 v27, v27
	v_exp_f32_e32 v28, v28
	v_exp_f32_e32 v29, v29
	v_exp_f32_e32 v30, v30
	v_exp_f32_e32 v31, v31
	v_pk_add_f32 v[0:1], v[0:1], 1.0 op_sel_hi:[1,0]
	v_pk_add_f32 v[2:3], v[2:3], 1.0 op_sel_hi:[1,0]
	v_pk_add_f32 v[4:5], v[4:5], 1.0 op_sel_hi:[1,0]
	v_pk_add_f32 v[6:7], v[6:7], 1.0 op_sel_hi:[1,0]
	v_pk_add_f32 v[8:9], v[8:9], 1.0 op_sel_hi:[1,0]
	v_pk_add_f32 v[10:11], v[10:11], 1.0 op_sel_hi:[1,0]
	v_pk_add_f32 v[12:13], v[12:13], 1.0 op_sel_hi:[1,0]
	v_pk_add_f32 v[14:15], v[14:15], 1.0 op_sel_hi:[1,0]
	v_pk_add_f32 v[16:17], v[16:17], 1.0 op_sel_hi:[1,0]
	v_pk_add_f32 v[18:19], v[18:19], 1.0 op_sel_hi:[1,0]
	v_pk_add_f32 v[20:21], v[20:21], 1.0 op_sel_hi:[1,0]
	v_pk_add_f32 v[22:23], v[22:23], 1.0 op_sel_hi:[1,0]
	v_pk_add_f32 v[24:25], v[24:25], 1.0 op_sel_hi:[1,0]
	v_pk_add_f32 v[26:27], v[26:27], 1.0 op_sel_hi:[1,0]
	v_pk_add_f32 v[28:29], v[28:29], 1.0 op_sel_hi:[1,0]
	v_pk_add_f32 v[30:31], v[30:31], 1.0 op_sel_hi:[1,0]
	v_rcp_f32_e32 v0, v0
	v_rcp_f32_e32 v1, v1
	v_rcp_f32_e32 v2, v2
	v_rcp_f32_e32 v3, v3
	v_rcp_f32_e32 v4, v4
	v_rcp_f32_e32 v5, v5
	v_rcp_f32_e32 v6, v6
	v_rcp_f32_e32 v7, v7
	v_rcp_f32_e32 v8, v8
	v_rcp_f32_e32 v9, v9
	v_rcp_f32_e32 v10, v10
	v_rcp_f32_e32 v11, v11
	v_rcp_f32_e32 v12, v12
	v_rcp_f32_e32 v13, v13
	v_rcp_f32_e32 v14, v14
	v_rcp_f32_e32 v15, v15
	v_rcp_f32_e32 v16, v16
	v_rcp_f32_e32 v17, v17
	v_rcp_f32_e32 v18, v18
	v_rcp_f32_e32 v19, v19
	v_rcp_f32_e32 v20, v20
	v_rcp_f32_e32 v21, v21
	v_rcp_f32_e32 v22, v22
	v_rcp_f32_e32 v23, v23
	v_rcp_f32_e32 v24, v24
	v_rcp_f32_e32 v25, v25
	v_rcp_f32_e32 v26, v26
	v_rcp_f32_e32 v27, v27
	v_rcp_f32_e32 v28, v28
	v_rcp_f32_e32 v29, v29
	v_rcp_f32_e32 v30, v30
	v_rcp_f32_e32 v31, v31
	v_pk_mul_f32 v[0:1], v[246:247], v[0:1]
	v_pk_mul_f32 v[2:3], v[246:247], v[2:3]
	v_pk_mul_f32 v[4:5], v[246:247], v[4:5]
	v_pk_mul_f32 v[6:7], v[246:247], v[6:7]
	v_pk_mul_f32 v[8:9], v[246:247], v[8:9]
	v_pk_mul_f32 v[10:11], v[246:247], v[10:11]
	v_pk_mul_f32 v[12:13], v[246:247], v[12:13]
	v_pk_mul_f32 v[14:15], v[246:247], v[14:15]
	v_lshlrev_b32_e32 v48, 16, v48
	v_lshlrev_b32_e32 v49, 16, v49
	v_lshlrev_b32_e32 v50, 16, v50
	v_lshlrev_b32_e32 v51, 16, v51
	v_lshlrev_b32_e32 v52, 16, v52
	v_lshlrev_b32_e32 v53, 16, v53
	v_lshlrev_b32_e32 v54, 16, v54
	v_lshlrev_b32_e32 v55, 16, v55
	v_lshlrev_b32_e32 v56, 16, v56
	v_lshlrev_b32_e32 v57, 16, v57
	v_lshlrev_b32_e32 v58, 16, v58
	v_lshlrev_b32_e32 v59, 16, v59
	v_lshlrev_b32_e32 v60, 16, v60
	v_lshlrev_b32_e32 v61, 16, v61
	v_lshlrev_b32_e32 v62, 16, v62
	v_lshlrev_b32_e32 v63, 16, v63
	v_exp_f32_e32 v0, v0
	v_exp_f32_e32 v1, v1
	v_exp_f32_e32 v2, v2
	v_exp_f32_e32 v3, v3
	v_exp_f32_e32 v4, v4
	v_exp_f32_e32 v5, v5
	v_exp_f32_e32 v6, v6
	v_exp_f32_e32 v7, v7
	v_exp_f32_e32 v8, v8
	v_exp_f32_e32 v9, v9
	v_exp_f32_e32 v10, v10
	v_exp_f32_e32 v11, v11
	v_exp_f32_e32 v12, v12
	v_exp_f32_e32 v13, v13
	v_exp_f32_e32 v14, v14
	v_exp_f32_e32 v15, v15
	v_fma_f32 v32, -v0, v0, 1.0
	v_fma_f32 v33, -v1, v1, 1.0
	v_fma_f32 v34, -v2, v2, 1.0
	v_fma_f32 v35, -v3, v3, 1.0
	v_fma_f32 v36, -v4, v4, 1.0
	v_fma_f32 v37, -v5, v5, 1.0
	v_fma_f32 v38, -v6, v6, 1.0
	v_fma_f32 v39, -v7, v7, 1.0
	v_fma_f32 v40, -v8, v8, 1.0
	v_fma_f32 v41, -v9, v9, 1.0
	v_fma_f32 v42, -v10, v10, 1.0
	v_fma_f32 v43, -v11, v11, 1.0
	v_fma_f32 v44, -v12, v12, 1.0
	v_fma_f32 v45, -v13, v13, 1.0
	v_fma_f32 v46, -v14, v14, 1.0
	v_fma_f32 v47, -v15, v15, 1.0
	v_max_f32_e32 v32, 0, v32
	v_max_f32_e32 v33, 0, v33
	v_max_f32_e32 v34, 0, v34
	v_max_f32_e32 v35, 0, v35
	v_max_f32_e32 v36, 0, v36
	v_max_f32_e32 v37, 0, v37
	v_max_f32_e32 v38, 0, v38
	v_max_f32_e32 v39, 0, v39
; __device__ __forceinline__ unsigned f2bf(float f) { unsigned r; asm("v_cvt_pk_bf16_f32 %0, %1, %1" : "=v"(r) : "v"(f)); return r & 0xffffu; }
; __device__ __forceinline__ float sigmoid_f(float x) { return rcpf_(1.f + __expf(-x)); }
; __device__ __forceinline__ float gelu_tanh_f(float x) { const float y = 0.7978845608028654f * (x + 0.044715f * x * x * x); return x * sigmoid_f(2.f * y); }
; template <bool FINAL, int D>
; __device__ __forceinline__ void rg_dir(PREF p, int l, int h, int ch, int sidx, int rowbase  , LAS bf16_t* sXc, LAS float* stg, int lane) {
;     ...
;         for (int ti = 0; ti < 16; ++ti) { const int tk = D ? 15 - ti : ti;
;             const float zr = stg[tk * 64 + lane] + ba, zi = stg[1024 + tk * 64 + lane] + bi;
;             const float r = sigmoid_f(zr), ig = sigmoid_f(zi);
;             const float a = __builtin_amdgcn_exp2f(r * sp8);
;             const float xc = bf2f(sXc[(mt * 16 + tk) * 72 + lane]);
;             av[ti] = a; iv[ti] = __builtin_amdgcn_sqrtf(fmaxf(1.f - a * a, 0.f)) * ig * xc;
;             if (FINAL && D == 1) grv[ti] = gelu_tanh_f(grv[ti]);
;         }
; #pragma unroll
;         for (int ti = 0; ti < 16; ++ti) { const int tk = D ? 15 - ti : ti;
;             hc = av[ti] * hc + iv[ti]; Ap *= av[ti];
;             if (FINAL) { const size_t row = (size_t)(rowbase + mt * 16 + tk);
;                 if (D == 0) TMP[row * 512 + ch] = (bf16_t)f2bf(hc);
	v_max_f32_e32 v40, 0, v40
	v_max_f32_e32 v41, 0, v41
	v_max_f32_e32 v42, 0, v42
	v_max_f32_e32 v43, 0, v43
	v_max_f32_e32 v44, 0, v44
	v_max_f32_e32 v45, 0, v45
	v_max_f32_e32 v46, 0, v46
	v_max_f32_e32 v47, 0, v47
	v_sqrt_f32_e32 v32, v32
	v_sqrt_f32_e32 v33, v33
	v_sqrt_f32_e32 v34, v34
	v_sqrt_f32_e32 v35, v35
	v_sqrt_f32_e32 v36, v36
	v_sqrt_f32_e32 v37, v37
	v_sqrt_f32_e32 v38, v38
	v_sqrt_f32_e32 v39, v39
	v_sqrt_f32_e32 v40, v40
	v_sqrt_f32_e32 v41, v41
	v_sqrt_f32_e32 v42, v42
	v_sqrt_f32_e32 v43, v43
	v_sqrt_f32_e32 v44, v44
	v_sqrt_f32_e32 v45, v45
	v_sqrt_f32_e32 v46, v46
	v_sqrt_f32_e32 v47, v47
	s_nop 0
	v_pk_mul_f32 v[16:17], v[16:17], v[32:33]
	v_pk_mul_f32 v[18:19], v[18:19], v[34:35]
	v_pk_mul_f32 v[20:21], v[20:21], v[36:37]
	v_pk_mul_f32 v[22:23], v[22:23], v[38:39]
	v_pk_mul_f32 v[24:25], v[24:25], v[40:41]
	v_pk_mul_f32 v[26:27], v[26:27], v[42:43]
	v_pk_mul_f32 v[28:29], v[28:29], v[44:45]
	v_pk_mul_f32 v[30:31], v[30:31], v[46:47]
	v_pk_mul_f32 v[16:17], v[16:17], v[48:49]
	v_pk_mul_f32 v[18:19], v[18:19], v[50:51]
	v_pk_mul_f32 v[20:21], v[20:21], v[52:53]
	v_pk_mul_f32 v[22:23], v[22:23], v[54:55]
	v_pk_mul_f32 v[24:25], v[24:25], v[56:57]
	v_pk_mul_f32 v[26:27], v[26:27], v[58:59]
	v_pk_mul_f32 v[28:29], v[28:29], v[60:61]
	v_pk_mul_f32 v[30:31], v[30:31], v[62:63]
	v_fma_f32 v32, v0, v250, v16
	v_fma_f32 v250, v1, v32, v17
	v_cvt_pk_bf16_f32 v158, v32, v250
	v_fma_f32 v32, v2, v250, v18
	v_fma_f32 v250, v3, v32, v19
	v_cvt_pk_bf16_f32 v159, v32, v250
	v_fma_f32 v32, v4, v250, v20
	v_fma_f32 v250, v5, v32, v21
	v_cvt_pk_bf16_f32 v160, v32, v250
	v_fma_f32 v32, v6, v250, v22
	v_fma_f32 v250, v7, v32, v23
	v_cvt_pk_bf16_f32 v161, v32, v250
	v_fma_f32 v32, v8, v250, v24
	v_fma_f32 v250, v9, v32, v25
	v_cvt_pk_bf16_f32 v162, v32, v250
	v_fma_f32 v32, v10, v250, v26
	v_fma_f32 v250, v11, v32, v27
	v_cvt_pk_bf16_f32 v163, v32, v250
	v_fma_f32 v32, v12, v250, v28
	v_fma_f32 v250, v13, v32, v29
	v_cvt_pk_bf16_f32 v164, v32, v250
	v_fma_f32 v32, v14, v250, v30
	v_fma_f32 v250, v15, v32, v31
	v_cvt_pk_bf16_f32 v165, v32, v250
	ds_read_b128 v[32:35], v236 offset:2304
	ds_read_b128 v[36:39], v236 offset:2368
	s_waitcnt lgkmcnt(0)
	v_mfma_f32_16x16x32_bf16 v[0:3], v[32:35], v[80:83], 0
	v_mfma_f32_16x16x32_bf16 v[4:7], v[32:35], v[88:91], 0
	v_mfma_f32_16x16x32_bf16 v[8:11], v[32:35], v[96:99], 0
	v_mfma_f32_16x16x32_bf16 v[12:15], v[32:35], v[104:107], 0
	v_mfma_f32_16x16x32_bf16 v[16:19], v[32:35], v[112:115], 0
	v_mfma_f32_16x16x32_bf16 v[20:23], v[32:35], v[120:123], 0
	v_mfma_f32_16x16x32_bf16 v[24:27], v[32:35], v[128:131], 0
	v_mfma_f32_16x16x32_bf16 v[28:31], v[32:35], v[136:139], 0
	v_mfma_f32_16x16x32_bf16 v[0:3], v[36:39], v[84:87], v[0:3]
	v_mfma_f32_16x16x32_bf16 v[4:7], v[36:39], v[92:95], v[4:7]
	v_mfma_f32_16x16x32_bf16 v[8:11], v[36:39], v[100:103], v[8:11]
	v_mfma_f32_16x16x32_bf16 v[12:15], v[36:39], v[108:111], v[12:15]
	v_mfma_f32_16x16x32_bf16 v[16:19], v[36:39], v[116:119], v[16:19]
	v_mfma_f32_16x16x32_bf16 v[20:23], v[36:39], v[124:127], v[20:23]
	v_mfma_f32_16x16x32_bf16 v[24:27], v[36:39], v[132:135], v[24:27]
	v_mfma_f32_16x16x32_bf16 v[28:31], v[36:39], v[228:231], v[28:31]
	s_nop 3
	ds_write2_b32 v237, v0, v4 offset0:0 offset1:16
	ds_write2_b32 v237, v8, v12 offset0:32 offset1:48
	ds_write2_b32 v237, v1, v5 offset0:64 offset1:80
	ds_write2_b32 v237, v9, v13 offset0:96 offset1:112
	ds_write2_b32 v237, v2, v6 offset0:128 offset1:144
	ds_write2_b32 v237, v10, v14 offset0:160 offset1:176
	ds_write2_b32 v237, v3, v7 offset0:192 offset1:208
	ds_write2_b32 v237, v11, v15 offset0:224 offset1:240
	ds_write2_b32 v238, v16, v20 offset0:0 offset1:16
	ds_write2_b32 v238, v24, v28 offset0:32 offset1:48
	ds_write2_b32 v238, v17, v21 offset0:64 offset1:80
	ds_write2_b32 v238, v25, v29 offset0:96 offset1:112
	ds_write2_b32 v238, v18, v22 offset0:128 offset1:144
	ds_write2_b32 v238, v26, v30 offset0:160 offset1:176
	ds_write2_b32 v238, v19, v23 offset0:192 offset1:208
	ds_write2_b32 v238, v27, v31 offset0:224 offset1:240
	s_waitcnt lgkmcnt(0)
	ds_read2st64_b32 v[0:1], v239 offset0:36 offset1:37
	ds_read2st64_b32 v[2:3], v239 offset0:38 offset1:39
	ds_read2st64_b32 v[4:5], v239 offset0:40 offset1:41
	ds_read2st64_b32 v[6:7], v239 offset0:42 offset1:43
	ds_read2st64_b32 v[8:9], v239 offset0:44 offset1:45
	ds_read2st64_b32 v[10:11], v239 offset0:46 offset1:47
	ds_read2st64_b32 v[12:13], v239 offset0:48 offset1:49
	ds_read2st64_b32 v[14:15], v239 offset0:50 offset1:51
	ds_read2st64_b32 v[16:17], v239 offset0:52 offset1:53
	ds_read2st64_b32 v[18:19], v239 offset0:54 offset1:55
	ds_read2st64_b32 v[20:21], v239 offset0:56 offset1:57
	ds_read2st64_b32 v[22:23], v239 offset0:58 offset1:59
	ds_read2st64_b32 v[24:25], v239 offset0:60 offset1:61
	ds_read2st64_b32 v[26:27], v239 offset0:62 offset1:63
	ds_read2st64_b32 v[28:29], v239 offset0:64 offset1:65
	ds_read2st64_b32 v[30:31], v239 offset0:66 offset1:67
	ds_read_u16 v48, v240 offset:2304
	ds_read_u16 v49, v240 offset:2448
	ds_read_u16 v50, v240 offset:2592
	ds_read_u16 v51, v240 offset:2736
	ds_read_u16 v52, v240 offset:2880
	ds_read_u16 v53, v240 offset:3024
	ds_read_u16 v54, v240 offset:3168
	ds_read_u16 v55, v240 offset:3312
	ds_read_u16 v56, v240 offset:3456
	ds_read_u16 v57, v240 offset:3600
	ds_read_u16 v58, v240 offset:3744
	ds_read_u16 v59, v240 offset:3888
	ds_read_u16 v60, v240 offset:4032
	ds_read_u16 v61, v240 offset:4176
	ds_read_u16 v62, v240 offset:4320
	ds_read_u16 v63, v240 offset:4464
	s_waitcnt lgkmcnt(0)
; __device__ __forceinline__ float sigmoid_f(float x) { return rcpf_(1.f + __expf(-x)); }
; template <bool FINAL, int D>
; __device__ __forceinline__ void rg_dir(PREF p, int l, int h, int ch, int sidx, int rowbase  , LAS bf16_t* sXc, LAS float* stg, int lane) {
;     ...
;         for (int ti = 0; ti < 16; ++ti) { const int tk = D ? 15 - ti : ti;
;             const float zr = stg[tk * 64 + lane] + ba, zi = stg[1024 + tk * 64 + lane] + bi;
;             const float r = sigmoid_f(zr), ig = sigmoid_f(zi);
;             const float a = __builtin_amdgcn_exp2f(r * sp8);
;             const float xc = bf2f(sXc[(mt * 16 + tk) * 72 + lane]);
;             av[ti] = a; iv[ti] = __builtin_amdgcn_sqrtf(fmaxf(1.f - a * a, 0.f)) * ig * xc;
	v_pk_add_f32 v[0:1], v[242:243], v[0:1]
	v_pk_add_f32 v[2:3], v[242:243], v[2:3]
	v_pk_add_f32 v[4:5], v[242:243], v[4:5]
	v_pk_add_f32 v[6:7], v[242:243], v[6:7]
	v_pk_add_f32 v[8:9], v[242:243], v[8:9]
	v_pk_add_f32 v[10:11], v[242:243], v[10:11]
	v_pk_add_f32 v[12:13], v[242:243], v[12:13]
	v_pk_add_f32 v[14:15], v[242:243], v[14:15]
	v_pk_add_f32 v[16:17], v[244:245], v[16:17]
	v_pk_add_f32 v[18:19], v[244:245], v[18:19]
	v_pk_add_f32 v[20:21], v[244:245], v[20:21]
	v_pk_add_f32 v[22:23], v[244:245], v[22:23]
	v_pk_add_f32 v[24:25], v[244:245], v[24:25]
	v_pk_add_f32 v[26:27], v[244:245], v[26:27]
	v_pk_add_f32 v[28:29], v[244:245], v[28:29]
	v_pk_add_f32 v[30:31], v[244:245], v[30:31]
	v_pk_mul_f32 v[0:1], v[248:249], v[0:1]
	v_pk_mul_f32 v[2:3], v[248:249], v[2:3]
	v_pk_mul_f32 v[4:5], v[248:249], v[4:5]
	v_pk_mul_f32 v[6:7], v[248:249], v[6:7]
	v_pk_mul_f32 v[8:9], v[248:249], v[8:9]
	v_pk_mul_f32 v[10:11], v[248:249], v[10:11]
	v_pk_mul_f32 v[12:13], v[248:249], v[12:13]
	v_pk_mul_f32 v[14:15], v[248:249], v[14:15]
	v_pk_mul_f32 v[16:17], v[248:249], v[16:17]
	v_pk_mul_f32 v[18:19], v[248:249], v[18:19]
	v_pk_mul_f32 v[20:21], v[248:249], v[20:21]
	v_pk_mul_f32 v[22:23], v[248:249], v[22:23]
	v_pk_mul_f32 v[24:25], v[248:249], v[24:25]
	v_pk_mul_f32 v[26:27], v[248:249], v[26:27]
	v_pk_mul_f32 v[28:29], v[248:249], v[28:29]
	v_pk_mul_f32 v[30:31], v[248:249], v[30:31]
	v_exp_f32_e32 v0, v0
	v_exp_f32_e32 v1, v1
	v_exp_f32_e32 v2, v2
	v_exp_f32_e32 v3, v3
	v_exp_f32_e32 v4, v4
	v_exp_f32_e32 v5, v5
	v_exp_f32_e32 v6, v6
	v_exp_f32_e32 v7, v7
	v_exp_f32_e32 v8, v8
	v_exp_f32_e32 v9, v9
	v_exp_f32_e32 v10, v10
	v_exp_f32_e32 v11, v11
	v_exp_f32_e32 v12, v12
	v_exp_f32_e32 v13, v13
	v_exp_f32_e32 v14, v14
	v_exp_f32_e32 v15, v15
	v_exp_f32_e32 v16, v16
	v_exp_f32_e32 v17, v17
	v_exp_f32_e32 v18, v18
	v_exp_f32_e32 v19, v19
	v_exp_f32_e32 v20, v20
	v_exp_f32_e32 v21, v21
	v_exp_f32_e32 v22, v22
	v_exp_f32_e32 v23, v23
	v_exp_f32_e32 v24, v24
	v_exp_f32_e32 v25, v25
	v_exp_f32_e32 v26, v26
	v_exp_f32_e32 v27, v27
	v_exp_f32_e32 v28, v28
	v_exp_f32_e32 v29, v29
	v_exp_f32_e32 v30, v30
	v_exp_f32_e32 v31, v31
	v_pk_add_f32 v[0:1], v[0:1], 1.0 op_sel_hi:[1,0]
	v_pk_add_f32 v[2:3], v[2:3], 1.0 op_sel_hi:[1,0]
	v_pk_add_f32 v[4:5], v[4:5], 1.0 op_sel_hi:[1,0]
	v_pk_add_f32 v[6:7], v[6:7], 1.0 op_sel_hi:[1,0]
	v_pk_add_f32 v[8:9], v[8:9], 1.0 op_sel_hi:[1,0]
	v_pk_add_f32 v[10:11], v[10:11], 1.0 op_sel_hi:[1,0]
	v_pk_add_f32 v[12:13], v[12:13], 1.0 op_sel_hi:[1,0]
	v_pk_add_f32 v[14:15], v[14:15], 1.0 op_sel_hi:[1,0]
	v_pk_add_f32 v[16:17], v[16:17], 1.0 op_sel_hi:[1,0]
	v_pk_add_f32 v[18:19], v[18:19], 1.0 op_sel_hi:[1,0]
	v_pk_add_f32 v[20:21], v[20:21], 1.0 op_sel_hi:[1,0]
	v_pk_add_f32 v[22:23], v[22:23], 1.0 op_sel_hi:[1,0]
	v_pk_add_f32 v[24:25], v[24:25], 1.0 op_sel_hi:[1,0]
	v_pk_add_f32 v[26:27], v[26:27], 1.0 op_sel_hi:[1,0]
	v_pk_add_f32 v[28:29], v[28:29], 1.0 op_sel_hi:[1,0]
	v_pk_add_f32 v[30:31], v[30:31], 1.0 op_sel_hi:[1,0]
	v_rcp_f32_e32 v0, v0
	v_rcp_f32_e32 v1, v1
	v_rcp_f32_e32 v2, v2
	v_rcp_f32_e32 v3, v3
	v_rcp_f32_e32 v4, v4
	v_rcp_f32_e32 v5, v5
	v_rcp_f32_e32 v6, v6
	v_rcp_f32_e32 v7, v7
	v_rcp_f32_e32 v8, v8
	v_rcp_f32_e32 v9, v9
	v_rcp_f32_e32 v10, v10
	v_rcp_f32_e32 v11, v11
	v_rcp_f32_e32 v12, v12
	v_rcp_f32_e32 v13, v13
	v_rcp_f32_e32 v14, v14
	v_rcp_f32_e32 v15, v15
	v_rcp_f32_e32 v16, v16
	v_rcp_f32_e32 v17, v17
	v_rcp_f32_e32 v18, v18
	v_rcp_f32_e32 v19, v19
	v_rcp_f32_e32 v20, v20
	v_rcp_f32_e32 v21, v21
	v_rcp_f32_e32 v22, v22
	v_rcp_f32_e32 v23, v23
	v_rcp_f32_e32 v24, v24
	v_rcp_f32_e32 v25, v25
	v_rcp_f32_e32 v26, v26
	v_rcp_f32_e32 v27, v27
	v_rcp_f32_e32 v28, v28
	v_rcp_f32_e32 v29, v29
	v_rcp_f32_e32 v30, v30
	v_rcp_f32_e32 v31, v31
	v_pk_mul_f32 v[0:1], v[246:247], v[0:1]
	v_pk_mul_f32 v[2:3], v[246:247], v[2:3]
	v_pk_mul_f32 v[4:5], v[246:247], v[4:5]
	v_pk_mul_f32 v[6:7], v[246:247], v[6:7]
	v_pk_mul_f32 v[8:9], v[246:247], v[8:9]
	v_pk_mul_f32 v[10:11], v[246:247], v[10:11]
	v_pk_mul_f32 v[12:13], v[246:247], v[12:13]
	v_pk_mul_f32 v[14:15], v[246:247], v[14:15]
	v_lshlrev_b32_e32 v48, 16, v48
	v_lshlrev_b32_e32 v49, 16, v49
	v_lshlrev_b32_e32 v50, 16, v50
	v_lshlrev_b32_e32 v51, 16, v51
	v_lshlrev_b32_e32 v52, 16, v52
	v_lshlrev_b32_e32 v53, 16, v53
	v_lshlrev_b32_e32 v54, 16, v54
	v_lshlrev_b32_e32 v55, 16, v55
	v_lshlrev_b32_e32 v56, 16, v56
	v_lshlrev_b32_e32 v57, 16, v57
	v_lshlrev_b32_e32 v58, 16, v58
	v_lshlrev_b32_e32 v59, 16, v59
	v_lshlrev_b32_e32 v60, 16, v60
	v_lshlrev_b32_e32 v61, 16, v61
	v_lshlrev_b32_e32 v62, 16, v62
	v_lshlrev_b32_e32 v63, 16, v63
	v_exp_f32_e32 v0, v0
	v_exp_f32_e32 v1, v1
	v_exp_f32_e32 v2, v2
	v_exp_f32_e32 v3, v3
	v_exp_f32_e32 v4, v4
	v_exp_f32_e32 v5, v5
	v_exp_f32_e32 v6, v6
	v_exp_f32_e32 v7, v7
	v_exp_f32_e32 v8, v8
	v_exp_f32_e32 v9, v9
	v_exp_f32_e32 v10, v10
	v_exp_f32_e32 v11, v11
	v_exp_f32_e32 v12, v12
	v_exp_f32_e32 v13, v13
	v_exp_f32_e32 v14, v14
	v_exp_f32_e32 v15, v15
	v_fma_f32 v32, -v0, v0, 1.0
	v_fma_f32 v33, -v1, v1, 1.0
	v_fma_f32 v34, -v2, v2, 1.0
	v_fma_f32 v35, -v3, v3, 1.0
	v_fma_f32 v36, -v4, v4, 1.0
	v_fma_f32 v37, -v5, v5, 1.0
	v_fma_f32 v38, -v6, v6, 1.0
	v_fma_f32 v39, -v7, v7, 1.0
	v_fma_f32 v40, -v8, v8, 1.0
	v_fma_f32 v41, -v9, v9, 1.0
	v_fma_f32 v42, -v10, v10, 1.0
	v_fma_f32 v43, -v11, v11, 1.0
	v_fma_f32 v44, -v12, v12, 1.0
	v_fma_f32 v45, -v13, v13, 1.0
	v_fma_f32 v46, -v14, v14, 1.0
	v_fma_f32 v47, -v15, v15, 1.0
	v_max_f32_e32 v32, 0, v32
	v_max_f32_e32 v33, 0, v33
	v_max_f32_e32 v34, 0, v34
	v_max_f32_e32 v35, 0, v35
	v_max_f32_e32 v36, 0, v36
	v_max_f32_e32 v37, 0, v37
	v_max_f32_e32 v38, 0, v38
	v_max_f32_e32 v39, 0, v39
; __device__ __forceinline__ unsigned f2bf(float f) { unsigned r; asm("v_cvt_pk_bf16_f32 %0, %1, %1" : "=v"(r) : "v"(f)); return r & 0xffffu; }
; __device__ __forceinline__ float sigmoid_f(float x) { return rcpf_(1.f + __expf(-x)); }
; __device__ __forceinline__ float gelu_tanh_f(float x) { const float y = 0.7978845608028654f * (x + 0.044715f * x * x * x); return x * sigmoid_f(2.f * y); }
; template <bool FINAL, int D>
; __device__ __forceinline__ void rg_dir(PREF p, int l, int h, int ch, int sidx, int rowbase  , LAS bf16_t* sXc, LAS float* stg, int lane) {
;     ...
;         for (int ti = 0; ti < 16; ++ti) { const int tk = D ? 15 - ti : ti;
;             const float zr = stg[tk * 64 + lane] + ba, zi = stg[1024 + tk * 64 + lane] + bi;
;             const float r = sigmoid_f(zr), ig = sigmoid_f(zi);
;             const float a = __builtin_amdgcn_exp2f(r * sp8);
;             const float xc = bf2f(sXc[(mt * 16 + tk) * 72 + lane]);
;             av[ti] = a; iv[ti] = __builtin_amdgcn_sqrtf(fmaxf(1.f - a * a, 0.f)) * ig * xc;
;             if (FINAL && D == 1) grv[ti] = gelu_tanh_f(grv[ti]);
;         }
; #pragma unroll
;         for (int ti = 0; ti < 16; ++ti) { const int tk = D ? 15 - ti : ti;
;             hc = av[ti] * hc + iv[ti]; Ap *= av[ti];
;             if (FINAL) { const size_t row = (size_t)(rowbase + mt * 16 + tk);
;                 if (D == 0) TMP[row * 512 + ch] = (bf16_t)f2bf(hc);
	v_max_f32_e32 v40, 0, v40
	v_max_f32_e32 v41, 0, v41
	v_max_f32_e32 v42, 0, v42
	v_max_f32_e32 v43, 0, v43
	v_max_f32_e32 v44, 0, v44
	v_max_f32_e32 v45, 0, v45
	v_max_f32_e32 v46, 0, v46
	v_max_f32_e32 v47, 0, v47
	v_sqrt_f32_e32 v32, v32
	v_sqrt_f32_e32 v33, v33
	v_sqrt_f32_e32 v34, v34
	v_sqrt_f32_e32 v35, v35
	v_sqrt_f32_e32 v36, v36
	v_sqrt_f32_e32 v37, v37
	v_sqrt_f32_e32 v38, v38
	v_sqrt_f32_e32 v39, v39
	v_sqrt_f32_e32 v40, v40
	v_sqrt_f32_e32 v41, v41
	v_sqrt_f32_e32 v42, v42
	v_sqrt_f32_e32 v43, v43
	v_sqrt_f32_e32 v44, v44
	v_sqrt_f32_e32 v45, v45
	v_sqrt_f32_e32 v46, v46
	v_sqrt_f32_e32 v47, v47
	s_nop 0
	v_pk_mul_f32 v[16:17], v[16:17], v[32:33]
	v_pk_mul_f32 v[18:19], v[18:19], v[34:35]
	v_pk_mul_f32 v[20:21], v[20:21], v[36:37]
	v_pk_mul_f32 v[22:23], v[22:23], v[38:39]
	v_pk_mul_f32 v[24:25], v[24:25], v[40:41]
	v_pk_mul_f32 v[26:27], v[26:27], v[42:43]
	v_pk_mul_f32 v[28:29], v[28:29], v[44:45]
	v_pk_mul_f32 v[30:31], v[30:31], v[46:47]
	v_pk_mul_f32 v[16:17], v[16:17], v[48:49]
	v_pk_mul_f32 v[18:19], v[18:19], v[50:51]
	v_pk_mul_f32 v[20:21], v[20:21], v[52:53]
	v_pk_mul_f32 v[22:23], v[22:23], v[54:55]
	v_pk_mul_f32 v[24:25], v[24:25], v[56:57]
	v_pk_mul_f32 v[26:27], v[26:27], v[58:59]
	v_pk_mul_f32 v[28:29], v[28:29], v[60:61]
	v_pk_mul_f32 v[30:31], v[30:31], v[62:63]
	v_fma_f32 v32, v0, v250, v16
	v_fma_f32 v250, v1, v32, v17
	v_cvt_pk_bf16_f32 v166, v32, v250
	v_fma_f32 v32, v2, v250, v18
	v_fma_f32 v250, v3, v32, v19
	v_cvt_pk_bf16_f32 v167, v32, v250
	v_fma_f32 v32, v4, v250, v20
	v_fma_f32 v250, v5, v32, v21
	v_cvt_pk_bf16_f32 v168, v32, v250
	v_fma_f32 v32, v6, v250, v22
	v_fma_f32 v250, v7, v32, v23
	v_cvt_pk_bf16_f32 v169, v32, v250
	v_fma_f32 v32, v8, v250, v24
	v_fma_f32 v250, v9, v32, v25
	v_cvt_pk_bf16_f32 v170, v32, v250
	v_fma_f32 v32, v10, v250, v26
	v_fma_f32 v250, v11, v32, v27
	v_cvt_pk_bf16_f32 v171, v32, v250
	v_fma_f32 v32, v12, v250, v28
	v_fma_f32 v250, v13, v32, v29
	v_cvt_pk_bf16_f32 v172, v32, v250
	v_fma_f32 v32, v14, v250, v30
	v_fma_f32 v250, v15, v32, v31
	v_cvt_pk_bf16_f32 v173, v32, v250
	ds_read_b128 v[32:35], v236 offset:4608
	ds_read_b128 v[36:39], v236 offset:4672
	s_waitcnt lgkmcnt(0)
	v_mfma_f32_16x16x32_bf16 v[0:3], v[32:35], v[80:83], 0
	v_mfma_f32_16x16x32_bf16 v[4:7], v[32:35], v[88:91], 0
	v_mfma_f32_16x16x32_bf16 v[8:11], v[32:35], v[96:99], 0
	v_mfma_f32_16x16x32_bf16 v[12:15], v[32:35], v[104:107], 0
	v_mfma_f32_16x16x32_bf16 v[16:19], v[32:35], v[112:115], 0
	v_mfma_f32_16x16x32_bf16 v[20:23], v[32:35], v[120:123], 0
	v_mfma_f32_16x16x32_bf16 v[24:27], v[32:35], v[128:131], 0
	v_mfma_f32_16x16x32_bf16 v[28:31], v[32:35], v[136:139], 0
	v_mfma_f32_16x16x32_bf16 v[0:3], v[36:39], v[84:87], v[0:3]
	v_mfma_f32_16x16x32_bf16 v[4:7], v[36:39], v[92:95], v[4:7]
	v_mfma_f32_16x16x32_bf16 v[8:11], v[36:39], v[100:103], v[8:11]
	v_mfma_f32_16x16x32_bf16 v[12:15], v[36:39], v[108:111], v[12:15]
	v_mfma_f32_16x16x32_bf16 v[16:19], v[36:39], v[116:119], v[16:19]
	v_mfma_f32_16x16x32_bf16 v[20:23], v[36:39], v[124:127], v[20:23]
	v_mfma_f32_16x16x32_bf16 v[24:27], v[36:39], v[132:135], v[24:27]
	v_mfma_f32_16x16x32_bf16 v[28:31], v[36:39], v[228:231], v[28:31]
	s_nop 3
	ds_write2_b32 v237, v0, v4 offset0:0 offset1:16
	ds_write2_b32 v237, v8, v12 offset0:32 offset1:48
	ds_write2_b32 v237, v1, v5 offset0:64 offset1:80
	ds_write2_b32 v237, v9, v13 offset0:96 offset1:112
	ds_write2_b32 v237, v2, v6 offset0:128 offset1:144
	ds_write2_b32 v237, v10, v14 offset0:160 offset1:176
	ds_write2_b32 v237, v3, v7 offset0:192 offset1:208
	ds_write2_b32 v237, v11, v15 offset0:224 offset1:240
	ds_write2_b32 v238, v16, v20 offset0:0 offset1:16
	ds_write2_b32 v238, v24, v28 offset0:32 offset1:48
	ds_write2_b32 v238, v17, v21 offset0:64 offset1:80
	ds_write2_b32 v238, v25, v29 offset0:96 offset1:112
	ds_write2_b32 v238, v18, v22 offset0:128 offset1:144
	ds_write2_b32 v238, v26, v30 offset0:160 offset1:176
	ds_write2_b32 v238, v19, v23 offset0:192 offset1:208
	ds_write2_b32 v238, v27, v31 offset0:224 offset1:240
	s_waitcnt lgkmcnt(0)
	ds_read2st64_b32 v[0:1], v239 offset0:36 offset1:37
	ds_read2st64_b32 v[2:3], v239 offset0:38 offset1:39
	ds_read2st64_b32 v[4:5], v239 offset0:40 offset1:41
	ds_read2st64_b32 v[6:7], v239 offset0:42 offset1:43
	ds_read2st64_b32 v[8:9], v239 offset0:44 offset1:45
	ds_read2st64_b32 v[10:11], v239 offset0:46 offset1:47
	ds_read2st64_b32 v[12:13], v239 offset0:48 offset1:49
	ds_read2st64_b32 v[14:15], v239 offset0:50 offset1:51
	ds_read2st64_b32 v[16:17], v239 offset0:52 offset1:53
	ds_read2st64_b32 v[18:19], v239 offset0:54 offset1:55
	ds_read2st64_b32 v[20:21], v239 offset0:56 offset1:57
	ds_read2st64_b32 v[22:23], v239 offset0:58 offset1:59
	ds_read2st64_b32 v[24:25], v239 offset0:60 offset1:61
	ds_read2st64_b32 v[26:27], v239 offset0:62 offset1:63
	ds_read2st64_b32 v[28:29], v239 offset0:64 offset1:65
	ds_read2st64_b32 v[30:31], v239 offset0:66 offset1:67
	ds_read_u16 v48, v240 offset:4608
	ds_read_u16 v49, v240 offset:4752
	ds_read_u16 v50, v240 offset:4896
	ds_read_u16 v51, v240 offset:5040
	ds_read_u16 v52, v240 offset:5184
	ds_read_u16 v53, v240 offset:5328
	ds_read_u16 v54, v240 offset:5472
	ds_read_u16 v55, v240 offset:5616
	ds_read_u16 v56, v240 offset:5760
	ds_read_u16 v57, v240 offset:5904
	ds_read_u16 v58, v240 offset:6048
	ds_read_u16 v59, v240 offset:6192
	ds_read_u16 v60, v240 offset:6336
	ds_read_u16 v61, v240 offset:6480
	ds_read_u16 v62, v240 offset:6624
	ds_read_u16 v63, v240 offset:6768
	s_waitcnt lgkmcnt(0)
; __device__ __forceinline__ float sigmoid_f(float x) { return rcpf_(1.f + __expf(-x)); }
; template <bool FINAL, int D>
; __device__ __forceinline__ void rg_dir(PREF p, int l, int h, int ch, int sidx, int rowbase  , LAS bf16_t* sXc, LAS float* stg, int lane) {
;     ...
;         for (int ti = 0; ti < 16; ++ti) { const int tk = D ? 15 - ti : ti;
;             const float zr = stg[tk * 64 + lane] + ba, zi = stg[1024 + tk * 64 + lane] + bi;
;             const float r = sigmoid_f(zr), ig = sigmoid_f(zi);
;             const float a = __builtin_amdgcn_exp2f(r * sp8);
;             const float xc = bf2f(sXc[(mt * 16 + tk) * 72 + lane]);
;             av[ti] = a; iv[ti] = __builtin_amdgcn_sqrtf(fmaxf(1.f - a * a, 0.f)) * ig * xc;
	v_pk_add_f32 v[0:1], v[242:243], v[0:1]
	v_pk_add_f32 v[2:3], v[242:243], v[2:3]
	v_pk_add_f32 v[4:5], v[242:243], v[4:5]
	v_pk_add_f32 v[6:7], v[242:243], v[6:7]
	v_pk_add_f32 v[8:9], v[242:243], v[8:9]
	v_pk_add_f32 v[10:11], v[242:243], v[10:11]
	v_pk_add_f32 v[12:13], v[242:243], v[12:13]
	v_pk_add_f32 v[14:15], v[242:243], v[14:15]
	v_pk_add_f32 v[16:17], v[244:245], v[16:17]
	v_pk_add_f32 v[18:19], v[244:245], v[18:19]
	v_pk_add_f32 v[20:21], v[244:245], v[20:21]
	v_pk_add_f32 v[22:23], v[244:245], v[22:23]
	v_pk_add_f32 v[24:25], v[244:245], v[24:25]
	v_pk_add_f32 v[26:27], v[244:245], v[26:27]
	v_pk_add_f32 v[28:29], v[244:245], v[28:29]
	v_pk_add_f32 v[30:31], v[244:245], v[30:31]
	v_pk_mul_f32 v[0:1], v[248:249], v[0:1]
	v_pk_mul_f32 v[2:3], v[248:249], v[2:3]
	v_pk_mul_f32 v[4:5], v[248:249], v[4:5]
	v_pk_mul_f32 v[6:7], v[248:249], v[6:7]
	v_pk_mul_f32 v[8:9], v[248:249], v[8:9]
	v_pk_mul_f32 v[10:11], v[248:249], v[10:11]
	v_pk_mul_f32 v[12:13], v[248:249], v[12:13]
	v_pk_mul_f32 v[14:15], v[248:249], v[14:15]
	v_pk_mul_f32 v[16:17], v[248:249], v[16:17]
	v_pk_mul_f32 v[18:19], v[248:249], v[18:19]
	v_pk_mul_f32 v[20:21], v[248:249], v[20:21]
	v_pk_mul_f32 v[22:23], v[248:249], v[22:23]
	v_pk_mul_f32 v[24:25], v[248:249], v[24:25]
	v_pk_mul_f32 v[26:27], v[248:249], v[26:27]
	v_pk_mul_f32 v[28:29], v[248:249], v[28:29]
	v_pk_mul_f32 v[30:31], v[248:249], v[30:31]
	v_exp_f32_e32 v0, v0
	v_exp_f32_e32 v1, v1
	v_exp_f32_e32 v2, v2
	v_exp_f32_e32 v3, v3
	v_exp_f32_e32 v4, v4
	v_exp_f32_e32 v5, v5
	v_exp_f32_e32 v6, v6
	v_exp_f32_e32 v7, v7
	v_exp_f32_e32 v8, v8
	v_exp_f32_e32 v9, v9
	v_exp_f32_e32 v10, v10
	v_exp_f32_e32 v11, v11
	v_exp_f32_e32 v12, v12
	v_exp_f32_e32 v13, v13
	v_exp_f32_e32 v14, v14
	v_exp_f32_e32 v15, v15
	v_exp_f32_e32 v16, v16
	v_exp_f32_e32 v17, v17
	v_exp_f32_e32 v18, v18
	v_exp_f32_e32 v19, v19
	v_exp_f32_e32 v20, v20
	v_exp_f32_e32 v21, v21
	v_exp_f32_e32 v22, v22
	v_exp_f32_e32 v23, v23
	v_exp_f32_e32 v24, v24
	v_exp_f32_e32 v25, v25
	v_exp_f32_e32 v26, v26
	v_exp_f32_e32 v27, v27
	v_exp_f32_e32 v28, v28
	v_exp_f32_e32 v29, v29
	v_exp_f32_e32 v30, v30
	v_exp_f32_e32 v31, v31
	v_pk_add_f32 v[0:1], v[0:1], 1.0 op_sel_hi:[1,0]
	v_pk_add_f32 v[2:3], v[2:3], 1.0 op_sel_hi:[1,0]
	v_pk_add_f32 v[4:5], v[4:5], 1.0 op_sel_hi:[1,0]
	v_pk_add_f32 v[6:7], v[6:7], 1.0 op_sel_hi:[1,0]
	v_pk_add_f32 v[8:9], v[8:9], 1.0 op_sel_hi:[1,0]
	v_pk_add_f32 v[10:11], v[10:11], 1.0 op_sel_hi:[1,0]
	v_pk_add_f32 v[12:13], v[12:13], 1.0 op_sel_hi:[1,0]
	v_pk_add_f32 v[14:15], v[14:15], 1.0 op_sel_hi:[1,0]
	v_pk_add_f32 v[16:17], v[16:17], 1.0 op_sel_hi:[1,0]
	v_pk_add_f32 v[18:19], v[18:19], 1.0 op_sel_hi:[1,0]
	v_pk_add_f32 v[20:21], v[20:21], 1.0 op_sel_hi:[1,0]
	v_pk_add_f32 v[22:23], v[22:23], 1.0 op_sel_hi:[1,0]
	v_pk_add_f32 v[24:25], v[24:25], 1.0 op_sel_hi:[1,0]
	v_pk_add_f32 v[26:27], v[26:27], 1.0 op_sel_hi:[1,0]
	v_pk_add_f32 v[28:29], v[28:29], 1.0 op_sel_hi:[1,0]
	v_pk_add_f32 v[30:31], v[30:31], 1.0 op_sel_hi:[1,0]
	v_rcp_f32_e32 v0, v0
	v_rcp_f32_e32 v1, v1
	v_rcp_f32_e32 v2, v2
	v_rcp_f32_e32 v3, v3
	v_rcp_f32_e32 v4, v4
	v_rcp_f32_e32 v5, v5
	v_rcp_f32_e32 v6, v6
	v_rcp_f32_e32 v7, v7
	v_rcp_f32_e32 v8, v8
	v_rcp_f32_e32 v9, v9
	v_rcp_f32_e32 v10, v10
	v_rcp_f32_e32 v11, v11
	v_rcp_f32_e32 v12, v12
	v_rcp_f32_e32 v13, v13
	v_rcp_f32_e32 v14, v14
	v_rcp_f32_e32 v15, v15
	v_rcp_f32_e32 v16, v16
	v_rcp_f32_e32 v17, v17
	v_rcp_f32_e32 v18, v18
	v_rcp_f32_e32 v19, v19
	v_rcp_f32_e32 v20, v20
	v_rcp_f32_e32 v21, v21
	v_rcp_f32_e32 v22, v22
	v_rcp_f32_e32 v23, v23
	v_rcp_f32_e32 v24, v24
	v_rcp_f32_e32 v25, v25
	v_rcp_f32_e32 v26, v26
	v_rcp_f32_e32 v27, v27
	v_rcp_f32_e32 v28, v28
	v_rcp_f32_e32 v29, v29
	v_rcp_f32_e32 v30, v30
	v_rcp_f32_e32 v31, v31
	v_pk_mul_f32 v[0:1], v[246:247], v[0:1]
	v_pk_mul_f32 v[2:3], v[246:247], v[2:3]
	v_pk_mul_f32 v[4:5], v[246:247], v[4:5]
	v_pk_mul_f32 v[6:7], v[246:247], v[6:7]
	v_pk_mul_f32 v[8:9], v[246:247], v[8:9]
	v_pk_mul_f32 v[10:11], v[246:247], v[10:11]
	v_pk_mul_f32 v[12:13], v[246:247], v[12:13]
	v_pk_mul_f32 v[14:15], v[246:247], v[14:15]
	v_lshlrev_b32_e32 v48, 16, v48
	v_lshlrev_b32_e32 v49, 16, v49
	v_lshlrev_b32_e32 v50, 16, v50
	v_lshlrev_b32_e32 v51, 16, v51
	v_lshlrev_b32_e32 v52, 16, v52
	v_lshlrev_b32_e32 v53, 16, v53
	v_lshlrev_b32_e32 v54, 16, v54
	v_lshlrev_b32_e32 v55, 16, v55
	v_lshlrev_b32_e32 v56, 16, v56
	v_lshlrev_b32_e32 v57, 16, v57
	v_lshlrev_b32_e32 v58, 16, v58
	v_lshlrev_b32_e32 v59, 16, v59
	v_lshlrev_b32_e32 v60, 16, v60
	v_lshlrev_b32_e32 v61, 16, v61
	v_lshlrev_b32_e32 v62, 16, v62
	v_lshlrev_b32_e32 v63, 16, v63
	v_exp_f32_e32 v0, v0
	v_exp_f32_e32 v1, v1
	v_exp_f32_e32 v2, v2
	v_exp_f32_e32 v3, v3
	v_exp_f32_e32 v4, v4
	v_exp_f32_e32 v5, v5
	v_exp_f32_e32 v6, v6
	v_exp_f32_e32 v7, v7
	v_exp_f32_e32 v8, v8
	v_exp_f32_e32 v9, v9
	v_exp_f32_e32 v10, v10
	v_exp_f32_e32 v11, v11
	v_exp_f32_e32 v12, v12
	v_exp_f32_e32 v13, v13
	v_exp_f32_e32 v14, v14
	v_exp_f32_e32 v15, v15
	v_fma_f32 v32, -v0, v0, 1.0
	v_fma_f32 v33, -v1, v1, 1.0
	v_fma_f32 v34, -v2, v2, 1.0
	v_fma_f32 v35, -v3, v3, 1.0
	v_fma_f32 v36, -v4, v4, 1.0
	v_fma_f32 v37, -v5, v5, 1.0
	v_fma_f32 v38, -v6, v6, 1.0
	v_fma_f32 v39, -v7, v7, 1.0
	v_fma_f32 v40, -v8, v8, 1.0
	v_fma_f32 v41, -v9, v9, 1.0
	v_fma_f32 v42, -v10, v10, 1.0
	v_fma_f32 v43, -v11, v11, 1.0
	v_fma_f32 v44, -v12, v12, 1.0
	v_fma_f32 v45, -v13, v13, 1.0
	v_fma_f32 v46, -v14, v14, 1.0
	v_fma_f32 v47, -v15, v15, 1.0
	v_max_f32_e32 v32, 0, v32
	v_max_f32_e32 v33, 0, v33
	v_max_f32_e32 v34, 0, v34
	v_max_f32_e32 v35, 0, v35
	v_max_f32_e32 v36, 0, v36
	v_max_f32_e32 v37, 0, v37
	v_max_f32_e32 v38, 0, v38
	v_max_f32_e32 v39, 0, v39
; #define LAS __attribute__((address_space(3)))
; #define WAVE_SYNC() asm volatile("s_waitcnt lgkmcnt(0)" ::: "memory")
; __device__ __forceinline__ unsigned f2bf(float f) { unsigned r; asm("v_cvt_pk_bf16_f32 %0, %1, %1" : "=v"(r) : "v"(f)); return r & 0xffffu; }
; template <bool FINAL, int D>
; __device__ __forceinline__ void rg_dir(PREF p, int l, int h, int ch, int sidx, int rowbase  , LAS bf16_t* sXc, LAS float* stg, int lane) {
;     ...
;     for (int nt = 0; nt < 4; ++nt) { const int o0 = (nt * 16 + (lane & 15)) * 64 + (lane >> 4) * 8;
;         Br[nt][0] = *(const bf16x8*)(wr_ + o0); Br[nt][1] = *(const bf16x8*)(wr_ + o0 + 32); Bi[nt][0] = *(const bf16x8*)(wi_ + o0); Bi[nt][1] = *(const bf16x8*)(wi_ + o0 + 32); }
;     ...
;         const bf16x8 A0 = *(const LAS bf16x8*)(sXc + (mt * 16 + (lane & 15)) * 72 + (lane >> 4) * 8), A1 = *(const LAS bf16x8*)(sXc + (mt * 16 + (lane & 15)) * 72 + 32 + (lane >> 4) * 8);
;         f32x4 ar[4], ai[4];
; #pragma unroll
;         for (int nt = 0; nt < 4; ++nt) { const f32x4 z = {0.f, 0.f, 0.f, 0.f};
;             ar[nt] = mfma16(A0, Br[nt][0], z); ar[nt] = mfma16(A1, Br[nt][1], ar[nt]); ai[nt] = mfma16(A0, Bi[nt][0], z); ai[nt] = mfma16(A1, Bi[nt][1], ai[nt]); }
;         WAVE_SYNC();
; #pragma unroll
;         for (int nt = 0; nt < 4; ++nt)
; #pragma unroll
;             for (int j = 0; j < 4; ++j) { const int o = ((lane >> 4) * 4 + j) * 64 + nt * 16 + (lane & 15); stg[o] = ar[nt][j]; stg[1024 + o] = ai[nt][j]; }
;         WAVE_SYNC();
;         float av[16], iv[16];
; #pragma unroll
;         for (int ti = 0; ti < 16; ++ti) { const int tk = D ? 15 - ti : ti;
;             const float zr = stg[tk * 64 + lane] + ba, zi = stg[1024 + tk * 64 + lane] + bi;
;             const float r = sigmoid_f(zr), ig = sigmoid_f(zi);
;             const float a = __builtin_amdgcn_exp2f(r * sp8);
;             const float xc = bf2f(sXc[(mt * 16 + tk) * 72 + lane]);
;             av[ti] = a; iv[ti] = __builtin_amdgcn_sqrtf(fmaxf(1.f - a * a, 0.f)) * ig * xc;
;             if (FINAL && D == 1) grv[ti] = gelu_tanh_f(grv[ti]);
;         }
; #pragma unroll
;         for (int ti = 0; ti < 16; ++ti) { const int tk = D ? 15 - ti : ti;
;             hc = av[ti] * hc + iv[ti]; Ap *= av[ti];
;             if (FINAL) { const size_t row = (size_t)(rowbase + mt * 16 + tk);
;                 if (D == 0) TMP[row * 512 + ch] = (bf16_t)f2bf(hc);
	v_max_f32_e32 v40, 0, v40
	v_max_f32_e32 v41, 0, v41
	v_max_f32_e32 v42, 0, v42
	v_max_f32_e32 v43, 0, v43
	v_max_f32_e32 v44, 0, v44
	v_max_f32_e32 v45, 0, v45
	v_max_f32_e32 v46, 0, v46
	v_max_f32_e32 v47, 0, v47
	v_sqrt_f32_e32 v32, v32
	v_sqrt_f32_e32 v33, v33
	v_sqrt_f32_e32 v34, v34
	v_sqrt_f32_e32 v35, v35
	v_sqrt_f32_e32 v36, v36
	v_sqrt_f32_e32 v37, v37
	v_sqrt_f32_e32 v38, v38
	v_sqrt_f32_e32 v39, v39
	v_sqrt_f32_e32 v40, v40
	v_sqrt_f32_e32 v41, v41
	v_sqrt_f32_e32 v42, v42
	v_sqrt_f32_e32 v43, v43
	v_sqrt_f32_e32 v44, v44
	v_sqrt_f32_e32 v45, v45
	v_sqrt_f32_e32 v46, v46
	v_sqrt_f32_e32 v47, v47
	s_nop 0
	v_pk_mul_f32 v[16:17], v[16:17], v[32:33]
	v_pk_mul_f32 v[18:19], v[18:19], v[34:35]
	v_pk_mul_f32 v[20:21], v[20:21], v[36:37]
	v_pk_mul_f32 v[22:23], v[22:23], v[38:39]
	v_pk_mul_f32 v[24:25], v[24:25], v[40:41]
	v_pk_mul_f32 v[26:27], v[26:27], v[42:43]
	v_pk_mul_f32 v[28:29], v[28:29], v[44:45]
	v_pk_mul_f32 v[30:31], v[30:31], v[46:47]
	v_pk_mul_f32 v[16:17], v[16:17], v[48:49]
	v_pk_mul_f32 v[18:19], v[18:19], v[50:51]
	v_pk_mul_f32 v[20:21], v[20:21], v[52:53]
	v_pk_mul_f32 v[22:23], v[22:23], v[54:55]
	v_pk_mul_f32 v[24:25], v[24:25], v[56:57]
	v_pk_mul_f32 v[26:27], v[26:27], v[58:59]
	v_pk_mul_f32 v[28:29], v[28:29], v[60:61]
	v_pk_mul_f32 v[30:31], v[30:31], v[62:63]
	v_fma_f32 v32, v0, v250, v16
	v_fma_f32 v250, v1, v32, v17
	v_cvt_pk_bf16_f32 v174, v32, v250
	v_fma_f32 v32, v2, v250, v18
	v_fma_f32 v250, v3, v32, v19
	v_cvt_pk_bf16_f32 v175, v32, v250
	v_fma_f32 v32, v4, v250, v20
	v_fma_f32 v250, v5, v32, v21
	v_cvt_pk_bf16_f32 v176, v32, v250
	v_fma_f32 v32, v6, v250, v22
	v_fma_f32 v250, v7, v32, v23
	v_cvt_pk_bf16_f32 v177, v32, v250
	v_fma_f32 v32, v8, v250, v24
	v_fma_f32 v250, v9, v32, v25
	v_cvt_pk_bf16_f32 v178, v32, v250
	v_fma_f32 v32, v10, v250, v26
	v_fma_f32 v250, v11, v32, v27
	v_cvt_pk_bf16_f32 v179, v32, v250
	v_fma_f32 v32, v12, v250, v28
	v_fma_f32 v250, v13, v32, v29
	v_cvt_pk_bf16_f32 v180, v32, v250
	v_fma_f32 v32, v14, v250, v30
	v_fma_f32 v250, v15, v32, v31
	v_cvt_pk_bf16_f32 v181, v32, v250
	ds_read_b128 v[32:35], v236 offset:6912
	ds_read_b128 v[36:39], v236 offset:6976
	s_waitcnt lgkmcnt(0)
	v_mfma_f32_16x16x32_bf16 v[0:3], v[32:35], v[80:83], 0
	v_mfma_f32_16x16x32_bf16 v[4:7], v[32:35], v[88:91], 0
	v_mfma_f32_16x16x32_bf16 v[8:11], v[32:35], v[96:99], 0
	v_mfma_f32_16x16x32_bf16 v[12:15], v[32:35], v[104:107], 0
	v_mfma_f32_16x16x32_bf16 v[16:19], v[32:35], v[112:115], 0
	v_mfma_f32_16x16x32_bf16 v[20:23], v[32:35], v[120:123], 0
	v_mfma_f32_16x16x32_bf16 v[24:27], v[32:35], v[128:131], 0
	v_mfma_f32_16x16x32_bf16 v[28:31], v[32:35], v[136:139], 0
	v_mfma_f32_16x16x32_bf16 v[0:3], v[36:39], v[84:87], v[0:3]
	v_mfma_f32_16x16x32_bf16 v[4:7], v[36:39], v[92:95], v[4:7]
	v_mfma_f32_16x16x32_bf16 v[8:11], v[36:39], v[100:103], v[8:11]
	v_mfma_f32_16x16x32_bf16 v[12:15], v[36:39], v[108:111], v[12:15]
	v_mfma_f32_16x16x32_bf16 v[16:19], v[36:39], v[116:119], v[16:19]
	v_mfma_f32_16x16x32_bf16 v[20:23], v[36:39], v[124:127], v[20:23]
	v_mfma_f32_16x16x32_bf16 v[24:27], v[36:39], v[132:135], v[24:27]
	v_mfma_f32_16x16x32_bf16 v[28:31], v[36:39], v[228:231], v[28:31]
	s_nop 3
	ds_write2_b32 v237, v0, v4 offset0:0 offset1:16
	ds_write2_b32 v237, v8, v12 offset0:32 offset1:48
	ds_write2_b32 v237, v1, v5 offset0:64 offset1:80
	ds_write2_b32 v237, v9, v13 offset0:96 offset1:112
	ds_write2_b32 v237, v2, v6 offset0:128 offset1:144
	ds_write2_b32 v237, v10, v14 offset0:160 offset1:176
	ds_write2_b32 v237, v3, v7 offset0:192 offset1:208
	ds_write2_b32 v237, v11, v15 offset0:224 offset1:240
	ds_write2_b32 v238, v16, v20 offset0:0 offset1:16
	ds_write2_b32 v238, v24, v28 offset0:32 offset1:48
	ds_write2_b32 v238, v17, v21 offset0:64 offset1:80
	ds_write2_b32 v238, v25, v29 offset0:96 offset1:112
	ds_write2_b32 v238, v18, v22 offset0:128 offset1:144
	ds_write2_b32 v238, v26, v30 offset0:160 offset1:176
	ds_write2_b32 v238, v19, v23 offset0:192 offset1:208
	ds_write2_b32 v238, v27, v31 offset0:224 offset1:240
	s_waitcnt lgkmcnt(0)
	ds_read2st64_b32 v[0:1], v239 offset0:36 offset1:37
	ds_read2st64_b32 v[2:3], v239 offset0:38 offset1:39
	ds_read2st64_b32 v[4:5], v239 offset0:40 offset1:41
	ds_read2st64_b32 v[6:7], v239 offset0:42 offset1:43
	ds_read2st64_b32 v[8:9], v239 offset0:44 offset1:45
	ds_read2st64_b32 v[10:11], v239 offset0:46 offset1:47
	ds_read2st64_b32 v[12:13], v239 offset0:48 offset1:49
	ds_read2st64_b32 v[14:15], v239 offset0:50 offset1:51
	ds_read2st64_b32 v[16:17], v239 offset0:52 offset1:53
	ds_read2st64_b32 v[18:19], v239 offset0:54 offset1:55
	ds_read2st64_b32 v[20:21], v239 offset0:56 offset1:57
	ds_read2st64_b32 v[22:23], v239 offset0:58 offset1:59
	ds_read2st64_b32 v[24:25], v239 offset0:60 offset1:61
	ds_read2st64_b32 v[26:27], v239 offset0:62 offset1:63
	ds_read2st64_b32 v[28:29], v239 offset0:64 offset1:65
	ds_read2st64_b32 v[30:31], v239 offset0:66 offset1:67
	ds_read_u16 v48, v240 offset:6912
	ds_read_u16 v49, v240 offset:7056
	ds_read_u16 v50, v240 offset:7200
	ds_read_u16 v51, v240 offset:7344
	ds_read_u16 v52, v240 offset:7488
	ds_read_u16 v53, v240 offset:7632
	ds_read_u16 v54, v240 offset:7776
	ds_read_u16 v55, v240 offset:7920
	ds_read_u16 v56, v240 offset:8064
	ds_read_u16 v57, v240 offset:8208
	ds_read_u16 v58, v240 offset:8352
	ds_read_u16 v59, v240 offset:8496
	ds_read_u16 v60, v240 offset:8640
	ds_read_u16 v61, v240 offset:8784
	ds_read_u16 v62, v240 offset:8928
	ds_read_u16 v63, v240 offset:9072
	s_add_u32 s90, s92, 0x20000
	s_addc_u32 s91, s93, 0
	global_load_dwordx4 v[80:83], v241, s[90:91]
	global_load_dwordx4 v[84:87], v241, s[90:91] offset:64
	global_load_dwordx4 v[88:91], v241, s[90:91] offset:2048
	global_load_dwordx4 v[92:95], v241, s[90:91] offset:2112
	s_add_u32 s90, s92, 0x21000
	s_addc_u32 s91, s93, 0
	global_load_dwordx4 v[96:99], v241, s[90:91]
	global_load_dwordx4 v[100:103], v241, s[90:91] offset:64
	global_load_dwordx4 v[104:107], v241, s[90:91] offset:2048
	global_load_dwordx4 v[108:111], v241, s[90:91] offset:2112
	s_add_u32 s90, s92, 0x30000
	s_addc_u32 s91, s93, 0
	global_load_dwordx4 v[112:115], v241, s[90:91]
	global_load_dwordx4 v[116:119], v241, s[90:91] offset:64
	global_load_dwordx4 v[120:123], v241, s[90:91] offset:2048
	global_load_dwordx4 v[124:127], v241, s[90:91] offset:2112
	s_add_u32 s90, s92, 0x31000
	s_addc_u32 s91, s93, 0
	global_load_dwordx4 v[128:131], v241, s[90:91]
	global_load_dwordx4 v[132:135], v241, s[90:91] offset:64
	global_load_dwordx4 v[136:139], v241, s[90:91] offset:2048
	global_load_dwordx4 v[228:231], v241, s[90:91] offset:2112
	s_waitcnt lgkmcnt(0)
; __device__ __forceinline__ float sigmoid_f(float x) { return rcpf_(1.f + __expf(-x)); }
; template <bool FINAL, int D>
; __device__ __forceinline__ void rg_dir(PREF p, int l, int h, int ch, int sidx, int rowbase  , LAS bf16_t* sXc, LAS float* stg, int lane) {
;     ...
;         for (int ti = 0; ti < 16; ++ti) { const int tk = D ? 15 - ti : ti;
;             const float zr = stg[tk * 64 + lane] + ba, zi = stg[1024 + tk * 64 + lane] + bi;
;             const float r = sigmoid_f(zr), ig = sigmoid_f(zi);
;             const float a = __builtin_amdgcn_exp2f(r * sp8);
;             const float xc = bf2f(sXc[(mt * 16 + tk) * 72 + lane]);
;             av[ti] = a; iv[ti] = __builtin_amdgcn_sqrtf(fmaxf(1.f - a * a, 0.f)) * ig * xc;
	v_pk_add_f32 v[0:1], v[242:243], v[0:1]
	v_pk_add_f32 v[2:3], v[242:243], v[2:3]
	v_pk_add_f32 v[4:5], v[242:243], v[4:5]
	v_pk_add_f32 v[6:7], v[242:243], v[6:7]
	v_pk_add_f32 v[8:9], v[242:243], v[8:9]
	v_pk_add_f32 v[10:11], v[242:243], v[10:11]
	v_pk_add_f32 v[12:13], v[242:243], v[12:13]
	v_pk_add_f32 v[14:15], v[242:243], v[14:15]
	v_pk_add_f32 v[16:17], v[244:245], v[16:17]
	v_pk_add_f32 v[18:19], v[244:245], v[18:19]
	v_pk_add_f32 v[20:21], v[244:245], v[20:21]
	v_pk_add_f32 v[22:23], v[244:245], v[22:23]
	v_pk_add_f32 v[24:25], v[244:245], v[24:25]
	v_pk_add_f32 v[26:27], v[244:245], v[26:27]
	v_pk_add_f32 v[28:29], v[244:245], v[28:29]
	v_pk_add_f32 v[30:31], v[244:245], v[30:31]
	v_pk_mul_f32 v[0:1], v[248:249], v[0:1]
	v_pk_mul_f32 v[2:3], v[248:249], v[2:3]
	v_pk_mul_f32 v[4:5], v[248:249], v[4:5]
	v_pk_mul_f32 v[6:7], v[248:249], v[6:7]
	v_pk_mul_f32 v[8:9], v[248:249], v[8:9]
	v_pk_mul_f32 v[10:11], v[248:249], v[10:11]
	v_pk_mul_f32 v[12:13], v[248:249], v[12:13]
	v_pk_mul_f32 v[14:15], v[248:249], v[14:15]
	v_pk_mul_f32 v[16:17], v[248:249], v[16:17]
	v_pk_mul_f32 v[18:19], v[248:249], v[18:19]
	v_pk_mul_f32 v[20:21], v[248:249], v[20:21]
	v_pk_mul_f32 v[22:23], v[248:249], v[22:23]
	v_pk_mul_f32 v[24:25], v[248:249], v[24:25]
	v_pk_mul_f32 v[26:27], v[248:249], v[26:27]
	v_pk_mul_f32 v[28:29], v[248:249], v[28:29]
	v_pk_mul_f32 v[30:31], v[248:249], v[30:31]
	v_exp_f32_e32 v0, v0
	v_exp_f32_e32 v1, v1
	v_exp_f32_e32 v2, v2
	v_exp_f32_e32 v3, v3
	v_exp_f32_e32 v4, v4
	v_exp_f32_e32 v5, v5
	v_exp_f32_e32 v6, v6
	v_exp_f32_e32 v7, v7
	v_exp_f32_e32 v8, v8
	v_exp_f32_e32 v9, v9
	v_exp_f32_e32 v10, v10
	v_exp_f32_e32 v11, v11
	v_exp_f32_e32 v12, v12
	v_exp_f32_e32 v13, v13
	v_exp_f32_e32 v14, v14
	v_exp_f32_e32 v15, v15
	v_exp_f32_e32 v16, v16
	v_exp_f32_e32 v17, v17
	v_exp_f32_e32 v18, v18
	v_exp_f32_e32 v19, v19
	v_exp_f32_e32 v20, v20
	v_exp_f32_e32 v21, v21
	v_exp_f32_e32 v22, v22
	v_exp_f32_e32 v23, v23
	v_exp_f32_e32 v24, v24
	v_exp_f32_e32 v25, v25
	v_exp_f32_e32 v26, v26
	v_exp_f32_e32 v27, v27
	v_exp_f32_e32 v28, v28
	v_exp_f32_e32 v29, v29
	v_exp_f32_e32 v30, v30
	v_exp_f32_e32 v31, v31
	v_pk_add_f32 v[0:1], v[0:1], 1.0 op_sel_hi:[1,0]
	v_pk_add_f32 v[2:3], v[2:3], 1.0 op_sel_hi:[1,0]
	v_pk_add_f32 v[4:5], v[4:5], 1.0 op_sel_hi:[1,0]
	v_pk_add_f32 v[6:7], v[6:7], 1.0 op_sel_hi:[1,0]
	v_pk_add_f32 v[8:9], v[8:9], 1.0 op_sel_hi:[1,0]
	v_pk_add_f32 v[10:11], v[10:11], 1.0 op_sel_hi:[1,0]
	v_pk_add_f32 v[12:13], v[12:13], 1.0 op_sel_hi:[1,0]
	v_pk_add_f32 v[14:15], v[14:15], 1.0 op_sel_hi:[1,0]
	v_pk_add_f32 v[16:17], v[16:17], 1.0 op_sel_hi:[1,0]
	v_pk_add_f32 v[18:19], v[18:19], 1.0 op_sel_hi:[1,0]
	v_pk_add_f32 v[20:21], v[20:21], 1.0 op_sel_hi:[1,0]
	v_pk_add_f32 v[22:23], v[22:23], 1.0 op_sel_hi:[1,0]
	v_pk_add_f32 v[24:25], v[24:25], 1.0 op_sel_hi:[1,0]
	v_pk_add_f32 v[26:27], v[26:27], 1.0 op_sel_hi:[1,0]
	v_pk_add_f32 v[28:29], v[28:29], 1.0 op_sel_hi:[1,0]
	v_pk_add_f32 v[30:31], v[30:31], 1.0 op_sel_hi:[1,0]
	v_rcp_f32_e32 v0, v0
	v_rcp_f32_e32 v1, v1
	v_rcp_f32_e32 v2, v2
	v_rcp_f32_e32 v3, v3
	v_rcp_f32_e32 v4, v4
	v_rcp_f32_e32 v5, v5
	v_rcp_f32_e32 v6, v6
	v_rcp_f32_e32 v7, v7
	v_rcp_f32_e32 v8, v8
	v_rcp_f32_e32 v9, v9
	v_rcp_f32_e32 v10, v10
	v_rcp_f32_e32 v11, v11
	v_rcp_f32_e32 v12, v12
	v_rcp_f32_e32 v13, v13
	v_rcp_f32_e32 v14, v14
	v_rcp_f32_e32 v15, v15
	v_rcp_f32_e32 v16, v16
	v_rcp_f32_e32 v17, v17
	v_rcp_f32_e32 v18, v18
	v_rcp_f32_e32 v19, v19
	v_rcp_f32_e32 v20, v20
	v_rcp_f32_e32 v21, v21
	v_rcp_f32_e32 v22, v22
	v_rcp_f32_e32 v23, v23
	v_rcp_f32_e32 v24, v24
	v_rcp_f32_e32 v25, v25
	v_rcp_f32_e32 v26, v26
	v_rcp_f32_e32 v27, v27
	v_rcp_f32_e32 v28, v28
	v_rcp_f32_e32 v29, v29
	v_rcp_f32_e32 v30, v30
	v_rcp_f32_e32 v31, v31
	v_pk_mul_f32 v[0:1], v[246:247], v[0:1]
	v_pk_mul_f32 v[2:3], v[246:247], v[2:3]
	v_pk_mul_f32 v[4:5], v[246:247], v[4:5]
	v_pk_mul_f32 v[6:7], v[246:247], v[6:7]
	v_pk_mul_f32 v[8:9], v[246:247], v[8:9]
	v_pk_mul_f32 v[10:11], v[246:247], v[10:11]
	v_pk_mul_f32 v[12:13], v[246:247], v[12:13]
	v_pk_mul_f32 v[14:15], v[246:247], v[14:15]
	v_lshlrev_b32_e32 v48, 16, v48
	v_lshlrev_b32_e32 v49, 16, v49
	v_lshlrev_b32_e32 v50, 16, v50
	v_lshlrev_b32_e32 v51, 16, v51
	v_lshlrev_b32_e32 v52, 16, v52
	v_lshlrev_b32_e32 v53, 16, v53
	v_lshlrev_b32_e32 v54, 16, v54
	v_lshlrev_b32_e32 v55, 16, v55
	v_lshlrev_b32_e32 v56, 16, v56
	v_lshlrev_b32_e32 v57, 16, v57
	v_lshlrev_b32_e32 v58, 16, v58
	v_lshlrev_b32_e32 v59, 16, v59
	v_lshlrev_b32_e32 v60, 16, v60
	v_lshlrev_b32_e32 v61, 16, v61
	v_lshlrev_b32_e32 v62, 16, v62
	v_lshlrev_b32_e32 v63, 16, v63
	v_exp_f32_e32 v0, v0
	v_exp_f32_e32 v1, v1
	v_exp_f32_e32 v2, v2
	v_exp_f32_e32 v3, v3
	v_exp_f32_e32 v4, v4
	v_exp_f32_e32 v5, v5
	v_exp_f32_e32 v6, v6
	v_exp_f32_e32 v7, v7
	v_exp_f32_e32 v8, v8
	v_exp_f32_e32 v9, v9
	v_exp_f32_e32 v10, v10
	v_exp_f32_e32 v11, v11
	v_exp_f32_e32 v12, v12
	v_exp_f32_e32 v13, v13
	v_exp_f32_e32 v14, v14
	v_exp_f32_e32 v15, v15
	v_fma_f32 v32, -v0, v0, 1.0
	v_fma_f32 v33, -v1, v1, 1.0
	v_fma_f32 v34, -v2, v2, 1.0
	v_fma_f32 v35, -v3, v3, 1.0
	v_fma_f32 v36, -v4, v4, 1.0
	v_fma_f32 v37, -v5, v5, 1.0
	v_fma_f32 v38, -v6, v6, 1.0
	v_fma_f32 v39, -v7, v7, 1.0
	v_fma_f32 v40, -v8, v8, 1.0
	v_fma_f32 v41, -v9, v9, 1.0
	v_fma_f32 v42, -v10, v10, 1.0
	v_fma_f32 v43, -v11, v11, 1.0
	v_fma_f32 v44, -v12, v12, 1.0
	v_fma_f32 v45, -v13, v13, 1.0
	v_fma_f32 v46, -v14, v14, 1.0
	v_fma_f32 v47, -v15, v15, 1.0
	v_max_f32_e32 v32, 0, v32
	v_max_f32_e32 v33, 0, v33
	v_max_f32_e32 v34, 0, v34
	v_max_f32_e32 v35, 0, v35
	v_max_f32_e32 v36, 0, v36
	v_max_f32_e32 v37, 0, v37
	v_max_f32_e32 v38, 0, v38
	v_max_f32_e32 v39, 0, v39
; #define LAS __attribute__((address_space(3)))
; __device__ __forceinline__ float rcpf_(float x) { return __builtin_amdgcn_rcpf(x); }
; template <bool FINAL, int D>
; __device__ __forceinline__ void rg_dir(PREF p, int l, int h, int ch, int sidx, int rowbase  , LAS bf16_t* sXc, LAS float* stg, int lane) {
;     ...
;     const float ba = p.rg_ba[(l * 2 + D) * 512 + ch], bi = p.rg_bi[(l * 2 + D) * 512 + ch], lam = p.rg_lam[(l * 2 + D) * 512 + ch];
;     const float e_ = __expf(-lam), u_ = 1.f + e_;
;     const float l1p = (u_ == 1.f) ? e_ : __logf(u_) * e_ * rcpf_(u_ - 1.f);
;     const float sp8 = -8.f * 1.4426950408889634f * l1p;
;     float hc = FINAL ? RGC[sidx] : 0.f, Ap = 1.f;
;     bf16x8 Br[4][2], Bi[4][2];
; #pragma unroll
;     for (int nt = 0; nt < 4; ++nt) { const int o0 = (nt * 16 + (lane & 15)) * 64 + (lane >> 4) * 8;
;         Br[nt][0] = *(const bf16x8*)(wr_ + o0); Br[nt][1] = *(const bf16x8*)(wr_ + o0 + 32); Bi[nt][0] = *(const bf16x8*)(wi_ + o0); Bi[nt][1] = *(const bf16x8*)(wi_ + o0 + 32); }
;     if (FINAL && D == 1) asm volatile("s_waitcnt vmcnt(0)" ::: "memory");
; #pragma unroll 1
;     for (int mi = 0; mi < 4; ++mi) { const int mt = D ? 3 - mi : mi;
;         float grv[16], hfv[16];
;         if (FINAL && D == 1) {
; #pragma unroll
;             for (int ti = 0; ti < 16; ++ti) { const size_t row = (size_t)(rowbase + mt * 16 + 15 - ti); grv[ti] = __builtin_bit_cast(float, (unsigned)P[row * PW + 512 + ch]); hfv[ti] = __builtin_bit_cast(float, (unsigned)TMP[row * 512 + ch]); }
;             __builtin_amdgcn_sched_barrier(0);
; #pragma unroll
;             for (int ti = 0; ti < 16; ++ti) { grv[ti] = bf2f(__builtin_bit_cast(unsigned, grv[ti])); hfv[ti] = bf2f(__builtin_bit_cast(unsigned, hfv[ti])); }
;         }
;         const bf16x8 A0 = *(const LAS bf16x8*)(sXc + (mt * 16 + (lane & 15)) * 72 + (lane >> 4) * 8), A1 = *(const LAS bf16x8*)(sXc + (mt * 16 + (lane & 15)) * 72 + 32 + (lane >> 4) * 8);
;         f32x4 ar[4], ai[4];
; #pragma unroll
;         for (int nt = 0; nt < 4; ++nt) { const f32x4 z = {0.f, 0.f, 0.f, 0.f};
;             ar[nt] = mfma16(A0, Br[nt][0], z); ar[nt] = mfma16(A1, Br[nt][1], ar[nt]); ai[nt] = mfma16(A0, Bi[nt][0], z); ai[nt] = mfma16(A1, Bi[nt][1], ai[nt]); }
;     ...
;         for (int ti = 0; ti < 16; ++ti) { const int tk = D ? 15 - ti : ti;
;             hc = av[ti] * hc + iv[ti]; Ap *= av[ti];
	v_max_f32_e32 v40, 0, v40
	v_max_f32_e32 v41, 0, v41
	v_max_f32_e32 v42, 0, v42
	v_max_f32_e32 v43, 0, v43
	v_max_f32_e32 v44, 0, v44
	v_max_f32_e32 v45, 0, v45
	v_max_f32_e32 v46, 0, v46
	v_max_f32_e32 v47, 0, v47
	v_sqrt_f32_e32 v32, v32
	v_sqrt_f32_e32 v33, v33
	v_sqrt_f32_e32 v34, v34
	v_sqrt_f32_e32 v35, v35
	v_sqrt_f32_e32 v36, v36
	v_sqrt_f32_e32 v37, v37
	v_sqrt_f32_e32 v38, v38
	v_sqrt_f32_e32 v39, v39
	v_sqrt_f32_e32 v40, v40
	v_sqrt_f32_e32 v41, v41
	v_sqrt_f32_e32 v42, v42
	v_sqrt_f32_e32 v43, v43
	v_sqrt_f32_e32 v44, v44
	v_sqrt_f32_e32 v45, v45
	v_sqrt_f32_e32 v46, v46
	v_sqrt_f32_e32 v47, v47
	s_nop 0
	v_pk_mul_f32 v[16:17], v[16:17], v[32:33]
	v_pk_mul_f32 v[18:19], v[18:19], v[34:35]
	v_pk_mul_f32 v[20:21], v[20:21], v[36:37]
	v_pk_mul_f32 v[22:23], v[22:23], v[38:39]
	v_pk_mul_f32 v[24:25], v[24:25], v[40:41]
	v_pk_mul_f32 v[26:27], v[26:27], v[42:43]
	v_pk_mul_f32 v[28:29], v[28:29], v[44:45]
	v_pk_mul_f32 v[30:31], v[30:31], v[46:47]
	v_pk_mul_f32 v[16:17], v[16:17], v[48:49]
	v_pk_mul_f32 v[18:19], v[18:19], v[50:51]
	v_pk_mul_f32 v[20:21], v[20:21], v[52:53]
	v_pk_mul_f32 v[22:23], v[22:23], v[54:55]
	v_pk_mul_f32 v[24:25], v[24:25], v[56:57]
	v_pk_mul_f32 v[26:27], v[26:27], v[58:59]
	v_pk_mul_f32 v[28:29], v[28:29], v[60:61]
	v_pk_mul_f32 v[30:31], v[30:31], v[62:63]
	global_load_dword v45, v235, s[76:77] offset:2048
	global_load_dword v46, v235, s[78:79] offset:2048
	global_load_dword v47, v235, s[80:81] offset:2048
	global_load_dword v251, v235, s[96:97] offset:2048
	v_fma_f32 v32, v0, v250, v16
	v_fma_f32 v250, v1, v32, v17
	v_cvt_pk_bf16_f32 v182, v32, v250
	v_fma_f32 v32, v2, v250, v18
	v_fma_f32 v250, v3, v32, v19
	v_cvt_pk_bf16_f32 v183, v32, v250
	v_fma_f32 v32, v4, v250, v20
	v_fma_f32 v250, v5, v32, v21
	v_cvt_pk_bf16_f32 v184, v32, v250
	v_fma_f32 v32, v6, v250, v22
	v_fma_f32 v250, v7, v32, v23
	v_cvt_pk_bf16_f32 v185, v32, v250
	v_fma_f32 v32, v8, v250, v24
	v_fma_f32 v250, v9, v32, v25
	v_cvt_pk_bf16_f32 v186, v32, v250
	v_fma_f32 v32, v10, v250, v26
	v_fma_f32 v250, v11, v32, v27
	v_cvt_pk_bf16_f32 v187, v32, v250
	v_fma_f32 v32, v12, v250, v28
	v_fma_f32 v250, v13, v32, v29
	v_cvt_pk_bf16_f32 v188, v32, v250
	v_fma_f32 v32, v14, v250, v30
	v_fma_f32 v250, v15, v32, v31
	v_cvt_pk_bf16_f32 v189, v32, v250
	s_waitcnt vmcnt(0)
	s_mov_b32 s8, 0x800000
	s_mov_b32 s9, 0x3f317217
	s_mov_b32 s14, 0x7f800000
	v_mul_f32_e32 v32, 0xbfb8aa3b, v45
	v_exp_f32_e32 v32, v32
	s_nop 0
	v_add_f32_e32 v33, 1.0, v32
	v_cmp_gt_f32_e32 vcc, s8, v33
	s_nop 1
	v_cndmask_b32_e64 v34, 0, 32, vcc
	v_ldexp_f32 v34, v33, v34
	v_log_f32_e32 v34, v34
	v_cndmask_b32_e32 v36, 0, v226, vcc
	v_cmp_eq_f32_e32 vcc, 1.0, v33
	v_mul_f32_e32 v35, 0x3f317217, v34
	v_fma_f32 v35, v34, s9, -v35
	v_fmac_f32_e32 v35, 0x3377d1cf, v34
	v_fmac_f32_e32 v35, 0x3f317217, v34
	v_cmp_lt_f32_e64 s[10:11], |v34|, s14
	s_nop 1
	v_cndmask_b32_e64 v34, v34, v35, s[10:11]
	v_add_f32_e32 v35, -1.0, v33
	v_rcp_f32_e32 v35, v35
	v_sub_f32_e32 v34, v34, v36
	v_mul_f32_e32 v34, v32, v34
	v_mul_f32_e32 v34, v34, v35
	v_cndmask_b32_e32 v32, v34, v32, vcc
	v_mul_f32_e32 v246, 0xc138aa3b, v32
	v_mov_b32_e32 v247, v246
	v_mov_b32_e32 v242, v46
	v_mov_b32_e32 v243, v46
	v_mov_b32_e32 v244, v47
	v_mov_b32_e32 v245, v47
	v_mov_b32_e32 v250, v251
	ds_read_b128 v[32:35], v236 offset:6912
	ds_read_b128 v[36:39], v236 offset:6976
	s_waitcnt lgkmcnt(0)
	v_mfma_f32_16x16x32_bf16 v[0:3], v[32:35], v[80:83], 0
	v_mfma_f32_16x16x32_bf16 v[4:7], v[32:35], v[88:91], 0
	v_mfma_f32_16x16x32_bf16 v[8:11], v[32:35], v[96:99], 0
	v_mfma_f32_16x16x32_bf16 v[12:15], v[32:35], v[104:107], 0
	v_mfma_f32_16x16x32_bf16 v[16:19], v[32:35], v[112:115], 0
	v_mfma_f32_16x16x32_bf16 v[20:23], v[32:35], v[120:123], 0
	v_mfma_f32_16x16x32_bf16 v[24:27], v[32:35], v[128:131], 0
	v_mfma_f32_16x16x32_bf16 v[28:31], v[32:35], v[136:139], 0
	v_mfma_f32_16x16x32_bf16 v[0:3], v[36:39], v[84:87], v[0:3]
	v_mfma_f32_16x16x32_bf16 v[4:7], v[36:39], v[92:95], v[4:7]
	v_mfma_f32_16x16x32_bf16 v[8:11], v[36:39], v[100:103], v[8:11]
	v_mfma_f32_16x16x32_bf16 v[12:15], v[36:39], v[108:111], v[12:15]
	v_mfma_f32_16x16x32_bf16 v[16:19], v[36:39], v[116:119], v[16:19]
	v_mfma_f32_16x16x32_bf16 v[20:23], v[36:39], v[124:127], v[20:23]
	v_mfma_f32_16x16x32_bf16 v[24:27], v[36:39], v[132:135], v[24:27]
	v_mfma_f32_16x16x32_bf16 v[28:31], v[36:39], v[228:231], v[28:31]
	s_nop 3
	ds_write2_b32 v237, v0, v4 offset0:0 offset1:16
	ds_write2_b32 v237, v8, v12 offset0:32 offset1:48
	ds_write2_b32 v237, v1, v5 offset0:64 offset1:80
	ds_write2_b32 v237, v9, v13 offset0:96 offset1:112
	ds_write2_b32 v237, v2, v6 offset0:128 offset1:144
	ds_write2_b32 v237, v10, v14 offset0:160 offset1:176
	ds_write2_b32 v237, v3, v7 offset0:192 offset1:208
	ds_write2_b32 v237, v11, v15 offset0:224 offset1:240
	ds_write2_b32 v238, v16, v20 offset0:0 offset1:16
	ds_write2_b32 v238, v24, v28 offset0:32 offset1:48
	ds_write2_b32 v238, v17, v21 offset0:64 offset1:80
	ds_write2_b32 v238, v25, v29 offset0:96 offset1:112
	ds_write2_b32 v238, v18, v22 offset0:128 offset1:144
	ds_write2_b32 v238, v26, v30 offset0:160 offset1:176
	ds_write2_b32 v238, v19, v23 offset0:192 offset1:208
	ds_write2_b32 v238, v27, v31 offset0:224 offset1:240
	s_waitcnt lgkmcnt(0)
; #define WAVE_SYNC() asm volatile("s_waitcnt lgkmcnt(0)" ::: "memory")
; __device__ __forceinline__ float sigmoid_f(float x) { return rcpf_(1.f + __expf(-x)); }
; __device__ __forceinline__ float gelu_tanh_f(float x) { const float y = 0.7978845608028654f * (x + 0.044715f * x * x * x); return x * sigmoid_f(2.f * y); }
; template <bool FINAL, int D>
; __device__ __forceinline__ void rg_dir(PREF p, int l, int h, int ch, int sidx, int rowbase  , LAS bf16_t* sXc, LAS float* stg, int lane) {
;     ...
;             for (int j = 0; j < 4; ++j) { const int o = ((lane >> 4) * 4 + j) * 64 + nt * 16 + (lane & 15); stg[o] = ar[nt][j]; stg[1024 + o] = ai[nt][j]; }
;         WAVE_SYNC();
;         float av[16], iv[16];
; #pragma unroll
;         for (int ti = 0; ti < 16; ++ti) { const int tk = D ? 15 - ti : ti;
;             const float zr = stg[tk * 64 + lane] + ba, zi = stg[1024 + tk * 64 + lane] + bi;
;             const float r = sigmoid_f(zr), ig = sigmoid_f(zi);
;             const float a = __builtin_amdgcn_exp2f(r * sp8);
;             const float xc = bf2f(sXc[(mt * 16 + tk) * 72 + lane]);
;             av[ti] = a; iv[ti] = __builtin_amdgcn_sqrtf(fmaxf(1.f - a * a, 0.f)) * ig * xc;
;             if (FINAL && D == 1) grv[ti] = gelu_tanh_f(grv[ti]);
	ds_read2st64_b32 v[0:1], v239 offset0:36 offset1:37
	ds_read2st64_b32 v[2:3], v239 offset0:38 offset1:39
	ds_read2st64_b32 v[4:5], v239 offset0:40 offset1:41
	ds_read2st64_b32 v[6:7], v239 offset0:42 offset1:43
	ds_read2st64_b32 v[8:9], v239 offset0:44 offset1:45
	ds_read2st64_b32 v[10:11], v239 offset0:46 offset1:47
	ds_read2st64_b32 v[12:13], v239 offset0:48 offset1:49
	ds_read2st64_b32 v[14:15], v239 offset0:50 offset1:51
	ds_read2st64_b32 v[16:17], v239 offset0:52 offset1:53
	ds_read2st64_b32 v[18:19], v239 offset0:54 offset1:55
	ds_read2st64_b32 v[20:21], v239 offset0:56 offset1:57
	ds_read2st64_b32 v[22:23], v239 offset0:58 offset1:59
	ds_read2st64_b32 v[24:25], v239 offset0:60 offset1:61
	ds_read2st64_b32 v[26:27], v239 offset0:62 offset1:63
	ds_read2st64_b32 v[28:29], v239 offset0:64 offset1:65
	ds_read2st64_b32 v[30:31], v239 offset0:66 offset1:67
	ds_read_u16 v48, v240 offset:6912
	ds_read_u16 v49, v240 offset:7056
	ds_read_u16 v50, v240 offset:7200
	ds_read_u16 v51, v240 offset:7344
	ds_read_u16 v52, v240 offset:7488
	ds_read_u16 v53, v240 offset:7632
	ds_read_u16 v54, v240 offset:7776
	ds_read_u16 v55, v240 offset:7920
	ds_read_u16 v56, v240 offset:8064
	ds_read_u16 v57, v240 offset:8208
	ds_read_u16 v58, v240 offset:8352
	ds_read_u16 v59, v240 offset:8496
	ds_read_u16 v60, v240 offset:8640
	ds_read_u16 v61, v240 offset:8784
	ds_read_u16 v62, v240 offset:8928
	ds_read_u16 v63, v240 offset:9072
	v_lshlrev_b32_e32 v206, 16, v190
	v_lshlrev_b32_e32 v207, 16, v191
	v_lshlrev_b32_e32 v208, 16, v192
	v_lshlrev_b32_e32 v209, 16, v193
	v_lshlrev_b32_e32 v210, 16, v194
	v_lshlrev_b32_e32 v211, 16, v195
	v_lshlrev_b32_e32 v212, 16, v196
	v_lshlrev_b32_e32 v213, 16, v197
	v_lshlrev_b32_e32 v214, 16, v198
	v_lshlrev_b32_e32 v215, 16, v199
	v_lshlrev_b32_e32 v216, 16, v200
	v_lshlrev_b32_e32 v217, 16, v201
	v_lshlrev_b32_e32 v218, 16, v202
	v_lshlrev_b32_e32 v219, 16, v203
	v_lshlrev_b32_e32 v222, 16, v204
	v_lshlrev_b32_e32 v223, 16, v205
	v_pk_mul_f32 v[32:33], v[140:141], v[206:207]
	v_pk_mul_f32 v[34:35], v[140:141], v[208:209]
	v_pk_mul_f32 v[36:37], v[140:141], v[210:211]
	v_pk_mul_f32 v[38:39], v[140:141], v[212:213]
	v_pk_mul_f32 v[40:41], v[140:141], v[214:215]
	v_pk_mul_f32 v[42:43], v[140:141], v[216:217]
	v_pk_mul_f32 v[44:45], v[140:141], v[218:219]
	v_pk_mul_f32 v[46:47], v[140:141], v[222:223]
	v_pk_mul_f32 v[32:33], v[32:33], v[206:207]
	v_pk_mul_f32 v[34:35], v[34:35], v[208:209]
	v_pk_mul_f32 v[36:37], v[36:37], v[210:211]
	v_pk_mul_f32 v[38:39], v[38:39], v[212:213]
	v_pk_mul_f32 v[40:41], v[40:41], v[214:215]
	v_pk_mul_f32 v[42:43], v[42:43], v[216:217]
	v_pk_mul_f32 v[44:45], v[44:45], v[218:219]
	v_pk_mul_f32 v[46:47], v[46:47], v[222:223]
	v_fma_f32 v32, v32, v206, v206
	v_fma_f32 v33, v33, v207, v207
	v_fma_f32 v34, v34, v208, v208
	v_fma_f32 v35, v35, v209, v209
	v_fma_f32 v36, v36, v210, v210
	v_fma_f32 v37, v37, v211, v211
	v_fma_f32 v38, v38, v212, v212
	v_fma_f32 v39, v39, v213, v213
	v_fma_f32 v40, v40, v214, v214
	v_fma_f32 v41, v41, v215, v215
	v_fma_f32 v42, v42, v216, v216
	v_fma_f32 v43, v43, v217, v217
	v_fma_f32 v44, v44, v218, v218
	v_fma_f32 v45, v45, v219, v219
	v_fma_f32 v46, v46, v222, v222
	v_fma_f32 v47, v47, v223, v223
	v_mul_f32_e32 v32, 0x3f4c422a, v32
	v_mul_f32_e32 v33, 0x3f4c422a, v33
	v_mul_f32_e32 v34, 0x3f4c422a, v34
	v_mul_f32_e32 v35, 0x3f4c422a, v35
	v_mul_f32_e32 v36, 0x3f4c422a, v36
	v_mul_f32_e32 v37, 0x3f4c422a, v37
	v_mul_f32_e32 v38, 0x3f4c422a, v38
	v_mul_f32_e32 v39, 0x3f4c422a, v39
	v_mul_f32_e32 v40, 0x3f4c422a, v40
	v_mul_f32_e32 v41, 0x3f4c422a, v41
	v_mul_f32_e32 v42, 0x3f4c422a, v42
	v_mul_f32_e32 v43, 0x3f4c422a, v43
	v_mul_f32_e32 v44, 0x3f4c422a, v44
	v_mul_f32_e32 v45, 0x3f4c422a, v45
	v_mul_f32_e32 v46, 0x3f4c422a, v46
	v_mul_f32_e32 v47, 0x3f4c422a, v47
	v_pk_add_f32 v[32:33], v[32:33], v[32:33]
	v_pk_add_f32 v[34:35], v[34:35], v[34:35]
	v_pk_add_f32 v[36:37], v[36:37], v[36:37]
	v_pk_add_f32 v[38:39], v[38:39], v[38:39]
	v_pk_add_f32 v[40:41], v[40:41], v[40:41]
	v_pk_add_f32 v[42:43], v[42:43], v[42:43]
	v_pk_add_f32 v[44:45], v[44:45], v[44:45]
	v_pk_add_f32 v[46:47], v[46:47], v[46:47]
	v_pk_mul_f32 v[32:33], v[248:249], v[32:33]
	v_pk_mul_f32 v[34:35], v[248:249], v[34:35]
	v_pk_mul_f32 v[36:37], v[248:249], v[36:37]
	v_pk_mul_f32 v[38:39], v[248:249], v[38:39]
	v_pk_mul_f32 v[40:41], v[248:249], v[40:41]
	v_pk_mul_f32 v[42:43], v[248:249], v[42:43]
	v_pk_mul_f32 v[44:45], v[248:249], v[44:45]
	v_pk_mul_f32 v[46:47], v[248:249], v[46:47]
	v_exp_f32_e32 v32, v32
	v_exp_f32_e32 v33, v33
	v_exp_f32_e32 v34, v34
	v_exp_f32_e32 v35, v35
	v_exp_f32_e32 v36, v36
	v_exp_f32_e32 v37, v37
	v_exp_f32_e32 v38, v38
	v_exp_f32_e32 v39, v39
	v_exp_f32_e32 v40, v40
	v_exp_f32_e32 v41, v41
	v_exp_f32_e32 v42, v42
	v_exp_f32_e32 v43, v43
	v_exp_f32_e32 v44, v44
	v_exp_f32_e32 v45, v45
	v_exp_f32_e32 v46, v46
	v_exp_f32_e32 v47, v47
	v_pk_add_f32 v[32:33], v[32:33], 1.0 op_sel_hi:[1,0]
	v_pk_add_f32 v[34:35], v[34:35], 1.0 op_sel_hi:[1,0]
	v_pk_add_f32 v[36:37], v[36:37], 1.0 op_sel_hi:[1,0]
	v_pk_add_f32 v[38:39], v[38:39], 1.0 op_sel_hi:[1,0]
	v_pk_add_f32 v[40:41], v[40:41], 1.0 op_sel_hi:[1,0]
	v_pk_add_f32 v[42:43], v[42:43], 1.0 op_sel_hi:[1,0]
	v_pk_add_f32 v[44:45], v[44:45], 1.0 op_sel_hi:[1,0]
	v_pk_add_f32 v[46:47], v[46:47], 1.0 op_sel_hi:[1,0]
	v_rcp_f32_e32 v32, v32
	v_rcp_f32_e32 v33, v33
	v_rcp_f32_e32 v34, v34
	v_rcp_f32_e32 v35, v35
	v_rcp_f32_e32 v36, v36
	v_rcp_f32_e32 v37, v37
	v_rcp_f32_e32 v38, v38
	v_rcp_f32_e32 v39, v39
	v_rcp_f32_e32 v40, v40
	v_rcp_f32_e32 v41, v41
	v_rcp_f32_e32 v42, v42
	v_rcp_f32_e32 v43, v43
	v_rcp_f32_e32 v44, v44
; #define LAS __attribute__((address_space(3)))
; #define WAVE_SYNC() asm volatile("s_waitcnt lgkmcnt(0)" ::: "memory")
; __device__ __forceinline__ float sigmoid_f(float x) { return rcpf_(1.f + __expf(-x)); }
; __device__ __forceinline__ f32x4 mfma16(bf16x8 a, bf16x8 b, f32x4 c) { return __builtin_amdgcn_mfma_f32_16x16x32_bf16(a, b, c, 0, 0, 0); }
; template <bool FINAL, int D>
; __device__ __forceinline__ void rg_dir(PREF p, int l, int h, int ch, int sidx, int rowbase  , LAS bf16_t* sXc, LAS float* stg, int lane) {
;     ...
;             for (int ti = 0; ti < 16; ++ti) { const size_t row = (size_t)(rowbase + mt * 16 + 15 - ti); grv[ti] = __builtin_bit_cast(float, (unsigned)P[row * PW + 512 + ch]); hfv[ti] = __builtin_bit_cast(float, (unsigned)TMP[row * 512 + ch]); }
;             __builtin_amdgcn_sched_barrier(0);
; #pragma unroll
;             for (int ti = 0; ti < 16; ++ti) { grv[ti] = bf2f(__builtin_bit_cast(unsigned, grv[ti])); hfv[ti] = bf2f(__builtin_bit_cast(unsigned, hfv[ti])); }
;         }
;         const bf16x8 A0 = *(const LAS bf16x8*)(sXc + (mt * 16 + (lane & 15)) * 72 + (lane >> 4) * 8), A1 = *(const LAS bf16x8*)(sXc + (mt * 16 + (lane & 15)) * 72 + 32 + (lane >> 4) * 8);
;         f32x4 ar[4], ai[4];
; #pragma unroll
;         for (int nt = 0; nt < 4; ++nt) { const f32x4 z = {0.f, 0.f, 0.f, 0.f};
;             ar[nt] = mfma16(A0, Br[nt][0], z); ar[nt] = mfma16(A1, Br[nt][1], ar[nt]); ai[nt] = mfma16(A0, Bi[nt][0], z); ai[nt] = mfma16(A1, Bi[nt][1], ai[nt]); }
;         WAVE_SYNC();
; #pragma unroll
;         for (int nt = 0; nt < 4; ++nt)
; #pragma unroll
;             for (int j = 0; j < 4; ++j) { const int o = ((lane >> 4) * 4 + j) * 64 + nt * 16 + (lane & 15); stg[o] = ar[nt][j]; stg[1024 + o] = ai[nt][j]; }
;         WAVE_SYNC();
;         float av[16], iv[16];
; #pragma unroll
;         for (int ti = 0; ti < 16; ++ti) { const int tk = D ? 15 - ti : ti;
;             const float zr = stg[tk * 64 + lane] + ba, zi = stg[1024 + tk * 64 + lane] + bi;
;             const float r = sigmoid_f(zr), ig = sigmoid_f(zi);
;             const float a = __builtin_amdgcn_exp2f(r * sp8);
;             const float xc = bf2f(sXc[(mt * 16 + tk) * 72 + lane]);
;             av[ti] = a; iv[ti] = __builtin_amdgcn_sqrtf(fmaxf(1.f - a * a, 0.f)) * ig * xc;
	v_rcp_f32_e32 v45, v45
	v_rcp_f32_e32 v46, v46
	v_rcp_f32_e32 v47, v47
	s_nop 0
	v_pk_mul_f32 v[206:207], v[32:33], v[206:207]
	v_pk_mul_f32 v[208:209], v[34:35], v[208:209]
	v_pk_mul_f32 v[210:211], v[36:37], v[210:211]
	v_pk_mul_f32 v[212:213], v[38:39], v[212:213]
	v_pk_mul_f32 v[214:215], v[40:41], v[214:215]
	v_pk_mul_f32 v[216:217], v[42:43], v[216:217]
	v_pk_mul_f32 v[218:219], v[44:45], v[218:219]
	v_pk_mul_f32 v[222:223], v[46:47], v[222:223]
	s_add_i32 s39, s15, 32
	s_mul_hi_u32 s83, s39, 0x1600
	s_mul_i32 s82, s39, 0x1600
	s_add_u32 s82, s82, s0
	s_addc_u32 s83, s83, s1
	s_add_u32 s82, s82, 0xbc00400
	s_addc_u32 s83, s83, 0
	global_load_ushort v190, v234, s[82:83]
	s_add_u32 s82, s82, 0x1600
	s_addc_u32 s83, s83, 0
	global_load_ushort v191, v234, s[82:83]
	s_add_u32 s82, s82, 0x1600
	s_addc_u32 s83, s83, 0
	global_load_ushort v192, v234, s[82:83]
	s_add_u32 s82, s82, 0x1600
	s_addc_u32 s83, s83, 0
	global_load_ushort v193, v234, s[82:83]
	s_add_u32 s82, s82, 0x1600
	s_addc_u32 s83, s83, 0
	global_load_ushort v194, v234, s[82:83]
	s_add_u32 s82, s82, 0x1600
	s_addc_u32 s83, s83, 0
	global_load_ushort v195, v234, s[82:83]
	s_add_u32 s82, s82, 0x1600
	s_addc_u32 s83, s83, 0
	global_load_ushort v196, v234, s[82:83]
	s_add_u32 s82, s82, 0x1600
	s_addc_u32 s83, s83, 0
	global_load_ushort v197, v234, s[82:83]
	s_add_u32 s82, s82, 0x1600
	s_addc_u32 s83, s83, 0
	global_load_ushort v198, v234, s[82:83]
	s_add_u32 s82, s82, 0x1600
	s_addc_u32 s83, s83, 0
	global_load_ushort v199, v234, s[82:83]
	s_add_u32 s82, s82, 0x1600
	s_addc_u32 s83, s83, 0
	global_load_ushort v200, v234, s[82:83]
	s_add_u32 s82, s82, 0x1600
	s_addc_u32 s83, s83, 0
	global_load_ushort v201, v234, s[82:83]
	s_add_u32 s82, s82, 0x1600
	s_addc_u32 s83, s83, 0
	global_load_ushort v202, v234, s[82:83]
	s_add_u32 s82, s82, 0x1600
	s_addc_u32 s83, s83, 0
	global_load_ushort v203, v234, s[82:83]
	s_add_u32 s82, s82, 0x1600
	s_addc_u32 s83, s83, 0
	global_load_ushort v204, v234, s[82:83]
	s_add_u32 s82, s82, 0x1600
	s_addc_u32 s83, s83, 0
	global_load_ushort v205, v234, s[82:83]
	s_waitcnt lgkmcnt(0)
	v_pk_add_f32 v[0:1], v[242:243], v[0:1]
	v_pk_add_f32 v[2:3], v[242:243], v[2:3]
	v_pk_add_f32 v[4:5], v[242:243], v[4:5]
	v_pk_add_f32 v[6:7], v[242:243], v[6:7]
	v_pk_add_f32 v[8:9], v[242:243], v[8:9]
	v_pk_add_f32 v[10:11], v[242:243], v[10:11]
	v_pk_add_f32 v[12:13], v[242:243], v[12:13]
	v_pk_add_f32 v[14:15], v[242:243], v[14:15]
	v_pk_add_f32 v[16:17], v[244:245], v[16:17]
	v_pk_add_f32 v[18:19], v[244:245], v[18:19]
	v_pk_add_f32 v[20:21], v[244:245], v[20:21]
	v_pk_add_f32 v[22:23], v[244:245], v[22:23]
	v_pk_add_f32 v[24:25], v[244:245], v[24:25]
	v_pk_add_f32 v[26:27], v[244:245], v[26:27]
	v_pk_add_f32 v[28:29], v[244:245], v[28:29]
	v_pk_add_f32 v[30:31], v[244:245], v[30:31]
	v_pk_mul_f32 v[0:1], v[248:249], v[0:1]
	v_pk_mul_f32 v[2:3], v[248:249], v[2:3]
	v_pk_mul_f32 v[4:5], v[248:249], v[4:5]
	v_pk_mul_f32 v[6:7], v[248:249], v[6:7]
	v_pk_mul_f32 v[8:9], v[248:249], v[8:9]
	v_pk_mul_f32 v[10:11], v[248:249], v[10:11]
	v_pk_mul_f32 v[12:13], v[248:249], v[12:13]
	v_pk_mul_f32 v[14:15], v[248:249], v[14:15]
	v_pk_mul_f32 v[16:17], v[248:249], v[16:17]
	v_pk_mul_f32 v[18:19], v[248:249], v[18:19]
	v_pk_mul_f32 v[20:21], v[248:249], v[20:21]
	v_pk_mul_f32 v[22:23], v[248:249], v[22:23]
	v_pk_mul_f32 v[24:25], v[248:249], v[24:25]
	v_pk_mul_f32 v[26:27], v[248:249], v[26:27]
	v_pk_mul_f32 v[28:29], v[248:249], v[28:29]
	v_pk_mul_f32 v[30:31], v[248:249], v[30:31]
	v_exp_f32_e32 v0, v0
	v_exp_f32_e32 v1, v1
	v_exp_f32_e32 v2, v2
	v_exp_f32_e32 v3, v3
	v_exp_f32_e32 v4, v4
	v_exp_f32_e32 v5, v5
	v_exp_f32_e32 v6, v6
	v_exp_f32_e32 v7, v7
	v_exp_f32_e32 v8, v8
	v_exp_f32_e32 v9, v9
	v_exp_f32_e32 v10, v10
	v_exp_f32_e32 v11, v11
	v_exp_f32_e32 v12, v12
	v_exp_f32_e32 v13, v13
	v_exp_f32_e32 v14, v14
	v_exp_f32_e32 v15, v15
	v_exp_f32_e32 v16, v16
	v_exp_f32_e32 v17, v17
	v_exp_f32_e32 v18, v18
	v_exp_f32_e32 v19, v19
	v_exp_f32_e32 v20, v20
	v_exp_f32_e32 v21, v21
	v_exp_f32_e32 v22, v22
	v_exp_f32_e32 v23, v23
	v_exp_f32_e32 v24, v24
	v_exp_f32_e32 v25, v25
	v_exp_f32_e32 v26, v26
	v_exp_f32_e32 v27, v27
	v_exp_f32_e32 v28, v28
	v_exp_f32_e32 v29, v29
	v_exp_f32_e32 v30, v30
	v_exp_f32_e32 v31, v31
	v_pk_add_f32 v[0:1], v[0:1], 1.0 op_sel_hi:[1,0]
	v_pk_add_f32 v[2:3], v[2:3], 1.0 op_sel_hi:[1,0]
	v_pk_add_f32 v[4:5], v[4:5], 1.0 op_sel_hi:[1,0]
	v_pk_add_f32 v[6:7], v[6:7], 1.0 op_sel_hi:[1,0]
	v_pk_add_f32 v[8:9], v[8:9], 1.0 op_sel_hi:[1,0]
	v_pk_add_f32 v[10:11], v[10:11], 1.0 op_sel_hi:[1,0]
	v_pk_add_f32 v[12:13], v[12:13], 1.0 op_sel_hi:[1,0]
	v_pk_add_f32 v[14:15], v[14:15], 1.0 op_sel_hi:[1,0]
	v_pk_add_f32 v[16:17], v[16:17], 1.0 op_sel_hi:[1,0]
	v_pk_add_f32 v[18:19], v[18:19], 1.0 op_sel_hi:[1,0]
	v_pk_add_f32 v[20:21], v[20:21], 1.0 op_sel_hi:[1,0]
	v_pk_add_f32 v[22:23], v[22:23], 1.0 op_sel_hi:[1,0]
	v_pk_add_f32 v[24:25], v[24:25], 1.0 op_sel_hi:[1,0]
	v_pk_add_f32 v[26:27], v[26:27], 1.0 op_sel_hi:[1,0]
	v_pk_add_f32 v[28:29], v[28:29], 1.0 op_sel_hi:[1,0]
	v_pk_add_f32 v[30:31], v[30:31], 1.0 op_sel_hi:[1,0]
	v_rcp_f32_e32 v0, v0
	v_rcp_f32_e32 v1, v1
	v_rcp_f32_e32 v2, v2
	v_rcp_f32_e32 v3, v3
	v_rcp_f32_e32 v4, v4
	v_rcp_f32_e32 v5, v5
	v_rcp_f32_e32 v6, v6
	v_rcp_f32_e32 v7, v7
	v_rcp_f32_e32 v8, v8
	v_rcp_f32_e32 v9, v9
	v_rcp_f32_e32 v10, v10
	v_rcp_f32_e32 v11, v11
	v_rcp_f32_e32 v12, v12
	v_rcp_f32_e32 v13, v13
	v_rcp_f32_e32 v14, v14
	v_rcp_f32_e32 v15, v15
	v_rcp_f32_e32 v16, v16
	v_rcp_f32_e32 v17, v17
	v_rcp_f32_e32 v18, v18
	v_rcp_f32_e32 v19, v19
	v_rcp_f32_e32 v20, v20
	v_rcp_f32_e32 v21, v21
	v_rcp_f32_e32 v22, v22
	v_rcp_f32_e32 v23, v23
; __device__ __forceinline__ unsigned f2bf(float f) { unsigned r; asm("v_cvt_pk_bf16_f32 %0, %1, %1" : "=v"(r) : "v"(f)); return r & 0xffffu; }
; __device__ __forceinline__ float sigmoid_f(float x) { return rcpf_(1.f + __expf(-x)); }
; __device__ __forceinline__ float gelu_tanh_f(float x) { const float y = 0.7978845608028654f * (x + 0.044715f * x * x * x); return x * sigmoid_f(2.f * y); }
; template <bool FINAL, int D>
; __device__ __forceinline__ void rg_dir(PREF p, int l, int h, int ch, int sidx, int rowbase  , LAS bf16_t* sXc, LAS float* stg, int lane) {
;     ...
;         for (int ti = 0; ti < 16; ++ti) { const int tk = D ? 15 - ti : ti;
;             const float zr = stg[tk * 64 + lane] + ba, zi = stg[1024 + tk * 64 + lane] + bi;
;             const float r = sigmoid_f(zr), ig = sigmoid_f(zi);
;             const float a = __builtin_amdgcn_exp2f(r * sp8);
;             const float xc = bf2f(sXc[(mt * 16 + tk) * 72 + lane]);
;             av[ti] = a; iv[ti] = __builtin_amdgcn_sqrtf(fmaxf(1.f - a * a, 0.f)) * ig * xc;
;             if (FINAL && D == 1) grv[ti] = gelu_tanh_f(grv[ti]);
;         }
; #pragma unroll
;         for (int ti = 0; ti < 16; ++ti) { const int tk = D ? 15 - ti : ti;
;             hc = av[ti] * hc + iv[ti]; Ap *= av[ti];
;             if (FINAL) { const size_t row = (size_t)(rowbase + mt * 16 + tk);
;                 if (D == 0) TMP[row * 512 + ch] = (bf16_t)f2bf(hc);
;                 else MIX[row * DM + ch] = (bf16_t)f2bf(grv[ti] * (hfv[ti] + hc)); }
	v_rcp_f32_e32 v24, v24
	v_rcp_f32_e32 v25, v25
	v_rcp_f32_e32 v26, v26
	v_rcp_f32_e32 v27, v27
	v_rcp_f32_e32 v28, v28
	v_rcp_f32_e32 v29, v29
	v_rcp_f32_e32 v30, v30
	v_rcp_f32_e32 v31, v31
	v_pk_mul_f32 v[0:1], v[246:247], v[0:1]
	v_pk_mul_f32 v[2:3], v[246:247], v[2:3]
	v_pk_mul_f32 v[4:5], v[246:247], v[4:5]
	v_pk_mul_f32 v[6:7], v[246:247], v[6:7]
	v_pk_mul_f32 v[8:9], v[246:247], v[8:9]
	v_pk_mul_f32 v[10:11], v[246:247], v[10:11]
	v_pk_mul_f32 v[12:13], v[246:247], v[12:13]
	v_pk_mul_f32 v[14:15], v[246:247], v[14:15]
	v_lshlrev_b32_e32 v48, 16, v48
	v_lshlrev_b32_e32 v49, 16, v49
	v_lshlrev_b32_e32 v50, 16, v50
	v_lshlrev_b32_e32 v51, 16, v51
	v_lshlrev_b32_e32 v52, 16, v52
	v_lshlrev_b32_e32 v53, 16, v53
	v_lshlrev_b32_e32 v54, 16, v54
	v_lshlrev_b32_e32 v55, 16, v55
	v_lshlrev_b32_e32 v56, 16, v56
	v_lshlrev_b32_e32 v57, 16, v57
	v_lshlrev_b32_e32 v58, 16, v58
	v_lshlrev_b32_e32 v59, 16, v59
	v_lshlrev_b32_e32 v60, 16, v60
	v_lshlrev_b32_e32 v61, 16, v61
	v_lshlrev_b32_e32 v62, 16, v62
	v_lshlrev_b32_e32 v63, 16, v63
	v_exp_f32_e32 v0, v0
	v_exp_f32_e32 v1, v1
	v_exp_f32_e32 v2, v2
	v_exp_f32_e32 v3, v3
	v_exp_f32_e32 v4, v4
	v_exp_f32_e32 v5, v5
	v_exp_f32_e32 v6, v6
	v_exp_f32_e32 v7, v7
	v_exp_f32_e32 v8, v8
	v_exp_f32_e32 v9, v9
	v_exp_f32_e32 v10, v10
	v_exp_f32_e32 v11, v11
	v_exp_f32_e32 v12, v12
	v_exp_f32_e32 v13, v13
	v_exp_f32_e32 v14, v14
	v_exp_f32_e32 v15, v15
	v_fma_f32 v32, -v0, v0, 1.0
	v_fma_f32 v33, -v1, v1, 1.0
	v_fma_f32 v34, -v2, v2, 1.0
	v_fma_f32 v35, -v3, v3, 1.0
	v_fma_f32 v36, -v4, v4, 1.0
	v_fma_f32 v37, -v5, v5, 1.0
	v_fma_f32 v38, -v6, v6, 1.0
	v_fma_f32 v39, -v7, v7, 1.0
	v_fma_f32 v40, -v8, v8, 1.0
	v_fma_f32 v41, -v9, v9, 1.0
	v_fma_f32 v42, -v10, v10, 1.0
	v_fma_f32 v43, -v11, v11, 1.0
	v_fma_f32 v44, -v12, v12, 1.0
	v_fma_f32 v45, -v13, v13, 1.0
	v_fma_f32 v46, -v14, v14, 1.0
	v_fma_f32 v47, -v15, v15, 1.0
	v_max_f32_e32 v32, 0, v32
	v_max_f32_e32 v33, 0, v33
	v_max_f32_e32 v34, 0, v34
	v_max_f32_e32 v35, 0, v35
	v_max_f32_e32 v36, 0, v36
	v_max_f32_e32 v37, 0, v37
	v_max_f32_e32 v38, 0, v38
	v_max_f32_e32 v39, 0, v39
	v_max_f32_e32 v40, 0, v40
	v_max_f32_e32 v41, 0, v41
	v_max_f32_e32 v42, 0, v42
	v_max_f32_e32 v43, 0, v43
	v_max_f32_e32 v44, 0, v44
	v_max_f32_e32 v45, 0, v45
	v_max_f32_e32 v46, 0, v46
	v_max_f32_e32 v47, 0, v47
	v_sqrt_f32_e32 v32, v32
	v_sqrt_f32_e32 v33, v33
	v_sqrt_f32_e32 v34, v34
	v_sqrt_f32_e32 v35, v35
	v_sqrt_f32_e32 v36, v36
	v_sqrt_f32_e32 v37, v37
	v_sqrt_f32_e32 v38, v38
	v_sqrt_f32_e32 v39, v39
	v_sqrt_f32_e32 v40, v40
	v_sqrt_f32_e32 v41, v41
	v_sqrt_f32_e32 v42, v42
	v_sqrt_f32_e32 v43, v43
	v_sqrt_f32_e32 v44, v44
	v_sqrt_f32_e32 v45, v45
	v_sqrt_f32_e32 v46, v46
	v_sqrt_f32_e32 v47, v47
	s_nop 0
	v_pk_mul_f32 v[16:17], v[16:17], v[32:33]
	v_pk_mul_f32 v[18:19], v[18:19], v[34:35]
	v_pk_mul_f32 v[20:21], v[20:21], v[36:37]
	v_pk_mul_f32 v[22:23], v[22:23], v[38:39]
	v_pk_mul_f32 v[24:25], v[24:25], v[40:41]
	v_pk_mul_f32 v[26:27], v[26:27], v[42:43]
	v_pk_mul_f32 v[28:29], v[28:29], v[44:45]
	v_pk_mul_f32 v[30:31], v[30:31], v[46:47]
	v_pk_mul_f32 v[16:17], v[16:17], v[48:49]
	v_pk_mul_f32 v[18:19], v[18:19], v[50:51]
	v_pk_mul_f32 v[20:21], v[20:21], v[52:53]
	v_pk_mul_f32 v[22:23], v[22:23], v[54:55]
	v_pk_mul_f32 v[24:25], v[24:25], v[56:57]
	v_pk_mul_f32 v[26:27], v[26:27], v[58:59]
	v_pk_mul_f32 v[28:29], v[28:29], v[60:61]
	v_pk_mul_f32 v[30:31], v[30:31], v[62:63]
	s_add_i32 s39, s15, 63
	s_lshl_b32 s39, s39, 11
	s_add_u32 s90, s0, 0x7b00000
	s_addc_u32 s91, s1, 0
	s_add_u32 s90, s90, s39
	s_addc_u32 s91, s91, 0
	v_lshlrev_b32_e32 v48, 16, v182
	v_and_b32_e32 v49, 0xffff0000, v182
	v_lshlrev_b32_e32 v50, 16, v183
	v_and_b32_e32 v51, 0xffff0000, v183
	v_lshlrev_b32_e32 v52, 16, v184
	v_and_b32_e32 v53, 0xffff0000, v184
	v_lshlrev_b32_e32 v54, 16, v185
	v_and_b32_e32 v55, 0xffff0000, v185
	v_lshlrev_b32_e32 v56, 16, v186
	v_and_b32_e32 v57, 0xffff0000, v186
	v_lshlrev_b32_e32 v58, 16, v187
	v_and_b32_e32 v59, 0xffff0000, v187
	v_lshlrev_b32_e32 v60, 16, v188
	v_and_b32_e32 v61, 0xffff0000, v188
	v_lshlrev_b32_e32 v62, 16, v189
	v_and_b32_e32 v63, 0xffff0000, v189
	v_fma_f32 v47, v15, v250, v31
	v_fma_f32 v46, v14, v47, v30
	v_fma_f32 v45, v13, v46, v29
	v_fma_f32 v44, v12, v45, v28
	v_fma_f32 v43, v11, v44, v27
	v_fma_f32 v42, v10, v43, v26
	v_fma_f32 v41, v9, v42, v25
	v_fma_f32 v40, v8, v41, v24
	v_fma_f32 v39, v7, v40, v23
	v_fma_f32 v38, v6, v39, v22
	v_fma_f32 v37, v5, v38, v21
	v_fma_f32 v36, v4, v37, v20
	v_fma_f32 v35, v3, v36, v19
	v_fma_f32 v34, v2, v35, v18
	v_fma_f32 v33, v1, v34, v17
	v_fma_f32 v32, v0, v33, v16
	v_mov_b32_e32 v250, v32
	v_pk_add_f32 v[48:49], v[48:49], v[32:33]
	v_pk_add_f32 v[50:51], v[50:51], v[34:35]
	v_pk_add_f32 v[52:53], v[52:53], v[36:37]
	v_pk_add_f32 v[54:55], v[54:55], v[38:39]
	v_pk_add_f32 v[56:57], v[56:57], v[40:41]
	v_pk_add_f32 v[58:59], v[58:59], v[42:43]
	v_pk_add_f32 v[60:61], v[60:61], v[44:45]
	v_pk_add_f32 v[62:63], v[62:63], v[46:47]
	v_pk_mul_f32 v[48:49], v[206:207], v[48:49]
	v_pk_mul_f32 v[50:51], v[208:209], v[50:51]
	v_pk_mul_f32 v[52:53], v[210:211], v[52:53]
	v_pk_mul_f32 v[54:55], v[212:213], v[54:55]
	v_pk_mul_f32 v[56:57], v[214:215], v[56:57]
	v_pk_mul_f32 v[58:59], v[216:217], v[58:59]
	v_pk_mul_f32 v[60:61], v[218:219], v[60:61]
	v_pk_mul_f32 v[62:63], v[222:223], v[62:63]
	v_cvt_pk_bf16_f32 v48, v48, v48
	v_cvt_pk_bf16_f32 v49, v49, v49
	v_cvt_pk_bf16_f32 v50, v50, v50
	v_cvt_pk_bf16_f32 v51, v51, v51
	v_cvt_pk_bf16_f32 v52, v52, v52
	v_cvt_pk_bf16_f32 v53, v53, v53
	v_cvt_pk_bf16_f32 v54, v54, v54
	v_cvt_pk_bf16_f32 v55, v55, v55
	v_cvt_pk_bf16_f32 v56, v56, v56
	v_cvt_pk_bf16_f32 v57, v57, v57
; #define LAS __attribute__((address_space(3)))
; #define WAVE_SYNC() asm volatile("s_waitcnt lgkmcnt(0)" ::: "memory")
; __device__ __forceinline__ unsigned f2bf(float f) { unsigned r; asm("v_cvt_pk_bf16_f32 %0, %1, %1" : "=v"(r) : "v"(f)); return r & 0xffffu; }
; __device__ __forceinline__ f32x4 mfma16(bf16x8 a, bf16x8 b, f32x4 c) { return __builtin_amdgcn_mfma_f32_16x16x32_bf16(a, b, c, 0, 0, 0); }
; template <bool FINAL, int D>
; __device__ __forceinline__ void rg_dir(PREF p, int l, int h, int ch, int sidx, int rowbase  , LAS bf16_t* sXc, LAS float* stg, int lane) {
;     ...
;         const bf16x8 A0 = *(const LAS bf16x8*)(sXc + (mt * 16 + (lane & 15)) * 72 + (lane >> 4) * 8), A1 = *(const LAS bf16x8*)(sXc + (mt * 16 + (lane & 15)) * 72 + 32 + (lane >> 4) * 8);
;         f32x4 ar[4], ai[4];
; #pragma unroll
;         for (int nt = 0; nt < 4; ++nt) { const f32x4 z = {0.f, 0.f, 0.f, 0.f};
;             ar[nt] = mfma16(A0, Br[nt][0], z); ar[nt] = mfma16(A1, Br[nt][1], ar[nt]); ai[nt] = mfma16(A0, Bi[nt][0], z); ai[nt] = mfma16(A1, Bi[nt][1], ai[nt]); }
;         WAVE_SYNC();
; #pragma unroll
;         for (int nt = 0; nt < 4; ++nt)
; #pragma unroll
;             for (int j = 0; j < 4; ++j) { const int o = ((lane >> 4) * 4 + j) * 64 + nt * 16 + (lane & 15); stg[o] = ar[nt][j]; stg[1024 + o] = ai[nt][j]; }
;         WAVE_SYNC();
;         float av[16], iv[16];
; #pragma unroll
;         for (int ti = 0; ti < 16; ++ti) { const int tk = D ? 15 - ti : ti;
;             const float zr = stg[tk * 64 + lane] + ba, zi = stg[1024 + tk * 64 + lane] + bi;
;     ...
;         for (int ti = 0; ti < 16; ++ti) { const int tk = D ? 15 - ti : ti;
;             hc = av[ti] * hc + iv[ti]; Ap *= av[ti];
;             if (FINAL) { const size_t row = (size_t)(rowbase + mt * 16 + tk);
;                 if (D == 0) TMP[row * 512 + ch] = (bf16_t)f2bf(hc);
;                 else MIX[row * DM + ch] = (bf16_t)f2bf(grv[ti] * (hfv[ti] + hc)); }
	v_cvt_pk_bf16_f32 v58, v58, v58
	v_cvt_pk_bf16_f32 v59, v59, v59
	v_cvt_pk_bf16_f32 v60, v60, v60
	v_cvt_pk_bf16_f32 v61, v61, v61
	v_cvt_pk_bf16_f32 v62, v62, v62
	v_cvt_pk_bf16_f32 v63, v63, v63
	global_store_short v234, v63, s[90:91]
	s_sub_u32 s90, s90, 0x800
	s_subb_u32 s91, s91, 0
	global_store_short v234, v62, s[90:91]
	s_sub_u32 s90, s90, 0x800
	s_subb_u32 s91, s91, 0
	global_store_short v234, v61, s[90:91]
	s_sub_u32 s90, s90, 0x800
	s_subb_u32 s91, s91, 0
	global_store_short v234, v60, s[90:91]
	s_sub_u32 s90, s90, 0x800
	s_subb_u32 s91, s91, 0
	global_store_short v234, v59, s[90:91]
	s_sub_u32 s90, s90, 0x800
	s_subb_u32 s91, s91, 0
	global_store_short v234, v58, s[90:91]
	s_sub_u32 s90, s90, 0x800
	s_subb_u32 s91, s91, 0
	global_store_short v234, v57, s[90:91]
	s_sub_u32 s90, s90, 0x800
	s_subb_u32 s91, s91, 0
	global_store_short v234, v56, s[90:91]
	s_sub_u32 s90, s90, 0x800
	s_subb_u32 s91, s91, 0
	global_store_short v234, v55, s[90:91]
	s_sub_u32 s90, s90, 0x800
	s_subb_u32 s91, s91, 0
	global_store_short v234, v54, s[90:91]
	s_sub_u32 s90, s90, 0x800
	s_subb_u32 s91, s91, 0
	global_store_short v234, v53, s[90:91]
	s_sub_u32 s90, s90, 0x800
	s_subb_u32 s91, s91, 0
	global_store_short v234, v52, s[90:91]
	s_sub_u32 s90, s90, 0x800
	s_subb_u32 s91, s91, 0
	global_store_short v234, v51, s[90:91]
	s_sub_u32 s90, s90, 0x800
	s_subb_u32 s91, s91, 0
	global_store_short v234, v50, s[90:91]
	s_sub_u32 s90, s90, 0x800
	s_subb_u32 s91, s91, 0
	global_store_short v234, v49, s[90:91]
	s_sub_u32 s90, s90, 0x800
	s_subb_u32 s91, s91, 0
	global_store_short v234, v48, s[90:91]
	ds_read_b128 v[32:35], v236 offset:4608
	ds_read_b128 v[36:39], v236 offset:4672
	s_waitcnt lgkmcnt(0)
	v_mfma_f32_16x16x32_bf16 v[0:3], v[32:35], v[80:83], 0
	v_mfma_f32_16x16x32_bf16 v[4:7], v[32:35], v[88:91], 0
	v_mfma_f32_16x16x32_bf16 v[8:11], v[32:35], v[96:99], 0
	v_mfma_f32_16x16x32_bf16 v[12:15], v[32:35], v[104:107], 0
	v_mfma_f32_16x16x32_bf16 v[16:19], v[32:35], v[112:115], 0
	v_mfma_f32_16x16x32_bf16 v[20:23], v[32:35], v[120:123], 0
	v_mfma_f32_16x16x32_bf16 v[24:27], v[32:35], v[128:131], 0
	v_mfma_f32_16x16x32_bf16 v[28:31], v[32:35], v[136:139], 0
	v_mfma_f32_16x16x32_bf16 v[0:3], v[36:39], v[84:87], v[0:3]
	v_mfma_f32_16x16x32_bf16 v[4:7], v[36:39], v[92:95], v[4:7]
	v_mfma_f32_16x16x32_bf16 v[8:11], v[36:39], v[100:103], v[8:11]
	v_mfma_f32_16x16x32_bf16 v[12:15], v[36:39], v[108:111], v[12:15]
	v_mfma_f32_16x16x32_bf16 v[16:19], v[36:39], v[116:119], v[16:19]
	v_mfma_f32_16x16x32_bf16 v[20:23], v[36:39], v[124:127], v[20:23]
	v_mfma_f32_16x16x32_bf16 v[24:27], v[36:39], v[132:135], v[24:27]
	v_mfma_f32_16x16x32_bf16 v[28:31], v[36:39], v[228:231], v[28:31]
	s_nop 3
	ds_write2_b32 v237, v0, v4 offset0:0 offset1:16
	ds_write2_b32 v237, v8, v12 offset0:32 offset1:48
	ds_write2_b32 v237, v1, v5 offset0:64 offset1:80
	ds_write2_b32 v237, v9, v13 offset0:96 offset1:112
	ds_write2_b32 v237, v2, v6 offset0:128 offset1:144
	ds_write2_b32 v237, v10, v14 offset0:160 offset1:176
	ds_write2_b32 v237, v3, v7 offset0:192 offset1:208
	ds_write2_b32 v237, v11, v15 offset0:224 offset1:240
	ds_write2_b32 v238, v16, v20 offset0:0 offset1:16
	ds_write2_b32 v238, v24, v28 offset0:32 offset1:48
	ds_write2_b32 v238, v17, v21 offset0:64 offset1:80
	ds_write2_b32 v238, v25, v29 offset0:96 offset1:112
	ds_write2_b32 v238, v18, v22 offset0:128 offset1:144
	ds_write2_b32 v238, v26, v30 offset0:160 offset1:176
	ds_write2_b32 v238, v19, v23 offset0:192 offset1:208
	ds_write2_b32 v238, v27, v31 offset0:224 offset1:240
	s_waitcnt lgkmcnt(0)
	ds_read2st64_b32 v[0:1], v239 offset0:36 offset1:37
	ds_read2st64_b32 v[2:3], v239 offset0:38 offset1:39
	ds_read2st64_b32 v[4:5], v239 offset0:40 offset1:41
	ds_read2st64_b32 v[6:7], v239 offset0:42 offset1:43
	ds_read2st64_b32 v[8:9], v239 offset0:44 offset1:45
	ds_read2st64_b32 v[10:11], v239 offset0:46 offset1:47
	ds_read2st64_b32 v[12:13], v239 offset0:48 offset1:49
	ds_read2st64_b32 v[14:15], v239 offset0:50 offset1:51
	ds_read2st64_b32 v[16:17], v239 offset0:52 offset1:53
	ds_read2st64_b32 v[18:19], v239 offset0:54 offset1:55
	ds_read2st64_b32 v[20:21], v239 offset0:56 offset1:57
	ds_read2st64_b32 v[22:23], v239 offset0:58 offset1:59
	ds_read2st64_b32 v[24:25], v239 offset0:60 offset1:61
	ds_read2st64_b32 v[26:27], v239 offset0:62 offset1:63
	ds_read2st64_b32 v[28:29], v239 offset0:64 offset1:65
	ds_read2st64_b32 v[30:31], v239 offset0:66 offset1:67
	ds_read_u16 v48, v240 offset:4608
	ds_read_u16 v49, v240 offset:4752
	ds_read_u16 v50, v240 offset:4896
	ds_read_u16 v51, v240 offset:5040
	ds_read_u16 v52, v240 offset:5184
	ds_read_u16 v53, v240 offset:5328
	ds_read_u16 v54, v240 offset:5472
	ds_read_u16 v55, v240 offset:5616
	ds_read_u16 v56, v240 offset:5760
	ds_read_u16 v57, v240 offset:5904
	ds_read_u16 v58, v240 offset:6048
	ds_read_u16 v59, v240 offset:6192
	ds_read_u16 v60, v240 offset:6336
	ds_read_u16 v61, v240 offset:6480
	ds_read_u16 v62, v240 offset:6624
	ds_read_u16 v63, v240 offset:6768
	s_waitcnt vmcnt(16)
; #define LAS __attribute__((address_space(3)))
; #define WAVE_SYNC() asm volatile("s_waitcnt lgkmcnt(0)" ::: "memory")
; __device__ __forceinline__ float sigmoid_f(float x) { return rcpf_(1.f + __expf(-x)); }
; template <bool FINAL, int D>
; __device__ __forceinline__ void rg_dir(PREF p, int l, int h, int ch, int sidx, int rowbase  , LAS bf16_t* sXc, LAS float* stg, int lane) {
;     ...
;         if (FINAL && D == 1) {
; #pragma unroll
;             for (int ti = 0; ti < 16; ++ti) { const size_t row = (size_t)(rowbase + mt * 16 + 15 - ti); grv[ti] = __builtin_bit_cast(float, (unsigned)P[row * PW + 512 + ch]); hfv[ti] = __builtin_bit_cast(float, (unsigned)TMP[row * 512 + ch]); }
;             __builtin_amdgcn_sched_barrier(0);
; #pragma unroll
;             for (int ti = 0; ti < 16; ++ti) { grv[ti] = bf2f(__builtin_bit_cast(unsigned, grv[ti])); hfv[ti] = bf2f(__builtin_bit_cast(unsigned, hfv[ti])); }
;         }
;         const bf16x8 A0 = *(const LAS bf16x8*)(sXc + (mt * 16 + (lane & 15)) * 72 + (lane >> 4) * 8), A1 = *(const LAS bf16x8*)(sXc + (mt * 16 + (lane & 15)) * 72 + 32 + (lane >> 4) * 8);
;         f32x4 ar[4], ai[4];
; #pragma unroll
;         for (int nt = 0; nt < 4; ++nt) { const f32x4 z = {0.f, 0.f, 0.f, 0.f};
;             ar[nt] = mfma16(A0, Br[nt][0], z); ar[nt] = mfma16(A1, Br[nt][1], ar[nt]); ai[nt] = mfma16(A0, Bi[nt][0], z); ai[nt] = mfma16(A1, Bi[nt][1], ai[nt]); }
;         WAVE_SYNC();
; #pragma unroll
;         for (int nt = 0; nt < 4; ++nt)
; #pragma unroll
;             for (int j = 0; j < 4; ++j) { const int o = ((lane >> 4) * 4 + j) * 64 + nt * 16 + (lane & 15); stg[o] = ar[nt][j]; stg[1024 + o] = ai[nt][j]; }
;         WAVE_SYNC();
;         float av[16], iv[16];
; #pragma unroll
;         for (int ti = 0; ti < 16; ++ti) { const int tk = D ? 15 - ti : ti;
;             const float zr = stg[tk * 64 + lane] + ba, zi = stg[1024 + tk * 64 + lane] + bi;
;             const float r = sigmoid_f(zr), ig = sigmoid_f(zi);
;             const float a = __builtin_amdgcn_exp2f(r * sp8);
;             const float xc = bf2f(sXc[(mt * 16 + tk) * 72 + lane]);
;             av[ti] = a; iv[ti] = __builtin_amdgcn_sqrtf(fmaxf(1.f - a * a, 0.f)) * ig * xc;
;             if (FINAL && D == 1) grv[ti] = gelu_tanh_f(grv[ti]);
	v_lshlrev_b32_e32 v206, 16, v190
	v_lshlrev_b32_e32 v207, 16, v191
	v_lshlrev_b32_e32 v208, 16, v192
	v_lshlrev_b32_e32 v209, 16, v193
	v_lshlrev_b32_e32 v210, 16, v194
	v_lshlrev_b32_e32 v211, 16, v195
	v_lshlrev_b32_e32 v212, 16, v196
	v_lshlrev_b32_e32 v213, 16, v197
	v_lshlrev_b32_e32 v214, 16, v198
	v_lshlrev_b32_e32 v215, 16, v199
	v_lshlrev_b32_e32 v216, 16, v200
	v_lshlrev_b32_e32 v217, 16, v201
	v_lshlrev_b32_e32 v218, 16, v202
	v_lshlrev_b32_e32 v219, 16, v203
	v_lshlrev_b32_e32 v222, 16, v204
	v_lshlrev_b32_e32 v223, 16, v205
	v_pk_mul_f32 v[32:33], v[140:141], v[206:207]
	v_pk_mul_f32 v[34:35], v[140:141], v[208:209]
	v_pk_mul_f32 v[36:37], v[140:141], v[210:211]
	v_pk_mul_f32 v[38:39], v[140:141], v[212:213]
	v_pk_mul_f32 v[40:41], v[140:141], v[214:215]
	v_pk_mul_f32 v[42:43], v[140:141], v[216:217]
	v_pk_mul_f32 v[44:45], v[140:141], v[218:219]
	v_pk_mul_f32 v[46:47], v[140:141], v[222:223]
	v_pk_mul_f32 v[32:33], v[32:33], v[206:207]
	v_pk_mul_f32 v[34:35], v[34:35], v[208:209]
	v_pk_mul_f32 v[36:37], v[36:37], v[210:211]
	v_pk_mul_f32 v[38:39], v[38:39], v[212:213]
	v_pk_mul_f32 v[40:41], v[40:41], v[214:215]
	v_pk_mul_f32 v[42:43], v[42:43], v[216:217]
	v_pk_mul_f32 v[44:45], v[44:45], v[218:219]
	v_pk_mul_f32 v[46:47], v[46:47], v[222:223]
	v_fma_f32 v32, v32, v206, v206
	v_fma_f32 v33, v33, v207, v207
	v_fma_f32 v34, v34, v208, v208
	v_fma_f32 v35, v35, v209, v209
	v_fma_f32 v36, v36, v210, v210
	v_fma_f32 v37, v37, v211, v211
	v_fma_f32 v38, v38, v212, v212
	v_fma_f32 v39, v39, v213, v213
	v_fma_f32 v40, v40, v214, v214
	v_fma_f32 v41, v41, v215, v215
	v_fma_f32 v42, v42, v216, v216
	v_fma_f32 v43, v43, v217, v217
	v_fma_f32 v44, v44, v218, v218
	v_fma_f32 v45, v45, v219, v219
	v_fma_f32 v46, v46, v222, v222
	v_fma_f32 v47, v47, v223, v223
	v_mul_f32_e32 v32, 0x3f4c422a, v32
	v_mul_f32_e32 v33, 0x3f4c422a, v33
	v_mul_f32_e32 v34, 0x3f4c422a, v34
	v_mul_f32_e32 v35, 0x3f4c422a, v35
	v_mul_f32_e32 v36, 0x3f4c422a, v36
	v_mul_f32_e32 v37, 0x3f4c422a, v37
	v_mul_f32_e32 v38, 0x3f4c422a, v38
	v_mul_f32_e32 v39, 0x3f4c422a, v39
	v_mul_f32_e32 v40, 0x3f4c422a, v40
	v_mul_f32_e32 v41, 0x3f4c422a, v41
	v_mul_f32_e32 v42, 0x3f4c422a, v42
	v_mul_f32_e32 v43, 0x3f4c422a, v43
	v_mul_f32_e32 v44, 0x3f4c422a, v44
	v_mul_f32_e32 v45, 0x3f4c422a, v45
	v_mul_f32_e32 v46, 0x3f4c422a, v46
	v_mul_f32_e32 v47, 0x3f4c422a, v47
	v_pk_add_f32 v[32:33], v[32:33], v[32:33]
	v_pk_add_f32 v[34:35], v[34:35], v[34:35]
	v_pk_add_f32 v[36:37], v[36:37], v[36:37]
	v_pk_add_f32 v[38:39], v[38:39], v[38:39]
	v_pk_add_f32 v[40:41], v[40:41], v[40:41]
	v_pk_add_f32 v[42:43], v[42:43], v[42:43]
	v_pk_add_f32 v[44:45], v[44:45], v[44:45]
	v_pk_add_f32 v[46:47], v[46:47], v[46:47]
	v_pk_mul_f32 v[32:33], v[248:249], v[32:33]
	v_pk_mul_f32 v[34:35], v[248:249], v[34:35]
	v_pk_mul_f32 v[36:37], v[248:249], v[36:37]
	v_pk_mul_f32 v[38:39], v[248:249], v[38:39]
	v_pk_mul_f32 v[40:41], v[248:249], v[40:41]
	v_pk_mul_f32 v[42:43], v[248:249], v[42:43]
	v_pk_mul_f32 v[44:45], v[248:249], v[44:45]
	v_pk_mul_f32 v[46:47], v[248:249], v[46:47]
	v_exp_f32_e32 v32, v32
	v_exp_f32_e32 v33, v33
	v_exp_f32_e32 v34, v34
	v_exp_f32_e32 v35, v35
	v_exp_f32_e32 v36, v36
	v_exp_f32_e32 v37, v37
	v_exp_f32_e32 v38, v38
	v_exp_f32_e32 v39, v39
	v_exp_f32_e32 v40, v40
	v_exp_f32_e32 v41, v41
	v_exp_f32_e32 v42, v42
	v_exp_f32_e32 v43, v43
	v_exp_f32_e32 v44, v44
	v_exp_f32_e32 v45, v45
	v_exp_f32_e32 v46, v46
	v_exp_f32_e32 v47, v47
	v_pk_add_f32 v[32:33], v[32:33], 1.0 op_sel_hi:[1,0]
	v_pk_add_f32 v[34:35], v[34:35], 1.0 op_sel_hi:[1,0]
	v_pk_add_f32 v[36:37], v[36:37], 1.0 op_sel_hi:[1,0]
	v_pk_add_f32 v[38:39], v[38:39], 1.0 op_sel_hi:[1,0]
	v_pk_add_f32 v[40:41], v[40:41], 1.0 op_sel_hi:[1,0]
	v_pk_add_f32 v[42:43], v[42:43], 1.0 op_sel_hi:[1,0]
	v_pk_add_f32 v[44:45], v[44:45], 1.0 op_sel_hi:[1,0]
	v_pk_add_f32 v[46:47], v[46:47], 1.0 op_sel_hi:[1,0]
	v_rcp_f32_e32 v32, v32
	v_rcp_f32_e32 v33, v33
	v_rcp_f32_e32 v34, v34
	v_rcp_f32_e32 v35, v35
	v_rcp_f32_e32 v36, v36
	v_rcp_f32_e32 v37, v37
	v_rcp_f32_e32 v38, v38
	v_rcp_f32_e32 v39, v39
	v_rcp_f32_e32 v40, v40
	v_rcp_f32_e32 v41, v41
	v_rcp_f32_e32 v42, v42
	v_rcp_f32_e32 v43, v43
	v_rcp_f32_e32 v44, v44
	v_rcp_f32_e32 v45, v45
	v_rcp_f32_e32 v46, v46
	v_rcp_f32_e32 v47, v47
	s_nop 0
	v_pk_mul_f32 v[206:207], v[32:33], v[206:207]
	v_pk_mul_f32 v[208:209], v[34:35], v[208:209]
	v_pk_mul_f32 v[210:211], v[36:37], v[210:211]
	v_pk_mul_f32 v[212:213], v[38:39], v[212:213]
	v_pk_mul_f32 v[214:215], v[40:41], v[214:215]
	v_pk_mul_f32 v[216:217], v[42:43], v[216:217]
	v_pk_mul_f32 v[218:219], v[44:45], v[218:219]
	v_pk_mul_f32 v[222:223], v[46:47], v[222:223]
	s_add_i32 s39, s15, 16
	s_mul_hi_u32 s83, s39, 0x1600
	s_mul_i32 s82, s39, 0x1600
	s_add_u32 s82, s82, s0
	s_addc_u32 s83, s83, s1
	s_add_u32 s82, s82, 0xbc00400
	s_addc_u32 s83, s83, 0
	global_load_ushort v190, v234, s[82:83]
	s_add_u32 s82, s82, 0x1600
	s_addc_u32 s83, s83, 0
	global_load_ushort v191, v234, s[82:83]
	s_add_u32 s82, s82, 0x1600
	s_addc_u32 s83, s83, 0
	global_load_ushort v192, v234, s[82:83]
	s_add_u32 s82, s82, 0x1600
	s_addc_u32 s83, s83, 0
	global_load_ushort v193, v234, s[82:83]
	s_add_u32 s82, s82, 0x1600
	s_addc_u32 s83, s83, 0
	global_load_ushort v194, v234, s[82:83]
	s_add_u32 s82, s82, 0x1600
	s_addc_u32 s83, s83, 0
	global_load_ushort v195, v234, s[82:83]
	s_add_u32 s82, s82, 0x1600
	s_addc_u32 s83, s83, 0
	global_load_ushort v196, v234, s[82:83]
	s_add_u32 s82, s82, 0x1600
	s_addc_u32 s83, s83, 0
	global_load_ushort v197, v234, s[82:83]
	s_add_u32 s82, s82, 0x1600
	s_addc_u32 s83, s83, 0
	global_load_ushort v198, v234, s[82:83]
	s_add_u32 s82, s82, 0x1600
	s_addc_u32 s83, s83, 0
	global_load_ushort v199, v234, s[82:83]
	s_add_u32 s82, s82, 0x1600
	s_addc_u32 s83, s83, 0
	global_load_ushort v200, v234, s[82:83]
	s_add_u32 s82, s82, 0x1600
	s_addc_u32 s83, s83, 0
	global_load_ushort v201, v234, s[82:83]
	s_add_u32 s82, s82, 0x1600
	s_addc_u32 s83, s83, 0
	global_load_ushort v202, v234, s[82:83]
	s_add_u32 s82, s82, 0x1600
	s_addc_u32 s83, s83, 0
	global_load_ushort v203, v234, s[82:83]
	s_add_u32 s82, s82, 0x1600
	s_addc_u32 s83, s83, 0
	global_load_ushort v204, v234, s[82:83]
	s_add_u32 s82, s82, 0x1600
	s_addc_u32 s83, s83, 0
	global_load_ushort v205, v234, s[82:83]
	s_waitcnt lgkmcnt(0)
; __device__ __forceinline__ float sigmoid_f(float x) { return rcpf_(1.f + __expf(-x)); }
; template <bool FINAL, int D>
; __device__ __forceinline__ void rg_dir(PREF p, int l, int h, int ch, int sidx, int rowbase  , LAS bf16_t* sXc, LAS float* stg, int lane) {
;     ...
;         for (int ti = 0; ti < 16; ++ti) { const int tk = D ? 15 - ti : ti;
;             const float zr = stg[tk * 64 + lane] + ba, zi = stg[1024 + tk * 64 + lane] + bi;
;             const float r = sigmoid_f(zr), ig = sigmoid_f(zi);
;             const float a = __builtin_amdgcn_exp2f(r * sp8);
;             const float xc = bf2f(sXc[(mt * 16 + tk) * 72 + lane]);
;             av[ti] = a; iv[ti] = __builtin_amdgcn_sqrtf(fmaxf(1.f - a * a, 0.f)) * ig * xc;
	v_pk_add_f32 v[0:1], v[242:243], v[0:1]
	v_pk_add_f32 v[2:3], v[242:243], v[2:3]
	v_pk_add_f32 v[4:5], v[242:243], v[4:5]
	v_pk_add_f32 v[6:7], v[242:243], v[6:7]
	v_pk_add_f32 v[8:9], v[242:243], v[8:9]
	v_pk_add_f32 v[10:11], v[242:243], v[10:11]
	v_pk_add_f32 v[12:13], v[242:243], v[12:13]
	v_pk_add_f32 v[14:15], v[242:243], v[14:15]
	v_pk_add_f32 v[16:17], v[244:245], v[16:17]
	v_pk_add_f32 v[18:19], v[244:245], v[18:19]
	v_pk_add_f32 v[20:21], v[244:245], v[20:21]
	v_pk_add_f32 v[22:23], v[244:245], v[22:23]
	v_pk_add_f32 v[24:25], v[244:245], v[24:25]
	v_pk_add_f32 v[26:27], v[244:245], v[26:27]
	v_pk_add_f32 v[28:29], v[244:245], v[28:29]
	v_pk_add_f32 v[30:31], v[244:245], v[30:31]
	v_pk_mul_f32 v[0:1], v[248:249], v[0:1]
	v_pk_mul_f32 v[2:3], v[248:249], v[2:3]
	v_pk_mul_f32 v[4:5], v[248:249], v[4:5]
	v_pk_mul_f32 v[6:7], v[248:249], v[6:7]
	v_pk_mul_f32 v[8:9], v[248:249], v[8:9]
	v_pk_mul_f32 v[10:11], v[248:249], v[10:11]
	v_pk_mul_f32 v[12:13], v[248:249], v[12:13]
	v_pk_mul_f32 v[14:15], v[248:249], v[14:15]
	v_pk_mul_f32 v[16:17], v[248:249], v[16:17]
	v_pk_mul_f32 v[18:19], v[248:249], v[18:19]
	v_pk_mul_f32 v[20:21], v[248:249], v[20:21]
	v_pk_mul_f32 v[22:23], v[248:249], v[22:23]
	v_pk_mul_f32 v[24:25], v[248:249], v[24:25]
	v_pk_mul_f32 v[26:27], v[248:249], v[26:27]
	v_pk_mul_f32 v[28:29], v[248:249], v[28:29]
	v_pk_mul_f32 v[30:31], v[248:249], v[30:31]
	v_exp_f32_e32 v0, v0
	v_exp_f32_e32 v1, v1
	v_exp_f32_e32 v2, v2
	v_exp_f32_e32 v3, v3
	v_exp_f32_e32 v4, v4
	v_exp_f32_e32 v5, v5
	v_exp_f32_e32 v6, v6
	v_exp_f32_e32 v7, v7
	v_exp_f32_e32 v8, v8
	v_exp_f32_e32 v9, v9
	v_exp_f32_e32 v10, v10
	v_exp_f32_e32 v11, v11
	v_exp_f32_e32 v12, v12
	v_exp_f32_e32 v13, v13
	v_exp_f32_e32 v14, v14
	v_exp_f32_e32 v15, v15
	v_exp_f32_e32 v16, v16
	v_exp_f32_e32 v17, v17
	v_exp_f32_e32 v18, v18
	v_exp_f32_e32 v19, v19
	v_exp_f32_e32 v20, v20
	v_exp_f32_e32 v21, v21
	v_exp_f32_e32 v22, v22
	v_exp_f32_e32 v23, v23
	v_exp_f32_e32 v24, v24
	v_exp_f32_e32 v25, v25
	v_exp_f32_e32 v26, v26
	v_exp_f32_e32 v27, v27
	v_exp_f32_e32 v28, v28
	v_exp_f32_e32 v29, v29
	v_exp_f32_e32 v30, v30
	v_exp_f32_e32 v31, v31
	v_pk_add_f32 v[0:1], v[0:1], 1.0 op_sel_hi:[1,0]
	v_pk_add_f32 v[2:3], v[2:3], 1.0 op_sel_hi:[1,0]
	v_pk_add_f32 v[4:5], v[4:5], 1.0 op_sel_hi:[1,0]
	v_pk_add_f32 v[6:7], v[6:7], 1.0 op_sel_hi:[1,0]
	v_pk_add_f32 v[8:9], v[8:9], 1.0 op_sel_hi:[1,0]
	v_pk_add_f32 v[10:11], v[10:11], 1.0 op_sel_hi:[1,0]
	v_pk_add_f32 v[12:13], v[12:13], 1.0 op_sel_hi:[1,0]
	v_pk_add_f32 v[14:15], v[14:15], 1.0 op_sel_hi:[1,0]
	v_pk_add_f32 v[16:17], v[16:17], 1.0 op_sel_hi:[1,0]
	v_pk_add_f32 v[18:19], v[18:19], 1.0 op_sel_hi:[1,0]
	v_pk_add_f32 v[20:21], v[20:21], 1.0 op_sel_hi:[1,0]
	v_pk_add_f32 v[22:23], v[22:23], 1.0 op_sel_hi:[1,0]
	v_pk_add_f32 v[24:25], v[24:25], 1.0 op_sel_hi:[1,0]
	v_pk_add_f32 v[26:27], v[26:27], 1.0 op_sel_hi:[1,0]
	v_pk_add_f32 v[28:29], v[28:29], 1.0 op_sel_hi:[1,0]
	v_pk_add_f32 v[30:31], v[30:31], 1.0 op_sel_hi:[1,0]
	v_rcp_f32_e32 v0, v0
	v_rcp_f32_e32 v1, v1
	v_rcp_f32_e32 v2, v2
	v_rcp_f32_e32 v3, v3
	v_rcp_f32_e32 v4, v4
	v_rcp_f32_e32 v5, v5
	v_rcp_f32_e32 v6, v6
	v_rcp_f32_e32 v7, v7
	v_rcp_f32_e32 v8, v8
	v_rcp_f32_e32 v9, v9
	v_rcp_f32_e32 v10, v10
	v_rcp_f32_e32 v11, v11
	v_rcp_f32_e32 v12, v12
	v_rcp_f32_e32 v13, v13
	v_rcp_f32_e32 v14, v14
	v_rcp_f32_e32 v15, v15
	v_rcp_f32_e32 v16, v16
	v_rcp_f32_e32 v17, v17
	v_rcp_f32_e32 v18, v18
	v_rcp_f32_e32 v19, v19
	v_rcp_f32_e32 v20, v20
	v_rcp_f32_e32 v21, v21
	v_rcp_f32_e32 v22, v22
	v_rcp_f32_e32 v23, v23
	v_rcp_f32_e32 v24, v24
	v_rcp_f32_e32 v25, v25
	v_rcp_f32_e32 v26, v26
	v_rcp_f32_e32 v27, v27
	v_rcp_f32_e32 v28, v28
	v_rcp_f32_e32 v29, v29
	v_rcp_f32_e32 v30, v30
	v_rcp_f32_e32 v31, v31
	v_pk_mul_f32 v[0:1], v[246:247], v[0:1]
	v_pk_mul_f32 v[2:3], v[246:247], v[2:3]
	v_pk_mul_f32 v[4:5], v[246:247], v[4:5]
	v_pk_mul_f32 v[6:7], v[246:247], v[6:7]
	v_pk_mul_f32 v[8:9], v[246:247], v[8:9]
	v_pk_mul_f32 v[10:11], v[246:247], v[10:11]
	v_pk_mul_f32 v[12:13], v[246:247], v[12:13]
	v_pk_mul_f32 v[14:15], v[246:247], v[14:15]
	v_lshlrev_b32_e32 v48, 16, v48
	v_lshlrev_b32_e32 v49, 16, v49
	v_lshlrev_b32_e32 v50, 16, v50
	v_lshlrev_b32_e32 v51, 16, v51
	v_lshlrev_b32_e32 v52, 16, v52
	v_lshlrev_b32_e32 v53, 16, v53
	v_lshlrev_b32_e32 v54, 16, v54
	v_lshlrev_b32_e32 v55, 16, v55
	v_lshlrev_b32_e32 v56, 16, v56
	v_lshlrev_b32_e32 v57, 16, v57
	v_lshlrev_b32_e32 v58, 16, v58
	v_lshlrev_b32_e32 v59, 16, v59
	v_lshlrev_b32_e32 v60, 16, v60
	v_lshlrev_b32_e32 v61, 16, v61
	v_lshlrev_b32_e32 v62, 16, v62
	v_lshlrev_b32_e32 v63, 16, v63
	v_exp_f32_e32 v0, v0
	v_exp_f32_e32 v1, v1
	v_exp_f32_e32 v2, v2
	v_exp_f32_e32 v3, v3
	v_exp_f32_e32 v4, v4
	v_exp_f32_e32 v5, v5
	v_exp_f32_e32 v6, v6
	v_exp_f32_e32 v7, v7
	v_exp_f32_e32 v8, v8
	v_exp_f32_e32 v9, v9
	v_exp_f32_e32 v10, v10
	v_exp_f32_e32 v11, v11
	v_exp_f32_e32 v12, v12
	v_exp_f32_e32 v13, v13
	v_exp_f32_e32 v14, v14
	v_exp_f32_e32 v15, v15
	v_fma_f32 v32, -v0, v0, 1.0
	v_fma_f32 v33, -v1, v1, 1.0
	v_fma_f32 v34, -v2, v2, 1.0
	v_fma_f32 v35, -v3, v3, 1.0
	v_fma_f32 v36, -v4, v4, 1.0
	v_fma_f32 v37, -v5, v5, 1.0
	v_fma_f32 v38, -v6, v6, 1.0
	v_fma_f32 v39, -v7, v7, 1.0
	v_fma_f32 v40, -v8, v8, 1.0
	v_fma_f32 v41, -v9, v9, 1.0
	v_fma_f32 v42, -v10, v10, 1.0
	v_fma_f32 v43, -v11, v11, 1.0
	v_fma_f32 v44, -v12, v12, 1.0
	v_fma_f32 v45, -v13, v13, 1.0
	v_fma_f32 v46, -v14, v14, 1.0
	v_fma_f32 v47, -v15, v15, 1.0
	v_max_f32_e32 v32, 0, v32
	v_max_f32_e32 v33, 0, v33
	v_max_f32_e32 v34, 0, v34
	v_max_f32_e32 v35, 0, v35
	v_max_f32_e32 v36, 0, v36
	v_max_f32_e32 v37, 0, v37
	v_max_f32_e32 v38, 0, v38
	v_max_f32_e32 v39, 0, v39
; __device__ __forceinline__ unsigned f2bf(float f) { unsigned r; asm("v_cvt_pk_bf16_f32 %0, %1, %1" : "=v"(r) : "v"(f)); return r & 0xffffu; }
; __device__ __forceinline__ float sigmoid_f(float x) { return rcpf_(1.f + __expf(-x)); }
; __device__ __forceinline__ float gelu_tanh_f(float x) { const float y = 0.7978845608028654f * (x + 0.044715f * x * x * x); return x * sigmoid_f(2.f * y); }
; template <bool FINAL, int D>
; __device__ __forceinline__ void rg_dir(PREF p, int l, int h, int ch, int sidx, int rowbase  , LAS bf16_t* sXc, LAS float* stg, int lane) {
;     ...
;         for (int ti = 0; ti < 16; ++ti) { const int tk = D ? 15 - ti : ti;
;             const float zr = stg[tk * 64 + lane] + ba, zi = stg[1024 + tk * 64 + lane] + bi;
;             const float r = sigmoid_f(zr), ig = sigmoid_f(zi);
;             const float a = __builtin_amdgcn_exp2f(r * sp8);
;             const float xc = bf2f(sXc[(mt * 16 + tk) * 72 + lane]);
;             av[ti] = a; iv[ti] = __builtin_amdgcn_sqrtf(fmaxf(1.f - a * a, 0.f)) * ig * xc;
;             if (FINAL && D == 1) grv[ti] = gelu_tanh_f(grv[ti]);
;         }
; #pragma unroll
;         for (int ti = 0; ti < 16; ++ti) { const int tk = D ? 15 - ti : ti;
;             hc = av[ti] * hc + iv[ti]; Ap *= av[ti];
;             if (FINAL) { const size_t row = (size_t)(rowbase + mt * 16 + tk);
;                 if (D == 0) TMP[row * 512 + ch] = (bf16_t)f2bf(hc);
;                 else MIX[row * DM + ch] = (bf16_t)f2bf(grv[ti] * (hfv[ti] + hc)); }
	v_max_f32_e32 v40, 0, v40
	v_max_f32_e32 v41, 0, v41
	v_max_f32_e32 v42, 0, v42
	v_max_f32_e32 v43, 0, v43
	v_max_f32_e32 v44, 0, v44
	v_max_f32_e32 v45, 0, v45
	v_max_f32_e32 v46, 0, v46
	v_max_f32_e32 v47, 0, v47
	v_sqrt_f32_e32 v32, v32
	v_sqrt_f32_e32 v33, v33
	v_sqrt_f32_e32 v34, v34
	v_sqrt_f32_e32 v35, v35
	v_sqrt_f32_e32 v36, v36
	v_sqrt_f32_e32 v37, v37
	v_sqrt_f32_e32 v38, v38
	v_sqrt_f32_e32 v39, v39
	v_sqrt_f32_e32 v40, v40
	v_sqrt_f32_e32 v41, v41
	v_sqrt_f32_e32 v42, v42
	v_sqrt_f32_e32 v43, v43
	v_sqrt_f32_e32 v44, v44
	v_sqrt_f32_e32 v45, v45
	v_sqrt_f32_e32 v46, v46
	v_sqrt_f32_e32 v47, v47
	s_nop 0
	v_pk_mul_f32 v[16:17], v[16:17], v[32:33]
	v_pk_mul_f32 v[18:19], v[18:19], v[34:35]
	v_pk_mul_f32 v[20:21], v[20:21], v[36:37]
	v_pk_mul_f32 v[22:23], v[22:23], v[38:39]
	v_pk_mul_f32 v[24:25], v[24:25], v[40:41]
	v_pk_mul_f32 v[26:27], v[26:27], v[42:43]
	v_pk_mul_f32 v[28:29], v[28:29], v[44:45]
	v_pk_mul_f32 v[30:31], v[30:31], v[46:47]
	v_pk_mul_f32 v[16:17], v[16:17], v[48:49]
	v_pk_mul_f32 v[18:19], v[18:19], v[50:51]
	v_pk_mul_f32 v[20:21], v[20:21], v[52:53]
	v_pk_mul_f32 v[22:23], v[22:23], v[54:55]
	v_pk_mul_f32 v[24:25], v[24:25], v[56:57]
	v_pk_mul_f32 v[26:27], v[26:27], v[58:59]
	v_pk_mul_f32 v[28:29], v[28:29], v[60:61]
	v_pk_mul_f32 v[30:31], v[30:31], v[62:63]
	s_add_i32 s39, s15, 47
	s_lshl_b32 s39, s39, 11
	s_add_u32 s90, s0, 0x7b00000
	s_addc_u32 s91, s1, 0
	s_add_u32 s90, s90, s39
	s_addc_u32 s91, s91, 0
	v_lshlrev_b32_e32 v48, 16, v174
	v_and_b32_e32 v49, 0xffff0000, v174
	v_lshlrev_b32_e32 v50, 16, v175
	v_and_b32_e32 v51, 0xffff0000, v175
	v_lshlrev_b32_e32 v52, 16, v176
	v_and_b32_e32 v53, 0xffff0000, v176
	v_lshlrev_b32_e32 v54, 16, v177
	v_and_b32_e32 v55, 0xffff0000, v177
	v_lshlrev_b32_e32 v56, 16, v178
	v_and_b32_e32 v57, 0xffff0000, v178
	v_lshlrev_b32_e32 v58, 16, v179
	v_and_b32_e32 v59, 0xffff0000, v179
	v_lshlrev_b32_e32 v60, 16, v180
	v_and_b32_e32 v61, 0xffff0000, v180
	v_lshlrev_b32_e32 v62, 16, v181
	v_and_b32_e32 v63, 0xffff0000, v181
	v_fma_f32 v47, v15, v250, v31
	v_fma_f32 v46, v14, v47, v30
	v_fma_f32 v45, v13, v46, v29
	v_fma_f32 v44, v12, v45, v28
	v_fma_f32 v43, v11, v44, v27
	v_fma_f32 v42, v10, v43, v26
	v_fma_f32 v41, v9, v42, v25
	v_fma_f32 v40, v8, v41, v24
	v_fma_f32 v39, v7, v40, v23
	v_fma_f32 v38, v6, v39, v22
	v_fma_f32 v37, v5, v38, v21
	v_fma_f32 v36, v4, v37, v20
	v_fma_f32 v35, v3, v36, v19
	v_fma_f32 v34, v2, v35, v18
	v_fma_f32 v33, v1, v34, v17
	v_fma_f32 v32, v0, v33, v16
	v_mov_b32_e32 v250, v32
	v_pk_add_f32 v[48:49], v[48:49], v[32:33]
	v_pk_add_f32 v[50:51], v[50:51], v[34:35]
	v_pk_add_f32 v[52:53], v[52:53], v[36:37]
	v_pk_add_f32 v[54:55], v[54:55], v[38:39]
	v_pk_add_f32 v[56:57], v[56:57], v[40:41]
	v_pk_add_f32 v[58:59], v[58:59], v[42:43]
	v_pk_add_f32 v[60:61], v[60:61], v[44:45]
	v_pk_add_f32 v[62:63], v[62:63], v[46:47]
	v_pk_mul_f32 v[48:49], v[206:207], v[48:49]
	v_pk_mul_f32 v[50:51], v[208:209], v[50:51]
	v_pk_mul_f32 v[52:53], v[210:211], v[52:53]
	v_pk_mul_f32 v[54:55], v[212:213], v[54:55]
	v_pk_mul_f32 v[56:57], v[214:215], v[56:57]
	v_pk_mul_f32 v[58:59], v[216:217], v[58:59]
	v_pk_mul_f32 v[60:61], v[218:219], v[60:61]
	v_pk_mul_f32 v[62:63], v[222:223], v[62:63]
	v_cvt_pk_bf16_f32 v48, v48, v48
	v_cvt_pk_bf16_f32 v49, v49, v49
	v_cvt_pk_bf16_f32 v50, v50, v50
	v_cvt_pk_bf16_f32 v51, v51, v51
	v_cvt_pk_bf16_f32 v52, v52, v52
	v_cvt_pk_bf16_f32 v53, v53, v53
	v_cvt_pk_bf16_f32 v54, v54, v54
	v_cvt_pk_bf16_f32 v55, v55, v55
	v_cvt_pk_bf16_f32 v56, v56, v56
	v_cvt_pk_bf16_f32 v57, v57, v57
	v_cvt_pk_bf16_f32 v58, v58, v58
	v_cvt_pk_bf16_f32 v59, v59, v59
	v_cvt_pk_bf16_f32 v60, v60, v60
	v_cvt_pk_bf16_f32 v61, v61, v61
	v_cvt_pk_bf16_f32 v62, v62, v62
	v_cvt_pk_bf16_f32 v63, v63, v63
	global_store_short v234, v63, s[90:91]
	s_sub_u32 s90, s90, 0x800
	s_subb_u32 s91, s91, 0
	global_store_short v234, v62, s[90:91]
	s_sub_u32 s90, s90, 0x800
	s_subb_u32 s91, s91, 0
	global_store_short v234, v61, s[90:91]
	s_sub_u32 s90, s90, 0x800
	s_subb_u32 s91, s91, 0
	global_store_short v234, v60, s[90:91]
	s_sub_u32 s90, s90, 0x800
	s_subb_u32 s91, s91, 0
	global_store_short v234, v59, s[90:91]
	s_sub_u32 s90, s90, 0x800
	s_subb_u32 s91, s91, 0
	global_store_short v234, v58, s[90:91]
	s_sub_u32 s90, s90, 0x800
	s_subb_u32 s91, s91, 0
	global_store_short v234, v57, s[90:91]
	s_sub_u32 s90, s90, 0x800
	s_subb_u32 s91, s91, 0
	global_store_short v234, v56, s[90:91]
	s_sub_u32 s90, s90, 0x800
	s_subb_u32 s91, s91, 0
	global_store_short v234, v55, s[90:91]
	s_sub_u32 s90, s90, 0x800
	s_subb_u32 s91, s91, 0
	global_store_short v234, v54, s[90:91]
	s_sub_u32 s90, s90, 0x800
	s_subb_u32 s91, s91, 0
	global_store_short v234, v53, s[90:91]
	s_sub_u32 s90, s90, 0x800
	s_subb_u32 s91, s91, 0
	global_store_short v234, v52, s[90:91]
	s_sub_u32 s90, s90, 0x800
	s_subb_u32 s91, s91, 0
	global_store_short v234, v51, s[90:91]
	s_sub_u32 s90, s90, 0x800
	s_subb_u32 s91, s91, 0
	global_store_short v234, v50, s[90:91]
	s_sub_u32 s90, s90, 0x800
	s_subb_u32 s91, s91, 0
	global_store_short v234, v49, s[90:91]
	s_sub_u32 s90, s90, 0x800
	s_subb_u32 s91, s91, 0
	global_store_short v234, v48, s[90:91]
	ds_read_b128 v[32:35], v236 offset:2304
	ds_read_b128 v[36:39], v236 offset:2368
	s_waitcnt lgkmcnt(0)
; #define LAS __attribute__((address_space(3)))
; #define WAVE_SYNC() asm volatile("s_waitcnt lgkmcnt(0)" ::: "memory")
; __device__ __forceinline__ float rcpf_(float x) { return __builtin_amdgcn_rcpf(x); }
; __device__ __forceinline__ float gelu_tanh_f(float x) { const float y = 0.7978845608028654f * (x + 0.044715f * x * x * x); return x * sigmoid_f(2.f * y); }
; __device__ __forceinline__ f32x4 mfma16(bf16x8 a, bf16x8 b, f32x4 c) { return __builtin_amdgcn_mfma_f32_16x16x32_bf16(a, b, c, 0, 0, 0); }
; __device__ __forceinline__ float sigmoid_f(float x) { return rcpf_(1.f + __expf(-x)); }
; __device__ __forceinline__ float silu_f(float x) { return x * sigmoid_f(x); }
; template <bool FINAL, int D>
; __device__ __forceinline__ void rg_dir(PREF p, int l, int h, int ch, int sidx, int rowbase  , LAS bf16_t* sXc, LAS float* stg, int lane) {
;     ...
;         const bf16x8 A0 = *(const LAS bf16x8*)(sXc + (mt * 16 + (lane & 15)) * 72 + (lane >> 4) * 8), A1 = *(const LAS bf16x8*)(sXc + (mt * 16 + (lane & 15)) * 72 + 32 + (lane >> 4) * 8);
;         f32x4 ar[4], ai[4];
; #pragma unroll
;         for (int nt = 0; nt < 4; ++nt) { const f32x4 z = {0.f, 0.f, 0.f, 0.f};
;             ar[nt] = mfma16(A0, Br[nt][0], z); ar[nt] = mfma16(A1, Br[nt][1], ar[nt]); ai[nt] = mfma16(A0, Bi[nt][0], z); ai[nt] = mfma16(A1, Bi[nt][1], ai[nt]); }
;         WAVE_SYNC();
; #pragma unroll
;         for (int nt = 0; nt < 4; ++nt)
; #pragma unroll
;             for (int j = 0; j < 4; ++j) { const int o = ((lane >> 4) * 4 + j) * 64 + nt * 16 + (lane & 15); stg[o] = ar[nt][j]; stg[1024 + o] = ai[nt][j]; }
;         WAVE_SYNC();
;         float av[16], iv[16];
; #pragma unroll
;         for (int ti = 0; ti < 16; ++ti) { const int tk = D ? 15 - ti : ti;
;             const float zr = stg[tk * 64 + lane] + ba, zi = stg[1024 + tk * 64 + lane] + bi;
;             const float r = sigmoid_f(zr), ig = sigmoid_f(zi);
;             const float a = __builtin_amdgcn_exp2f(r * sp8);
;             const float xc = bf2f(sXc[(mt * 16 + tk) * 72 + lane]);
;             av[ti] = a; iv[ti] = __builtin_amdgcn_sqrtf(fmaxf(1.f - a * a, 0.f)) * ig * xc;
;             if (FINAL && D == 1) grv[ti] = gelu_tanh_f(grv[ti]);
	v_mfma_f32_16x16x32_bf16 v[0:3], v[32:35], v[80:83], 0
	v_mfma_f32_16x16x32_bf16 v[4:7], v[32:35], v[88:91], 0
	v_mfma_f32_16x16x32_bf16 v[8:11], v[32:35], v[96:99], 0
	v_mfma_f32_16x16x32_bf16 v[12:15], v[32:35], v[104:107], 0
	v_mfma_f32_16x16x32_bf16 v[16:19], v[32:35], v[112:115], 0
	v_mfma_f32_16x16x32_bf16 v[20:23], v[32:35], v[120:123], 0
	v_mfma_f32_16x16x32_bf16 v[24:27], v[32:35], v[128:131], 0
	v_mfma_f32_16x16x32_bf16 v[28:31], v[32:35], v[136:139], 0
	v_mfma_f32_16x16x32_bf16 v[0:3], v[36:39], v[84:87], v[0:3]
	v_mfma_f32_16x16x32_bf16 v[4:7], v[36:39], v[92:95], v[4:7]
	v_mfma_f32_16x16x32_bf16 v[8:11], v[36:39], v[100:103], v[8:11]
	v_mfma_f32_16x16x32_bf16 v[12:15], v[36:39], v[108:111], v[12:15]
	v_mfma_f32_16x16x32_bf16 v[16:19], v[36:39], v[116:119], v[16:19]
	v_mfma_f32_16x16x32_bf16 v[20:23], v[36:39], v[124:127], v[20:23]
	v_mfma_f32_16x16x32_bf16 v[24:27], v[36:39], v[132:135], v[24:27]
	v_mfma_f32_16x16x32_bf16 v[28:31], v[36:39], v[228:231], v[28:31]
	s_nop 3
	ds_write2_b32 v237, v0, v4 offset0:0 offset1:16
	ds_write2_b32 v237, v8, v12 offset0:32 offset1:48
	ds_write2_b32 v237, v1, v5 offset0:64 offset1:80
	ds_write2_b32 v237, v9, v13 offset0:96 offset1:112
	ds_write2_b32 v237, v2, v6 offset0:128 offset1:144
	ds_write2_b32 v237, v10, v14 offset0:160 offset1:176
	ds_write2_b32 v237, v3, v7 offset0:192 offset1:208
	ds_write2_b32 v237, v11, v15 offset0:224 offset1:240
	ds_write2_b32 v238, v16, v20 offset0:0 offset1:16
	ds_write2_b32 v238, v24, v28 offset0:32 offset1:48
	ds_write2_b32 v238, v17, v21 offset0:64 offset1:80
	ds_write2_b32 v238, v25, v29 offset0:96 offset1:112
	ds_write2_b32 v238, v18, v22 offset0:128 offset1:144
	ds_write2_b32 v238, v26, v30 offset0:160 offset1:176
	ds_write2_b32 v238, v19, v23 offset0:192 offset1:208
	ds_write2_b32 v238, v27, v31 offset0:224 offset1:240
	s_waitcnt lgkmcnt(0)
	ds_read2st64_b32 v[0:1], v239 offset0:36 offset1:37
	ds_read2st64_b32 v[2:3], v239 offset0:38 offset1:39
	ds_read2st64_b32 v[4:5], v239 offset0:40 offset1:41
	ds_read2st64_b32 v[6:7], v239 offset0:42 offset1:43
	ds_read2st64_b32 v[8:9], v239 offset0:44 offset1:45
	ds_read2st64_b32 v[10:11], v239 offset0:46 offset1:47
	ds_read2st64_b32 v[12:13], v239 offset0:48 offset1:49
	ds_read2st64_b32 v[14:15], v239 offset0:50 offset1:51
	ds_read2st64_b32 v[16:17], v239 offset0:52 offset1:53
	ds_read2st64_b32 v[18:19], v239 offset0:54 offset1:55
	ds_read2st64_b32 v[20:21], v239 offset0:56 offset1:57
	ds_read2st64_b32 v[22:23], v239 offset0:58 offset1:59
	ds_read2st64_b32 v[24:25], v239 offset0:60 offset1:61
	ds_read2st64_b32 v[26:27], v239 offset0:62 offset1:63
	ds_read2st64_b32 v[28:29], v239 offset0:64 offset1:65
	ds_read2st64_b32 v[30:31], v239 offset0:66 offset1:67
	ds_read_u16 v48, v240 offset:2304
	ds_read_u16 v49, v240 offset:2448
	ds_read_u16 v50, v240 offset:2592
	ds_read_u16 v51, v240 offset:2736
	ds_read_u16 v52, v240 offset:2880
	ds_read_u16 v53, v240 offset:3024
	ds_read_u16 v54, v240 offset:3168
	ds_read_u16 v55, v240 offset:3312
	ds_read_u16 v56, v240 offset:3456
	ds_read_u16 v57, v240 offset:3600
	ds_read_u16 v58, v240 offset:3744
	ds_read_u16 v59, v240 offset:3888
	ds_read_u16 v60, v240 offset:4032
	ds_read_u16 v61, v240 offset:4176
	ds_read_u16 v62, v240 offset:4320
	ds_read_u16 v63, v240 offset:4464
	s_waitcnt vmcnt(16)
	v_lshlrev_b32_e32 v206, 16, v190
	v_lshlrev_b32_e32 v207, 16, v191
	v_lshlrev_b32_e32 v208, 16, v192
	v_lshlrev_b32_e32 v209, 16, v193
	v_lshlrev_b32_e32 v210, 16, v194
	v_lshlrev_b32_e32 v211, 16, v195
	v_lshlrev_b32_e32 v212, 16, v196
	v_lshlrev_b32_e32 v213, 16, v197
	v_lshlrev_b32_e32 v214, 16, v198
	v_lshlrev_b32_e32 v215, 16, v199
	v_lshlrev_b32_e32 v216, 16, v200
	v_lshlrev_b32_e32 v217, 16, v201
	v_lshlrev_b32_e32 v218, 16, v202
	v_lshlrev_b32_e32 v219, 16, v203
	v_lshlrev_b32_e32 v222, 16, v204
	v_lshlrev_b32_e32 v223, 16, v205
	v_pk_mul_f32 v[32:33], v[140:141], v[206:207]
	v_pk_mul_f32 v[34:35], v[140:141], v[208:209]
	v_pk_mul_f32 v[36:37], v[140:141], v[210:211]
	v_pk_mul_f32 v[38:39], v[140:141], v[212:213]
	v_pk_mul_f32 v[40:41], v[140:141], v[214:215]
	v_pk_mul_f32 v[42:43], v[140:141], v[216:217]
	v_pk_mul_f32 v[44:45], v[140:141], v[218:219]
	v_pk_mul_f32 v[46:47], v[140:141], v[222:223]
	v_pk_mul_f32 v[32:33], v[32:33], v[206:207]
	v_pk_mul_f32 v[34:35], v[34:35], v[208:209]
	v_pk_mul_f32 v[36:37], v[36:37], v[210:211]
	v_pk_mul_f32 v[38:39], v[38:39], v[212:213]
	v_pk_mul_f32 v[40:41], v[40:41], v[214:215]
	v_pk_mul_f32 v[42:43], v[42:43], v[216:217]
	v_pk_mul_f32 v[44:45], v[44:45], v[218:219]
	v_pk_mul_f32 v[46:47], v[46:47], v[222:223]
	v_fma_f32 v32, v32, v206, v206
	v_fma_f32 v33, v33, v207, v207
	v_fma_f32 v34, v34, v208, v208
	v_fma_f32 v35, v35, v209, v209
	v_fma_f32 v36, v36, v210, v210
	v_fma_f32 v37, v37, v211, v211
	v_fma_f32 v38, v38, v212, v212
	v_fma_f32 v39, v39, v213, v213
	v_fma_f32 v40, v40, v214, v214
	v_fma_f32 v41, v41, v215, v215
	v_fma_f32 v42, v42, v216, v216
	v_fma_f32 v43, v43, v217, v217
	v_fma_f32 v44, v44, v218, v218
	v_fma_f32 v45, v45, v219, v219
	v_fma_f32 v46, v46, v222, v222
	v_fma_f32 v47, v47, v223, v223
	v_mul_f32_e32 v32, 0x3f4c422a, v32
	v_mul_f32_e32 v33, 0x3f4c422a, v33
	v_mul_f32_e32 v34, 0x3f4c422a, v34
	v_mul_f32_e32 v35, 0x3f4c422a, v35
	v_mul_f32_e32 v36, 0x3f4c422a, v36
	v_mul_f32_e32 v37, 0x3f4c422a, v37
	v_mul_f32_e32 v38, 0x3f4c422a, v38
	v_mul_f32_e32 v39, 0x3f4c422a, v39
	v_mul_f32_e32 v40, 0x3f4c422a, v40
	v_mul_f32_e32 v41, 0x3f4c422a, v41
	v_mul_f32_e32 v42, 0x3f4c422a, v42
	v_mul_f32_e32 v43, 0x3f4c422a, v43
	v_mul_f32_e32 v44, 0x3f4c422a, v44
	v_mul_f32_e32 v45, 0x3f4c422a, v45
	v_mul_f32_e32 v46, 0x3f4c422a, v46
; #define LAS __attribute__((address_space(3)))
; #define WAVE_SYNC() asm volatile("s_waitcnt lgkmcnt(0)" ::: "memory")
; __device__ __forceinline__ float sigmoid_f(float x) { return rcpf_(1.f + __expf(-x)); }
; __device__ __forceinline__ f32x4 mfma16(bf16x8 a, bf16x8 b, f32x4 c) { return __builtin_amdgcn_mfma_f32_16x16x32_bf16(a, b, c, 0, 0, 0); }
; template <bool FINAL, int D>
; __device__ __forceinline__ void rg_dir(PREF p, int l, int h, int ch, int sidx, int rowbase  , LAS bf16_t* sXc, LAS float* stg, int lane) {
;     ...
;             for (int ti = 0; ti < 16; ++ti) { const size_t row = (size_t)(rowbase + mt * 16 + 15 - ti); grv[ti] = __builtin_bit_cast(float, (unsigned)P[row * PW + 512 + ch]); hfv[ti] = __builtin_bit_cast(float, (unsigned)TMP[row * 512 + ch]); }
;             __builtin_amdgcn_sched_barrier(0);
; #pragma unroll
;             for (int ti = 0; ti < 16; ++ti) { grv[ti] = bf2f(__builtin_bit_cast(unsigned, grv[ti])); hfv[ti] = bf2f(__builtin_bit_cast(unsigned, hfv[ti])); }
;         }
;         const bf16x8 A0 = *(const LAS bf16x8*)(sXc + (mt * 16 + (lane & 15)) * 72 + (lane >> 4) * 8), A1 = *(const LAS bf16x8*)(sXc + (mt * 16 + (lane & 15)) * 72 + 32 + (lane >> 4) * 8);
;         f32x4 ar[4], ai[4];
; #pragma unroll
;         for (int nt = 0; nt < 4; ++nt) { const f32x4 z = {0.f, 0.f, 0.f, 0.f};
;             ar[nt] = mfma16(A0, Br[nt][0], z); ar[nt] = mfma16(A1, Br[nt][1], ar[nt]); ai[nt] = mfma16(A0, Bi[nt][0], z); ai[nt] = mfma16(A1, Bi[nt][1], ai[nt]); }
;         WAVE_SYNC();
; #pragma unroll
;         for (int nt = 0; nt < 4; ++nt)
; #pragma unroll
;             for (int j = 0; j < 4; ++j) { const int o = ((lane >> 4) * 4 + j) * 64 + nt * 16 + (lane & 15); stg[o] = ar[nt][j]; stg[1024 + o] = ai[nt][j]; }
;         WAVE_SYNC();
;         float av[16], iv[16];
; #pragma unroll
;         for (int ti = 0; ti < 16; ++ti) { const int tk = D ? 15 - ti : ti;
;             const float zr = stg[tk * 64 + lane] + ba, zi = stg[1024 + tk * 64 + lane] + bi;
;             const float r = sigmoid_f(zr), ig = sigmoid_f(zi);
;             const float a = __builtin_amdgcn_exp2f(r * sp8);
;             const float xc = bf2f(sXc[(mt * 16 + tk) * 72 + lane]);
;             av[ti] = a; iv[ti] = __builtin_amdgcn_sqrtf(fmaxf(1.f - a * a, 0.f)) * ig * xc;
	v_mul_f32_e32 v47, 0x3f4c422a, v47
	v_pk_add_f32 v[32:33], v[32:33], v[32:33]
	v_pk_add_f32 v[34:35], v[34:35], v[34:35]
	v_pk_add_f32 v[36:37], v[36:37], v[36:37]
	v_pk_add_f32 v[38:39], v[38:39], v[38:39]
	v_pk_add_f32 v[40:41], v[40:41], v[40:41]
	v_pk_add_f32 v[42:43], v[42:43], v[42:43]
	v_pk_add_f32 v[44:45], v[44:45], v[44:45]
	v_pk_add_f32 v[46:47], v[46:47], v[46:47]
	v_pk_mul_f32 v[32:33], v[248:249], v[32:33]
	v_pk_mul_f32 v[34:35], v[248:249], v[34:35]
	v_pk_mul_f32 v[36:37], v[248:249], v[36:37]
	v_pk_mul_f32 v[38:39], v[248:249], v[38:39]
	v_pk_mul_f32 v[40:41], v[248:249], v[40:41]
	v_pk_mul_f32 v[42:43], v[248:249], v[42:43]
	v_pk_mul_f32 v[44:45], v[248:249], v[44:45]
	v_pk_mul_f32 v[46:47], v[248:249], v[46:47]
	v_exp_f32_e32 v32, v32
	v_exp_f32_e32 v33, v33
	v_exp_f32_e32 v34, v34
	v_exp_f32_e32 v35, v35
	v_exp_f32_e32 v36, v36
	v_exp_f32_e32 v37, v37
	v_exp_f32_e32 v38, v38
	v_exp_f32_e32 v39, v39
	v_exp_f32_e32 v40, v40
	v_exp_f32_e32 v41, v41
	v_exp_f32_e32 v42, v42
	v_exp_f32_e32 v43, v43
	v_exp_f32_e32 v44, v44
	v_exp_f32_e32 v45, v45
	v_exp_f32_e32 v46, v46
	v_exp_f32_e32 v47, v47
	v_pk_add_f32 v[32:33], v[32:33], 1.0 op_sel_hi:[1,0]
	v_pk_add_f32 v[34:35], v[34:35], 1.0 op_sel_hi:[1,0]
	v_pk_add_f32 v[36:37], v[36:37], 1.0 op_sel_hi:[1,0]
	v_pk_add_f32 v[38:39], v[38:39], 1.0 op_sel_hi:[1,0]
	v_pk_add_f32 v[40:41], v[40:41], 1.0 op_sel_hi:[1,0]
	v_pk_add_f32 v[42:43], v[42:43], 1.0 op_sel_hi:[1,0]
	v_pk_add_f32 v[44:45], v[44:45], 1.0 op_sel_hi:[1,0]
	v_pk_add_f32 v[46:47], v[46:47], 1.0 op_sel_hi:[1,0]
	v_rcp_f32_e32 v32, v32
	v_rcp_f32_e32 v33, v33
	v_rcp_f32_e32 v34, v34
	v_rcp_f32_e32 v35, v35
	v_rcp_f32_e32 v36, v36
	v_rcp_f32_e32 v37, v37
	v_rcp_f32_e32 v38, v38
	v_rcp_f32_e32 v39, v39
	v_rcp_f32_e32 v40, v40
	v_rcp_f32_e32 v41, v41
	v_rcp_f32_e32 v42, v42
	v_rcp_f32_e32 v43, v43
	v_rcp_f32_e32 v44, v44
	v_rcp_f32_e32 v45, v45
	v_rcp_f32_e32 v46, v46
	v_rcp_f32_e32 v47, v47
	s_nop 0
	v_pk_mul_f32 v[206:207], v[32:33], v[206:207]
	v_pk_mul_f32 v[208:209], v[34:35], v[208:209]
	v_pk_mul_f32 v[210:211], v[36:37], v[210:211]
	v_pk_mul_f32 v[212:213], v[38:39], v[212:213]
	v_pk_mul_f32 v[214:215], v[40:41], v[214:215]
	v_pk_mul_f32 v[216:217], v[42:43], v[216:217]
	v_pk_mul_f32 v[218:219], v[44:45], v[218:219]
	v_pk_mul_f32 v[222:223], v[46:47], v[222:223]
	s_add_i32 s39, s15, 0
	s_mul_hi_u32 s83, s39, 0x1600
	s_mul_i32 s82, s39, 0x1600
	s_add_u32 s82, s82, s0
	s_addc_u32 s83, s83, s1
	s_add_u32 s82, s82, 0xbc00400
	s_addc_u32 s83, s83, 0
	global_load_ushort v190, v234, s[82:83]
	s_add_u32 s82, s82, 0x1600
	s_addc_u32 s83, s83, 0
	global_load_ushort v191, v234, s[82:83]
	s_add_u32 s82, s82, 0x1600
	s_addc_u32 s83, s83, 0
	global_load_ushort v192, v234, s[82:83]
	s_add_u32 s82, s82, 0x1600
	s_addc_u32 s83, s83, 0
	global_load_ushort v193, v234, s[82:83]
	s_add_u32 s82, s82, 0x1600
	s_addc_u32 s83, s83, 0
	global_load_ushort v194, v234, s[82:83]
	s_add_u32 s82, s82, 0x1600
	s_addc_u32 s83, s83, 0
	global_load_ushort v195, v234, s[82:83]
	s_add_u32 s82, s82, 0x1600
	s_addc_u32 s83, s83, 0
	global_load_ushort v196, v234, s[82:83]
	s_add_u32 s82, s82, 0x1600
	s_addc_u32 s83, s83, 0
	global_load_ushort v197, v234, s[82:83]
	s_add_u32 s82, s82, 0x1600
	s_addc_u32 s83, s83, 0
	global_load_ushort v198, v234, s[82:83]
	s_add_u32 s82, s82, 0x1600
	s_addc_u32 s83, s83, 0
	global_load_ushort v199, v234, s[82:83]
	s_add_u32 s82, s82, 0x1600
	s_addc_u32 s83, s83, 0
	global_load_ushort v200, v234, s[82:83]
	s_add_u32 s82, s82, 0x1600
	s_addc_u32 s83, s83, 0
	global_load_ushort v201, v234, s[82:83]
	s_add_u32 s82, s82, 0x1600
	s_addc_u32 s83, s83, 0
	global_load_ushort v202, v234, s[82:83]
	s_add_u32 s82, s82, 0x1600
	s_addc_u32 s83, s83, 0
	global_load_ushort v203, v234, s[82:83]
	s_add_u32 s82, s82, 0x1600
	s_addc_u32 s83, s83, 0
	global_load_ushort v204, v234, s[82:83]
	s_add_u32 s82, s82, 0x1600
	s_addc_u32 s83, s83, 0
	global_load_ushort v205, v234, s[82:83]
	s_waitcnt lgkmcnt(0)
	v_pk_add_f32 v[0:1], v[242:243], v[0:1]
	v_pk_add_f32 v[2:3], v[242:243], v[2:3]
	v_pk_add_f32 v[4:5], v[242:243], v[4:5]
	v_pk_add_f32 v[6:7], v[242:243], v[6:7]
	v_pk_add_f32 v[8:9], v[242:243], v[8:9]
	v_pk_add_f32 v[10:11], v[242:243], v[10:11]
	v_pk_add_f32 v[12:13], v[242:243], v[12:13]
	v_pk_add_f32 v[14:15], v[242:243], v[14:15]
	v_pk_add_f32 v[16:17], v[244:245], v[16:17]
	v_pk_add_f32 v[18:19], v[244:245], v[18:19]
	v_pk_add_f32 v[20:21], v[244:245], v[20:21]
	v_pk_add_f32 v[22:23], v[244:245], v[22:23]
	v_pk_add_f32 v[24:25], v[244:245], v[24:25]
	v_pk_add_f32 v[26:27], v[244:245], v[26:27]
	v_pk_add_f32 v[28:29], v[244:245], v[28:29]
	v_pk_add_f32 v[30:31], v[244:245], v[30:31]
	v_pk_mul_f32 v[0:1], v[248:249], v[0:1]
	v_pk_mul_f32 v[2:3], v[248:249], v[2:3]
	v_pk_mul_f32 v[4:5], v[248:249], v[4:5]
	v_pk_mul_f32 v[6:7], v[248:249], v[6:7]
	v_pk_mul_f32 v[8:9], v[248:249], v[8:9]
	v_pk_mul_f32 v[10:11], v[248:249], v[10:11]
	v_pk_mul_f32 v[12:13], v[248:249], v[12:13]
	v_pk_mul_f32 v[14:15], v[248:249], v[14:15]
	v_pk_mul_f32 v[16:17], v[248:249], v[16:17]
	v_pk_mul_f32 v[18:19], v[248:249], v[18:19]
	v_pk_mul_f32 v[20:21], v[248:249], v[20:21]
	v_pk_mul_f32 v[22:23], v[248:249], v[22:23]
	v_pk_mul_f32 v[24:25], v[248:249], v[24:25]
	v_pk_mul_f32 v[26:27], v[248:249], v[26:27]
	v_pk_mul_f32 v[28:29], v[248:249], v[28:29]
	v_pk_mul_f32 v[30:31], v[248:249], v[30:31]
	v_exp_f32_e32 v0, v0
	v_exp_f32_e32 v1, v1
	v_exp_f32_e32 v2, v2
	v_exp_f32_e32 v3, v3
	v_exp_f32_e32 v4, v4
	v_exp_f32_e32 v5, v5
	v_exp_f32_e32 v6, v6
	v_exp_f32_e32 v7, v7
	v_exp_f32_e32 v8, v8
	v_exp_f32_e32 v9, v9
	v_exp_f32_e32 v10, v10
	v_exp_f32_e32 v11, v11
; __device__ __forceinline__ unsigned f2bf(float f) { unsigned r; asm("v_cvt_pk_bf16_f32 %0, %1, %1" : "=v"(r) : "v"(f)); return r & 0xffffu; }
; __device__ __forceinline__ float rcpf_(float x) { return __builtin_amdgcn_rcpf(x); }
; __device__ __forceinline__ float gelu_tanh_f(float x) { const float y = 0.7978845608028654f * (x + 0.044715f * x * x * x); return x * sigmoid_f(2.f * y); }
; __device__ __forceinline__ float sigmoid_f(float x) { return rcpf_(1.f + __expf(-x)); }
; template <bool FINAL, int D>
; __device__ __forceinline__ void rg_dir(PREF p, int l, int h, int ch, int sidx, int rowbase  , LAS bf16_t* sXc, LAS float* stg, int lane) {
;     ...
;         for (int ti = 0; ti < 16; ++ti) { const int tk = D ? 15 - ti : ti;
;             const float zr = stg[tk * 64 + lane] + ba, zi = stg[1024 + tk * 64 + lane] + bi;
;             const float r = sigmoid_f(zr), ig = sigmoid_f(zi);
;             const float a = __builtin_amdgcn_exp2f(r * sp8);
;             const float xc = bf2f(sXc[(mt * 16 + tk) * 72 + lane]);
;             av[ti] = a; iv[ti] = __builtin_amdgcn_sqrtf(fmaxf(1.f - a * a, 0.f)) * ig * xc;
;             if (FINAL && D == 1) grv[ti] = gelu_tanh_f(grv[ti]);
;         }
; #pragma unroll
;         for (int ti = 0; ti < 16; ++ti) { const int tk = D ? 15 - ti : ti;
;             hc = av[ti] * hc + iv[ti]; Ap *= av[ti];
;             if (FINAL) { const size_t row = (size_t)(rowbase + mt * 16 + tk);
;                 if (D == 0) TMP[row * 512 + ch] = (bf16_t)f2bf(hc);
;                 else MIX[row * DM + ch] = (bf16_t)f2bf(grv[ti] * (hfv[ti] + hc)); }
	v_exp_f32_e32 v12, v12
	v_exp_f32_e32 v13, v13
	v_exp_f32_e32 v14, v14
	v_exp_f32_e32 v15, v15
	v_exp_f32_e32 v16, v16
	v_exp_f32_e32 v17, v17
	v_exp_f32_e32 v18, v18
	v_exp_f32_e32 v19, v19
	v_exp_f32_e32 v20, v20
	v_exp_f32_e32 v21, v21
	v_exp_f32_e32 v22, v22
	v_exp_f32_e32 v23, v23
	v_exp_f32_e32 v24, v24
	v_exp_f32_e32 v25, v25
	v_exp_f32_e32 v26, v26
	v_exp_f32_e32 v27, v27
	v_exp_f32_e32 v28, v28
	v_exp_f32_e32 v29, v29
	v_exp_f32_e32 v30, v30
	v_exp_f32_e32 v31, v31
	v_pk_add_f32 v[0:1], v[0:1], 1.0 op_sel_hi:[1,0]
	v_pk_add_f32 v[2:3], v[2:3], 1.0 op_sel_hi:[1,0]
	v_pk_add_f32 v[4:5], v[4:5], 1.0 op_sel_hi:[1,0]
	v_pk_add_f32 v[6:7], v[6:7], 1.0 op_sel_hi:[1,0]
	v_pk_add_f32 v[8:9], v[8:9], 1.0 op_sel_hi:[1,0]
	v_pk_add_f32 v[10:11], v[10:11], 1.0 op_sel_hi:[1,0]
	v_pk_add_f32 v[12:13], v[12:13], 1.0 op_sel_hi:[1,0]
	v_pk_add_f32 v[14:15], v[14:15], 1.0 op_sel_hi:[1,0]
	v_pk_add_f32 v[16:17], v[16:17], 1.0 op_sel_hi:[1,0]
	v_pk_add_f32 v[18:19], v[18:19], 1.0 op_sel_hi:[1,0]
	v_pk_add_f32 v[20:21], v[20:21], 1.0 op_sel_hi:[1,0]
	v_pk_add_f32 v[22:23], v[22:23], 1.0 op_sel_hi:[1,0]
	v_pk_add_f32 v[24:25], v[24:25], 1.0 op_sel_hi:[1,0]
	v_pk_add_f32 v[26:27], v[26:27], 1.0 op_sel_hi:[1,0]
	v_pk_add_f32 v[28:29], v[28:29], 1.0 op_sel_hi:[1,0]
	v_pk_add_f32 v[30:31], v[30:31], 1.0 op_sel_hi:[1,0]
	v_rcp_f32_e32 v0, v0
	v_rcp_f32_e32 v1, v1
	v_rcp_f32_e32 v2, v2
	v_rcp_f32_e32 v3, v3
	v_rcp_f32_e32 v4, v4
	v_rcp_f32_e32 v5, v5
	v_rcp_f32_e32 v6, v6
	v_rcp_f32_e32 v7, v7
	v_rcp_f32_e32 v8, v8
	v_rcp_f32_e32 v9, v9
	v_rcp_f32_e32 v10, v10
	v_rcp_f32_e32 v11, v11
	v_rcp_f32_e32 v12, v12
	v_rcp_f32_e32 v13, v13
	v_rcp_f32_e32 v14, v14
	v_rcp_f32_e32 v15, v15
	v_rcp_f32_e32 v16, v16
	v_rcp_f32_e32 v17, v17
	v_rcp_f32_e32 v18, v18
	v_rcp_f32_e32 v19, v19
	v_rcp_f32_e32 v20, v20
	v_rcp_f32_e32 v21, v21
	v_rcp_f32_e32 v22, v22
	v_rcp_f32_e32 v23, v23
	v_rcp_f32_e32 v24, v24
	v_rcp_f32_e32 v25, v25
	v_rcp_f32_e32 v26, v26
	v_rcp_f32_e32 v27, v27
	v_rcp_f32_e32 v28, v28
	v_rcp_f32_e32 v29, v29
	v_rcp_f32_e32 v30, v30
	v_rcp_f32_e32 v31, v31
	v_pk_mul_f32 v[0:1], v[246:247], v[0:1]
	v_pk_mul_f32 v[2:3], v[246:247], v[2:3]
	v_pk_mul_f32 v[4:5], v[246:247], v[4:5]
	v_pk_mul_f32 v[6:7], v[246:247], v[6:7]
	v_pk_mul_f32 v[8:9], v[246:247], v[8:9]
	v_pk_mul_f32 v[10:11], v[246:247], v[10:11]
	v_pk_mul_f32 v[12:13], v[246:247], v[12:13]
	v_pk_mul_f32 v[14:15], v[246:247], v[14:15]
	v_lshlrev_b32_e32 v48, 16, v48
	v_lshlrev_b32_e32 v49, 16, v49
	v_lshlrev_b32_e32 v50, 16, v50
	v_lshlrev_b32_e32 v51, 16, v51
	v_lshlrev_b32_e32 v52, 16, v52
	v_lshlrev_b32_e32 v53, 16, v53
	v_lshlrev_b32_e32 v54, 16, v54
	v_lshlrev_b32_e32 v55, 16, v55
	v_lshlrev_b32_e32 v56, 16, v56
	v_lshlrev_b32_e32 v57, 16, v57
	v_lshlrev_b32_e32 v58, 16, v58
	v_lshlrev_b32_e32 v59, 16, v59
	v_lshlrev_b32_e32 v60, 16, v60
	v_lshlrev_b32_e32 v61, 16, v61
	v_lshlrev_b32_e32 v62, 16, v62
	v_lshlrev_b32_e32 v63, 16, v63
	v_exp_f32_e32 v0, v0
	v_exp_f32_e32 v1, v1
	v_exp_f32_e32 v2, v2
	v_exp_f32_e32 v3, v3
	v_exp_f32_e32 v4, v4
	v_exp_f32_e32 v5, v5
	v_exp_f32_e32 v6, v6
	v_exp_f32_e32 v7, v7
	v_exp_f32_e32 v8, v8
	v_exp_f32_e32 v9, v9
	v_exp_f32_e32 v10, v10
	v_exp_f32_e32 v11, v11
	v_exp_f32_e32 v12, v12
	v_exp_f32_e32 v13, v13
	v_exp_f32_e32 v14, v14
	v_exp_f32_e32 v15, v15
	v_fma_f32 v32, -v0, v0, 1.0
	v_fma_f32 v33, -v1, v1, 1.0
	v_fma_f32 v34, -v2, v2, 1.0
	v_fma_f32 v35, -v3, v3, 1.0
	v_fma_f32 v36, -v4, v4, 1.0
	v_fma_f32 v37, -v5, v5, 1.0
	v_fma_f32 v38, -v6, v6, 1.0
	v_fma_f32 v39, -v7, v7, 1.0
	v_fma_f32 v40, -v8, v8, 1.0
	v_fma_f32 v41, -v9, v9, 1.0
	v_fma_f32 v42, -v10, v10, 1.0
	v_fma_f32 v43, -v11, v11, 1.0
	v_fma_f32 v44, -v12, v12, 1.0
	v_fma_f32 v45, -v13, v13, 1.0
	v_fma_f32 v46, -v14, v14, 1.0
	v_fma_f32 v47, -v15, v15, 1.0
	v_max_f32_e32 v32, 0, v32
	v_max_f32_e32 v33, 0, v33
	v_max_f32_e32 v34, 0, v34
	v_max_f32_e32 v35, 0, v35
	v_max_f32_e32 v36, 0, v36
	v_max_f32_e32 v37, 0, v37
	v_max_f32_e32 v38, 0, v38
	v_max_f32_e32 v39, 0, v39
	v_max_f32_e32 v40, 0, v40
	v_max_f32_e32 v41, 0, v41
	v_max_f32_e32 v42, 0, v42
	v_max_f32_e32 v43, 0, v43
	v_max_f32_e32 v44, 0, v44
	v_max_f32_e32 v45, 0, v45
	v_max_f32_e32 v46, 0, v46
	v_max_f32_e32 v47, 0, v47
	v_sqrt_f32_e32 v32, v32
	v_sqrt_f32_e32 v33, v33
	v_sqrt_f32_e32 v34, v34
	v_sqrt_f32_e32 v35, v35
	v_sqrt_f32_e32 v36, v36
	v_sqrt_f32_e32 v37, v37
	v_sqrt_f32_e32 v38, v38
	v_sqrt_f32_e32 v39, v39
	v_sqrt_f32_e32 v40, v40
	v_sqrt_f32_e32 v41, v41
	v_sqrt_f32_e32 v42, v42
	v_sqrt_f32_e32 v43, v43
	v_sqrt_f32_e32 v44, v44
	v_sqrt_f32_e32 v45, v45
	v_sqrt_f32_e32 v46, v46
	v_sqrt_f32_e32 v47, v47
	s_nop 0
	v_pk_mul_f32 v[16:17], v[16:17], v[32:33]
	v_pk_mul_f32 v[18:19], v[18:19], v[34:35]
	v_pk_mul_f32 v[20:21], v[20:21], v[36:37]
	v_pk_mul_f32 v[22:23], v[22:23], v[38:39]
	v_pk_mul_f32 v[24:25], v[24:25], v[40:41]
	v_pk_mul_f32 v[26:27], v[26:27], v[42:43]
	v_pk_mul_f32 v[28:29], v[28:29], v[44:45]
	v_pk_mul_f32 v[30:31], v[30:31], v[46:47]
	v_pk_mul_f32 v[16:17], v[16:17], v[48:49]
	v_pk_mul_f32 v[18:19], v[18:19], v[50:51]
	v_pk_mul_f32 v[20:21], v[20:21], v[52:53]
	v_pk_mul_f32 v[22:23], v[22:23], v[54:55]
	v_pk_mul_f32 v[24:25], v[24:25], v[56:57]
	v_pk_mul_f32 v[26:27], v[26:27], v[58:59]
	v_pk_mul_f32 v[28:29], v[28:29], v[60:61]
	v_pk_mul_f32 v[30:31], v[30:31], v[62:63]
	s_add_i32 s39, s15, 31
	s_lshl_b32 s39, s39, 11
	s_add_u32 s90, s0, 0x7b00000
	s_addc_u32 s91, s1, 0
	s_add_u32 s90, s90, s39
	s_addc_u32 s91, s91, 0
	v_lshlrev_b32_e32 v48, 16, v166
	v_and_b32_e32 v49, 0xffff0000, v166
	v_lshlrev_b32_e32 v50, 16, v167
	v_and_b32_e32 v51, 0xffff0000, v167
	v_lshlrev_b32_e32 v52, 16, v168
	v_and_b32_e32 v53, 0xffff0000, v168
; #define LAS __attribute__((address_space(3)))
; #define WAVE_SYNC() asm volatile("s_waitcnt lgkmcnt(0)" ::: "memory")
; __device__ __forceinline__ unsigned f2bf(float f) { unsigned r; asm("v_cvt_pk_bf16_f32 %0, %1, %1" : "=v"(r) : "v"(f)); return r & 0xffffu; }
; __device__ __forceinline__ f32x4 mfma16(bf16x8 a, bf16x8 b, f32x4 c) { return __builtin_amdgcn_mfma_f32_16x16x32_bf16(a, b, c, 0, 0, 0); }
; template <bool FINAL, int D>
; __device__ __forceinline__ void rg_dir(PREF p, int l, int h, int ch, int sidx, int rowbase  , LAS bf16_t* sXc, LAS float* stg, int lane) {
;     ...
;         const bf16x8 A0 = *(const LAS bf16x8*)(sXc + (mt * 16 + (lane & 15)) * 72 + (lane >> 4) * 8), A1 = *(const LAS bf16x8*)(sXc + (mt * 16 + (lane & 15)) * 72 + 32 + (lane >> 4) * 8);
;         f32x4 ar[4], ai[4];
; #pragma unroll
;         for (int nt = 0; nt < 4; ++nt) { const f32x4 z = {0.f, 0.f, 0.f, 0.f};
;             ar[nt] = mfma16(A0, Br[nt][0], z); ar[nt] = mfma16(A1, Br[nt][1], ar[nt]); ai[nt] = mfma16(A0, Bi[nt][0], z); ai[nt] = mfma16(A1, Bi[nt][1], ai[nt]); }
;         WAVE_SYNC();
; #pragma unroll
;         for (int nt = 0; nt < 4; ++nt)
; #pragma unroll
;             for (int j = 0; j < 4; ++j) { const int o = ((lane >> 4) * 4 + j) * 64 + nt * 16 + (lane & 15); stg[o] = ar[nt][j]; stg[1024 + o] = ai[nt][j]; }
;         WAVE_SYNC();
;     ...
;         for (int ti = 0; ti < 16; ++ti) { const int tk = D ? 15 - ti : ti;
;             hc = av[ti] * hc + iv[ti]; Ap *= av[ti];
;             if (FINAL) { const size_t row = (size_t)(rowbase + mt * 16 + tk);
;                 if (D == 0) TMP[row * 512 + ch] = (bf16_t)f2bf(hc);
;                 else MIX[row * DM + ch] = (bf16_t)f2bf(grv[ti] * (hfv[ti] + hc)); }
	v_lshlrev_b32_e32 v54, 16, v169
	v_and_b32_e32 v55, 0xffff0000, v169
	v_lshlrev_b32_e32 v56, 16, v170
	v_and_b32_e32 v57, 0xffff0000, v170
	v_lshlrev_b32_e32 v58, 16, v171
	v_and_b32_e32 v59, 0xffff0000, v171
	v_lshlrev_b32_e32 v60, 16, v172
	v_and_b32_e32 v61, 0xffff0000, v172
	v_lshlrev_b32_e32 v62, 16, v173
	v_and_b32_e32 v63, 0xffff0000, v173
	v_fma_f32 v47, v15, v250, v31
	v_fma_f32 v46, v14, v47, v30
	v_fma_f32 v45, v13, v46, v29
	v_fma_f32 v44, v12, v45, v28
	v_fma_f32 v43, v11, v44, v27
	v_fma_f32 v42, v10, v43, v26
	v_fma_f32 v41, v9, v42, v25
	v_fma_f32 v40, v8, v41, v24
	v_fma_f32 v39, v7, v40, v23
	v_fma_f32 v38, v6, v39, v22
	v_fma_f32 v37, v5, v38, v21
	v_fma_f32 v36, v4, v37, v20
	v_fma_f32 v35, v3, v36, v19
	v_fma_f32 v34, v2, v35, v18
	v_fma_f32 v33, v1, v34, v17
	v_fma_f32 v32, v0, v33, v16
	v_mov_b32_e32 v250, v32
	v_pk_add_f32 v[48:49], v[48:49], v[32:33]
	v_pk_add_f32 v[50:51], v[50:51], v[34:35]
	v_pk_add_f32 v[52:53], v[52:53], v[36:37]
	v_pk_add_f32 v[54:55], v[54:55], v[38:39]
	v_pk_add_f32 v[56:57], v[56:57], v[40:41]
	v_pk_add_f32 v[58:59], v[58:59], v[42:43]
	v_pk_add_f32 v[60:61], v[60:61], v[44:45]
	v_pk_add_f32 v[62:63], v[62:63], v[46:47]
	v_pk_mul_f32 v[48:49], v[206:207], v[48:49]
	v_pk_mul_f32 v[50:51], v[208:209], v[50:51]
	v_pk_mul_f32 v[52:53], v[210:211], v[52:53]
	v_pk_mul_f32 v[54:55], v[212:213], v[54:55]
	v_pk_mul_f32 v[56:57], v[214:215], v[56:57]
	v_pk_mul_f32 v[58:59], v[216:217], v[58:59]
	v_pk_mul_f32 v[60:61], v[218:219], v[60:61]
	v_pk_mul_f32 v[62:63], v[222:223], v[62:63]
	v_cvt_pk_bf16_f32 v48, v48, v48
	v_cvt_pk_bf16_f32 v49, v49, v49
	v_cvt_pk_bf16_f32 v50, v50, v50
	v_cvt_pk_bf16_f32 v51, v51, v51
	v_cvt_pk_bf16_f32 v52, v52, v52
	v_cvt_pk_bf16_f32 v53, v53, v53
	v_cvt_pk_bf16_f32 v54, v54, v54
	v_cvt_pk_bf16_f32 v55, v55, v55
	v_cvt_pk_bf16_f32 v56, v56, v56
	v_cvt_pk_bf16_f32 v57, v57, v57
	v_cvt_pk_bf16_f32 v58, v58, v58
	v_cvt_pk_bf16_f32 v59, v59, v59
	v_cvt_pk_bf16_f32 v60, v60, v60
	v_cvt_pk_bf16_f32 v61, v61, v61
	v_cvt_pk_bf16_f32 v62, v62, v62
	v_cvt_pk_bf16_f32 v63, v63, v63
	global_store_short v234, v63, s[90:91]
	s_sub_u32 s90, s90, 0x800
	s_subb_u32 s91, s91, 0
	global_store_short v234, v62, s[90:91]
	s_sub_u32 s90, s90, 0x800
	s_subb_u32 s91, s91, 0
	global_store_short v234, v61, s[90:91]
	s_sub_u32 s90, s90, 0x800
	s_subb_u32 s91, s91, 0
	global_store_short v234, v60, s[90:91]
	s_sub_u32 s90, s90, 0x800
	s_subb_u32 s91, s91, 0
	global_store_short v234, v59, s[90:91]
	s_sub_u32 s90, s90, 0x800
	s_subb_u32 s91, s91, 0
	global_store_short v234, v58, s[90:91]
	s_sub_u32 s90, s90, 0x800
	s_subb_u32 s91, s91, 0
	global_store_short v234, v57, s[90:91]
	s_sub_u32 s90, s90, 0x800
	s_subb_u32 s91, s91, 0
	global_store_short v234, v56, s[90:91]
	s_sub_u32 s90, s90, 0x800
	s_subb_u32 s91, s91, 0
	global_store_short v234, v55, s[90:91]
	s_sub_u32 s90, s90, 0x800
	s_subb_u32 s91, s91, 0
	global_store_short v234, v54, s[90:91]
	s_sub_u32 s90, s90, 0x800
	s_subb_u32 s91, s91, 0
	global_store_short v234, v53, s[90:91]
	s_sub_u32 s90, s90, 0x800
	s_subb_u32 s91, s91, 0
	global_store_short v234, v52, s[90:91]
	s_sub_u32 s90, s90, 0x800
	s_subb_u32 s91, s91, 0
	global_store_short v234, v51, s[90:91]
	s_sub_u32 s90, s90, 0x800
	s_subb_u32 s91, s91, 0
	global_store_short v234, v50, s[90:91]
	s_sub_u32 s90, s90, 0x800
	s_subb_u32 s91, s91, 0
	global_store_short v234, v49, s[90:91]
	s_sub_u32 s90, s90, 0x800
	s_subb_u32 s91, s91, 0
	global_store_short v234, v48, s[90:91]
	ds_read_b128 v[32:35], v236 offset:0
	ds_read_b128 v[36:39], v236 offset:64
	s_waitcnt lgkmcnt(0)
	v_mfma_f32_16x16x32_bf16 v[0:3], v[32:35], v[80:83], 0
	v_mfma_f32_16x16x32_bf16 v[4:7], v[32:35], v[88:91], 0
	v_mfma_f32_16x16x32_bf16 v[8:11], v[32:35], v[96:99], 0
	v_mfma_f32_16x16x32_bf16 v[12:15], v[32:35], v[104:107], 0
	v_mfma_f32_16x16x32_bf16 v[16:19], v[32:35], v[112:115], 0
	v_mfma_f32_16x16x32_bf16 v[20:23], v[32:35], v[120:123], 0
	v_mfma_f32_16x16x32_bf16 v[24:27], v[32:35], v[128:131], 0
	v_mfma_f32_16x16x32_bf16 v[28:31], v[32:35], v[136:139], 0
	v_mfma_f32_16x16x32_bf16 v[0:3], v[36:39], v[84:87], v[0:3]
	v_mfma_f32_16x16x32_bf16 v[4:7], v[36:39], v[92:95], v[4:7]
	v_mfma_f32_16x16x32_bf16 v[8:11], v[36:39], v[100:103], v[8:11]
	v_mfma_f32_16x16x32_bf16 v[12:15], v[36:39], v[108:111], v[12:15]
	v_mfma_f32_16x16x32_bf16 v[16:19], v[36:39], v[116:119], v[16:19]
	v_mfma_f32_16x16x32_bf16 v[20:23], v[36:39], v[124:127], v[20:23]
	v_mfma_f32_16x16x32_bf16 v[24:27], v[36:39], v[132:135], v[24:27]
	v_mfma_f32_16x16x32_bf16 v[28:31], v[36:39], v[228:231], v[28:31]
	s_nop 3
	ds_write2_b32 v237, v0, v4 offset0:0 offset1:16
	ds_write2_b32 v237, v8, v12 offset0:32 offset1:48
	ds_write2_b32 v237, v1, v5 offset0:64 offset1:80
	ds_write2_b32 v237, v9, v13 offset0:96 offset1:112
	ds_write2_b32 v237, v2, v6 offset0:128 offset1:144
	ds_write2_b32 v237, v10, v14 offset0:160 offset1:176
	ds_write2_b32 v237, v3, v7 offset0:192 offset1:208
	ds_write2_b32 v237, v11, v15 offset0:224 offset1:240
	ds_write2_b32 v238, v16, v20 offset0:0 offset1:16
	ds_write2_b32 v238, v24, v28 offset0:32 offset1:48
	ds_write2_b32 v238, v17, v21 offset0:64 offset1:80
	ds_write2_b32 v238, v25, v29 offset0:96 offset1:112
	ds_write2_b32 v238, v18, v22 offset0:128 offset1:144
	ds_write2_b32 v238, v26, v30 offset0:160 offset1:176
	ds_write2_b32 v238, v19, v23 offset0:192 offset1:208
	ds_write2_b32 v238, v27, v31 offset0:224 offset1:240
	s_waitcnt lgkmcnt(0)
; __device__ __forceinline__ float rcpf_(float x) { return __builtin_amdgcn_rcpf(x); }
; __device__ __forceinline__ float gelu_tanh_f(float x) { const float y = 0.7978845608028654f * (x + 0.044715f * x * x * x); return x * sigmoid_f(2.f * y); }
; __device__ __forceinline__ float sigmoid_f(float x) { return rcpf_(1.f + __expf(-x)); }
; __device__ __forceinline__ float silu_f(float x) { return x * sigmoid_f(x); }
; template <bool FINAL, int D>
; __device__ __forceinline__ void rg_dir(PREF p, int l, int h, int ch, int sidx, int rowbase  , LAS bf16_t* sXc, LAS float* stg, int lane) {
;     ...
;         float av[16], iv[16];
; #pragma unroll
;         for (int ti = 0; ti < 16; ++ti) { const int tk = D ? 15 - ti : ti;
;             const float zr = stg[tk * 64 + lane] + ba, zi = stg[1024 + tk * 64 + lane] + bi;
;             const float r = sigmoid_f(zr), ig = sigmoid_f(zi);
;             const float a = __builtin_amdgcn_exp2f(r * sp8);
;             const float xc = bf2f(sXc[(mt * 16 + tk) * 72 + lane]);
;             av[ti] = a; iv[ti] = __builtin_amdgcn_sqrtf(fmaxf(1.f - a * a, 0.f)) * ig * xc;
;             if (FINAL && D == 1) grv[ti] = gelu_tanh_f(grv[ti]);
	ds_read2st64_b32 v[0:1], v239 offset0:36 offset1:37
	ds_read2st64_b32 v[2:3], v239 offset0:38 offset1:39
	ds_read2st64_b32 v[4:5], v239 offset0:40 offset1:41
	ds_read2st64_b32 v[6:7], v239 offset0:42 offset1:43
	ds_read2st64_b32 v[8:9], v239 offset0:44 offset1:45
	ds_read2st64_b32 v[10:11], v239 offset0:46 offset1:47
	ds_read2st64_b32 v[12:13], v239 offset0:48 offset1:49
	ds_read2st64_b32 v[14:15], v239 offset0:50 offset1:51
	ds_read2st64_b32 v[16:17], v239 offset0:52 offset1:53
	ds_read2st64_b32 v[18:19], v239 offset0:54 offset1:55
	ds_read2st64_b32 v[20:21], v239 offset0:56 offset1:57
	ds_read2st64_b32 v[22:23], v239 offset0:58 offset1:59
	ds_read2st64_b32 v[24:25], v239 offset0:60 offset1:61
	ds_read2st64_b32 v[26:27], v239 offset0:62 offset1:63
	ds_read2st64_b32 v[28:29], v239 offset0:64 offset1:65
	ds_read2st64_b32 v[30:31], v239 offset0:66 offset1:67
	ds_read_u16 v48, v240 offset:0
	ds_read_u16 v49, v240 offset:144
	ds_read_u16 v50, v240 offset:288
	ds_read_u16 v51, v240 offset:432
	ds_read_u16 v52, v240 offset:576
	ds_read_u16 v53, v240 offset:720
	ds_read_u16 v54, v240 offset:864
	ds_read_u16 v55, v240 offset:1008
	ds_read_u16 v56, v240 offset:1152
	ds_read_u16 v57, v240 offset:1296
	ds_read_u16 v58, v240 offset:1440
	ds_read_u16 v59, v240 offset:1584
	ds_read_u16 v60, v240 offset:1728
	ds_read_u16 v61, v240 offset:1872
	ds_read_u16 v62, v240 offset:2016
	ds_read_u16 v63, v240 offset:2160
	s_waitcnt vmcnt(16)
	v_lshlrev_b32_e32 v206, 16, v190
	v_lshlrev_b32_e32 v207, 16, v191
	v_lshlrev_b32_e32 v208, 16, v192
	v_lshlrev_b32_e32 v209, 16, v193
	v_lshlrev_b32_e32 v210, 16, v194
	v_lshlrev_b32_e32 v211, 16, v195
	v_lshlrev_b32_e32 v212, 16, v196
	v_lshlrev_b32_e32 v213, 16, v197
	v_lshlrev_b32_e32 v214, 16, v198
	v_lshlrev_b32_e32 v215, 16, v199
	v_lshlrev_b32_e32 v216, 16, v200
	v_lshlrev_b32_e32 v217, 16, v201
	v_lshlrev_b32_e32 v218, 16, v202
	v_lshlrev_b32_e32 v219, 16, v203
	v_lshlrev_b32_e32 v222, 16, v204
	v_lshlrev_b32_e32 v223, 16, v205
	v_pk_mul_f32 v[32:33], v[140:141], v[206:207]
	v_pk_mul_f32 v[34:35], v[140:141], v[208:209]
	v_pk_mul_f32 v[36:37], v[140:141], v[210:211]
	v_pk_mul_f32 v[38:39], v[140:141], v[212:213]
	v_pk_mul_f32 v[40:41], v[140:141], v[214:215]
	v_pk_mul_f32 v[42:43], v[140:141], v[216:217]
	v_pk_mul_f32 v[44:45], v[140:141], v[218:219]
	v_pk_mul_f32 v[46:47], v[140:141], v[222:223]
	v_pk_mul_f32 v[32:33], v[32:33], v[206:207]
	v_pk_mul_f32 v[34:35], v[34:35], v[208:209]
	v_pk_mul_f32 v[36:37], v[36:37], v[210:211]
	v_pk_mul_f32 v[38:39], v[38:39], v[212:213]
	v_pk_mul_f32 v[40:41], v[40:41], v[214:215]
	v_pk_mul_f32 v[42:43], v[42:43], v[216:217]
	v_pk_mul_f32 v[44:45], v[44:45], v[218:219]
	v_pk_mul_f32 v[46:47], v[46:47], v[222:223]
	v_fma_f32 v32, v32, v206, v206
	v_fma_f32 v33, v33, v207, v207
	v_fma_f32 v34, v34, v208, v208
	v_fma_f32 v35, v35, v209, v209
	v_fma_f32 v36, v36, v210, v210
	v_fma_f32 v37, v37, v211, v211
	v_fma_f32 v38, v38, v212, v212
	v_fma_f32 v39, v39, v213, v213
	v_fma_f32 v40, v40, v214, v214
	v_fma_f32 v41, v41, v215, v215
	v_fma_f32 v42, v42, v216, v216
	v_fma_f32 v43, v43, v217, v217
	v_fma_f32 v44, v44, v218, v218
	v_fma_f32 v45, v45, v219, v219
	v_fma_f32 v46, v46, v222, v222
	v_fma_f32 v47, v47, v223, v223
	v_mul_f32_e32 v32, 0x3f4c422a, v32
	v_mul_f32_e32 v33, 0x3f4c422a, v33
	v_mul_f32_e32 v34, 0x3f4c422a, v34
	v_mul_f32_e32 v35, 0x3f4c422a, v35
	v_mul_f32_e32 v36, 0x3f4c422a, v36
	v_mul_f32_e32 v37, 0x3f4c422a, v37
	v_mul_f32_e32 v38, 0x3f4c422a, v38
	v_mul_f32_e32 v39, 0x3f4c422a, v39
	v_mul_f32_e32 v40, 0x3f4c422a, v40
	v_mul_f32_e32 v41, 0x3f4c422a, v41
	v_mul_f32_e32 v42, 0x3f4c422a, v42
	v_mul_f32_e32 v43, 0x3f4c422a, v43
	v_mul_f32_e32 v44, 0x3f4c422a, v44
	v_mul_f32_e32 v45, 0x3f4c422a, v45
	v_mul_f32_e32 v46, 0x3f4c422a, v46
	v_mul_f32_e32 v47, 0x3f4c422a, v47
	v_pk_add_f32 v[32:33], v[32:33], v[32:33]
	v_pk_add_f32 v[34:35], v[34:35], v[34:35]
	v_pk_add_f32 v[36:37], v[36:37], v[36:37]
	v_pk_add_f32 v[38:39], v[38:39], v[38:39]
	v_pk_add_f32 v[40:41], v[40:41], v[40:41]
	v_pk_add_f32 v[42:43], v[42:43], v[42:43]
	v_pk_add_f32 v[44:45], v[44:45], v[44:45]
	v_pk_add_f32 v[46:47], v[46:47], v[46:47]
	v_pk_mul_f32 v[32:33], v[248:249], v[32:33]
	v_pk_mul_f32 v[34:35], v[248:249], v[34:35]
	v_pk_mul_f32 v[36:37], v[248:249], v[36:37]
	v_pk_mul_f32 v[38:39], v[248:249], v[38:39]
	v_pk_mul_f32 v[40:41], v[248:249], v[40:41]
	v_pk_mul_f32 v[42:43], v[248:249], v[42:43]
	v_pk_mul_f32 v[44:45], v[248:249], v[44:45]
	v_pk_mul_f32 v[46:47], v[248:249], v[46:47]
	v_exp_f32_e32 v32, v32
	v_exp_f32_e32 v33, v33
	v_exp_f32_e32 v34, v34
	v_exp_f32_e32 v35, v35
	v_exp_f32_e32 v36, v36
	v_exp_f32_e32 v37, v37
	v_exp_f32_e32 v38, v38
	v_exp_f32_e32 v39, v39
	v_exp_f32_e32 v40, v40
	v_exp_f32_e32 v41, v41
	v_exp_f32_e32 v42, v42
	v_exp_f32_e32 v43, v43
	v_exp_f32_e32 v44, v44
	v_exp_f32_e32 v45, v45
	v_exp_f32_e32 v46, v46
	v_exp_f32_e32 v47, v47
	v_pk_add_f32 v[32:33], v[32:33], 1.0 op_sel_hi:[1,0]
	v_pk_add_f32 v[34:35], v[34:35], 1.0 op_sel_hi:[1,0]
	v_pk_add_f32 v[36:37], v[36:37], 1.0 op_sel_hi:[1,0]
	v_pk_add_f32 v[38:39], v[38:39], 1.0 op_sel_hi:[1,0]
	v_pk_add_f32 v[40:41], v[40:41], 1.0 op_sel_hi:[1,0]
	v_pk_add_f32 v[42:43], v[42:43], 1.0 op_sel_hi:[1,0]
	v_pk_add_f32 v[44:45], v[44:45], 1.0 op_sel_hi:[1,0]
	v_pk_add_f32 v[46:47], v[46:47], 1.0 op_sel_hi:[1,0]
	v_rcp_f32_e32 v32, v32
	v_rcp_f32_e32 v33, v33
	v_rcp_f32_e32 v34, v34
	v_rcp_f32_e32 v35, v35
	v_rcp_f32_e32 v36, v36
	v_rcp_f32_e32 v37, v37
	v_rcp_f32_e32 v38, v38
	v_rcp_f32_e32 v39, v39
	v_rcp_f32_e32 v40, v40
	v_rcp_f32_e32 v41, v41
	v_rcp_f32_e32 v42, v42
	v_rcp_f32_e32 v43, v43
	v_rcp_f32_e32 v44, v44
	v_rcp_f32_e32 v45, v45
	v_rcp_f32_e32 v46, v46
	v_rcp_f32_e32 v47, v47
	s_nop 0
	v_pk_mul_f32 v[206:207], v[32:33], v[206:207]
	v_pk_mul_f32 v[208:209], v[34:35], v[208:209]
	v_pk_mul_f32 v[210:211], v[36:37], v[210:211]
	v_pk_mul_f32 v[212:213], v[38:39], v[212:213]
	v_pk_mul_f32 v[214:215], v[40:41], v[214:215]
	v_pk_mul_f32 v[216:217], v[42:43], v[216:217]
	v_pk_mul_f32 v[218:219], v[44:45], v[218:219]
	v_pk_mul_f32 v[222:223], v[46:47], v[222:223]
	s_waitcnt lgkmcnt(0)
; __device__ __forceinline__ float sigmoid_f(float x) { return rcpf_(1.f + __expf(-x)); }
; template <bool FINAL, int D>
; __device__ __forceinline__ void rg_dir(PREF p, int l, int h, int ch, int sidx, int rowbase  , LAS bf16_t* sXc, LAS float* stg, int lane) {
;     ...
;         for (int ti = 0; ti < 16; ++ti) { const int tk = D ? 15 - ti : ti;
;             const float zr = stg[tk * 64 + lane] + ba, zi = stg[1024 + tk * 64 + lane] + bi;
;             const float r = sigmoid_f(zr), ig = sigmoid_f(zi);
;             const float a = __builtin_amdgcn_exp2f(r * sp8);
;             const float xc = bf2f(sXc[(mt * 16 + tk) * 72 + lane]);
;             av[ti] = a; iv[ti] = __builtin_amdgcn_sqrtf(fmaxf(1.f - a * a, 0.f)) * ig * xc;
	v_pk_add_f32 v[0:1], v[242:243], v[0:1]
	v_pk_add_f32 v[2:3], v[242:243], v[2:3]
	v_pk_add_f32 v[4:5], v[242:243], v[4:5]
	v_pk_add_f32 v[6:7], v[242:243], v[6:7]
	v_pk_add_f32 v[8:9], v[242:243], v[8:9]
	v_pk_add_f32 v[10:11], v[242:243], v[10:11]
	v_pk_add_f32 v[12:13], v[242:243], v[12:13]
	v_pk_add_f32 v[14:15], v[242:243], v[14:15]
	v_pk_add_f32 v[16:17], v[244:245], v[16:17]
	v_pk_add_f32 v[18:19], v[244:245], v[18:19]
	v_pk_add_f32 v[20:21], v[244:245], v[20:21]
	v_pk_add_f32 v[22:23], v[244:245], v[22:23]
	v_pk_add_f32 v[24:25], v[244:245], v[24:25]
	v_pk_add_f32 v[26:27], v[244:245], v[26:27]
	v_pk_add_f32 v[28:29], v[244:245], v[28:29]
	v_pk_add_f32 v[30:31], v[244:245], v[30:31]
	v_pk_mul_f32 v[0:1], v[248:249], v[0:1]
	v_pk_mul_f32 v[2:3], v[248:249], v[2:3]
	v_pk_mul_f32 v[4:5], v[248:249], v[4:5]
	v_pk_mul_f32 v[6:7], v[248:249], v[6:7]
	v_pk_mul_f32 v[8:9], v[248:249], v[8:9]
	v_pk_mul_f32 v[10:11], v[248:249], v[10:11]
	v_pk_mul_f32 v[12:13], v[248:249], v[12:13]
	v_pk_mul_f32 v[14:15], v[248:249], v[14:15]
	v_pk_mul_f32 v[16:17], v[248:249], v[16:17]
	v_pk_mul_f32 v[18:19], v[248:249], v[18:19]
	v_pk_mul_f32 v[20:21], v[248:249], v[20:21]
	v_pk_mul_f32 v[22:23], v[248:249], v[22:23]
	v_pk_mul_f32 v[24:25], v[248:249], v[24:25]
	v_pk_mul_f32 v[26:27], v[248:249], v[26:27]
	v_pk_mul_f32 v[28:29], v[248:249], v[28:29]
	v_pk_mul_f32 v[30:31], v[248:249], v[30:31]
	v_exp_f32_e32 v0, v0
	v_exp_f32_e32 v1, v1
	v_exp_f32_e32 v2, v2
	v_exp_f32_e32 v3, v3
	v_exp_f32_e32 v4, v4
	v_exp_f32_e32 v5, v5
	v_exp_f32_e32 v6, v6
	v_exp_f32_e32 v7, v7
	v_exp_f32_e32 v8, v8
	v_exp_f32_e32 v9, v9
	v_exp_f32_e32 v10, v10
	v_exp_f32_e32 v11, v11
	v_exp_f32_e32 v12, v12
	v_exp_f32_e32 v13, v13
	v_exp_f32_e32 v14, v14
	v_exp_f32_e32 v15, v15
	v_exp_f32_e32 v16, v16
	v_exp_f32_e32 v17, v17
	v_exp_f32_e32 v18, v18
	v_exp_f32_e32 v19, v19
	v_exp_f32_e32 v20, v20
	v_exp_f32_e32 v21, v21
	v_exp_f32_e32 v22, v22
	v_exp_f32_e32 v23, v23
	v_exp_f32_e32 v24, v24
	v_exp_f32_e32 v25, v25
	v_exp_f32_e32 v26, v26
	v_exp_f32_e32 v27, v27
	v_exp_f32_e32 v28, v28
	v_exp_f32_e32 v29, v29
	v_exp_f32_e32 v30, v30
	v_exp_f32_e32 v31, v31
	v_pk_add_f32 v[0:1], v[0:1], 1.0 op_sel_hi:[1,0]
	v_pk_add_f32 v[2:3], v[2:3], 1.0 op_sel_hi:[1,0]
	v_pk_add_f32 v[4:5], v[4:5], 1.0 op_sel_hi:[1,0]
	v_pk_add_f32 v[6:7], v[6:7], 1.0 op_sel_hi:[1,0]
	v_pk_add_f32 v[8:9], v[8:9], 1.0 op_sel_hi:[1,0]
	v_pk_add_f32 v[10:11], v[10:11], 1.0 op_sel_hi:[1,0]
	v_pk_add_f32 v[12:13], v[12:13], 1.0 op_sel_hi:[1,0]
	v_pk_add_f32 v[14:15], v[14:15], 1.0 op_sel_hi:[1,0]
	v_pk_add_f32 v[16:17], v[16:17], 1.0 op_sel_hi:[1,0]
	v_pk_add_f32 v[18:19], v[18:19], 1.0 op_sel_hi:[1,0]
	v_pk_add_f32 v[20:21], v[20:21], 1.0 op_sel_hi:[1,0]
	v_pk_add_f32 v[22:23], v[22:23], 1.0 op_sel_hi:[1,0]
	v_pk_add_f32 v[24:25], v[24:25], 1.0 op_sel_hi:[1,0]
	v_pk_add_f32 v[26:27], v[26:27], 1.0 op_sel_hi:[1,0]
	v_pk_add_f32 v[28:29], v[28:29], 1.0 op_sel_hi:[1,0]
	v_pk_add_f32 v[30:31], v[30:31], 1.0 op_sel_hi:[1,0]
	v_rcp_f32_e32 v0, v0
	v_rcp_f32_e32 v1, v1
	v_rcp_f32_e32 v2, v2
	v_rcp_f32_e32 v3, v3
	v_rcp_f32_e32 v4, v4
	v_rcp_f32_e32 v5, v5
	v_rcp_f32_e32 v6, v6
	v_rcp_f32_e32 v7, v7
	v_rcp_f32_e32 v8, v8
	v_rcp_f32_e32 v9, v9
	v_rcp_f32_e32 v10, v10
	v_rcp_f32_e32 v11, v11
	v_rcp_f32_e32 v12, v12
	v_rcp_f32_e32 v13, v13
	v_rcp_f32_e32 v14, v14
	v_rcp_f32_e32 v15, v15
	v_rcp_f32_e32 v16, v16
	v_rcp_f32_e32 v17, v17
	v_rcp_f32_e32 v18, v18
	v_rcp_f32_e32 v19, v19
	v_rcp_f32_e32 v20, v20
	v_rcp_f32_e32 v21, v21
	v_rcp_f32_e32 v22, v22
	v_rcp_f32_e32 v23, v23
	v_rcp_f32_e32 v24, v24
	v_rcp_f32_e32 v25, v25
	v_rcp_f32_e32 v26, v26
	v_rcp_f32_e32 v27, v27
	v_rcp_f32_e32 v28, v28
	v_rcp_f32_e32 v29, v29
	v_rcp_f32_e32 v30, v30
	v_rcp_f32_e32 v31, v31
	v_pk_mul_f32 v[0:1], v[246:247], v[0:1]
	v_pk_mul_f32 v[2:3], v[246:247], v[2:3]
	v_pk_mul_f32 v[4:5], v[246:247], v[4:5]
	v_pk_mul_f32 v[6:7], v[246:247], v[6:7]
	v_pk_mul_f32 v[8:9], v[246:247], v[8:9]
	v_pk_mul_f32 v[10:11], v[246:247], v[10:11]
	v_pk_mul_f32 v[12:13], v[246:247], v[12:13]
	v_pk_mul_f32 v[14:15], v[246:247], v[14:15]
	v_lshlrev_b32_e32 v48, 16, v48
	v_lshlrev_b32_e32 v49, 16, v49
	v_lshlrev_b32_e32 v50, 16, v50
	v_lshlrev_b32_e32 v51, 16, v51
	v_lshlrev_b32_e32 v52, 16, v52
	v_lshlrev_b32_e32 v53, 16, v53
	v_lshlrev_b32_e32 v54, 16, v54
	v_lshlrev_b32_e32 v55, 16, v55
	v_lshlrev_b32_e32 v56, 16, v56
	v_lshlrev_b32_e32 v57, 16, v57
	v_lshlrev_b32_e32 v58, 16, v58
	v_lshlrev_b32_e32 v59, 16, v59
	v_lshlrev_b32_e32 v60, 16, v60
	v_lshlrev_b32_e32 v61, 16, v61
	v_lshlrev_b32_e32 v62, 16, v62
	v_lshlrev_b32_e32 v63, 16, v63
	v_exp_f32_e32 v0, v0
	v_exp_f32_e32 v1, v1
	v_exp_f32_e32 v2, v2
	v_exp_f32_e32 v3, v3
	v_exp_f32_e32 v4, v4
	v_exp_f32_e32 v5, v5
	v_exp_f32_e32 v6, v6
	v_exp_f32_e32 v7, v7
	v_exp_f32_e32 v8, v8
	v_exp_f32_e32 v9, v9
	v_exp_f32_e32 v10, v10
	v_exp_f32_e32 v11, v11
	v_exp_f32_e32 v12, v12
	v_exp_f32_e32 v13, v13
	v_exp_f32_e32 v14, v14
	v_exp_f32_e32 v15, v15
	v_fma_f32 v32, -v0, v0, 1.0
	v_fma_f32 v33, -v1, v1, 1.0
	v_fma_f32 v34, -v2, v2, 1.0
	v_fma_f32 v35, -v3, v3, 1.0
	v_fma_f32 v36, -v4, v4, 1.0
	v_fma_f32 v37, -v5, v5, 1.0
	v_fma_f32 v38, -v6, v6, 1.0
	v_fma_f32 v39, -v7, v7, 1.0
	v_fma_f32 v40, -v8, v8, 1.0
	v_fma_f32 v41, -v9, v9, 1.0
	v_fma_f32 v42, -v10, v10, 1.0
	v_fma_f32 v43, -v11, v11, 1.0
	v_fma_f32 v44, -v12, v12, 1.0
	v_fma_f32 v45, -v13, v13, 1.0
	v_fma_f32 v46, -v14, v14, 1.0
	v_fma_f32 v47, -v15, v15, 1.0
	v_max_f32_e32 v32, 0, v32
	v_max_f32_e32 v33, 0, v33
	v_max_f32_e32 v34, 0, v34
	v_max_f32_e32 v35, 0, v35
	v_max_f32_e32 v36, 0, v36
	v_max_f32_e32 v37, 0, v37
	v_max_f32_e32 v38, 0, v38
	v_max_f32_e32 v39, 0, v39
; __device__ __forceinline__ unsigned f2bf(float f) { unsigned r; asm("v_cvt_pk_bf16_f32 %0, %1, %1" : "=v"(r) : "v"(f)); return r & 0xffffu; }
; template <bool FINAL, int D>
; __device__ __forceinline__ void rg_dir(PREF p, int l, int h, int ch, int sidx, int rowbase  , LAS bf16_t* sXc, LAS float* stg, int lane) {
;     ...
;         for (int ti = 0; ti < 16; ++ti) { const int tk = D ? 15 - ti : ti;
;             hc = av[ti] * hc + iv[ti]; Ap *= av[ti];
;             if (FINAL) { const size_t row = (size_t)(rowbase + mt * 16 + tk);
;                 if (D == 0) TMP[row * 512 + ch] = (bf16_t)f2bf(hc);
;                 else MIX[row * DM + ch] = (bf16_t)f2bf(grv[ti] * (hfv[ti] + hc)); }
;         }
; __global__ void __launch_bounds__(NTHREADS, 2) mega_fwd(Params p_arg) {
;     ...
;             for (int item = gw; item < nrg; item += NGW) rg_item<true>(p, l, item, lds + wave * 18432, lane);
	v_max_f32_e32 v40, 0, v40
	v_max_f32_e32 v41, 0, v41
	v_max_f32_e32 v42, 0, v42
	v_max_f32_e32 v43, 0, v43
	v_max_f32_e32 v44, 0, v44
	v_max_f32_e32 v45, 0, v45
	v_max_f32_e32 v46, 0, v46
	v_max_f32_e32 v47, 0, v47
	v_sqrt_f32_e32 v32, v32
	v_sqrt_f32_e32 v33, v33
	v_sqrt_f32_e32 v34, v34
	v_sqrt_f32_e32 v35, v35
	v_sqrt_f32_e32 v36, v36
	v_sqrt_f32_e32 v37, v37
	v_sqrt_f32_e32 v38, v38
	v_sqrt_f32_e32 v39, v39
	v_sqrt_f32_e32 v40, v40
	v_sqrt_f32_e32 v41, v41
	v_sqrt_f32_e32 v42, v42
	v_sqrt_f32_e32 v43, v43
	v_sqrt_f32_e32 v44, v44
	v_sqrt_f32_e32 v45, v45
	v_sqrt_f32_e32 v46, v46
	v_sqrt_f32_e32 v47, v47
	s_nop 0
	v_pk_mul_f32 v[16:17], v[16:17], v[32:33]
	v_pk_mul_f32 v[18:19], v[18:19], v[34:35]
	v_pk_mul_f32 v[20:21], v[20:21], v[36:37]
	v_pk_mul_f32 v[22:23], v[22:23], v[38:39]
	v_pk_mul_f32 v[24:25], v[24:25], v[40:41]
	v_pk_mul_f32 v[26:27], v[26:27], v[42:43]
	v_pk_mul_f32 v[28:29], v[28:29], v[44:45]
	v_pk_mul_f32 v[30:31], v[30:31], v[46:47]
	v_pk_mul_f32 v[16:17], v[16:17], v[48:49]
	v_pk_mul_f32 v[18:19], v[18:19], v[50:51]
	v_pk_mul_f32 v[20:21], v[20:21], v[52:53]
	v_pk_mul_f32 v[22:23], v[22:23], v[54:55]
	v_pk_mul_f32 v[24:25], v[24:25], v[56:57]
	v_pk_mul_f32 v[26:27], v[26:27], v[58:59]
	v_pk_mul_f32 v[28:29], v[28:29], v[60:61]
	v_pk_mul_f32 v[30:31], v[30:31], v[62:63]
	s_add_i32 s39, s15, 15
	s_lshl_b32 s39, s39, 11
	s_add_u32 s90, s0, 0x7b00000
	s_addc_u32 s91, s1, 0
	s_add_u32 s90, s90, s39
	s_addc_u32 s91, s91, 0
	v_lshlrev_b32_e32 v48, 16, v158
	v_and_b32_e32 v49, 0xffff0000, v158
	v_lshlrev_b32_e32 v50, 16, v159
	v_and_b32_e32 v51, 0xffff0000, v159
	v_lshlrev_b32_e32 v52, 16, v160
	v_and_b32_e32 v53, 0xffff0000, v160
	v_lshlrev_b32_e32 v54, 16, v161
	v_and_b32_e32 v55, 0xffff0000, v161
	v_lshlrev_b32_e32 v56, 16, v162
	v_and_b32_e32 v57, 0xffff0000, v162
	v_lshlrev_b32_e32 v58, 16, v163
	v_and_b32_e32 v59, 0xffff0000, v163
	v_lshlrev_b32_e32 v60, 16, v164
	v_and_b32_e32 v61, 0xffff0000, v164
	v_lshlrev_b32_e32 v62, 16, v165
	v_and_b32_e32 v63, 0xffff0000, v165
	v_fma_f32 v47, v15, v250, v31
	v_fma_f32 v46, v14, v47, v30
	v_fma_f32 v45, v13, v46, v29
	v_fma_f32 v44, v12, v45, v28
	v_fma_f32 v43, v11, v44, v27
	v_fma_f32 v42, v10, v43, v26
	v_fma_f32 v41, v9, v42, v25
	v_fma_f32 v40, v8, v41, v24
	v_fma_f32 v39, v7, v40, v23
	v_fma_f32 v38, v6, v39, v22
	v_fma_f32 v37, v5, v38, v21
	v_fma_f32 v36, v4, v37, v20
	v_fma_f32 v35, v3, v36, v19
	v_fma_f32 v34, v2, v35, v18
	v_fma_f32 v33, v1, v34, v17
	v_fma_f32 v32, v0, v33, v16
	v_mov_b32_e32 v250, v32
	v_pk_add_f32 v[48:49], v[48:49], v[32:33]
	v_pk_add_f32 v[50:51], v[50:51], v[34:35]
	v_pk_add_f32 v[52:53], v[52:53], v[36:37]
	v_pk_add_f32 v[54:55], v[54:55], v[38:39]
	v_pk_add_f32 v[56:57], v[56:57], v[40:41]
	v_pk_add_f32 v[58:59], v[58:59], v[42:43]
	v_pk_add_f32 v[60:61], v[60:61], v[44:45]
	v_pk_add_f32 v[62:63], v[62:63], v[46:47]
	v_pk_mul_f32 v[48:49], v[206:207], v[48:49]
	v_pk_mul_f32 v[50:51], v[208:209], v[50:51]
	v_pk_mul_f32 v[52:53], v[210:211], v[52:53]
	v_pk_mul_f32 v[54:55], v[212:213], v[54:55]
	v_pk_mul_f32 v[56:57], v[214:215], v[56:57]
	v_pk_mul_f32 v[58:59], v[216:217], v[58:59]
	v_pk_mul_f32 v[60:61], v[218:219], v[60:61]
	v_pk_mul_f32 v[62:63], v[222:223], v[62:63]
	v_cvt_pk_bf16_f32 v48, v48, v48
	v_cvt_pk_bf16_f32 v49, v49, v49
	v_cvt_pk_bf16_f32 v50, v50, v50
	v_cvt_pk_bf16_f32 v51, v51, v51
	v_cvt_pk_bf16_f32 v52, v52, v52
	v_cvt_pk_bf16_f32 v53, v53, v53
	v_cvt_pk_bf16_f32 v54, v54, v54
	v_cvt_pk_bf16_f32 v55, v55, v55
	v_cvt_pk_bf16_f32 v56, v56, v56
	v_cvt_pk_bf16_f32 v57, v57, v57
	v_cvt_pk_bf16_f32 v58, v58, v58
	v_cvt_pk_bf16_f32 v59, v59, v59
	v_cvt_pk_bf16_f32 v60, v60, v60
	v_cvt_pk_bf16_f32 v61, v61, v61
	v_cvt_pk_bf16_f32 v62, v62, v62
	v_cvt_pk_bf16_f32 v63, v63, v63
	global_store_short v234, v63, s[90:91]
	s_sub_u32 s90, s90, 0x800
	s_subb_u32 s91, s91, 0
	global_store_short v234, v62, s[90:91]
	s_sub_u32 s90, s90, 0x800
	s_subb_u32 s91, s91, 0
	global_store_short v234, v61, s[90:91]
	s_sub_u32 s90, s90, 0x800
	s_subb_u32 s91, s91, 0
	global_store_short v234, v60, s[90:91]
	s_sub_u32 s90, s90, 0x800
	s_subb_u32 s91, s91, 0
	global_store_short v234, v59, s[90:91]
	s_sub_u32 s90, s90, 0x800
	s_subb_u32 s91, s91, 0
	global_store_short v234, v58, s[90:91]
	s_sub_u32 s90, s90, 0x800
	s_subb_u32 s91, s91, 0
	global_store_short v234, v57, s[90:91]
	s_sub_u32 s90, s90, 0x800
	s_subb_u32 s91, s91, 0
	global_store_short v234, v56, s[90:91]
	s_sub_u32 s90, s90, 0x800
	s_subb_u32 s91, s91, 0
	global_store_short v234, v55, s[90:91]
	s_sub_u32 s90, s90, 0x800
	s_subb_u32 s91, s91, 0
	global_store_short v234, v54, s[90:91]
	s_sub_u32 s90, s90, 0x800
	s_subb_u32 s91, s91, 0
	global_store_short v234, v53, s[90:91]
	s_sub_u32 s90, s90, 0x800
	s_subb_u32 s91, s91, 0
	global_store_short v234, v52, s[90:91]
	s_sub_u32 s90, s90, 0x800
	s_subb_u32 s91, s91, 0
	global_store_short v234, v51, s[90:91]
	s_sub_u32 s90, s90, 0x800
	s_subb_u32 s91, s91, 0
	global_store_short v234, v50, s[90:91]
	s_sub_u32 s90, s90, 0x800
	s_subb_u32 s91, s91, 0
	global_store_short v234, v49, s[90:91]
	s_sub_u32 s90, s90, 0x800
	s_subb_u32 s91, s91, 0
	global_store_short v234, v48, s[90:91]
	s_waitcnt lgkmcnt(0)
	v_readlane_b32 s84, v253, 29
	s_add_i32 s12, s12, s84
	s_cmpk_lt_i32 s12, 0x1000
	s_cbranch_scc1 .Lrg7_keep
	s_sub_i32 s0, s12, 0x1000
	s_lshr_b32 s1, s0, 5
	s_and_b32 s0, s0, 31
	s_and_b32 s12, s1, 7
	s_add_i32 s1, s1, 0x1000
	s_cmp_eq_u32 s0, s12
	s_cselect_b32 s12, s1, 0x2000
.Lrg7_keep:
	v_readlane_b32 s0, v254, 56
	s_movk_i32 s94, 0x90
	s_cmp_ge_i32 s12, s0
	s_cbranch_scc0 .LBB0_77
	v_readlane_b32 s76, v253, 22
	v_readlane_b32 s82, v253, 27
	v_readlane_b32 s74, v253, 20
	v_readlane_b32 s77, v253, 23
	v_readlane_b32 s79, v253, 25
	v_readlane_b32 s83, v253, 28
	v_readlane_b32 s90, v254, 15
	v_readlane_b32 s92, v253, 35
	v_readlane_b32 s38, v253, 55
	v_readlane_b32 s72, v253, 61
	v_readlane_b32 s6, v255, 3
	v_mov_b32_e32 v84, v149
	v_mov_b32_e32 v144, v150
	v_readlane_b32 s75, v253, 21
	v_readlane_b32 s78, v253, 24
	v_readlane_b32 s95, v253, 26
	v_readlane_b32 s91, v254, 16
	v_readlane_b32 s76, v253, 32
	v_readlane_b32 s77, v253, 33
	v_readlane_b32 s79, v253, 34
	v_readlane_b32 s93, v253, 36
	v_readlane_b32 s85, v253, 37
	v_readlane_b32 s96, v253, 40
	v_readlane_b32 s83, v253, 41
	v_readlane_b32 s80, v254, 8
	v_readlane_b32 s39, v253, 56
	v_readlane_b32 s97, v254, 7
	v_readlane_b32 s73, v253, 62
	v_readlane_b32 s36, v254, 12
	v_readlane_b32 s44, v254, 14
	v_readlane_b32 s7, v255, 4
	v_readlane_b32 s9, v255, 5
	v_readlane_b32 s8, v255, 6
	v_readlane_b32 s81, v253, 31
	v_readlane_b32 s37, v254, 13

; __device__ __forceinline__ void gl3_item(PREF p, int l, int item, bool valid, LAS unsigned char* sl, int w4, int t256, int lane) {
;     ...
;     const int h = item & 3, rest = item >> 2;
;     const int cj = rest < 512 ? 4 + (rest & 255) : ((rest - 512) & 3), b = rest < 512 ? (rest >> 8) : ((rest - 512) >> 2);
;     int row0, rstride; gla_rows(b, cj, row0, rstride);
; __global__ void __launch_bounds__(NTHREADS, 2) mega_fwd(Params p_arg) {
;     ...
;             const int NS = G * 2, sgid = NS - 1 - (blockIdx.x * 2 + (wave >> 2));
;             for (int r2 = 0; r2 < ((DUP_MASK & (64 | 256)) ? 2 : 1); ++r2)
;             for (int it = 0; it * NS < ngl; ++it) { const int item = it * NS + sgid; gl3_item(p, l, item, item < ngl, lds + (wave >> 2) * 64512, wave & 3, tid & 255, lane); }
.LBB0_86:
	s_add_i32 s59, s6, s16
	s_cmpk_lt_i32 s59, 0x800
	s_cbranch_scc1 .Lbal_gl3_keep
	s_sub_i32 s16, 0x9ff, s59
	s_lshr_b32 s17, s16, 4
	s_and_b32 s16, s16, 15
	s_and_b32 s59, s17, 3
	s_add_i32 s16, s16, s59
	s_add_i32 s17, s17, 0x800
	s_cmp_eq_u32 s16, 15
	s_cselect_b32 s59, s17, 0x9ff
.Lbal_gl3_keep:
	s_ashr_i32 s16, s59, 2
	s_cmpk_gt_i32 s16, 0x1ff
	s_cselect_b64 s[86:87], -1, 0
	s_and_b32 s17, s16, 0xff
	s_add_i32 s19, s17, 4
	s_ashr_i32 s33, s59, 10
	s_cmpk_lt_i32 s16, 0x200
	s_mov_b64 s[88:89], -1
	s_cbranch_scc0 .LBB0_88
	s_lshl_b32 s46, s19, 12
	s_lshl_b32 s18, s33, 14
	s_and_b32 s46, s46, 0x3000
	s_or_b32 s18, s46, s18
	s_lshr_b32 s17, s17, 2
	s_or_b32 s18, s18, s17
	s_mov_b64 s[88:89], 0

; #define LAS __attribute__((address_space(3)))
; template <bool FINAL>
; __device__ __forceinline__ void rg_item(PREF p, int l, int item, LAS unsigned char* wl, int lane) {
;     const bf16_t* __restrict__ P = (const bf16_t*)(p.ws + WS_GP);
;     const int h = item & 7, rest = item >> 3;
;     const int ci = rest < 512 ? 4 + (rest & 255) : ((rest - 512) & 3), b = rest < 512 ? (rest >> 8) : ((rest - 512) >> 2);
;     const int seq_row0 = ci < 4 ? TL + b * 256 : b * 16384;
;     const int t0 = ci < 4 ? ci * 64 : (ci - 4) * 64;
;     const int seqlen = ci < 4 ? 256 : 16384;
;     const int ch = h * 64 + lane;
;     LAS bf16_t* sXc = (LAS bf16_t*)wl;
;     LAS float* stg = (LAS float*)(wl + 9216);
; __global__ void __launch_bounds__(NTHREADS, 2) mega_fwd(Params p_arg) {
;     ...
;             for (int item = gw; item < 2 * NCH * 8; item += NGW) rg_item<false>(p, l, item, lds + wave * 18432, lane);
.LBB0_174:
	v_writelane_b32 v253, s20, 57
	v_lshrrev_b32_e32 v3, 1, v117
	v_and_b32_e32 v64, 63, v117
	v_writelane_b32 v253, s21, 58
	v_writelane_b32 v253, s16, 59
	s_andn2_b64 vcc, exec, s[4:5]
	v_and_b32_e32 v118, 24, v3
	v_writelane_b32 v253, s17, 60
	v_writelane_b32 v253, s18, 63
	s_nop 1
	v_writelane_b32 v254, s19, 0
	v_writelane_b32 v254, s34, 1
	v_writelane_b32 v254, s25, 2
	s_cbranch_vccnz .LBB0_182
	s_load_dwordx2 s[8:9], s[38:39], 0xc0
	v_writelane_b32 v254, s87, 3
	s_mul_i32 s4, s0, 0x4800
	v_writelane_b32 v254, s63, 4
	s_add_i32 s5, s4, 0
	v_writelane_b32 v254, s64, 5
	s_waitcnt lgkmcnt(0)
	s_add_u32 s16, s8, 0x700000
	v_writelane_b32 v254, s65, 6
	s_addc_u32 s17, s9, 0
	v_writelane_b32 v254, s97, 7
	s_add_u32 s0, s8, 0x400000
	v_writelane_b32 v254, s80, 8
	s_addc_u32 s1, s9, 0
	v_writelane_b32 v254, s0, 9
	v_lshlrev_b32_e32 v0, 6, v64
	s_movk_i32 s6, 0x3c0
	v_writelane_b32 v254, s1, 10
	s_load_dwordx4 s[0:3], s[38:39], 0x58
	v_and_or_b32 v0, v0, s6, v118
	s_add_u32 s6, s8, 0x300000
	s_addc_u32 s7, s9, 0
	s_bfe_u32 s8, s10, 0x30006
	v_lshl_or_b32 v122, s8, 6, v64
	v_lshlrev_b32_e32 v9, 10, v2
	s_waitcnt lgkmcnt(0)
	v_mov_b32_e32 v2, s0
	v_mov_b32_e32 v3, s1
	v_or_b32_e32 v144, s28, v122
	v_lshl_add_u64 v[66:67], v[144:145], 2, v[2:3]
	s_mov_b64 s[0:1], 0x1800
	v_writelane_b32 v254, s10, 11
	v_lshl_add_u64 v[70:71], v[66:67], 0, s[0:1]
	s_mov_b32 s0, s36
	v_writelane_b32 v254, s0, 12
	v_lshlrev_b32_e32 v0, 1, v0
	v_mov_b32_e32 v4, s2
	v_writelane_b32 v254, s1, 13
	s_or_b32 s0, s8, s44
	s_lshl_b32 s0, s0, 13
	s_add_u32 s0, s6, s0
	s_addc_u32 s1, s7, 0
	s_add_u32 s2, s0, 0x10000
	v_mov_b32_e32 v5, s3
	v_or_b32_e32 v144, s36, v122
	s_addc_u32 s3, s1, 0
	v_or_b32_e32 v2, 0x800, v0
	v_mov_b32_e32 v3, v145
	v_lshl_add_u64 v[72:73], v[144:145], 2, v[4:5]
	v_mov_b32_e32 v1, v145
	v_lshl_add_u64 v[80:81], s[2:3], 0, v[2:3]
	v_or_b32_e32 v2, 0x1000, v0
	v_or_b32_e32 v4, 0x1800, v0
	v_mov_b32_e32 v5, v145
	v_lshl_add_u64 v[78:79], s[2:3], 0, v[0:1]
	v_lshl_add_u64 v[84:85], s[2:3], 0, v[2:3]
	v_lshl_add_u64 v[88:89], s[2:3], 0, v[4:5]
	s_or_b32 s2, s8, s22
	v_lshl_add_u64 v[76:77], s[0:1], 0, v[0:1]
	v_lshl_add_u64 v[82:83], s[0:1], 0, v[2:3]
	v_lshl_add_u64 v[86:87], s[0:1], 0, v[4:5]
	s_lshl_b32 s0, s2, 13
	v_writelane_b32 v254, s44, 14
	s_add_u32 s0, s6, s0
	s_mov_b32 s3, s91
	s_addc_u32 s1, s7, 0
	s_or_b32 s90, s2, 8
	v_writelane_b32 v254, s2, 15
	v_lshlrev_b32_e32 v144, 1, v122
	v_lshl_add_u64 v[90:91], s[0:1], 0, v[0:1]
	v_writelane_b32 v254, s3, 16
	s_lshl_b64 s[2:3], s[90:91], 13
	s_add_u32 s2, s6, s2
	s_addc_u32 s3, s7, s3
	v_lshl_add_u64 v[92:93], s[2:3], 0, v[0:1]
	v_mov_b32_e32 v0, s4
	v_writelane_b32 v253, s72, 61
	v_lshl_add_u32 v8, v116, 2, s5
	v_lshl_add_u64 v[74:75], s[70:71], 0, v[144:145]
	v_or_b32_e32 v144, s23, v122
	v_or_b32_e32 v6, s15, v122
	v_mov_b32_e32 v7, v145
	v_mad_u32_u24 v0, v116, s94, v0
	v_writelane_b32 v254, s16, 17
	v_writelane_b32 v253, s73, 62
	v_lshl_add_u32 v120, v64, 1, s5
	v_lshl_add_u32 v121, v64, 2, s5
	v_lshl_add_u64 v[68:69], v[66:67], 0, s[88:89]
	v_lshl_add_u64 v[94:95], s[0:1], 0, v[2:3]
	v_lshl_add_u64 v[96:97], s[2:3], 0, v[2:3]
	v_lshl_add_u64 v[98:99], s[0:1], 0, v[4:5]
	v_lshl_add_u64 v[100:101], s[2:3], 0, v[4:5]
	v_add_u32_e32 v123, s5, v119
	v_add3_u32 v124, v0, v119, 0
	v_or_b32_e32 v125, 48, v116
	v_lshlrev_b64 v[102:103], 2, v[144:145]
	v_lshlrev_b64 v[104:105], 2, v[6:7]
	v_add_u32_e32 v126, v8, v9
	v_writelane_b32 v254, s17, 18
	s_mov_b32 s12, s11
.LBB0_176:
	v_readlane_b32 s2, v253, 55
	v_readlane_b32 s3, v253, 56
	v_readlane_b32 s57, v254, 5
	v_readlane_b32 s44, v254, 11
	s_nop 3
	s_load_dwordx2 s[0:1], s[2:3], 0xc0
	s_load_dwordx4 s[72:75], s[2:3], 0x58
	s_load_dwordx2 s[76:77], s[2:3], 0x68
	s_load_dwordx2 s[78:79], s[2:3], 0x78
	s_load_dwordx2 s[80:81], s[2:3], 0x88
	v_mbcnt_lo_u32_b32 v233, -1, 0
	v_mbcnt_hi_u32_b32 v233, -1, v233
	s_and_b32 s7, s12, 7
	s_lshr_b32 s6, s12, 3
	s_and_b32 s8, s6, 0xff
	s_lshr_b32 s9, s6, 8
	s_lshl_b32 s10, s8, 6
	s_lshl_b32 s11, s9, 14
	s_add_i32 s8, s8, 4
	s_mov_b32 s14, 0x4000
	s_cmpk_lt_u32 s6, 0x200
	s_cbranch_scc1 .Lrg5_dec
	s_sub_i32 s15, s6, 0x200
	s_and_b32 s8, s15, 3
	s_lshr_b32 s9, s15, 2
	s_lshl_b32 s10, s8, 6
	s_lshl_b32 s11, s9, 8
	s_add_i32 s11, s11, 0x8000
	s_movk_i32 s14, 0x100
; #define LAS __attribute__((address_space(3)))
; template <bool FINAL>
; __device__ __forceinline__ void rg_item(PREF p, int l, int item, LAS unsigned char* wl, int lane) {
;     ...
;     const int h = item & 7, rest = item >> 3;
;     const int ci = rest < 512 ? 4 + (rest & 255) : ((rest - 512) & 3), b = rest < 512 ? (rest >> 8) : ((rest - 512) >> 2);
;     const int seq_row0 = ci < 4 ? TL + b * 256 : b * 16384;
;     const int t0 = ci < 4 ? ci * 64 : (ci - 4) * 64;
;     const int seqlen = ci < 4 ? 256 : 16384;
;     const int ch = h * 64 + lane;
;     LAS bf16_t* sXc = (LAS bf16_t*)wl;
;     LAS float* stg = (LAS float*)(wl + 9216);
;     {
;         const float cw0 = p.conv_w[(l * 4 + 0) * 512 + ch], cw1 = p.conv_w[(l * 4 + 1) * 512 + ch], cw2 = p.conv_w[(l * 4 + 2) * 512 + ch], cw3 = p.conv_w[(l * 4 + 3) * 512 + ch];
;         const float cb = p.conv_b[l * 512 + ch];
;         float xv[67]; unsigned xr_[67];
; #pragma unroll
;         for (int i = 0; i < 67; ++i) { const int t = t0 - 2 + i; const int tc = t < 0 ? 0 : (t >= seqlen ? seqlen - 1 : t);
;             xr_[i] = P[(size_t)(seq_row0 + tc) * PW + ch]; }
;     ...
;     const int sidx0 = ((b * NCH + ci) * 2) * 512 + ch;
.Lrg5_dec:
	s_add_i32 s15, s11, s10
	s_mul_i32 s36, s9, 0x104
	s_add_i32 s36, s36, s8
	s_lshl_b32 s36, s36, 12
	s_cmp_eq_u32 s10, 0
	s_cselect_b32 s37, 0, -1
	s_add_i32 s38, s10, 64
	s_cmp_eq_u32 s38, s14
	s_cselect_b32 s38, 0, -1
	s_bfe_u32 s44, s44, 0x30006
	s_mul_i32 s44, s44, 0x4800
	v_lshl_or_b32 v234, s7, 6, v233
	v_lshlrev_b32_e32 v235, 2, v234
	v_lshlrev_b32_e32 v234, 1, v234
	v_and_b32_e32 v236, 15, v233
	v_lshrrev_b32_e32 v241, 4, v233
	s_movk_i32 s39, 0x90
	v_mul_u32_u24_e32 v237, 0x90, v236
	v_lshl_add_u32 v237, v241, 4, v237
	v_lshlrev_b32_e32 v238, 7, v236
	v_lshl_add_u32 v238, v241, 4, v238
	v_lshlrev_b32_e32 v239, 10, v241
	v_lshl_add_u32 v239, v236, 2, v239
	v_mov_b32_e32 v241, v238
	v_add_u32_e32 v236, s44, v237
	s_add_i32 s39, s44, 0x2400
	v_add_u32_e32 v237, s39, v239
	v_add_u32_e32 v238, 0x1000, v237
	v_lshl_add_u32 v239, v233, 2, s44
	v_lshl_add_u32 v240, v233, 1, s44
	s_add_i32 s39, s15, -2
	s_mul_hi_i32 s83, s39, 0x1600
	s_mul_i32 s82, s39, 0x1600
	s_waitcnt lgkmcnt(0)
	s_add_u32 s82, s82, s0
	s_addc_u32 s83, s83, s1
	s_add_u32 s82, s82, 0xbc00000
	s_addc_u32 s83, s83, 0
	global_load_ushort v158, v234, s[82:83]
	s_add_u32 s82, s82, 0x1600
	s_addc_u32 s83, s83, 0
	global_load_ushort v159, v234, s[82:83]
	s_add_u32 s82, s82, 0x1600
	s_addc_u32 s83, s83, 0
	global_load_ushort v160, v234, s[82:83]
	s_add_u32 s82, s82, 0x1600
	s_addc_u32 s83, s83, 0
	global_load_ushort v161, v234, s[82:83]
	s_add_u32 s82, s82, 0x1600
	s_addc_u32 s83, s83, 0
	global_load_ushort v162, v234, s[82:83]
	s_add_u32 s82, s82, 0x1600
	s_addc_u32 s83, s83, 0
	global_load_ushort v163, v234, s[82:83]
	s_add_u32 s82, s82, 0x1600
	s_addc_u32 s83, s83, 0
	global_load_ushort v164, v234, s[82:83]
	s_add_u32 s82, s82, 0x1600
	s_addc_u32 s83, s83, 0
	global_load_ushort v165, v234, s[82:83]
	s_add_u32 s82, s82, 0x1600
	s_addc_u32 s83, s83, 0
	global_load_ushort v166, v234, s[82:83]
	s_add_u32 s82, s82, 0x1600
	s_addc_u32 s83, s83, 0
	global_load_ushort v167, v234, s[82:83]
	s_add_u32 s82, s82, 0x1600
	s_addc_u32 s83, s83, 0
	global_load_ushort v168, v234, s[82:83]
	s_add_u32 s82, s82, 0x1600
	s_addc_u32 s83, s83, 0
	global_load_ushort v169, v234, s[82:83]
	s_add_u32 s82, s82, 0x1600
	s_addc_u32 s83, s83, 0
	global_load_ushort v170, v234, s[82:83]
	s_add_u32 s82, s82, 0x1600
	s_addc_u32 s83, s83, 0
	global_load_ushort v171, v234, s[82:83]
	s_add_u32 s82, s82, 0x1600
	s_addc_u32 s83, s83, 0
	global_load_ushort v172, v234, s[82:83]
	s_add_u32 s82, s82, 0x1600
	s_addc_u32 s83, s83, 0
	global_load_ushort v173, v234, s[82:83]
	s_add_u32 s82, s82, 0x1600
	s_addc_u32 s83, s83, 0
	global_load_ushort v174, v234, s[82:83]
	s_add_u32 s82, s82, 0x1600
	s_addc_u32 s83, s83, 0
	global_load_ushort v175, v234, s[82:83]
	s_add_u32 s82, s82, 0x1600
	s_addc_u32 s83, s83, 0
	global_load_ushort v176, v234, s[82:83]
	s_add_u32 s82, s82, 0x1600
	s_addc_u32 s83, s83, 0
	global_load_ushort v177, v234, s[82:83]
	s_add_u32 s82, s82, 0x1600
	s_addc_u32 s83, s83, 0
	global_load_ushort v178, v234, s[82:83]
	s_add_u32 s82, s82, 0x1600
	s_addc_u32 s83, s83, 0
	global_load_ushort v179, v234, s[82:83]
	s_add_u32 s82, s82, 0x1600
	s_addc_u32 s83, s83, 0
	global_load_ushort v180, v234, s[82:83]
	s_add_u32 s82, s82, 0x1600
	s_addc_u32 s83, s83, 0
	global_load_ushort v181, v234, s[82:83]
	s_add_u32 s82, s82, 0x1600
	s_addc_u32 s83, s83, 0
	global_load_ushort v182, v234, s[82:83]
	s_add_u32 s82, s82, 0x1600
	s_addc_u32 s83, s83, 0
	global_load_ushort v183, v234, s[82:83]
	s_add_u32 s82, s82, 0x1600
	s_addc_u32 s83, s83, 0
	global_load_ushort v184, v234, s[82:83]
	s_add_u32 s82, s82, 0x1600
	s_addc_u32 s83, s83, 0
	global_load_ushort v185, v234, s[82:83]
	s_add_u32 s82, s82, 0x1600
	s_addc_u32 s83, s83, 0
	global_load_ushort v186, v234, s[82:83]
	s_add_u32 s82, s82, 0x1600
	s_addc_u32 s83, s83, 0
	global_load_ushort v187, v234, s[82:83]
	s_add_u32 s82, s82, 0x1600
	s_addc_u32 s83, s83, 0
	global_load_ushort v188, v234, s[82:83]
	s_add_u32 s82, s82, 0x1600
	s_addc_u32 s83, s83, 0
	global_load_ushort v189, v234, s[82:83]
	s_add_u32 s82, s82, 0x1600
	s_addc_u32 s83, s83, 0
	global_load_ushort v190, v234, s[82:83]
	s_add_u32 s82, s82, 0x1600
	s_addc_u32 s83, s83, 0
	global_load_ushort v191, v234, s[82:83]
	s_add_u32 s82, s82, 0x1600
	s_addc_u32 s83, s83, 0
	global_load_ushort v192, v234, s[82:83]
	s_add_u32 s82, s82, 0x1600
	s_addc_u32 s83, s83, 0
	global_load_ushort v193, v234, s[82:83]
	s_add_u32 s82, s82, 0x1600
	s_addc_u32 s83, s83, 0
	global_load_ushort v194, v234, s[82:83]
	s_add_u32 s82, s82, 0x1600
	s_addc_u32 s83, s83, 0
	global_load_ushort v195, v234, s[82:83]
	s_add_u32 s82, s82, 0x1600
	s_addc_u32 s83, s83, 0
	global_load_ushort v196, v234, s[82:83]
	s_add_u32 s82, s82, 0x1600
	s_addc_u32 s83, s83, 0
	global_load_ushort v197, v234, s[82:83]
	s_add_u32 s82, s82, 0x1600
	s_addc_u32 s83, s83, 0
	global_load_ushort v198, v234, s[82:83]
	s_add_u32 s82, s82, 0x1600
	s_addc_u32 s83, s83, 0
	global_load_ushort v199, v234, s[82:83]
	s_add_u32 s82, s82, 0x1600
	s_addc_u32 s83, s83, 0
	global_load_ushort v200, v234, s[82:83]
	s_add_u32 s82, s82, 0x1600
	s_addc_u32 s83, s83, 0
	global_load_ushort v201, v234, s[82:83]
	s_add_u32 s82, s82, 0x1600
	s_addc_u32 s83, s83, 0
	global_load_ushort v202, v234, s[82:83]
	s_add_u32 s82, s82, 0x1600
	s_addc_u32 s83, s83, 0
	global_load_ushort v203, v234, s[82:83]
	s_add_u32 s82, s82, 0x1600
	s_addc_u32 s83, s83, 0
	global_load_ushort v204, v234, s[82:83]
	s_add_u32 s82, s82, 0x1600
	s_addc_u32 s83, s83, 0
	global_load_ushort v205, v234, s[82:83]
	s_add_u32 s82, s82, 0x1600
	s_addc_u32 s83, s83, 0
	global_load_ushort v206, v234, s[82:83]
	s_add_u32 s82, s82, 0x1600
; template <bool FINAL, int D>
; __device__ __forceinline__ void rg_dir(PREF p, int l, int h, int ch, int sidx, int rowbase  , LAS bf16_t* sXc, LAS float* stg, int lane) {
;     ...
;     bf16x8 Br[4][2], Bi[4][2];
; #pragma unroll
;     for (int nt = 0; nt < 4; ++nt) { const int o0 = (nt * 16 + (lane & 15)) * 64 + (lane >> 4) * 8;
;         Br[nt][0] = *(const bf16x8*)(wr_ + o0); Br[nt][1] = *(const bf16x8*)(wr_ + o0 + 32); Bi[nt][0] = *(const bf16x8*)(wi_ + o0); Bi[nt][1] = *(const bf16x8*)(wi_ + o0 + 32); }
; template <bool FINAL>
; __device__ __forceinline__ void rg_item(PREF p, int l, int item, LAS unsigned char* wl, int lane) {
;     ...
;         const float cw0 = p.conv_w[(l * 4 + 0) * 512 + ch], cw1 = p.conv_w[(l * 4 + 1) * 512 + ch], cw2 = p.conv_w[(l * 4 + 2) * 512 + ch], cw3 = p.conv_w[(l * 4 + 3) * 512 + ch];
;         const float cb = p.conv_b[l * 512 + ch];
;         float xv[67]; unsigned xr_[67];
; #pragma unroll
;         for (int i = 0; i < 67; ++i) { const int t = t0 - 2 + i; const int tc = t < 0 ? 0 : (t >= seqlen ? seqlen - 1 : t);
;             xr_[i] = P[(size_t)(seq_row0 + tc) * PW + ch]; }
	s_addc_u32 s83, s83, 0
	global_load_ushort v207, v234, s[82:83]
	s_add_u32 s82, s82, 0x1600
	s_addc_u32 s83, s83, 0
	global_load_ushort v208, v234, s[82:83]
	s_add_u32 s82, s82, 0x1600
	s_addc_u32 s83, s83, 0
	global_load_ushort v209, v234, s[82:83]
	s_add_u32 s82, s82, 0x1600
	s_addc_u32 s83, s83, 0
	global_load_ushort v210, v234, s[82:83]
	s_add_u32 s82, s82, 0x1600
	s_addc_u32 s83, s83, 0
	global_load_ushort v211, v234, s[82:83]
	s_add_u32 s82, s82, 0x1600
	s_addc_u32 s83, s83, 0
	global_load_ushort v212, v234, s[82:83]
	s_add_u32 s82, s82, 0x1600
	s_addc_u32 s83, s83, 0
	global_load_ushort v213, v234, s[82:83]
	s_add_u32 s82, s82, 0x1600
	s_addc_u32 s83, s83, 0
	global_load_ushort v214, v234, s[82:83]
	s_add_u32 s82, s82, 0x1600
	s_addc_u32 s83, s83, 0
	global_load_ushort v215, v234, s[82:83]
	s_add_u32 s82, s82, 0x1600
	s_addc_u32 s83, s83, 0
	global_load_ushort v216, v234, s[82:83]
	s_add_u32 s82, s82, 0x1600
	s_addc_u32 s83, s83, 0
	global_load_ushort v217, v234, s[82:83]
	s_add_u32 s82, s82, 0x1600
	s_addc_u32 s83, s83, 0
	global_load_ushort v218, v234, s[82:83]
	s_add_u32 s82, s82, 0x1600
	s_addc_u32 s83, s83, 0
	global_load_ushort v219, v234, s[82:83]
	s_add_u32 s82, s82, 0x1600
	s_addc_u32 s83, s83, 0
	global_load_ushort v222, v234, s[82:83]
	s_add_u32 s82, s82, 0x1600
	s_addc_u32 s83, s83, 0
	global_load_ushort v223, v234, s[82:83]
	s_add_u32 s82, s82, 0x1600
	s_addc_u32 s83, s83, 0
	global_load_ushort v140, v234, s[82:83]
	s_add_u32 s82, s82, 0x1600
	s_addc_u32 s83, s83, 0
	global_load_ushort v141, v234, s[82:83]
	s_add_u32 s82, s82, 0x1600
	s_addc_u32 s83, s83, 0
	global_load_ushort v232, v234, s[82:83]
	s_lshl_b32 s39, s57, 13
	s_add_u32 s72, s72, s39
	s_addc_u32 s73, s73, 0
	global_load_dword v40, v235, s[72:73]
	global_load_dword v41, v235, s[72:73] offset:2048
	s_add_u32 s72, s72, 0x1000
	s_addc_u32 s73, s73, 0
	global_load_dword v42, v235, s[72:73]
	global_load_dword v43, v235, s[72:73] offset:2048
	s_lshl_b32 s39, s57, 11
	s_add_u32 s74, s74, s39
	s_addc_u32 s75, s75, 0
	global_load_dword v44, v235, s[74:75]
	s_lshl_b32 s39, s57, 12
	s_add_u32 s76, s76, s39
	s_addc_u32 s77, s77, 0
	s_add_u32 s78, s78, s39
	s_addc_u32 s79, s79, 0
	s_add_u32 s80, s80, s39
	s_addc_u32 s81, s81, 0
	s_lshl_b32 s39, s57, 5
	s_add_i32 s39, s39, s7
	s_lshl_b32 s39, s39, 13
	s_add_u32 s92, s0, 0x300000
	s_addc_u32 s93, s1, 0
	s_add_u32 s92, s92, s39
	s_addc_u32 s93, s93, 0
	global_load_dword v45, v235, s[76:77]
	global_load_dword v46, v235, s[78:79]
	global_load_dword v47, v235, s[80:81]
	s_add_u32 s90, s92, 0x0
	s_addc_u32 s91, s93, 0
	global_load_dwordx4 v[80:83], v241, s[90:91]
	global_load_dwordx4 v[84:87], v241, s[90:91] offset:64
	global_load_dwordx4 v[88:91], v241, s[90:91] offset:2048
	global_load_dwordx4 v[92:95], v241, s[90:91] offset:2112
	s_add_u32 s90, s92, 0x1000
	s_addc_u32 s91, s93, 0
	global_load_dwordx4 v[96:99], v241, s[90:91]
	global_load_dwordx4 v[100:103], v241, s[90:91] offset:64
	global_load_dwordx4 v[104:107], v241, s[90:91] offset:2048
	global_load_dwordx4 v[108:111], v241, s[90:91] offset:2112
	s_add_u32 s90, s92, 0x10000
	s_addc_u32 s91, s93, 0
	global_load_dwordx4 v[112:115], v241, s[90:91]
	global_load_dwordx4 v[148:151], v241, s[90:91] offset:64
	global_load_dwordx4 v[120:123], v241, s[90:91] offset:2048
	global_load_dwordx4 v[124:127], v241, s[90:91] offset:2112
	s_add_u32 s90, s92, 0x11000
	s_addc_u32 s91, s93, 0
	global_load_dwordx4 v[128:131], v241, s[90:91]
	global_load_dwordx4 v[132:135], v241, s[90:91] offset:64
	global_load_dwordx4 v[136:139], v241, s[90:91] offset:2048
	global_load_dwordx4 v[228:231], v241, s[90:91] offset:2112
	s_waitcnt vmcnt(19)
	v_lshlrev_b32_e32 v158, 16, v158
	v_lshlrev_b32_e32 v159, 16, v159
	v_lshlrev_b32_e32 v160, 16, v160
	v_lshlrev_b32_e32 v161, 16, v161
	v_lshlrev_b32_e32 v162, 16, v162
	v_lshlrev_b32_e32 v163, 16, v163
	v_lshlrev_b32_e32 v164, 16, v164
	v_lshlrev_b32_e32 v165, 16, v165
	v_lshlrev_b32_e32 v166, 16, v166
	v_lshlrev_b32_e32 v167, 16, v167
	v_lshlrev_b32_e32 v168, 16, v168
	v_lshlrev_b32_e32 v169, 16, v169
	v_lshlrev_b32_e32 v170, 16, v170
	v_lshlrev_b32_e32 v171, 16, v171
	v_lshlrev_b32_e32 v172, 16, v172
	v_lshlrev_b32_e32 v173, 16, v173
	v_lshlrev_b32_e32 v174, 16, v174
	v_lshlrev_b32_e32 v175, 16, v175
	v_lshlrev_b32_e32 v176, 16, v176
	v_lshlrev_b32_e32 v177, 16, v177
	v_lshlrev_b32_e32 v178, 16, v178
	v_lshlrev_b32_e32 v179, 16, v179
	v_lshlrev_b32_e32 v180, 16, v180
	v_lshlrev_b32_e32 v181, 16, v181
	v_lshlrev_b32_e32 v182, 16, v182
	v_lshlrev_b32_e32 v183, 16, v183
	v_lshlrev_b32_e32 v184, 16, v184
	v_lshlrev_b32_e32 v185, 16, v185
	v_lshlrev_b32_e32 v186, 16, v186
	v_lshlrev_b32_e32 v187, 16, v187
	v_lshlrev_b32_e32 v188, 16, v188
	v_lshlrev_b32_e32 v189, 16, v189
	v_lshlrev_b32_e32 v190, 16, v190
	v_lshlrev_b32_e32 v191, 16, v191
	v_lshlrev_b32_e32 v192, 16, v192
	v_lshlrev_b32_e32 v193, 16, v193
	v_lshlrev_b32_e32 v194, 16, v194
	v_lshlrev_b32_e32 v195, 16, v195
	v_lshlrev_b32_e32 v196, 16, v196
	v_lshlrev_b32_e32 v197, 16, v197
	v_lshlrev_b32_e32 v198, 16, v198
	v_lshlrev_b32_e32 v199, 16, v199
	v_lshlrev_b32_e32 v200, 16, v200
	v_lshlrev_b32_e32 v201, 16, v201
	v_lshlrev_b32_e32 v202, 16, v202
	v_lshlrev_b32_e32 v203, 16, v203
	v_lshlrev_b32_e32 v204, 16, v204
	v_lshlrev_b32_e32 v205, 16, v205
	v_lshlrev_b32_e32 v206, 16, v206
	v_lshlrev_b32_e32 v207, 16, v207
	v_lshlrev_b32_e32 v208, 16, v208
	v_lshlrev_b32_e32 v209, 16, v209
	v_lshlrev_b32_e32 v210, 16, v210
	v_lshlrev_b32_e32 v211, 16, v211
	v_lshlrev_b32_e32 v212, 16, v212
	v_lshlrev_b32_e32 v213, 16, v213
	v_lshlrev_b32_e32 v214, 16, v214
	v_lshlrev_b32_e32 v215, 16, v215
	v_lshlrev_b32_e32 v216, 16, v216
; __device__ __forceinline__ unsigned f2bf(float f) { unsigned r; asm("v_cvt_pk_bf16_f32 %0, %1, %1" : "=v"(r) : "v"(f)); return r & 0xffffu; }
; template <bool FINAL>
; __device__ __forceinline__ void rg_item(PREF p, int l, int item, LAS unsigned char* wl, int lane) {
;     ...
;         for (int i = 0; i < 67; ++i) { const int t = t0 - 2 + i; const int tc = t < 0 ? 0 : (t >= seqlen ? seqlen - 1 : t); xv[i] = (t == tc) ? bf2f(xr_[i]) : 0.f; }
; #pragma unroll
;         for (int tt = 0; tt < 64; ++tt) { const float xc = xv[tt] * cw0 + xv[tt + 1] * cw1 + xv[tt + 2] * cw2 + xv[tt + 3] * cw3 + cb; sXc[tt * 72 + lane] = (bf16_t)f2bf(xc); }
	v_lshlrev_b32_e32 v217, 16, v217
	v_lshlrev_b32_e32 v218, 16, v218
	v_lshlrev_b32_e32 v219, 16, v219
	v_lshlrev_b32_e32 v222, 16, v222
	v_lshlrev_b32_e32 v223, 16, v223
	v_lshlrev_b32_e32 v140, 16, v140
	v_lshlrev_b32_e32 v141, 16, v141
	v_lshlrev_b32_e32 v232, 16, v232
	v_and_b32_e32 v158, s37, v158
	v_and_b32_e32 v159, s37, v159
	v_and_b32_e32 v232, s38, v232
	v_mul_f32_e32 v32, v41, v159
	v_mul_f32_e32 v33, v41, v160
	v_mul_f32_e32 v34, v41, v161
	v_mul_f32_e32 v35, v41, v162
	v_mul_f32_e32 v36, v41, v163
	v_mul_f32_e32 v37, v41, v164
	v_mul_f32_e32 v38, v41, v165
	v_mul_f32_e32 v39, v41, v166
	v_fmac_f32_e32 v32, v40, v158
	v_fmac_f32_e32 v33, v40, v159
	v_fmac_f32_e32 v34, v40, v160
	v_fmac_f32_e32 v35, v40, v161
	v_fmac_f32_e32 v36, v40, v162
	v_fmac_f32_e32 v37, v40, v163
	v_fmac_f32_e32 v38, v40, v164
	v_fmac_f32_e32 v39, v40, v165
	v_fmac_f32_e32 v32, v42, v160
	v_fmac_f32_e32 v33, v42, v161
	v_fmac_f32_e32 v34, v42, v162
	v_fmac_f32_e32 v35, v42, v163
	v_fmac_f32_e32 v36, v42, v164
	v_fmac_f32_e32 v37, v42, v165
	v_fmac_f32_e32 v38, v42, v166
	v_fmac_f32_e32 v39, v42, v167
	v_fmac_f32_e32 v32, v43, v161
	v_fmac_f32_e32 v33, v43, v162
	v_fmac_f32_e32 v34, v43, v163
	v_fmac_f32_e32 v35, v43, v164
	v_fmac_f32_e32 v36, v43, v165
	v_fmac_f32_e32 v37, v43, v166
	v_fmac_f32_e32 v38, v43, v167
	v_fmac_f32_e32 v39, v43, v168
	v_add_f32_e32 v32, v44, v32
	v_add_f32_e32 v33, v44, v33
	v_add_f32_e32 v34, v44, v34
	v_add_f32_e32 v35, v44, v35
	v_add_f32_e32 v36, v44, v36
	v_add_f32_e32 v37, v44, v37
	v_add_f32_e32 v38, v44, v38
	v_add_f32_e32 v39, v44, v39
	v_cvt_pk_bf16_f32 v32, v32, v33
	v_cvt_pk_bf16_f32 v34, v34, v35
	v_cvt_pk_bf16_f32 v36, v36, v37
	v_cvt_pk_bf16_f32 v38, v38, v39
	ds_write_b16 v240, v32 offset:0
	ds_write_b16_d16_hi v240, v32 offset:144
	ds_write_b16 v240, v34 offset:288
	ds_write_b16_d16_hi v240, v34 offset:432
	ds_write_b16 v240, v36 offset:576
	ds_write_b16_d16_hi v240, v36 offset:720
	ds_write_b16 v240, v38 offset:864
	ds_write_b16_d16_hi v240, v38 offset:1008
	v_mul_f32_e32 v32, v41, v167
	v_mul_f32_e32 v33, v41, v168
	v_mul_f32_e32 v34, v41, v169
	v_mul_f32_e32 v35, v41, v170
	v_mul_f32_e32 v36, v41, v171
	v_mul_f32_e32 v37, v41, v172
	v_mul_f32_e32 v38, v41, v173
	v_mul_f32_e32 v39, v41, v174
	v_fmac_f32_e32 v32, v40, v166
	v_fmac_f32_e32 v33, v40, v167
	v_fmac_f32_e32 v34, v40, v168
	v_fmac_f32_e32 v35, v40, v169
	v_fmac_f32_e32 v36, v40, v170
	v_fmac_f32_e32 v37, v40, v171
	v_fmac_f32_e32 v38, v40, v172
	v_fmac_f32_e32 v39, v40, v173
	v_fmac_f32_e32 v32, v42, v168
	v_fmac_f32_e32 v33, v42, v169
	v_fmac_f32_e32 v34, v42, v170
	v_fmac_f32_e32 v35, v42, v171
	v_fmac_f32_e32 v36, v42, v172
	v_fmac_f32_e32 v37, v42, v173
	v_fmac_f32_e32 v38, v42, v174
	v_fmac_f32_e32 v39, v42, v175
	v_fmac_f32_e32 v32, v43, v169
	v_fmac_f32_e32 v33, v43, v170
	v_fmac_f32_e32 v34, v43, v171
	v_fmac_f32_e32 v35, v43, v172
	v_fmac_f32_e32 v36, v43, v173
	v_fmac_f32_e32 v37, v43, v174
	v_fmac_f32_e32 v38, v43, v175
	v_fmac_f32_e32 v39, v43, v176
	v_add_f32_e32 v32, v44, v32
	v_add_f32_e32 v33, v44, v33
	v_add_f32_e32 v34, v44, v34
	v_add_f32_e32 v35, v44, v35
	v_add_f32_e32 v36, v44, v36
	v_add_f32_e32 v37, v44, v37
	v_add_f32_e32 v38, v44, v38
	v_add_f32_e32 v39, v44, v39
	v_cvt_pk_bf16_f32 v32, v32, v33
	v_cvt_pk_bf16_f32 v34, v34, v35
	v_cvt_pk_bf16_f32 v36, v36, v37
	v_cvt_pk_bf16_f32 v38, v38, v39
	ds_write_b16 v240, v32 offset:1152
	ds_write_b16_d16_hi v240, v32 offset:1296
	ds_write_b16 v240, v34 offset:1440
	ds_write_b16_d16_hi v240, v34 offset:1584
	ds_write_b16 v240, v36 offset:1728
	ds_write_b16_d16_hi v240, v36 offset:1872
	ds_write_b16 v240, v38 offset:2016
	ds_write_b16_d16_hi v240, v38 offset:2160
	v_mul_f32_e32 v32, v41, v175
	v_mul_f32_e32 v33, v41, v176
	v_mul_f32_e32 v34, v41, v177
	v_mul_f32_e32 v35, v41, v178
	v_mul_f32_e32 v36, v41, v179
	v_mul_f32_e32 v37, v41, v180
	v_mul_f32_e32 v38, v41, v181
	v_mul_f32_e32 v39, v41, v182
	v_fmac_f32_e32 v32, v40, v174
	v_fmac_f32_e32 v33, v40, v175
	v_fmac_f32_e32 v34, v40, v176
	v_fmac_f32_e32 v35, v40, v177
	v_fmac_f32_e32 v36, v40, v178
	v_fmac_f32_e32 v37, v40, v179
	v_fmac_f32_e32 v38, v40, v180
	v_fmac_f32_e32 v39, v40, v181
	v_fmac_f32_e32 v32, v42, v176
	v_fmac_f32_e32 v33, v42, v177
	v_fmac_f32_e32 v34, v42, v178
	v_fmac_f32_e32 v35, v42, v179
	v_fmac_f32_e32 v36, v42, v180
	v_fmac_f32_e32 v37, v42, v181
	v_fmac_f32_e32 v38, v42, v182
	v_fmac_f32_e32 v39, v42, v183
	v_fmac_f32_e32 v32, v43, v177
	v_fmac_f32_e32 v33, v43, v178
	v_fmac_f32_e32 v34, v43, v179
	v_fmac_f32_e32 v35, v43, v180
	v_fmac_f32_e32 v36, v43, v181
	v_fmac_f32_e32 v37, v43, v182
	v_fmac_f32_e32 v38, v43, v183
	v_fmac_f32_e32 v39, v43, v184
	v_add_f32_e32 v32, v44, v32
	v_add_f32_e32 v33, v44, v33
	v_add_f32_e32 v34, v44, v34
	v_add_f32_e32 v35, v44, v35
	v_add_f32_e32 v36, v44, v36
	v_add_f32_e32 v37, v44, v37
	v_add_f32_e32 v38, v44, v38
	v_add_f32_e32 v39, v44, v39
	v_cvt_pk_bf16_f32 v32, v32, v33
	v_cvt_pk_bf16_f32 v34, v34, v35
	v_cvt_pk_bf16_f32 v36, v36, v37
	v_cvt_pk_bf16_f32 v38, v38, v39
	ds_write_b16 v240, v32 offset:2304
	ds_write_b16_d16_hi v240, v32 offset:2448
	ds_write_b16 v240, v34 offset:2592
	ds_write_b16_d16_hi v240, v34 offset:2736
	ds_write_b16 v240, v36 offset:2880
	ds_write_b16_d16_hi v240, v36 offset:3024
	ds_write_b16 v240, v38 offset:3168
	ds_write_b16_d16_hi v240, v38 offset:3312
	v_mul_f32_e32 v32, v41, v183
	v_mul_f32_e32 v33, v41, v184
	v_mul_f32_e32 v34, v41, v185
	v_mul_f32_e32 v35, v41, v186
	v_mul_f32_e32 v36, v41, v187
	v_mul_f32_e32 v37, v41, v188
	v_mul_f32_e32 v38, v41, v189
	v_mul_f32_e32 v39, v41, v190
	v_fmac_f32_e32 v32, v40, v182
	v_fmac_f32_e32 v33, v40, v183
; __device__ __forceinline__ unsigned f2bf(float f) { unsigned r; asm("v_cvt_pk_bf16_f32 %0, %1, %1" : "=v"(r) : "v"(f)); return r & 0xffffu; }
; template <bool FINAL>
; __device__ __forceinline__ void rg_item(PREF p, int l, int item, LAS unsigned char* wl, int lane) {
;     ...
;         for (int tt = 0; tt < 64; ++tt) { const float xc = xv[tt] * cw0 + xv[tt + 1] * cw1 + xv[tt + 2] * cw2 + xv[tt + 3] * cw3 + cb; sXc[tt * 72 + lane] = (bf16_t)f2bf(xc); }
	v_fmac_f32_e32 v34, v40, v184
	v_fmac_f32_e32 v35, v40, v185
	v_fmac_f32_e32 v36, v40, v186
	v_fmac_f32_e32 v37, v40, v187
	v_fmac_f32_e32 v38, v40, v188
	v_fmac_f32_e32 v39, v40, v189
	v_fmac_f32_e32 v32, v42, v184
	v_fmac_f32_e32 v33, v42, v185
	v_fmac_f32_e32 v34, v42, v186
	v_fmac_f32_e32 v35, v42, v187
	v_fmac_f32_e32 v36, v42, v188
	v_fmac_f32_e32 v37, v42, v189
	v_fmac_f32_e32 v38, v42, v190
	v_fmac_f32_e32 v39, v42, v191
	v_fmac_f32_e32 v32, v43, v185
	v_fmac_f32_e32 v33, v43, v186
	v_fmac_f32_e32 v34, v43, v187
	v_fmac_f32_e32 v35, v43, v188
	v_fmac_f32_e32 v36, v43, v189
	v_fmac_f32_e32 v37, v43, v190
	v_fmac_f32_e32 v38, v43, v191
	v_fmac_f32_e32 v39, v43, v192
	v_add_f32_e32 v32, v44, v32
	v_add_f32_e32 v33, v44, v33
	v_add_f32_e32 v34, v44, v34
	v_add_f32_e32 v35, v44, v35
	v_add_f32_e32 v36, v44, v36
	v_add_f32_e32 v37, v44, v37
	v_add_f32_e32 v38, v44, v38
	v_add_f32_e32 v39, v44, v39
	v_cvt_pk_bf16_f32 v32, v32, v33
	v_cvt_pk_bf16_f32 v34, v34, v35
	v_cvt_pk_bf16_f32 v36, v36, v37
	v_cvt_pk_bf16_f32 v38, v38, v39
	ds_write_b16 v240, v32 offset:3456
	ds_write_b16_d16_hi v240, v32 offset:3600
	ds_write_b16 v240, v34 offset:3744
	ds_write_b16_d16_hi v240, v34 offset:3888
	ds_write_b16 v240, v36 offset:4032
	ds_write_b16_d16_hi v240, v36 offset:4176
	ds_write_b16 v240, v38 offset:4320
	ds_write_b16_d16_hi v240, v38 offset:4464
	v_mul_f32_e32 v32, v41, v191
	v_mul_f32_e32 v33, v41, v192
	v_mul_f32_e32 v34, v41, v193
	v_mul_f32_e32 v35, v41, v194
	v_mul_f32_e32 v36, v41, v195
	v_mul_f32_e32 v37, v41, v196
	v_mul_f32_e32 v38, v41, v197
	v_mul_f32_e32 v39, v41, v198
	v_fmac_f32_e32 v32, v40, v190
	v_fmac_f32_e32 v33, v40, v191
	v_fmac_f32_e32 v34, v40, v192
	v_fmac_f32_e32 v35, v40, v193
	v_fmac_f32_e32 v36, v40, v194
	v_fmac_f32_e32 v37, v40, v195
	v_fmac_f32_e32 v38, v40, v196
	v_fmac_f32_e32 v39, v40, v197
	v_fmac_f32_e32 v32, v42, v192
	v_fmac_f32_e32 v33, v42, v193
	v_fmac_f32_e32 v34, v42, v194
	v_fmac_f32_e32 v35, v42, v195
	v_fmac_f32_e32 v36, v42, v196
	v_fmac_f32_e32 v37, v42, v197
	v_fmac_f32_e32 v38, v42, v198
	v_fmac_f32_e32 v39, v42, v199
	v_fmac_f32_e32 v32, v43, v193
	v_fmac_f32_e32 v33, v43, v194
	v_fmac_f32_e32 v34, v43, v195
	v_fmac_f32_e32 v35, v43, v196
	v_fmac_f32_e32 v36, v43, v197
	v_fmac_f32_e32 v37, v43, v198
	v_fmac_f32_e32 v38, v43, v199
	v_fmac_f32_e32 v39, v43, v200
	v_add_f32_e32 v32, v44, v32
	v_add_f32_e32 v33, v44, v33
	v_add_f32_e32 v34, v44, v34
	v_add_f32_e32 v35, v44, v35
	v_add_f32_e32 v36, v44, v36
	v_add_f32_e32 v37, v44, v37
	v_add_f32_e32 v38, v44, v38
	v_add_f32_e32 v39, v44, v39
	v_cvt_pk_bf16_f32 v32, v32, v33
	v_cvt_pk_bf16_f32 v34, v34, v35
	v_cvt_pk_bf16_f32 v36, v36, v37
	v_cvt_pk_bf16_f32 v38, v38, v39
	ds_write_b16 v240, v32 offset:4608
	ds_write_b16_d16_hi v240, v32 offset:4752
	ds_write_b16 v240, v34 offset:4896
	ds_write_b16_d16_hi v240, v34 offset:5040
	ds_write_b16 v240, v36 offset:5184
	ds_write_b16_d16_hi v240, v36 offset:5328
	ds_write_b16 v240, v38 offset:5472
	ds_write_b16_d16_hi v240, v38 offset:5616
	v_mul_f32_e32 v32, v41, v199
	v_mul_f32_e32 v33, v41, v200
	v_mul_f32_e32 v34, v41, v201
	v_mul_f32_e32 v35, v41, v202
	v_mul_f32_e32 v36, v41, v203
	v_mul_f32_e32 v37, v41, v204
	v_mul_f32_e32 v38, v41, v205
	v_mul_f32_e32 v39, v41, v206
	v_fmac_f32_e32 v32, v40, v198
	v_fmac_f32_e32 v33, v40, v199
	v_fmac_f32_e32 v34, v40, v200
	v_fmac_f32_e32 v35, v40, v201
	v_fmac_f32_e32 v36, v40, v202
	v_fmac_f32_e32 v37, v40, v203
	v_fmac_f32_e32 v38, v40, v204
	v_fmac_f32_e32 v39, v40, v205
	v_fmac_f32_e32 v32, v42, v200
	v_fmac_f32_e32 v33, v42, v201
	v_fmac_f32_e32 v34, v42, v202
	v_fmac_f32_e32 v35, v42, v203
	v_fmac_f32_e32 v36, v42, v204
	v_fmac_f32_e32 v37, v42, v205
	v_fmac_f32_e32 v38, v42, v206
	v_fmac_f32_e32 v39, v42, v207
	v_fmac_f32_e32 v32, v43, v201
	v_fmac_f32_e32 v33, v43, v202
	v_fmac_f32_e32 v34, v43, v203
	v_fmac_f32_e32 v35, v43, v204
	v_fmac_f32_e32 v36, v43, v205
	v_fmac_f32_e32 v37, v43, v206
	v_fmac_f32_e32 v38, v43, v207
	v_fmac_f32_e32 v39, v43, v208
	v_add_f32_e32 v32, v44, v32
	v_add_f32_e32 v33, v44, v33
	v_add_f32_e32 v34, v44, v34
	v_add_f32_e32 v35, v44, v35
	v_add_f32_e32 v36, v44, v36
	v_add_f32_e32 v37, v44, v37
	v_add_f32_e32 v38, v44, v38
	v_add_f32_e32 v39, v44, v39
	v_cvt_pk_bf16_f32 v32, v32, v33
	v_cvt_pk_bf16_f32 v34, v34, v35
	v_cvt_pk_bf16_f32 v36, v36, v37
	v_cvt_pk_bf16_f32 v38, v38, v39
	ds_write_b16 v240, v32 offset:5760
	ds_write_b16_d16_hi v240, v32 offset:5904
	ds_write_b16 v240, v34 offset:6048
	ds_write_b16_d16_hi v240, v34 offset:6192
	ds_write_b16 v240, v36 offset:6336
	ds_write_b16_d16_hi v240, v36 offset:6480
	ds_write_b16 v240, v38 offset:6624
	ds_write_b16_d16_hi v240, v38 offset:6768
	v_mul_f32_e32 v32, v41, v207
	v_mul_f32_e32 v33, v41, v208
	v_mul_f32_e32 v34, v41, v209
	v_mul_f32_e32 v35, v41, v210
	v_mul_f32_e32 v36, v41, v211
	v_mul_f32_e32 v37, v41, v212
	v_mul_f32_e32 v38, v41, v213
	v_mul_f32_e32 v39, v41, v214
	v_fmac_f32_e32 v32, v40, v206
	v_fmac_f32_e32 v33, v40, v207
	v_fmac_f32_e32 v34, v40, v208
	v_fmac_f32_e32 v35, v40, v209
	v_fmac_f32_e32 v36, v40, v210
	v_fmac_f32_e32 v37, v40, v211
	v_fmac_f32_e32 v38, v40, v212
	v_fmac_f32_e32 v39, v40, v213
	v_fmac_f32_e32 v32, v42, v208
	v_fmac_f32_e32 v33, v42, v209
	v_fmac_f32_e32 v34, v42, v210
	v_fmac_f32_e32 v35, v42, v211
	v_fmac_f32_e32 v36, v42, v212
	v_fmac_f32_e32 v37, v42, v213
	v_fmac_f32_e32 v38, v42, v214
	v_fmac_f32_e32 v39, v42, v215
	v_fmac_f32_e32 v32, v43, v209
	v_fmac_f32_e32 v33, v43, v210
	v_fmac_f32_e32 v34, v43, v211
	v_fmac_f32_e32 v35, v43, v212
	v_fmac_f32_e32 v36, v43, v213
	v_fmac_f32_e32 v37, v43, v214
	v_fmac_f32_e32 v38, v43, v215
; template <bool FINAL, int D>
; __device__ __forceinline__ void rg_dir(PREF p, int l, int h, int ch, int sidx, int rowbase  , LAS bf16_t* sXc, LAS float* stg, int lane) {
;     ...
;     const float ba = p.rg_ba[(l * 2 + D) * 512 + ch], bi = p.rg_bi[(l * 2 + D) * 512 + ch], lam = p.rg_lam[(l * 2 + D) * 512 + ch];
;     const float e_ = __expf(-lam), u_ = 1.f + e_;
;     const float l1p = (u_ == 1.f) ? e_ : __logf(u_) * e_ * rcpf_(u_ - 1.f);
;     const float sp8 = -8.f * 1.4426950408889634f * l1p;
;     float hc = FINAL ? RGC[sidx] : 0.f, Ap = 1.f;
;     bf16x8 Br[4][2], Bi[4][2];
; #pragma unroll
;     for (int nt = 0; nt < 4; ++nt) { const int o0 = (nt * 16 + (lane & 15)) * 64 + (lane >> 4) * 8;
;         Br[nt][0] = *(const bf16x8*)(wr_ + o0); Br[nt][1] = *(const bf16x8*)(wr_ + o0 + 32); Bi[nt][0] = *(const bf16x8*)(wi_ + o0); Bi[nt][1] = *(const bf16x8*)(wi_ + o0 + 32); }
;     if (FINAL && D == 1) asm volatile("s_waitcnt vmcnt(0)" ::: "memory");
; #pragma unroll 1
;     for (int mi = 0; mi < 4; ++mi) { const int mt = D ? 3 - mi : mi;
;         float grv[16], hfv[16];
;         if (FINAL && D == 1) {
; #pragma unroll
;             for (int ti = 0; ti < 16; ++ti) { const size_t row = (size_t)(rowbase + mt * 16 + 15 - ti); grv[ti] = __builtin_bit_cast(float, (unsigned)P[row * PW + 512 + ch]); hfv[ti] = __builtin_bit_cast(float, (unsigned)TMP[row * 512 + ch]); }
;             __builtin_amdgcn_sched_barrier(0);
; #pragma unroll
;             for (int ti = 0; ti < 16; ++ti) { grv[ti] = bf2f(__builtin_bit_cast(unsigned, grv[ti])); hfv[ti] = bf2f(__builtin_bit_cast(unsigned, hfv[ti])); }
;         }
;         const bf16x8 A0 = *(const LAS bf16x8*)(sXc + (mt * 16 + (lane & 15)) * 72 + (lane >> 4) * 8), A1 = *(const LAS bf16x8*)(sXc + (mt * 16 + (lane & 15)) * 72 + 32 + (lane >> 4) * 8);
;         f32x4 ar[4], ai[4];
; #pragma unroll
;         for (int nt = 0; nt < 4; ++nt) { const f32x4 z = {0.f, 0.f, 0.f, 0.f};
;             ar[nt] = mfma16(A0, Br[nt][0], z); ar[nt] = mfma16(A1, Br[nt][1], ar[nt]); ai[nt] = mfma16(A0, Bi[nt][0], z); ai[nt] = mfma16(A1, Bi[nt][1], ai[nt]); }
;         WAVE_SYNC();
; #pragma unroll
;         for (int nt = 0; nt < 4; ++nt)
; #pragma unroll
;             for (int j = 0; j < 4; ++j) { const int o = ((lane >> 4) * 4 + j) * 64 + nt * 16 + (lane & 15); stg[o] = ar[nt][j]; stg[1024 + o] = ai[nt][j]; }
;         WAVE_SYNC();
	v_fmac_f32_e32 v39, v43, v216
	v_add_f32_e32 v32, v44, v32
	v_add_f32_e32 v33, v44, v33
	v_add_f32_e32 v34, v44, v34
	v_add_f32_e32 v35, v44, v35
	v_add_f32_e32 v36, v44, v36
	v_add_f32_e32 v37, v44, v37
	v_add_f32_e32 v38, v44, v38
	v_add_f32_e32 v39, v44, v39
	v_cvt_pk_bf16_f32 v32, v32, v33
	v_cvt_pk_bf16_f32 v34, v34, v35
	v_cvt_pk_bf16_f32 v36, v36, v37
	v_cvt_pk_bf16_f32 v38, v38, v39
	ds_write_b16 v240, v32 offset:6912
	ds_write_b16_d16_hi v240, v32 offset:7056
	ds_write_b16 v240, v34 offset:7200
	ds_write_b16_d16_hi v240, v34 offset:7344
	ds_write_b16 v240, v36 offset:7488
	ds_write_b16_d16_hi v240, v36 offset:7632
	ds_write_b16 v240, v38 offset:7776
	ds_write_b16_d16_hi v240, v38 offset:7920
	v_mul_f32_e32 v32, v41, v215
	v_mul_f32_e32 v33, v41, v216
	v_mul_f32_e32 v34, v41, v217
	v_mul_f32_e32 v35, v41, v218
	v_mul_f32_e32 v36, v41, v219
	v_mul_f32_e32 v37, v41, v222
	v_mul_f32_e32 v38, v41, v223
	v_mul_f32_e32 v39, v41, v140
	v_fmac_f32_e32 v32, v40, v214
	v_fmac_f32_e32 v33, v40, v215
	v_fmac_f32_e32 v34, v40, v216
	v_fmac_f32_e32 v35, v40, v217
	v_fmac_f32_e32 v36, v40, v218
	v_fmac_f32_e32 v37, v40, v219
	v_fmac_f32_e32 v38, v40, v222
	v_fmac_f32_e32 v39, v40, v223
	v_fmac_f32_e32 v32, v42, v216
	v_fmac_f32_e32 v33, v42, v217
	v_fmac_f32_e32 v34, v42, v218
	v_fmac_f32_e32 v35, v42, v219
	v_fmac_f32_e32 v36, v42, v222
	v_fmac_f32_e32 v37, v42, v223
	v_fmac_f32_e32 v38, v42, v140
	v_fmac_f32_e32 v39, v42, v141
	v_fmac_f32_e32 v32, v43, v217
	v_fmac_f32_e32 v33, v43, v218
	v_fmac_f32_e32 v34, v43, v219
	v_fmac_f32_e32 v35, v43, v222
	v_fmac_f32_e32 v36, v43, v223
	v_fmac_f32_e32 v37, v43, v140
	v_fmac_f32_e32 v38, v43, v141
	v_fmac_f32_e32 v39, v43, v232
	v_add_f32_e32 v32, v44, v32
	v_add_f32_e32 v33, v44, v33
	v_add_f32_e32 v34, v44, v34
	v_add_f32_e32 v35, v44, v35
	v_add_f32_e32 v36, v44, v36
	v_add_f32_e32 v37, v44, v37
	v_add_f32_e32 v38, v44, v38
	v_add_f32_e32 v39, v44, v39
	v_cvt_pk_bf16_f32 v32, v32, v33
	v_cvt_pk_bf16_f32 v34, v34, v35
	v_cvt_pk_bf16_f32 v36, v36, v37
	v_cvt_pk_bf16_f32 v38, v38, v39
	ds_write_b16 v240, v32 offset:8064
	ds_write_b16_d16_hi v240, v32 offset:8208
	ds_write_b16 v240, v34 offset:8352
	ds_write_b16_d16_hi v240, v34 offset:8496
	ds_write_b16 v240, v36 offset:8640
	ds_write_b16_d16_hi v240, v36 offset:8784
	ds_write_b16 v240, v38 offset:8928
	ds_write_b16_d16_hi v240, v38 offset:9072
	v_mov_b32_e32 v248, 0xbfb8aa3b
	v_mov_b32_e32 v249, 0xbfb8aa3b
	s_waitcnt vmcnt(16)
	s_mov_b32 s8, 0x800000
	s_mov_b32 s9, 0x3f317217
	s_mov_b32 s14, 0x7f800000
	v_mul_f32_e32 v32, 0xbfb8aa3b, v45
	v_exp_f32_e32 v32, v32
	s_nop 0
	v_add_f32_e32 v33, 1.0, v32
	v_cmp_gt_f32_e32 vcc, s8, v33
	s_nop 1
	v_cndmask_b32_e64 v34, 0, 32, vcc
	v_ldexp_f32 v34, v33, v34
	v_log_f32_e32 v34, v34
	v_cndmask_b32_e32 v36, 0, v226, vcc
	v_cmp_eq_f32_e32 vcc, 1.0, v33
	v_mul_f32_e32 v35, 0x3f317217, v34
	v_fma_f32 v35, v34, s9, -v35
	v_fmac_f32_e32 v35, 0x3377d1cf, v34
	v_fmac_f32_e32 v35, 0x3f317217, v34
	v_cmp_lt_f32_e64 s[10:11], |v34|, s14
	s_nop 1
	v_cndmask_b32_e64 v34, v34, v35, s[10:11]
	v_add_f32_e32 v35, -1.0, v33
	v_rcp_f32_e32 v35, v35
	v_sub_f32_e32 v34, v34, v36
	v_mul_f32_e32 v34, v32, v34
	v_mul_f32_e32 v34, v34, v35
	v_cndmask_b32_e32 v32, v34, v32, vcc
	v_mul_f32_e32 v246, 0xc138aa3b, v32
	v_mov_b32_e32 v247, v246
	v_mov_b32_e32 v242, v46
	v_mov_b32_e32 v243, v46
	v_mov_b32_e32 v244, v47
	v_mov_b32_e32 v245, v47
	v_mov_b32_e32 v250, 0
	v_mov_b32_e32 v232, 1.0
	s_waitcnt vmcnt(0)
	ds_read_b128 v[32:35], v236 offset:0
	ds_read_b128 v[36:39], v236 offset:64
	s_waitcnt lgkmcnt(0)
	v_mfma_f32_16x16x32_bf16 v[0:3], v[32:35], v[80:83], 0
	v_mfma_f32_16x16x32_bf16 v[4:7], v[32:35], v[88:91], 0
	v_mfma_f32_16x16x32_bf16 v[8:11], v[32:35], v[96:99], 0
	v_mfma_f32_16x16x32_bf16 v[12:15], v[32:35], v[104:107], 0
	v_mfma_f32_16x16x32_bf16 v[16:19], v[32:35], v[112:115], 0
	v_mfma_f32_16x16x32_bf16 v[20:23], v[32:35], v[120:123], 0
	v_mfma_f32_16x16x32_bf16 v[24:27], v[32:35], v[128:131], 0
	v_mfma_f32_16x16x32_bf16 v[28:31], v[32:35], v[136:139], 0
	v_mfma_f32_16x16x32_bf16 v[0:3], v[36:39], v[84:87], v[0:3]
	v_mfma_f32_16x16x32_bf16 v[4:7], v[36:39], v[92:95], v[4:7]
	v_mfma_f32_16x16x32_bf16 v[8:11], v[36:39], v[100:103], v[8:11]
	v_mfma_f32_16x16x32_bf16 v[12:15], v[36:39], v[108:111], v[12:15]
	v_mfma_f32_16x16x32_bf16 v[16:19], v[36:39], v[148:151], v[16:19]
	v_mfma_f32_16x16x32_bf16 v[20:23], v[36:39], v[124:127], v[20:23]
	v_mfma_f32_16x16x32_bf16 v[24:27], v[36:39], v[132:135], v[24:27]
	v_mfma_f32_16x16x32_bf16 v[28:31], v[36:39], v[228:231], v[28:31]
	s_nop 3
	ds_write2_b32 v237, v0, v4 offset0:0 offset1:16
	ds_write2_b32 v237, v8, v12 offset0:32 offset1:48
	ds_write2_b32 v237, v1, v5 offset0:64 offset1:80
	ds_write2_b32 v237, v9, v13 offset0:96 offset1:112
	ds_write2_b32 v237, v2, v6 offset0:128 offset1:144
	ds_write2_b32 v237, v10, v14 offset0:160 offset1:176
	ds_write2_b32 v237, v3, v7 offset0:192 offset1:208
	ds_write2_b32 v237, v11, v15 offset0:224 offset1:240
	ds_write2_b32 v238, v16, v20 offset0:0 offset1:16
	ds_write2_b32 v238, v24, v28 offset0:32 offset1:48
	ds_write2_b32 v238, v17, v21 offset0:64 offset1:80
	ds_write2_b32 v238, v25, v29 offset0:96 offset1:112
	ds_write2_b32 v238, v18, v22 offset0:128 offset1:144
	ds_write2_b32 v238, v26, v30 offset0:160 offset1:176
	ds_write2_b32 v238, v19, v23 offset0:192 offset1:208
	ds_write2_b32 v238, v27, v31 offset0:224 offset1:240
	s_waitcnt lgkmcnt(0)
; #define WAVE_SYNC() asm volatile("s_waitcnt lgkmcnt(0)" ::: "memory")
; __device__ __forceinline__ float sigmoid_f(float x) { return rcpf_(1.f + __expf(-x)); }
; template <bool FINAL, int D>
; __device__ __forceinline__ void rg_dir(PREF p, int l, int h, int ch, int sidx, int rowbase  , LAS bf16_t* sXc, LAS float* stg, int lane) {
;     ...
;             for (int j = 0; j < 4; ++j) { const int o = ((lane >> 4) * 4 + j) * 64 + nt * 16 + (lane & 15); stg[o] = ar[nt][j]; stg[1024 + o] = ai[nt][j]; }
;         WAVE_SYNC();
;         float av[16], iv[16];
; #pragma unroll
;         for (int ti = 0; ti < 16; ++ti) { const int tk = D ? 15 - ti : ti;
;             const float zr = stg[tk * 64 + lane] + ba, zi = stg[1024 + tk * 64 + lane] + bi;
;             const float r = sigmoid_f(zr), ig = sigmoid_f(zi);
;             const float a = __builtin_amdgcn_exp2f(r * sp8);
;             const float xc = bf2f(sXc[(mt * 16 + tk) * 72 + lane]);
;             av[ti] = a; iv[ti] = __builtin_amdgcn_sqrtf(fmaxf(1.f - a * a, 0.f)) * ig * xc;
	ds_read2st64_b32 v[0:1], v239 offset0:36 offset1:37
	ds_read2st64_b32 v[2:3], v239 offset0:38 offset1:39
	ds_read2st64_b32 v[4:5], v239 offset0:40 offset1:41
	ds_read2st64_b32 v[6:7], v239 offset0:42 offset1:43
	ds_read2st64_b32 v[8:9], v239 offset0:44 offset1:45
	ds_read2st64_b32 v[10:11], v239 offset0:46 offset1:47
	ds_read2st64_b32 v[12:13], v239 offset0:48 offset1:49
	ds_read2st64_b32 v[14:15], v239 offset0:50 offset1:51
	ds_read2st64_b32 v[16:17], v239 offset0:52 offset1:53
	ds_read2st64_b32 v[18:19], v239 offset0:54 offset1:55
	ds_read2st64_b32 v[20:21], v239 offset0:56 offset1:57
	ds_read2st64_b32 v[22:23], v239 offset0:58 offset1:59
	ds_read2st64_b32 v[24:25], v239 offset0:60 offset1:61
	ds_read2st64_b32 v[26:27], v239 offset0:62 offset1:63
	ds_read2st64_b32 v[28:29], v239 offset0:64 offset1:65
	ds_read2st64_b32 v[30:31], v239 offset0:66 offset1:67
	ds_read_u16 v48, v240 offset:0
	ds_read_u16 v49, v240 offset:144
	ds_read_u16 v50, v240 offset:288
	ds_read_u16 v51, v240 offset:432
	ds_read_u16 v52, v240 offset:576
	ds_read_u16 v53, v240 offset:720
	ds_read_u16 v54, v240 offset:864
	ds_read_u16 v55, v240 offset:1008
	ds_read_u16 v56, v240 offset:1152
	ds_read_u16 v57, v240 offset:1296
	ds_read_u16 v58, v240 offset:1440
	ds_read_u16 v59, v240 offset:1584
	ds_read_u16 v60, v240 offset:1728
	ds_read_u16 v61, v240 offset:1872
	ds_read_u16 v62, v240 offset:2016
	ds_read_u16 v63, v240 offset:2160
	s_waitcnt lgkmcnt(0)
	v_pk_add_f32 v[0:1], v[242:243], v[0:1]
	v_pk_add_f32 v[2:3], v[242:243], v[2:3]
	v_pk_add_f32 v[4:5], v[242:243], v[4:5]
	v_pk_add_f32 v[6:7], v[242:243], v[6:7]
	v_pk_add_f32 v[8:9], v[242:243], v[8:9]
	v_pk_add_f32 v[10:11], v[242:243], v[10:11]
	v_pk_add_f32 v[12:13], v[242:243], v[12:13]
	v_pk_add_f32 v[14:15], v[242:243], v[14:15]
	v_pk_add_f32 v[16:17], v[244:245], v[16:17]
	v_pk_add_f32 v[18:19], v[244:245], v[18:19]
	v_pk_add_f32 v[20:21], v[244:245], v[20:21]
	v_pk_add_f32 v[22:23], v[244:245], v[22:23]
	v_pk_add_f32 v[24:25], v[244:245], v[24:25]
	v_pk_add_f32 v[26:27], v[244:245], v[26:27]
	v_pk_add_f32 v[28:29], v[244:245], v[28:29]
	v_pk_add_f32 v[30:31], v[244:245], v[30:31]
	v_pk_mul_f32 v[0:1], v[248:249], v[0:1]
	v_pk_mul_f32 v[2:3], v[248:249], v[2:3]
	v_pk_mul_f32 v[4:5], v[248:249], v[4:5]
	v_pk_mul_f32 v[6:7], v[248:249], v[6:7]
	v_pk_mul_f32 v[8:9], v[248:249], v[8:9]
	v_pk_mul_f32 v[10:11], v[248:249], v[10:11]
	v_pk_mul_f32 v[12:13], v[248:249], v[12:13]
	v_pk_mul_f32 v[14:15], v[248:249], v[14:15]
	v_pk_mul_f32 v[16:17], v[248:249], v[16:17]
	v_pk_mul_f32 v[18:19], v[248:249], v[18:19]
	v_pk_mul_f32 v[20:21], v[248:249], v[20:21]
	v_pk_mul_f32 v[22:23], v[248:249], v[22:23]
	v_pk_mul_f32 v[24:25], v[248:249], v[24:25]
	v_pk_mul_f32 v[26:27], v[248:249], v[26:27]
	v_pk_mul_f32 v[28:29], v[248:249], v[28:29]
	v_pk_mul_f32 v[30:31], v[248:249], v[30:31]
	v_exp_f32_e32 v0, v0
	v_exp_f32_e32 v1, v1
	v_exp_f32_e32 v2, v2
	v_exp_f32_e32 v3, v3
	v_exp_f32_e32 v4, v4
	v_exp_f32_e32 v5, v5
	v_exp_f32_e32 v6, v6
	v_exp_f32_e32 v7, v7
	v_exp_f32_e32 v8, v8
	v_exp_f32_e32 v9, v9
	v_exp_f32_e32 v10, v10
	v_exp_f32_e32 v11, v11
	v_exp_f32_e32 v12, v12
	v_exp_f32_e32 v13, v13
	v_exp_f32_e32 v14, v14
	v_exp_f32_e32 v15, v15
	v_exp_f32_e32 v16, v16
	v_exp_f32_e32 v17, v17
	v_exp_f32_e32 v18, v18
	v_exp_f32_e32 v19, v19
	v_exp_f32_e32 v20, v20
	v_exp_f32_e32 v21, v21
	v_exp_f32_e32 v22, v22
	v_exp_f32_e32 v23, v23
	v_exp_f32_e32 v24, v24
	v_exp_f32_e32 v25, v25
	v_exp_f32_e32 v26, v26
	v_exp_f32_e32 v27, v27
	v_exp_f32_e32 v28, v28
	v_exp_f32_e32 v29, v29
	v_exp_f32_e32 v30, v30
	v_exp_f32_e32 v31, v31
	v_pk_add_f32 v[0:1], v[0:1], 1.0 op_sel_hi:[1,0]
	v_pk_add_f32 v[2:3], v[2:3], 1.0 op_sel_hi:[1,0]
	v_pk_add_f32 v[4:5], v[4:5], 1.0 op_sel_hi:[1,0]
	v_pk_add_f32 v[6:7], v[6:7], 1.0 op_sel_hi:[1,0]
	v_pk_add_f32 v[8:9], v[8:9], 1.0 op_sel_hi:[1,0]
	v_pk_add_f32 v[10:11], v[10:11], 1.0 op_sel_hi:[1,0]
	v_pk_add_f32 v[12:13], v[12:13], 1.0 op_sel_hi:[1,0]
	v_pk_add_f32 v[14:15], v[14:15], 1.0 op_sel_hi:[1,0]
	v_pk_add_f32 v[16:17], v[16:17], 1.0 op_sel_hi:[1,0]
	v_pk_add_f32 v[18:19], v[18:19], 1.0 op_sel_hi:[1,0]
	v_pk_add_f32 v[20:21], v[20:21], 1.0 op_sel_hi:[1,0]
	v_pk_add_f32 v[22:23], v[22:23], 1.0 op_sel_hi:[1,0]
	v_pk_add_f32 v[24:25], v[24:25], 1.0 op_sel_hi:[1,0]
	v_pk_add_f32 v[26:27], v[26:27], 1.0 op_sel_hi:[1,0]
	v_pk_add_f32 v[28:29], v[28:29], 1.0 op_sel_hi:[1,0]
	v_pk_add_f32 v[30:31], v[30:31], 1.0 op_sel_hi:[1,0]
	v_rcp_f32_e32 v0, v0
	v_rcp_f32_e32 v1, v1
	v_rcp_f32_e32 v2, v2
	v_rcp_f32_e32 v3, v3
	v_rcp_f32_e32 v4, v4
	v_rcp_f32_e32 v5, v5
	v_rcp_f32_e32 v6, v6
	v_rcp_f32_e32 v7, v7
	v_rcp_f32_e32 v8, v8
	v_rcp_f32_e32 v9, v9
	v_rcp_f32_e32 v10, v10
	v_rcp_f32_e32 v11, v11
	v_rcp_f32_e32 v12, v12
	v_rcp_f32_e32 v13, v13
	v_rcp_f32_e32 v14, v14
	v_rcp_f32_e32 v15, v15
	v_rcp_f32_e32 v16, v16
	v_rcp_f32_e32 v17, v17
	v_rcp_f32_e32 v18, v18
	v_rcp_f32_e32 v19, v19
	v_rcp_f32_e32 v20, v20
	v_rcp_f32_e32 v21, v21
	v_rcp_f32_e32 v22, v22
	v_rcp_f32_e32 v23, v23
	v_rcp_f32_e32 v24, v24
	v_rcp_f32_e32 v25, v25
	v_rcp_f32_e32 v26, v26
	v_rcp_f32_e32 v27, v27
	v_rcp_f32_e32 v28, v28
	v_rcp_f32_e32 v29, v29
	v_rcp_f32_e32 v30, v30
	v_rcp_f32_e32 v31, v31
	v_pk_mul_f32 v[0:1], v[246:247], v[0:1]
	v_pk_mul_f32 v[2:3], v[246:247], v[2:3]
	v_pk_mul_f32 v[4:5], v[246:247], v[4:5]
	v_pk_mul_f32 v[6:7], v[246:247], v[6:7]
	v_pk_mul_f32 v[8:9], v[246:247], v[8:9]
	v_pk_mul_f32 v[10:11], v[246:247], v[10:11]
	v_pk_mul_f32 v[12:13], v[246:247], v[12:13]
	v_pk_mul_f32 v[14:15], v[246:247], v[14:15]
	v_lshlrev_b32_e32 v48, 16, v48
	v_lshlrev_b32_e32 v49, 16, v49
	v_lshlrev_b32_e32 v50, 16, v50
	v_lshlrev_b32_e32 v51, 16, v51
; #define LAS __attribute__((address_space(3)))
; #define WAVE_SYNC() asm volatile("s_waitcnt lgkmcnt(0)" ::: "memory")
; __device__ __forceinline__ float sigmoid_f(float x) { return rcpf_(1.f + __expf(-x)); }
; __device__ __forceinline__ float gelu_tanh_f(float x) { const float y = 0.7978845608028654f * (x + 0.044715f * x * x * x); return x * sigmoid_f(2.f * y); }
; __device__ __forceinline__ f32x4 mfma16(bf16x8 a, bf16x8 b, f32x4 c) { return __builtin_amdgcn_mfma_f32_16x16x32_bf16(a, b, c, 0, 0, 0); }
; template <bool FINAL, int D>
; __device__ __forceinline__ void rg_dir(PREF p, int l, int h, int ch, int sidx, int rowbase  , LAS bf16_t* sXc, LAS float* stg, int lane) {
;     ...
;         const bf16x8 A0 = *(const LAS bf16x8*)(sXc + (mt * 16 + (lane & 15)) * 72 + (lane >> 4) * 8), A1 = *(const LAS bf16x8*)(sXc + (mt * 16 + (lane & 15)) * 72 + 32 + (lane >> 4) * 8);
;         f32x4 ar[4], ai[4];
; #pragma unroll
;         for (int nt = 0; nt < 4; ++nt) { const f32x4 z = {0.f, 0.f, 0.f, 0.f};
;             ar[nt] = mfma16(A0, Br[nt][0], z); ar[nt] = mfma16(A1, Br[nt][1], ar[nt]); ai[nt] = mfma16(A0, Bi[nt][0], z); ai[nt] = mfma16(A1, Bi[nt][1], ai[nt]); }
;         WAVE_SYNC();
; #pragma unroll
;         for (int nt = 0; nt < 4; ++nt)
; #pragma unroll
;             for (int j = 0; j < 4; ++j) { const int o = ((lane >> 4) * 4 + j) * 64 + nt * 16 + (lane & 15); stg[o] = ar[nt][j]; stg[1024 + o] = ai[nt][j]; }
;         WAVE_SYNC();
;     ...
;         for (int ti = 0; ti < 16; ++ti) { const int tk = D ? 15 - ti : ti;
;             const float zr = stg[tk * 64 + lane] + ba, zi = stg[1024 + tk * 64 + lane] + bi;
;             const float r = sigmoid_f(zr), ig = sigmoid_f(zi);
;             const float a = __builtin_amdgcn_exp2f(r * sp8);
;             const float xc = bf2f(sXc[(mt * 16 + tk) * 72 + lane]);
;             av[ti] = a; iv[ti] = __builtin_amdgcn_sqrtf(fmaxf(1.f - a * a, 0.f)) * ig * xc;
;             if (FINAL && D == 1) grv[ti] = gelu_tanh_f(grv[ti]);
;         }
; #pragma unroll
;         for (int ti = 0; ti < 16; ++ti) { const int tk = D ? 15 - ti : ti;
;             hc = av[ti] * hc + iv[ti]; Ap *= av[ti];
	v_lshlrev_b32_e32 v52, 16, v52
	v_lshlrev_b32_e32 v53, 16, v53
	v_lshlrev_b32_e32 v54, 16, v54
	v_lshlrev_b32_e32 v55, 16, v55
	v_lshlrev_b32_e32 v56, 16, v56
	v_lshlrev_b32_e32 v57, 16, v57
	v_lshlrev_b32_e32 v58, 16, v58
	v_lshlrev_b32_e32 v59, 16, v59
	v_lshlrev_b32_e32 v60, 16, v60
	v_lshlrev_b32_e32 v61, 16, v61
	v_lshlrev_b32_e32 v62, 16, v62
	v_lshlrev_b32_e32 v63, 16, v63
	v_exp_f32_e32 v0, v0
	v_exp_f32_e32 v1, v1
	v_exp_f32_e32 v2, v2
	v_exp_f32_e32 v3, v3
	v_exp_f32_e32 v4, v4
	v_exp_f32_e32 v5, v5
	v_exp_f32_e32 v6, v6
	v_exp_f32_e32 v7, v7
	v_exp_f32_e32 v8, v8
	v_exp_f32_e32 v9, v9
	v_exp_f32_e32 v10, v10
	v_exp_f32_e32 v11, v11
	v_exp_f32_e32 v12, v12
	v_exp_f32_e32 v13, v13
	v_exp_f32_e32 v14, v14
	v_exp_f32_e32 v15, v15
	v_fma_f32 v32, -v0, v0, 1.0
	v_fma_f32 v33, -v1, v1, 1.0
	v_fma_f32 v34, -v2, v2, 1.0
	v_fma_f32 v35, -v3, v3, 1.0
	v_fma_f32 v36, -v4, v4, 1.0
	v_fma_f32 v37, -v5, v5, 1.0
	v_fma_f32 v38, -v6, v6, 1.0
	v_fma_f32 v39, -v7, v7, 1.0
	v_fma_f32 v40, -v8, v8, 1.0
	v_fma_f32 v41, -v9, v9, 1.0
	v_fma_f32 v42, -v10, v10, 1.0
	v_fma_f32 v43, -v11, v11, 1.0
	v_fma_f32 v44, -v12, v12, 1.0
	v_fma_f32 v45, -v13, v13, 1.0
	v_fma_f32 v46, -v14, v14, 1.0
	v_fma_f32 v47, -v15, v15, 1.0
	v_max_f32_e32 v32, 0, v32
	v_max_f32_e32 v33, 0, v33
	v_max_f32_e32 v34, 0, v34
	v_max_f32_e32 v35, 0, v35
	v_max_f32_e32 v36, 0, v36
	v_max_f32_e32 v37, 0, v37
	v_max_f32_e32 v38, 0, v38
	v_max_f32_e32 v39, 0, v39
	v_max_f32_e32 v40, 0, v40
	v_max_f32_e32 v41, 0, v41
	v_max_f32_e32 v42, 0, v42
	v_max_f32_e32 v43, 0, v43
	v_max_f32_e32 v44, 0, v44
	v_max_f32_e32 v45, 0, v45
	v_max_f32_e32 v46, 0, v46
	v_max_f32_e32 v47, 0, v47
	v_sqrt_f32_e32 v32, v32
	v_sqrt_f32_e32 v33, v33
	v_sqrt_f32_e32 v34, v34
	v_sqrt_f32_e32 v35, v35
	v_sqrt_f32_e32 v36, v36
	v_sqrt_f32_e32 v37, v37
	v_sqrt_f32_e32 v38, v38
	v_sqrt_f32_e32 v39, v39
	v_sqrt_f32_e32 v40, v40
	v_sqrt_f32_e32 v41, v41
	v_sqrt_f32_e32 v42, v42
	v_sqrt_f32_e32 v43, v43
	v_sqrt_f32_e32 v44, v44
	v_sqrt_f32_e32 v45, v45
	v_sqrt_f32_e32 v46, v46
	v_sqrt_f32_e32 v47, v47
	s_nop 0
	v_pk_mul_f32 v[16:17], v[16:17], v[32:33]
	v_pk_mul_f32 v[18:19], v[18:19], v[34:35]
	v_pk_mul_f32 v[20:21], v[20:21], v[36:37]
	v_pk_mul_f32 v[22:23], v[22:23], v[38:39]
	v_pk_mul_f32 v[24:25], v[24:25], v[40:41]
	v_pk_mul_f32 v[26:27], v[26:27], v[42:43]
	v_pk_mul_f32 v[28:29], v[28:29], v[44:45]
	v_pk_mul_f32 v[30:31], v[30:31], v[46:47]
	v_pk_mul_f32 v[16:17], v[16:17], v[48:49]
	v_pk_mul_f32 v[18:19], v[18:19], v[50:51]
	v_pk_mul_f32 v[20:21], v[20:21], v[52:53]
	v_pk_mul_f32 v[22:23], v[22:23], v[54:55]
	v_pk_mul_f32 v[24:25], v[24:25], v[56:57]
	v_pk_mul_f32 v[26:27], v[26:27], v[58:59]
	v_pk_mul_f32 v[28:29], v[28:29], v[60:61]
	v_pk_mul_f32 v[30:31], v[30:31], v[62:63]
	v_fma_f32 v32, v0, v250, v16
	v_mul_f32_e32 v232, v232, v0
	v_fma_f32 v250, v1, v32, v17
	v_mul_f32_e32 v232, v232, v1
	v_fma_f32 v32, v2, v250, v18
	v_mul_f32_e32 v232, v232, v2
	v_fma_f32 v250, v3, v32, v19
	v_mul_f32_e32 v232, v232, v3
	v_fma_f32 v32, v4, v250, v20
	v_mul_f32_e32 v232, v232, v4
	v_fma_f32 v250, v5, v32, v21
	v_mul_f32_e32 v232, v232, v5
	v_fma_f32 v32, v6, v250, v22
	v_mul_f32_e32 v232, v232, v6
	v_fma_f32 v250, v7, v32, v23
	v_mul_f32_e32 v232, v232, v7
	v_fma_f32 v32, v8, v250, v24
	v_mul_f32_e32 v232, v232, v8
	v_fma_f32 v250, v9, v32, v25
	v_mul_f32_e32 v232, v232, v9
	v_fma_f32 v32, v10, v250, v26
	v_mul_f32_e32 v232, v232, v10
	v_fma_f32 v250, v11, v32, v27
	v_mul_f32_e32 v232, v232, v11
	v_fma_f32 v32, v12, v250, v28
	v_mul_f32_e32 v232, v232, v12
	v_fma_f32 v250, v13, v32, v29
	v_mul_f32_e32 v232, v232, v13
	v_fma_f32 v32, v14, v250, v30
	v_mul_f32_e32 v232, v232, v14
	v_fma_f32 v250, v15, v32, v31
	v_mul_f32_e32 v232, v232, v15
	ds_read_b128 v[32:35], v236 offset:2304
	ds_read_b128 v[36:39], v236 offset:2368
	s_waitcnt lgkmcnt(0)
	v_mfma_f32_16x16x32_bf16 v[0:3], v[32:35], v[80:83], 0
	v_mfma_f32_16x16x32_bf16 v[4:7], v[32:35], v[88:91], 0
	v_mfma_f32_16x16x32_bf16 v[8:11], v[32:35], v[96:99], 0
	v_mfma_f32_16x16x32_bf16 v[12:15], v[32:35], v[104:107], 0
	v_mfma_f32_16x16x32_bf16 v[16:19], v[32:35], v[112:115], 0
	v_mfma_f32_16x16x32_bf16 v[20:23], v[32:35], v[120:123], 0
	v_mfma_f32_16x16x32_bf16 v[24:27], v[32:35], v[128:131], 0
	v_mfma_f32_16x16x32_bf16 v[28:31], v[32:35], v[136:139], 0
	v_mfma_f32_16x16x32_bf16 v[0:3], v[36:39], v[84:87], v[0:3]
	v_mfma_f32_16x16x32_bf16 v[4:7], v[36:39], v[92:95], v[4:7]
	v_mfma_f32_16x16x32_bf16 v[8:11], v[36:39], v[100:103], v[8:11]
	v_mfma_f32_16x16x32_bf16 v[12:15], v[36:39], v[108:111], v[12:15]
	v_mfma_f32_16x16x32_bf16 v[16:19], v[36:39], v[148:151], v[16:19]
	v_mfma_f32_16x16x32_bf16 v[20:23], v[36:39], v[124:127], v[20:23]
	v_mfma_f32_16x16x32_bf16 v[24:27], v[36:39], v[132:135], v[24:27]
	v_mfma_f32_16x16x32_bf16 v[28:31], v[36:39], v[228:231], v[28:31]
	s_nop 3
	ds_write2_b32 v237, v0, v4 offset0:0 offset1:16
	ds_write2_b32 v237, v8, v12 offset0:32 offset1:48
	ds_write2_b32 v237, v1, v5 offset0:64 offset1:80
	ds_write2_b32 v237, v9, v13 offset0:96 offset1:112
	ds_write2_b32 v237, v2, v6 offset0:128 offset1:144
	ds_write2_b32 v237, v10, v14 offset0:160 offset1:176
	ds_write2_b32 v237, v3, v7 offset0:192 offset1:208
	ds_write2_b32 v237, v11, v15 offset0:224 offset1:240
	ds_write2_b32 v238, v16, v20 offset0:0 offset1:16
	ds_write2_b32 v238, v24, v28 offset0:32 offset1:48
	ds_write2_b32 v238, v17, v21 offset0:64 offset1:80
	ds_write2_b32 v238, v25, v29 offset0:96 offset1:112
	ds_write2_b32 v238, v18, v22 offset0:128 offset1:144
	ds_write2_b32 v238, v26, v30 offset0:160 offset1:176
	ds_write2_b32 v238, v19, v23 offset0:192 offset1:208
	ds_write2_b32 v238, v27, v31 offset0:224 offset1:240
	s_waitcnt lgkmcnt(0)
; __device__ __forceinline__ float sigmoid_f(float x) { return rcpf_(1.f + __expf(-x)); }
; template <bool FINAL, int D>
; __device__ __forceinline__ void rg_dir(PREF p, int l, int h, int ch, int sidx, int rowbase  , LAS bf16_t* sXc, LAS float* stg, int lane) {
;     ...
;         float av[16], iv[16];
; #pragma unroll
;         for (int ti = 0; ti < 16; ++ti) { const int tk = D ? 15 - ti : ti;
;             const float zr = stg[tk * 64 + lane] + ba, zi = stg[1024 + tk * 64 + lane] + bi;
;             const float r = sigmoid_f(zr), ig = sigmoid_f(zi);
;             const float a = __builtin_amdgcn_exp2f(r * sp8);
;             const float xc = bf2f(sXc[(mt * 16 + tk) * 72 + lane]);
;             av[ti] = a; iv[ti] = __builtin_amdgcn_sqrtf(fmaxf(1.f - a * a, 0.f)) * ig * xc;
	ds_read2st64_b32 v[0:1], v239 offset0:36 offset1:37
	ds_read2st64_b32 v[2:3], v239 offset0:38 offset1:39
	ds_read2st64_b32 v[4:5], v239 offset0:40 offset1:41
	ds_read2st64_b32 v[6:7], v239 offset0:42 offset1:43
	ds_read2st64_b32 v[8:9], v239 offset0:44 offset1:45
	ds_read2st64_b32 v[10:11], v239 offset0:46 offset1:47
	ds_read2st64_b32 v[12:13], v239 offset0:48 offset1:49
	ds_read2st64_b32 v[14:15], v239 offset0:50 offset1:51
	ds_read2st64_b32 v[16:17], v239 offset0:52 offset1:53
	ds_read2st64_b32 v[18:19], v239 offset0:54 offset1:55
	ds_read2st64_b32 v[20:21], v239 offset0:56 offset1:57
	ds_read2st64_b32 v[22:23], v239 offset0:58 offset1:59
	ds_read2st64_b32 v[24:25], v239 offset0:60 offset1:61
	ds_read2st64_b32 v[26:27], v239 offset0:62 offset1:63
	ds_read2st64_b32 v[28:29], v239 offset0:64 offset1:65
	ds_read2st64_b32 v[30:31], v239 offset0:66 offset1:67
	ds_read_u16 v48, v240 offset:2304
	ds_read_u16 v49, v240 offset:2448
	ds_read_u16 v50, v240 offset:2592
	ds_read_u16 v51, v240 offset:2736
	ds_read_u16 v52, v240 offset:2880
	ds_read_u16 v53, v240 offset:3024
	ds_read_u16 v54, v240 offset:3168
	ds_read_u16 v55, v240 offset:3312
	ds_read_u16 v56, v240 offset:3456
	ds_read_u16 v57, v240 offset:3600
	ds_read_u16 v58, v240 offset:3744
	ds_read_u16 v59, v240 offset:3888
	ds_read_u16 v60, v240 offset:4032
	ds_read_u16 v61, v240 offset:4176
	ds_read_u16 v62, v240 offset:4320
	ds_read_u16 v63, v240 offset:4464
	s_waitcnt lgkmcnt(0)
	v_pk_add_f32 v[0:1], v[242:243], v[0:1]
	v_pk_add_f32 v[2:3], v[242:243], v[2:3]
	v_pk_add_f32 v[4:5], v[242:243], v[4:5]
	v_pk_add_f32 v[6:7], v[242:243], v[6:7]
	v_pk_add_f32 v[8:9], v[242:243], v[8:9]
	v_pk_add_f32 v[10:11], v[242:243], v[10:11]
	v_pk_add_f32 v[12:13], v[242:243], v[12:13]
	v_pk_add_f32 v[14:15], v[242:243], v[14:15]
	v_pk_add_f32 v[16:17], v[244:245], v[16:17]
	v_pk_add_f32 v[18:19], v[244:245], v[18:19]
	v_pk_add_f32 v[20:21], v[244:245], v[20:21]
	v_pk_add_f32 v[22:23], v[244:245], v[22:23]
	v_pk_add_f32 v[24:25], v[244:245], v[24:25]
	v_pk_add_f32 v[26:27], v[244:245], v[26:27]
	v_pk_add_f32 v[28:29], v[244:245], v[28:29]
	v_pk_add_f32 v[30:31], v[244:245], v[30:31]
	v_pk_mul_f32 v[0:1], v[248:249], v[0:1]
	v_pk_mul_f32 v[2:3], v[248:249], v[2:3]
	v_pk_mul_f32 v[4:5], v[248:249], v[4:5]
	v_pk_mul_f32 v[6:7], v[248:249], v[6:7]
	v_pk_mul_f32 v[8:9], v[248:249], v[8:9]
	v_pk_mul_f32 v[10:11], v[248:249], v[10:11]
	v_pk_mul_f32 v[12:13], v[248:249], v[12:13]
	v_pk_mul_f32 v[14:15], v[248:249], v[14:15]
	v_pk_mul_f32 v[16:17], v[248:249], v[16:17]
	v_pk_mul_f32 v[18:19], v[248:249], v[18:19]
	v_pk_mul_f32 v[20:21], v[248:249], v[20:21]
	v_pk_mul_f32 v[22:23], v[248:249], v[22:23]
	v_pk_mul_f32 v[24:25], v[248:249], v[24:25]
	v_pk_mul_f32 v[26:27], v[248:249], v[26:27]
	v_pk_mul_f32 v[28:29], v[248:249], v[28:29]
	v_pk_mul_f32 v[30:31], v[248:249], v[30:31]
	v_exp_f32_e32 v0, v0
	v_exp_f32_e32 v1, v1
	v_exp_f32_e32 v2, v2
	v_exp_f32_e32 v3, v3
	v_exp_f32_e32 v4, v4
	v_exp_f32_e32 v5, v5
	v_exp_f32_e32 v6, v6
	v_exp_f32_e32 v7, v7
	v_exp_f32_e32 v8, v8
	v_exp_f32_e32 v9, v9
	v_exp_f32_e32 v10, v10
	v_exp_f32_e32 v11, v11
	v_exp_f32_e32 v12, v12
	v_exp_f32_e32 v13, v13
	v_exp_f32_e32 v14, v14
	v_exp_f32_e32 v15, v15
	v_exp_f32_e32 v16, v16
	v_exp_f32_e32 v17, v17
	v_exp_f32_e32 v18, v18
	v_exp_f32_e32 v19, v19
	v_exp_f32_e32 v20, v20
	v_exp_f32_e32 v21, v21
	v_exp_f32_e32 v22, v22
	v_exp_f32_e32 v23, v23
	v_exp_f32_e32 v24, v24
	v_exp_f32_e32 v25, v25
	v_exp_f32_e32 v26, v26
	v_exp_f32_e32 v27, v27
	v_exp_f32_e32 v28, v28
	v_exp_f32_e32 v29, v29
	v_exp_f32_e32 v30, v30
	v_exp_f32_e32 v31, v31
	v_pk_add_f32 v[0:1], v[0:1], 1.0 op_sel_hi:[1,0]
	v_pk_add_f32 v[2:3], v[2:3], 1.0 op_sel_hi:[1,0]
	v_pk_add_f32 v[4:5], v[4:5], 1.0 op_sel_hi:[1,0]
	v_pk_add_f32 v[6:7], v[6:7], 1.0 op_sel_hi:[1,0]
	v_pk_add_f32 v[8:9], v[8:9], 1.0 op_sel_hi:[1,0]
	v_pk_add_f32 v[10:11], v[10:11], 1.0 op_sel_hi:[1,0]
	v_pk_add_f32 v[12:13], v[12:13], 1.0 op_sel_hi:[1,0]
	v_pk_add_f32 v[14:15], v[14:15], 1.0 op_sel_hi:[1,0]
	v_pk_add_f32 v[16:17], v[16:17], 1.0 op_sel_hi:[1,0]
	v_pk_add_f32 v[18:19], v[18:19], 1.0 op_sel_hi:[1,0]
	v_pk_add_f32 v[20:21], v[20:21], 1.0 op_sel_hi:[1,0]
	v_pk_add_f32 v[22:23], v[22:23], 1.0 op_sel_hi:[1,0]
	v_pk_add_f32 v[24:25], v[24:25], 1.0 op_sel_hi:[1,0]
	v_pk_add_f32 v[26:27], v[26:27], 1.0 op_sel_hi:[1,0]
	v_pk_add_f32 v[28:29], v[28:29], 1.0 op_sel_hi:[1,0]
	v_pk_add_f32 v[30:31], v[30:31], 1.0 op_sel_hi:[1,0]
	v_rcp_f32_e32 v0, v0
	v_rcp_f32_e32 v1, v1
	v_rcp_f32_e32 v2, v2
	v_rcp_f32_e32 v3, v3
	v_rcp_f32_e32 v4, v4
	v_rcp_f32_e32 v5, v5
	v_rcp_f32_e32 v6, v6
	v_rcp_f32_e32 v7, v7
	v_rcp_f32_e32 v8, v8
	v_rcp_f32_e32 v9, v9
	v_rcp_f32_e32 v10, v10
	v_rcp_f32_e32 v11, v11
	v_rcp_f32_e32 v12, v12
	v_rcp_f32_e32 v13, v13
	v_rcp_f32_e32 v14, v14
	v_rcp_f32_e32 v15, v15
	v_rcp_f32_e32 v16, v16
	v_rcp_f32_e32 v17, v17
	v_rcp_f32_e32 v18, v18
	v_rcp_f32_e32 v19, v19
	v_rcp_f32_e32 v20, v20
	v_rcp_f32_e32 v21, v21
	v_rcp_f32_e32 v22, v22
	v_rcp_f32_e32 v23, v23
	v_rcp_f32_e32 v24, v24
	v_rcp_f32_e32 v25, v25
	v_rcp_f32_e32 v26, v26
	v_rcp_f32_e32 v27, v27
	v_rcp_f32_e32 v28, v28
	v_rcp_f32_e32 v29, v29
	v_rcp_f32_e32 v30, v30
	v_rcp_f32_e32 v31, v31
	v_pk_mul_f32 v[0:1], v[246:247], v[0:1]
	v_pk_mul_f32 v[2:3], v[246:247], v[2:3]
	v_pk_mul_f32 v[4:5], v[246:247], v[4:5]
	v_pk_mul_f32 v[6:7], v[246:247], v[6:7]
	v_pk_mul_f32 v[8:9], v[246:247], v[8:9]
	v_pk_mul_f32 v[10:11], v[246:247], v[10:11]
	v_pk_mul_f32 v[12:13], v[246:247], v[12:13]
	v_pk_mul_f32 v[14:15], v[246:247], v[14:15]
	v_lshlrev_b32_e32 v48, 16, v48
	v_lshlrev_b32_e32 v49, 16, v49
	v_lshlrev_b32_e32 v50, 16, v50
; #define LAS __attribute__((address_space(3)))
; #define WAVE_SYNC() asm volatile("s_waitcnt lgkmcnt(0)" ::: "memory")
; __device__ __forceinline__ float sigmoid_f(float x) { return rcpf_(1.f + __expf(-x)); }
; __device__ __forceinline__ float gelu_tanh_f(float x) { const float y = 0.7978845608028654f * (x + 0.044715f * x * x * x); return x * sigmoid_f(2.f * y); }
; __device__ __forceinline__ f32x4 mfma16(bf16x8 a, bf16x8 b, f32x4 c) { return __builtin_amdgcn_mfma_f32_16x16x32_bf16(a, b, c, 0, 0, 0); }
; template <bool FINAL, int D>
; __device__ __forceinline__ void rg_dir(PREF p, int l, int h, int ch, int sidx, int rowbase  , LAS bf16_t* sXc, LAS float* stg, int lane) {
;     ...
;         const bf16x8 A0 = *(const LAS bf16x8*)(sXc + (mt * 16 + (lane & 15)) * 72 + (lane >> 4) * 8), A1 = *(const LAS bf16x8*)(sXc + (mt * 16 + (lane & 15)) * 72 + 32 + (lane >> 4) * 8);
;         f32x4 ar[4], ai[4];
; #pragma unroll
;         for (int nt = 0; nt < 4; ++nt) { const f32x4 z = {0.f, 0.f, 0.f, 0.f};
;             ar[nt] = mfma16(A0, Br[nt][0], z); ar[nt] = mfma16(A1, Br[nt][1], ar[nt]); ai[nt] = mfma16(A0, Bi[nt][0], z); ai[nt] = mfma16(A1, Bi[nt][1], ai[nt]); }
;         WAVE_SYNC();
; #pragma unroll
;         for (int nt = 0; nt < 4; ++nt)
; #pragma unroll
;             for (int j = 0; j < 4; ++j) { const int o = ((lane >> 4) * 4 + j) * 64 + nt * 16 + (lane & 15); stg[o] = ar[nt][j]; stg[1024 + o] = ai[nt][j]; }
;         WAVE_SYNC();
;     ...
;         for (int ti = 0; ti < 16; ++ti) { const int tk = D ? 15 - ti : ti;
;             const float zr = stg[tk * 64 + lane] + ba, zi = stg[1024 + tk * 64 + lane] + bi;
;             const float r = sigmoid_f(zr), ig = sigmoid_f(zi);
;             const float a = __builtin_amdgcn_exp2f(r * sp8);
;             const float xc = bf2f(sXc[(mt * 16 + tk) * 72 + lane]);
;             av[ti] = a; iv[ti] = __builtin_amdgcn_sqrtf(fmaxf(1.f - a * a, 0.f)) * ig * xc;
;             if (FINAL && D == 1) grv[ti] = gelu_tanh_f(grv[ti]);
;         }
; #pragma unroll
;         for (int ti = 0; ti < 16; ++ti) { const int tk = D ? 15 - ti : ti;
;             hc = av[ti] * hc + iv[ti]; Ap *= av[ti];
	v_lshlrev_b32_e32 v51, 16, v51
	v_lshlrev_b32_e32 v52, 16, v52
	v_lshlrev_b32_e32 v53, 16, v53
	v_lshlrev_b32_e32 v54, 16, v54
	v_lshlrev_b32_e32 v55, 16, v55
	v_lshlrev_b32_e32 v56, 16, v56
	v_lshlrev_b32_e32 v57, 16, v57
	v_lshlrev_b32_e32 v58, 16, v58
	v_lshlrev_b32_e32 v59, 16, v59
	v_lshlrev_b32_e32 v60, 16, v60
	v_lshlrev_b32_e32 v61, 16, v61
	v_lshlrev_b32_e32 v62, 16, v62
	v_lshlrev_b32_e32 v63, 16, v63
	v_exp_f32_e32 v0, v0
	v_exp_f32_e32 v1, v1
	v_exp_f32_e32 v2, v2
	v_exp_f32_e32 v3, v3
	v_exp_f32_e32 v4, v4
	v_exp_f32_e32 v5, v5
	v_exp_f32_e32 v6, v6
	v_exp_f32_e32 v7, v7
	v_exp_f32_e32 v8, v8
	v_exp_f32_e32 v9, v9
	v_exp_f32_e32 v10, v10
	v_exp_f32_e32 v11, v11
	v_exp_f32_e32 v12, v12
	v_exp_f32_e32 v13, v13
	v_exp_f32_e32 v14, v14
	v_exp_f32_e32 v15, v15
	v_fma_f32 v32, -v0, v0, 1.0
	v_fma_f32 v33, -v1, v1, 1.0
	v_fma_f32 v34, -v2, v2, 1.0
	v_fma_f32 v35, -v3, v3, 1.0
	v_fma_f32 v36, -v4, v4, 1.0
	v_fma_f32 v37, -v5, v5, 1.0
	v_fma_f32 v38, -v6, v6, 1.0
	v_fma_f32 v39, -v7, v7, 1.0
	v_fma_f32 v40, -v8, v8, 1.0
	v_fma_f32 v41, -v9, v9, 1.0
	v_fma_f32 v42, -v10, v10, 1.0
	v_fma_f32 v43, -v11, v11, 1.0
	v_fma_f32 v44, -v12, v12, 1.0
	v_fma_f32 v45, -v13, v13, 1.0
	v_fma_f32 v46, -v14, v14, 1.0
	v_fma_f32 v47, -v15, v15, 1.0
	v_max_f32_e32 v32, 0, v32
	v_max_f32_e32 v33, 0, v33
	v_max_f32_e32 v34, 0, v34
	v_max_f32_e32 v35, 0, v35
	v_max_f32_e32 v36, 0, v36
	v_max_f32_e32 v37, 0, v37
	v_max_f32_e32 v38, 0, v38
	v_max_f32_e32 v39, 0, v39
	v_max_f32_e32 v40, 0, v40
	v_max_f32_e32 v41, 0, v41
	v_max_f32_e32 v42, 0, v42
	v_max_f32_e32 v43, 0, v43
	v_max_f32_e32 v44, 0, v44
	v_max_f32_e32 v45, 0, v45
	v_max_f32_e32 v46, 0, v46
	v_max_f32_e32 v47, 0, v47
	v_sqrt_f32_e32 v32, v32
	v_sqrt_f32_e32 v33, v33
	v_sqrt_f32_e32 v34, v34
	v_sqrt_f32_e32 v35, v35
	v_sqrt_f32_e32 v36, v36
	v_sqrt_f32_e32 v37, v37
	v_sqrt_f32_e32 v38, v38
	v_sqrt_f32_e32 v39, v39
	v_sqrt_f32_e32 v40, v40
	v_sqrt_f32_e32 v41, v41
	v_sqrt_f32_e32 v42, v42
	v_sqrt_f32_e32 v43, v43
	v_sqrt_f32_e32 v44, v44
	v_sqrt_f32_e32 v45, v45
	v_sqrt_f32_e32 v46, v46
	v_sqrt_f32_e32 v47, v47
	s_nop 0
	v_pk_mul_f32 v[16:17], v[16:17], v[32:33]
	v_pk_mul_f32 v[18:19], v[18:19], v[34:35]
	v_pk_mul_f32 v[20:21], v[20:21], v[36:37]
	v_pk_mul_f32 v[22:23], v[22:23], v[38:39]
	v_pk_mul_f32 v[24:25], v[24:25], v[40:41]
	v_pk_mul_f32 v[26:27], v[26:27], v[42:43]
	v_pk_mul_f32 v[28:29], v[28:29], v[44:45]
	v_pk_mul_f32 v[30:31], v[30:31], v[46:47]
	v_pk_mul_f32 v[16:17], v[16:17], v[48:49]
	v_pk_mul_f32 v[18:19], v[18:19], v[50:51]
	v_pk_mul_f32 v[20:21], v[20:21], v[52:53]
	v_pk_mul_f32 v[22:23], v[22:23], v[54:55]
	v_pk_mul_f32 v[24:25], v[24:25], v[56:57]
	v_pk_mul_f32 v[26:27], v[26:27], v[58:59]
	v_pk_mul_f32 v[28:29], v[28:29], v[60:61]
	v_pk_mul_f32 v[30:31], v[30:31], v[62:63]
	v_fma_f32 v32, v0, v250, v16
	v_mul_f32_e32 v232, v232, v0
	v_fma_f32 v250, v1, v32, v17
	v_mul_f32_e32 v232, v232, v1
	v_fma_f32 v32, v2, v250, v18
	v_mul_f32_e32 v232, v232, v2
	v_fma_f32 v250, v3, v32, v19
	v_mul_f32_e32 v232, v232, v3
	v_fma_f32 v32, v4, v250, v20
	v_mul_f32_e32 v232, v232, v4
	v_fma_f32 v250, v5, v32, v21
	v_mul_f32_e32 v232, v232, v5
	v_fma_f32 v32, v6, v250, v22
	v_mul_f32_e32 v232, v232, v6
	v_fma_f32 v250, v7, v32, v23
	v_mul_f32_e32 v232, v232, v7
	v_fma_f32 v32, v8, v250, v24
	v_mul_f32_e32 v232, v232, v8
	v_fma_f32 v250, v9, v32, v25
	v_mul_f32_e32 v232, v232, v9
	v_fma_f32 v32, v10, v250, v26
	v_mul_f32_e32 v232, v232, v10
	v_fma_f32 v250, v11, v32, v27
	v_mul_f32_e32 v232, v232, v11
	v_fma_f32 v32, v12, v250, v28
	v_mul_f32_e32 v232, v232, v12
	v_fma_f32 v250, v13, v32, v29
	v_mul_f32_e32 v232, v232, v13
	v_fma_f32 v32, v14, v250, v30
	v_mul_f32_e32 v232, v232, v14
	v_fma_f32 v250, v15, v32, v31
	v_mul_f32_e32 v232, v232, v15
	ds_read_b128 v[32:35], v236 offset:4608
	ds_read_b128 v[36:39], v236 offset:4672
	s_waitcnt lgkmcnt(0)
	v_mfma_f32_16x16x32_bf16 v[0:3], v[32:35], v[80:83], 0
	v_mfma_f32_16x16x32_bf16 v[4:7], v[32:35], v[88:91], 0
	v_mfma_f32_16x16x32_bf16 v[8:11], v[32:35], v[96:99], 0
	v_mfma_f32_16x16x32_bf16 v[12:15], v[32:35], v[104:107], 0
	v_mfma_f32_16x16x32_bf16 v[16:19], v[32:35], v[112:115], 0
	v_mfma_f32_16x16x32_bf16 v[20:23], v[32:35], v[120:123], 0
	v_mfma_f32_16x16x32_bf16 v[24:27], v[32:35], v[128:131], 0
	v_mfma_f32_16x16x32_bf16 v[28:31], v[32:35], v[136:139], 0
	v_mfma_f32_16x16x32_bf16 v[0:3], v[36:39], v[84:87], v[0:3]
	v_mfma_f32_16x16x32_bf16 v[4:7], v[36:39], v[92:95], v[4:7]
	v_mfma_f32_16x16x32_bf16 v[8:11], v[36:39], v[100:103], v[8:11]
	v_mfma_f32_16x16x32_bf16 v[12:15], v[36:39], v[108:111], v[12:15]
	v_mfma_f32_16x16x32_bf16 v[16:19], v[36:39], v[148:151], v[16:19]
	v_mfma_f32_16x16x32_bf16 v[20:23], v[36:39], v[124:127], v[20:23]
	v_mfma_f32_16x16x32_bf16 v[24:27], v[36:39], v[132:135], v[24:27]
	v_mfma_f32_16x16x32_bf16 v[28:31], v[36:39], v[228:231], v[28:31]
	s_nop 3
	ds_write2_b32 v237, v0, v4 offset0:0 offset1:16
	ds_write2_b32 v237, v8, v12 offset0:32 offset1:48
	ds_write2_b32 v237, v1, v5 offset0:64 offset1:80
	ds_write2_b32 v237, v9, v13 offset0:96 offset1:112
	ds_write2_b32 v237, v2, v6 offset0:128 offset1:144
	ds_write2_b32 v237, v10, v14 offset0:160 offset1:176
	ds_write2_b32 v237, v3, v7 offset0:192 offset1:208
	ds_write2_b32 v237, v11, v15 offset0:224 offset1:240
	ds_write2_b32 v238, v16, v20 offset0:0 offset1:16
	ds_write2_b32 v238, v24, v28 offset0:32 offset1:48
	ds_write2_b32 v238, v17, v21 offset0:64 offset1:80
	ds_write2_b32 v238, v25, v29 offset0:96 offset1:112
	ds_write2_b32 v238, v18, v22 offset0:128 offset1:144
	ds_write2_b32 v238, v26, v30 offset0:160 offset1:176
	ds_write2_b32 v238, v19, v23 offset0:192 offset1:208
	ds_write2_b32 v238, v27, v31 offset0:224 offset1:240
	s_waitcnt lgkmcnt(0)
; __device__ __forceinline__ float sigmoid_f(float x) { return rcpf_(1.f + __expf(-x)); }
; template <bool FINAL, int D>
; __device__ __forceinline__ void rg_dir(PREF p, int l, int h, int ch, int sidx, int rowbase  , LAS bf16_t* sXc, LAS float* stg, int lane) {
;     ...
;         float av[16], iv[16];
; #pragma unroll
;         for (int ti = 0; ti < 16; ++ti) { const int tk = D ? 15 - ti : ti;
;             const float zr = stg[tk * 64 + lane] + ba, zi = stg[1024 + tk * 64 + lane] + bi;
;             const float r = sigmoid_f(zr), ig = sigmoid_f(zi);
;             const float a = __builtin_amdgcn_exp2f(r * sp8);
;             const float xc = bf2f(sXc[(mt * 16 + tk) * 72 + lane]);
;             av[ti] = a; iv[ti] = __builtin_amdgcn_sqrtf(fmaxf(1.f - a * a, 0.f)) * ig * xc;
	ds_read2st64_b32 v[0:1], v239 offset0:36 offset1:37
	ds_read2st64_b32 v[2:3], v239 offset0:38 offset1:39
	ds_read2st64_b32 v[4:5], v239 offset0:40 offset1:41
	ds_read2st64_b32 v[6:7], v239 offset0:42 offset1:43
	ds_read2st64_b32 v[8:9], v239 offset0:44 offset1:45
	ds_read2st64_b32 v[10:11], v239 offset0:46 offset1:47
	ds_read2st64_b32 v[12:13], v239 offset0:48 offset1:49
	ds_read2st64_b32 v[14:15], v239 offset0:50 offset1:51
	ds_read2st64_b32 v[16:17], v239 offset0:52 offset1:53
	ds_read2st64_b32 v[18:19], v239 offset0:54 offset1:55
	ds_read2st64_b32 v[20:21], v239 offset0:56 offset1:57
	ds_read2st64_b32 v[22:23], v239 offset0:58 offset1:59
	ds_read2st64_b32 v[24:25], v239 offset0:60 offset1:61
	ds_read2st64_b32 v[26:27], v239 offset0:62 offset1:63
	ds_read2st64_b32 v[28:29], v239 offset0:64 offset1:65
	ds_read2st64_b32 v[30:31], v239 offset0:66 offset1:67
	ds_read_u16 v48, v240 offset:4608
	ds_read_u16 v49, v240 offset:4752
	ds_read_u16 v50, v240 offset:4896
	ds_read_u16 v51, v240 offset:5040
	ds_read_u16 v52, v240 offset:5184
	ds_read_u16 v53, v240 offset:5328
	ds_read_u16 v54, v240 offset:5472
	ds_read_u16 v55, v240 offset:5616
	ds_read_u16 v56, v240 offset:5760
	ds_read_u16 v57, v240 offset:5904
	ds_read_u16 v58, v240 offset:6048
	ds_read_u16 v59, v240 offset:6192
	ds_read_u16 v60, v240 offset:6336
	ds_read_u16 v61, v240 offset:6480
	ds_read_u16 v62, v240 offset:6624
	ds_read_u16 v63, v240 offset:6768
	s_waitcnt lgkmcnt(0)
	v_pk_add_f32 v[0:1], v[242:243], v[0:1]
	v_pk_add_f32 v[2:3], v[242:243], v[2:3]
	v_pk_add_f32 v[4:5], v[242:243], v[4:5]
	v_pk_add_f32 v[6:7], v[242:243], v[6:7]
	v_pk_add_f32 v[8:9], v[242:243], v[8:9]
	v_pk_add_f32 v[10:11], v[242:243], v[10:11]
	v_pk_add_f32 v[12:13], v[242:243], v[12:13]
	v_pk_add_f32 v[14:15], v[242:243], v[14:15]
	v_pk_add_f32 v[16:17], v[244:245], v[16:17]
	v_pk_add_f32 v[18:19], v[244:245], v[18:19]
	v_pk_add_f32 v[20:21], v[244:245], v[20:21]
	v_pk_add_f32 v[22:23], v[244:245], v[22:23]
	v_pk_add_f32 v[24:25], v[244:245], v[24:25]
	v_pk_add_f32 v[26:27], v[244:245], v[26:27]
	v_pk_add_f32 v[28:29], v[244:245], v[28:29]
	v_pk_add_f32 v[30:31], v[244:245], v[30:31]
	v_pk_mul_f32 v[0:1], v[248:249], v[0:1]
	v_pk_mul_f32 v[2:3], v[248:249], v[2:3]
	v_pk_mul_f32 v[4:5], v[248:249], v[4:5]
	v_pk_mul_f32 v[6:7], v[248:249], v[6:7]
	v_pk_mul_f32 v[8:9], v[248:249], v[8:9]
	v_pk_mul_f32 v[10:11], v[248:249], v[10:11]
	v_pk_mul_f32 v[12:13], v[248:249], v[12:13]
	v_pk_mul_f32 v[14:15], v[248:249], v[14:15]
	v_pk_mul_f32 v[16:17], v[248:249], v[16:17]
	v_pk_mul_f32 v[18:19], v[248:249], v[18:19]
	v_pk_mul_f32 v[20:21], v[248:249], v[20:21]
	v_pk_mul_f32 v[22:23], v[248:249], v[22:23]
	v_pk_mul_f32 v[24:25], v[248:249], v[24:25]
	v_pk_mul_f32 v[26:27], v[248:249], v[26:27]
	v_pk_mul_f32 v[28:29], v[248:249], v[28:29]
	v_pk_mul_f32 v[30:31], v[248:249], v[30:31]
	v_exp_f32_e32 v0, v0
	v_exp_f32_e32 v1, v1
	v_exp_f32_e32 v2, v2
	v_exp_f32_e32 v3, v3
	v_exp_f32_e32 v4, v4
	v_exp_f32_e32 v5, v5
	v_exp_f32_e32 v6, v6
	v_exp_f32_e32 v7, v7
	v_exp_f32_e32 v8, v8
	v_exp_f32_e32 v9, v9
	v_exp_f32_e32 v10, v10
	v_exp_f32_e32 v11, v11
	v_exp_f32_e32 v12, v12
	v_exp_f32_e32 v13, v13
	v_exp_f32_e32 v14, v14
	v_exp_f32_e32 v15, v15
	v_exp_f32_e32 v16, v16
	v_exp_f32_e32 v17, v17
	v_exp_f32_e32 v18, v18
	v_exp_f32_e32 v19, v19
	v_exp_f32_e32 v20, v20
	v_exp_f32_e32 v21, v21
	v_exp_f32_e32 v22, v22
	v_exp_f32_e32 v23, v23
	v_exp_f32_e32 v24, v24
	v_exp_f32_e32 v25, v25
	v_exp_f32_e32 v26, v26
	v_exp_f32_e32 v27, v27
	v_exp_f32_e32 v28, v28
	v_exp_f32_e32 v29, v29
	v_exp_f32_e32 v30, v30
	v_exp_f32_e32 v31, v31
	v_pk_add_f32 v[0:1], v[0:1], 1.0 op_sel_hi:[1,0]
	v_pk_add_f32 v[2:3], v[2:3], 1.0 op_sel_hi:[1,0]
	v_pk_add_f32 v[4:5], v[4:5], 1.0 op_sel_hi:[1,0]
	v_pk_add_f32 v[6:7], v[6:7], 1.0 op_sel_hi:[1,0]
	v_pk_add_f32 v[8:9], v[8:9], 1.0 op_sel_hi:[1,0]
	v_pk_add_f32 v[10:11], v[10:11], 1.0 op_sel_hi:[1,0]
	v_pk_add_f32 v[12:13], v[12:13], 1.0 op_sel_hi:[1,0]
	v_pk_add_f32 v[14:15], v[14:15], 1.0 op_sel_hi:[1,0]
	v_pk_add_f32 v[16:17], v[16:17], 1.0 op_sel_hi:[1,0]
	v_pk_add_f32 v[18:19], v[18:19], 1.0 op_sel_hi:[1,0]
	v_pk_add_f32 v[20:21], v[20:21], 1.0 op_sel_hi:[1,0]
	v_pk_add_f32 v[22:23], v[22:23], 1.0 op_sel_hi:[1,0]
	v_pk_add_f32 v[24:25], v[24:25], 1.0 op_sel_hi:[1,0]
	v_pk_add_f32 v[26:27], v[26:27], 1.0 op_sel_hi:[1,0]
	v_pk_add_f32 v[28:29], v[28:29], 1.0 op_sel_hi:[1,0]
	v_pk_add_f32 v[30:31], v[30:31], 1.0 op_sel_hi:[1,0]
	v_rcp_f32_e32 v0, v0
	v_rcp_f32_e32 v1, v1
	v_rcp_f32_e32 v2, v2
	v_rcp_f32_e32 v3, v3
	v_rcp_f32_e32 v4, v4
	v_rcp_f32_e32 v5, v5
	v_rcp_f32_e32 v6, v6
	v_rcp_f32_e32 v7, v7
	v_rcp_f32_e32 v8, v8
	v_rcp_f32_e32 v9, v9
	v_rcp_f32_e32 v10, v10
	v_rcp_f32_e32 v11, v11
	v_rcp_f32_e32 v12, v12
	v_rcp_f32_e32 v13, v13
	v_rcp_f32_e32 v14, v14
	v_rcp_f32_e32 v15, v15
	v_rcp_f32_e32 v16, v16
	v_rcp_f32_e32 v17, v17
	v_rcp_f32_e32 v18, v18
	v_rcp_f32_e32 v19, v19
	v_rcp_f32_e32 v20, v20
	v_rcp_f32_e32 v21, v21
	v_rcp_f32_e32 v22, v22
	v_rcp_f32_e32 v23, v23
	v_rcp_f32_e32 v24, v24
	v_rcp_f32_e32 v25, v25
	v_rcp_f32_e32 v26, v26
	v_rcp_f32_e32 v27, v27
	v_rcp_f32_e32 v28, v28
	v_rcp_f32_e32 v29, v29
	v_rcp_f32_e32 v30, v30
	v_rcp_f32_e32 v31, v31
	v_pk_mul_f32 v[0:1], v[246:247], v[0:1]
	v_pk_mul_f32 v[2:3], v[246:247], v[2:3]
	v_pk_mul_f32 v[4:5], v[246:247], v[4:5]
	v_pk_mul_f32 v[6:7], v[246:247], v[6:7]
	v_pk_mul_f32 v[8:9], v[246:247], v[8:9]
	v_pk_mul_f32 v[10:11], v[246:247], v[10:11]
	v_pk_mul_f32 v[12:13], v[246:247], v[12:13]
	v_pk_mul_f32 v[14:15], v[246:247], v[14:15]
	v_lshlrev_b32_e32 v48, 16, v48
	v_lshlrev_b32_e32 v49, 16, v49
	v_lshlrev_b32_e32 v50, 16, v50
; #define LAS __attribute__((address_space(3)))
; #define WAVE_SYNC() asm volatile("s_waitcnt lgkmcnt(0)" ::: "memory")
; __device__ __forceinline__ float sigmoid_f(float x) { return rcpf_(1.f + __expf(-x)); }
; __device__ __forceinline__ float gelu_tanh_f(float x) { const float y = 0.7978845608028654f * (x + 0.044715f * x * x * x); return x * sigmoid_f(2.f * y); }
; __device__ __forceinline__ f32x4 mfma16(bf16x8 a, bf16x8 b, f32x4 c) { return __builtin_amdgcn_mfma_f32_16x16x32_bf16(a, b, c, 0, 0, 0); }
; template <bool FINAL, int D>
; __device__ __forceinline__ void rg_dir(PREF p, int l, int h, int ch, int sidx, int rowbase  , LAS bf16_t* sXc, LAS float* stg, int lane) {
;     ...
;         const bf16x8 A0 = *(const LAS bf16x8*)(sXc + (mt * 16 + (lane & 15)) * 72 + (lane >> 4) * 8), A1 = *(const LAS bf16x8*)(sXc + (mt * 16 + (lane & 15)) * 72 + 32 + (lane >> 4) * 8);
;         f32x4 ar[4], ai[4];
; #pragma unroll
;         for (int nt = 0; nt < 4; ++nt) { const f32x4 z = {0.f, 0.f, 0.f, 0.f};
;             ar[nt] = mfma16(A0, Br[nt][0], z); ar[nt] = mfma16(A1, Br[nt][1], ar[nt]); ai[nt] = mfma16(A0, Bi[nt][0], z); ai[nt] = mfma16(A1, Bi[nt][1], ai[nt]); }
;         WAVE_SYNC();
; #pragma unroll
;         for (int nt = 0; nt < 4; ++nt)
; #pragma unroll
;             for (int j = 0; j < 4; ++j) { const int o = ((lane >> 4) * 4 + j) * 64 + nt * 16 + (lane & 15); stg[o] = ar[nt][j]; stg[1024 + o] = ai[nt][j]; }
;         WAVE_SYNC();
;     ...
;         for (int ti = 0; ti < 16; ++ti) { const int tk = D ? 15 - ti : ti;
;             const float zr = stg[tk * 64 + lane] + ba, zi = stg[1024 + tk * 64 + lane] + bi;
;             const float r = sigmoid_f(zr), ig = sigmoid_f(zi);
;             const float a = __builtin_amdgcn_exp2f(r * sp8);
;             const float xc = bf2f(sXc[(mt * 16 + tk) * 72 + lane]);
;             av[ti] = a; iv[ti] = __builtin_amdgcn_sqrtf(fmaxf(1.f - a * a, 0.f)) * ig * xc;
;             if (FINAL && D == 1) grv[ti] = gelu_tanh_f(grv[ti]);
;         }
; #pragma unroll
;         for (int ti = 0; ti < 16; ++ti) { const int tk = D ? 15 - ti : ti;
;             hc = av[ti] * hc + iv[ti]; Ap *= av[ti];
	v_lshlrev_b32_e32 v51, 16, v51
	v_lshlrev_b32_e32 v52, 16, v52
	v_lshlrev_b32_e32 v53, 16, v53
	v_lshlrev_b32_e32 v54, 16, v54
	v_lshlrev_b32_e32 v55, 16, v55
	v_lshlrev_b32_e32 v56, 16, v56
	v_lshlrev_b32_e32 v57, 16, v57
	v_lshlrev_b32_e32 v58, 16, v58
	v_lshlrev_b32_e32 v59, 16, v59
	v_lshlrev_b32_e32 v60, 16, v60
	v_lshlrev_b32_e32 v61, 16, v61
	v_lshlrev_b32_e32 v62, 16, v62
	v_lshlrev_b32_e32 v63, 16, v63
	v_exp_f32_e32 v0, v0
	v_exp_f32_e32 v1, v1
	v_exp_f32_e32 v2, v2
	v_exp_f32_e32 v3, v3
	v_exp_f32_e32 v4, v4
	v_exp_f32_e32 v5, v5
	v_exp_f32_e32 v6, v6
	v_exp_f32_e32 v7, v7
	v_exp_f32_e32 v8, v8
	v_exp_f32_e32 v9, v9
	v_exp_f32_e32 v10, v10
	v_exp_f32_e32 v11, v11
	v_exp_f32_e32 v12, v12
	v_exp_f32_e32 v13, v13
	v_exp_f32_e32 v14, v14
	v_exp_f32_e32 v15, v15
	v_fma_f32 v32, -v0, v0, 1.0
	v_fma_f32 v33, -v1, v1, 1.0
	v_fma_f32 v34, -v2, v2, 1.0
	v_fma_f32 v35, -v3, v3, 1.0
	v_fma_f32 v36, -v4, v4, 1.0
	v_fma_f32 v37, -v5, v5, 1.0
	v_fma_f32 v38, -v6, v6, 1.0
	v_fma_f32 v39, -v7, v7, 1.0
	v_fma_f32 v40, -v8, v8, 1.0
	v_fma_f32 v41, -v9, v9, 1.0
	v_fma_f32 v42, -v10, v10, 1.0
	v_fma_f32 v43, -v11, v11, 1.0
	v_fma_f32 v44, -v12, v12, 1.0
	v_fma_f32 v45, -v13, v13, 1.0
	v_fma_f32 v46, -v14, v14, 1.0
	v_fma_f32 v47, -v15, v15, 1.0
	v_max_f32_e32 v32, 0, v32
	v_max_f32_e32 v33, 0, v33
	v_max_f32_e32 v34, 0, v34
	v_max_f32_e32 v35, 0, v35
	v_max_f32_e32 v36, 0, v36
	v_max_f32_e32 v37, 0, v37
	v_max_f32_e32 v38, 0, v38
	v_max_f32_e32 v39, 0, v39
	v_max_f32_e32 v40, 0, v40
	v_max_f32_e32 v41, 0, v41
	v_max_f32_e32 v42, 0, v42
	v_max_f32_e32 v43, 0, v43
	v_max_f32_e32 v44, 0, v44
	v_max_f32_e32 v45, 0, v45
	v_max_f32_e32 v46, 0, v46
	v_max_f32_e32 v47, 0, v47
	v_sqrt_f32_e32 v32, v32
	v_sqrt_f32_e32 v33, v33
	v_sqrt_f32_e32 v34, v34
	v_sqrt_f32_e32 v35, v35
	v_sqrt_f32_e32 v36, v36
	v_sqrt_f32_e32 v37, v37
	v_sqrt_f32_e32 v38, v38
	v_sqrt_f32_e32 v39, v39
	v_sqrt_f32_e32 v40, v40
	v_sqrt_f32_e32 v41, v41
	v_sqrt_f32_e32 v42, v42
	v_sqrt_f32_e32 v43, v43
	v_sqrt_f32_e32 v44, v44
	v_sqrt_f32_e32 v45, v45
	v_sqrt_f32_e32 v46, v46
	v_sqrt_f32_e32 v47, v47
	s_nop 0
	v_pk_mul_f32 v[16:17], v[16:17], v[32:33]
	v_pk_mul_f32 v[18:19], v[18:19], v[34:35]
	v_pk_mul_f32 v[20:21], v[20:21], v[36:37]
	v_pk_mul_f32 v[22:23], v[22:23], v[38:39]
	v_pk_mul_f32 v[24:25], v[24:25], v[40:41]
	v_pk_mul_f32 v[26:27], v[26:27], v[42:43]
	v_pk_mul_f32 v[28:29], v[28:29], v[44:45]
	v_pk_mul_f32 v[30:31], v[30:31], v[46:47]
	v_pk_mul_f32 v[16:17], v[16:17], v[48:49]
	v_pk_mul_f32 v[18:19], v[18:19], v[50:51]
	v_pk_mul_f32 v[20:21], v[20:21], v[52:53]
	v_pk_mul_f32 v[22:23], v[22:23], v[54:55]
	v_pk_mul_f32 v[24:25], v[24:25], v[56:57]
	v_pk_mul_f32 v[26:27], v[26:27], v[58:59]
	v_pk_mul_f32 v[28:29], v[28:29], v[60:61]
	v_pk_mul_f32 v[30:31], v[30:31], v[62:63]
	v_fma_f32 v32, v0, v250, v16
	v_mul_f32_e32 v232, v232, v0
	v_fma_f32 v250, v1, v32, v17
	v_mul_f32_e32 v232, v232, v1
	v_fma_f32 v32, v2, v250, v18
	v_mul_f32_e32 v232, v232, v2
	v_fma_f32 v250, v3, v32, v19
	v_mul_f32_e32 v232, v232, v3
	v_fma_f32 v32, v4, v250, v20
	v_mul_f32_e32 v232, v232, v4
	v_fma_f32 v250, v5, v32, v21
	v_mul_f32_e32 v232, v232, v5
	v_fma_f32 v32, v6, v250, v22
	v_mul_f32_e32 v232, v232, v6
	v_fma_f32 v250, v7, v32, v23
	v_mul_f32_e32 v232, v232, v7
	v_fma_f32 v32, v8, v250, v24
	v_mul_f32_e32 v232, v232, v8
	v_fma_f32 v250, v9, v32, v25
	v_mul_f32_e32 v232, v232, v9
	v_fma_f32 v32, v10, v250, v26
	v_mul_f32_e32 v232, v232, v10
	v_fma_f32 v250, v11, v32, v27
	v_mul_f32_e32 v232, v232, v11
	v_fma_f32 v32, v12, v250, v28
	v_mul_f32_e32 v232, v232, v12
	v_fma_f32 v250, v13, v32, v29
	v_mul_f32_e32 v232, v232, v13
	v_fma_f32 v32, v14, v250, v30
	v_mul_f32_e32 v232, v232, v14
	v_fma_f32 v250, v15, v32, v31
	v_mul_f32_e32 v232, v232, v15
	ds_read_b128 v[32:35], v236 offset:6912
	ds_read_b128 v[36:39], v236 offset:6976
	s_waitcnt lgkmcnt(0)
	v_mfma_f32_16x16x32_bf16 v[0:3], v[32:35], v[80:83], 0
	v_mfma_f32_16x16x32_bf16 v[4:7], v[32:35], v[88:91], 0
	v_mfma_f32_16x16x32_bf16 v[8:11], v[32:35], v[96:99], 0
	v_mfma_f32_16x16x32_bf16 v[12:15], v[32:35], v[104:107], 0
	v_mfma_f32_16x16x32_bf16 v[16:19], v[32:35], v[112:115], 0
	v_mfma_f32_16x16x32_bf16 v[20:23], v[32:35], v[120:123], 0
	v_mfma_f32_16x16x32_bf16 v[24:27], v[32:35], v[128:131], 0
	v_mfma_f32_16x16x32_bf16 v[28:31], v[32:35], v[136:139], 0
	v_mfma_f32_16x16x32_bf16 v[0:3], v[36:39], v[84:87], v[0:3]
	v_mfma_f32_16x16x32_bf16 v[4:7], v[36:39], v[92:95], v[4:7]
	v_mfma_f32_16x16x32_bf16 v[8:11], v[36:39], v[100:103], v[8:11]
	v_mfma_f32_16x16x32_bf16 v[12:15], v[36:39], v[108:111], v[12:15]
	v_mfma_f32_16x16x32_bf16 v[16:19], v[36:39], v[148:151], v[16:19]
	v_mfma_f32_16x16x32_bf16 v[20:23], v[36:39], v[124:127], v[20:23]
	v_mfma_f32_16x16x32_bf16 v[24:27], v[36:39], v[132:135], v[24:27]
	v_mfma_f32_16x16x32_bf16 v[28:31], v[36:39], v[228:231], v[28:31]
	s_nop 3
	ds_write2_b32 v237, v0, v4 offset0:0 offset1:16
	ds_write2_b32 v237, v8, v12 offset0:32 offset1:48
	ds_write2_b32 v237, v1, v5 offset0:64 offset1:80
	ds_write2_b32 v237, v9, v13 offset0:96 offset1:112
	ds_write2_b32 v237, v2, v6 offset0:128 offset1:144
	ds_write2_b32 v237, v10, v14 offset0:160 offset1:176
	ds_write2_b32 v237, v3, v7 offset0:192 offset1:208
	ds_write2_b32 v237, v11, v15 offset0:224 offset1:240
	ds_write2_b32 v238, v16, v20 offset0:0 offset1:16
	ds_write2_b32 v238, v24, v28 offset0:32 offset1:48
	ds_write2_b32 v238, v17, v21 offset0:64 offset1:80
	ds_write2_b32 v238, v25, v29 offset0:96 offset1:112
	ds_write2_b32 v238, v18, v22 offset0:128 offset1:144
	ds_write2_b32 v238, v26, v30 offset0:160 offset1:176
	ds_write2_b32 v238, v19, v23 offset0:192 offset1:208
	ds_write2_b32 v238, v27, v31 offset0:224 offset1:240
	s_waitcnt lgkmcnt(0)
; __device__ __forceinline__ float sigmoid_f(float x) { return rcpf_(1.f + __expf(-x)); }
; template <bool FINAL, int D>
; __device__ __forceinline__ void rg_dir(PREF p, int l, int h, int ch, int sidx, int rowbase  , LAS bf16_t* sXc, LAS float* stg, int lane) {
;     ...
;     bf16x8 Br[4][2], Bi[4][2];
; #pragma unroll
;     for (int nt = 0; nt < 4; ++nt) { const int o0 = (nt * 16 + (lane & 15)) * 64 + (lane >> 4) * 8;
;         Br[nt][0] = *(const bf16x8*)(wr_ + o0); Br[nt][1] = *(const bf16x8*)(wr_ + o0 + 32); Bi[nt][0] = *(const bf16x8*)(wi_ + o0); Bi[nt][1] = *(const bf16x8*)(wi_ + o0 + 32); }
;     ...
;         float av[16], iv[16];
; #pragma unroll
;         for (int ti = 0; ti < 16; ++ti) { const int tk = D ? 15 - ti : ti;
;             const float zr = stg[tk * 64 + lane] + ba, zi = stg[1024 + tk * 64 + lane] + bi;
;             const float r = sigmoid_f(zr), ig = sigmoid_f(zi);
;             const float a = __builtin_amdgcn_exp2f(r * sp8);
;             const float xc = bf2f(sXc[(mt * 16 + tk) * 72 + lane]);
;             av[ti] = a; iv[ti] = __builtin_amdgcn_sqrtf(fmaxf(1.f - a * a, 0.f)) * ig * xc;
	ds_read2st64_b32 v[0:1], v239 offset0:36 offset1:37
	ds_read2st64_b32 v[2:3], v239 offset0:38 offset1:39
	ds_read2st64_b32 v[4:5], v239 offset0:40 offset1:41
	ds_read2st64_b32 v[6:7], v239 offset0:42 offset1:43
	ds_read2st64_b32 v[8:9], v239 offset0:44 offset1:45
	ds_read2st64_b32 v[10:11], v239 offset0:46 offset1:47
	ds_read2st64_b32 v[12:13], v239 offset0:48 offset1:49
	ds_read2st64_b32 v[14:15], v239 offset0:50 offset1:51
	ds_read2st64_b32 v[16:17], v239 offset0:52 offset1:53
	ds_read2st64_b32 v[18:19], v239 offset0:54 offset1:55
	ds_read2st64_b32 v[20:21], v239 offset0:56 offset1:57
	ds_read2st64_b32 v[22:23], v239 offset0:58 offset1:59
	ds_read2st64_b32 v[24:25], v239 offset0:60 offset1:61
	ds_read2st64_b32 v[26:27], v239 offset0:62 offset1:63
	ds_read2st64_b32 v[28:29], v239 offset0:64 offset1:65
	ds_read2st64_b32 v[30:31], v239 offset0:66 offset1:67
	ds_read_u16 v48, v240 offset:6912
	ds_read_u16 v49, v240 offset:7056
	ds_read_u16 v50, v240 offset:7200
	ds_read_u16 v51, v240 offset:7344
	ds_read_u16 v52, v240 offset:7488
	ds_read_u16 v53, v240 offset:7632
	ds_read_u16 v54, v240 offset:7776
	ds_read_u16 v55, v240 offset:7920
	ds_read_u16 v56, v240 offset:8064
	ds_read_u16 v57, v240 offset:8208
	ds_read_u16 v58, v240 offset:8352
	ds_read_u16 v59, v240 offset:8496
	ds_read_u16 v60, v240 offset:8640
	ds_read_u16 v61, v240 offset:8784
	ds_read_u16 v62, v240 offset:8928
	ds_read_u16 v63, v240 offset:9072
	s_add_u32 s90, s92, 0x20000
	s_addc_u32 s91, s93, 0
	global_load_dwordx4 v[80:83], v241, s[90:91]
	global_load_dwordx4 v[84:87], v241, s[90:91] offset:64
	global_load_dwordx4 v[88:91], v241, s[90:91] offset:2048
	global_load_dwordx4 v[92:95], v241, s[90:91] offset:2112
	s_add_u32 s90, s92, 0x21000
	s_addc_u32 s91, s93, 0
	global_load_dwordx4 v[96:99], v241, s[90:91]
	global_load_dwordx4 v[100:103], v241, s[90:91] offset:64
	global_load_dwordx4 v[104:107], v241, s[90:91] offset:2048
	global_load_dwordx4 v[108:111], v241, s[90:91] offset:2112
	s_add_u32 s90, s92, 0x30000
	s_addc_u32 s91, s93, 0
	global_load_dwordx4 v[112:115], v241, s[90:91]
	global_load_dwordx4 v[148:151], v241, s[90:91] offset:64
	global_load_dwordx4 v[120:123], v241, s[90:91] offset:2048
	global_load_dwordx4 v[124:127], v241, s[90:91] offset:2112
	s_add_u32 s90, s92, 0x31000
	s_addc_u32 s91, s93, 0
	global_load_dwordx4 v[128:131], v241, s[90:91]
	global_load_dwordx4 v[132:135], v241, s[90:91] offset:64
	global_load_dwordx4 v[136:139], v241, s[90:91] offset:2048
	global_load_dwordx4 v[228:231], v241, s[90:91] offset:2112
	s_waitcnt lgkmcnt(0)
	v_pk_add_f32 v[0:1], v[242:243], v[0:1]
	v_pk_add_f32 v[2:3], v[242:243], v[2:3]
	v_pk_add_f32 v[4:5], v[242:243], v[4:5]
	v_pk_add_f32 v[6:7], v[242:243], v[6:7]
	v_pk_add_f32 v[8:9], v[242:243], v[8:9]
	v_pk_add_f32 v[10:11], v[242:243], v[10:11]
	v_pk_add_f32 v[12:13], v[242:243], v[12:13]
	v_pk_add_f32 v[14:15], v[242:243], v[14:15]
	v_pk_add_f32 v[16:17], v[244:245], v[16:17]
	v_pk_add_f32 v[18:19], v[244:245], v[18:19]
	v_pk_add_f32 v[20:21], v[244:245], v[20:21]
	v_pk_add_f32 v[22:23], v[244:245], v[22:23]
	v_pk_add_f32 v[24:25], v[244:245], v[24:25]
	v_pk_add_f32 v[26:27], v[244:245], v[26:27]
	v_pk_add_f32 v[28:29], v[244:245], v[28:29]
	v_pk_add_f32 v[30:31], v[244:245], v[30:31]
	v_pk_mul_f32 v[0:1], v[248:249], v[0:1]
	v_pk_mul_f32 v[2:3], v[248:249], v[2:3]
	v_pk_mul_f32 v[4:5], v[248:249], v[4:5]
	v_pk_mul_f32 v[6:7], v[248:249], v[6:7]
	v_pk_mul_f32 v[8:9], v[248:249], v[8:9]
	v_pk_mul_f32 v[10:11], v[248:249], v[10:11]
	v_pk_mul_f32 v[12:13], v[248:249], v[12:13]
	v_pk_mul_f32 v[14:15], v[248:249], v[14:15]
	v_pk_mul_f32 v[16:17], v[248:249], v[16:17]
	v_pk_mul_f32 v[18:19], v[248:249], v[18:19]
	v_pk_mul_f32 v[20:21], v[248:249], v[20:21]
	v_pk_mul_f32 v[22:23], v[248:249], v[22:23]
	v_pk_mul_f32 v[24:25], v[248:249], v[24:25]
	v_pk_mul_f32 v[26:27], v[248:249], v[26:27]
	v_pk_mul_f32 v[28:29], v[248:249], v[28:29]
	v_pk_mul_f32 v[30:31], v[248:249], v[30:31]
	v_exp_f32_e32 v0, v0
	v_exp_f32_e32 v1, v1
	v_exp_f32_e32 v2, v2
	v_exp_f32_e32 v3, v3
	v_exp_f32_e32 v4, v4
	v_exp_f32_e32 v5, v5
	v_exp_f32_e32 v6, v6
	v_exp_f32_e32 v7, v7
	v_exp_f32_e32 v8, v8
	v_exp_f32_e32 v9, v9
	v_exp_f32_e32 v10, v10
	v_exp_f32_e32 v11, v11
	v_exp_f32_e32 v12, v12
	v_exp_f32_e32 v13, v13
	v_exp_f32_e32 v14, v14
	v_exp_f32_e32 v15, v15
	v_exp_f32_e32 v16, v16
	v_exp_f32_e32 v17, v17
	v_exp_f32_e32 v18, v18
	v_exp_f32_e32 v19, v19
	v_exp_f32_e32 v20, v20
	v_exp_f32_e32 v21, v21
	v_exp_f32_e32 v22, v22
	v_exp_f32_e32 v23, v23
	v_exp_f32_e32 v24, v24
	v_exp_f32_e32 v25, v25
	v_exp_f32_e32 v26, v26
	v_exp_f32_e32 v27, v27
	v_exp_f32_e32 v28, v28
	v_exp_f32_e32 v29, v29
	v_exp_f32_e32 v30, v30
	v_exp_f32_e32 v31, v31
	v_pk_add_f32 v[0:1], v[0:1], 1.0 op_sel_hi:[1,0]
	v_pk_add_f32 v[2:3], v[2:3], 1.0 op_sel_hi:[1,0]
	v_pk_add_f32 v[4:5], v[4:5], 1.0 op_sel_hi:[1,0]
	v_pk_add_f32 v[6:7], v[6:7], 1.0 op_sel_hi:[1,0]
	v_pk_add_f32 v[8:9], v[8:9], 1.0 op_sel_hi:[1,0]
	v_pk_add_f32 v[10:11], v[10:11], 1.0 op_sel_hi:[1,0]
	v_pk_add_f32 v[12:13], v[12:13], 1.0 op_sel_hi:[1,0]
	v_pk_add_f32 v[14:15], v[14:15], 1.0 op_sel_hi:[1,0]
	v_pk_add_f32 v[16:17], v[16:17], 1.0 op_sel_hi:[1,0]
	v_pk_add_f32 v[18:19], v[18:19], 1.0 op_sel_hi:[1,0]
	v_pk_add_f32 v[20:21], v[20:21], 1.0 op_sel_hi:[1,0]
	v_pk_add_f32 v[22:23], v[22:23], 1.0 op_sel_hi:[1,0]
	v_pk_add_f32 v[24:25], v[24:25], 1.0 op_sel_hi:[1,0]
	v_pk_add_f32 v[26:27], v[26:27], 1.0 op_sel_hi:[1,0]
	v_pk_add_f32 v[28:29], v[28:29], 1.0 op_sel_hi:[1,0]
	v_pk_add_f32 v[30:31], v[30:31], 1.0 op_sel_hi:[1,0]
	v_rcp_f32_e32 v0, v0
	v_rcp_f32_e32 v1, v1
	v_rcp_f32_e32 v2, v2
	v_rcp_f32_e32 v3, v3
; __device__ __forceinline__ unsigned f2bf(float f) { unsigned r; asm("v_cvt_pk_bf16_f32 %0, %1, %1" : "=v"(r) : "v"(f)); return r & 0xffffu; }
; __device__ __forceinline__ float sigmoid_f(float x) { return rcpf_(1.f + __expf(-x)); }
; __device__ __forceinline__ float gelu_tanh_f(float x) { const float y = 0.7978845608028654f * (x + 0.044715f * x * x * x); return x * sigmoid_f(2.f * y); }
; template <bool FINAL, int D>
; __device__ __forceinline__ void rg_dir(PREF p, int l, int h, int ch, int sidx, int rowbase  , LAS bf16_t* sXc, LAS float* stg, int lane) {
;     ...
;         for (int ti = 0; ti < 16; ++ti) { const int tk = D ? 15 - ti : ti;
;             const float zr = stg[tk * 64 + lane] + ba, zi = stg[1024 + tk * 64 + lane] + bi;
;             const float r = sigmoid_f(zr), ig = sigmoid_f(zi);
;             const float a = __builtin_amdgcn_exp2f(r * sp8);
;             const float xc = bf2f(sXc[(mt * 16 + tk) * 72 + lane]);
;             av[ti] = a; iv[ti] = __builtin_amdgcn_sqrtf(fmaxf(1.f - a * a, 0.f)) * ig * xc;
;             if (FINAL && D == 1) grv[ti] = gelu_tanh_f(grv[ti]);
;         }
; #pragma unroll
;         for (int ti = 0; ti < 16; ++ti) { const int tk = D ? 15 - ti : ti;
;             hc = av[ti] * hc + iv[ti]; Ap *= av[ti];
;             if (FINAL) { const size_t row = (size_t)(rowbase + mt * 16 + tk);
;                 if (D == 0) TMP[row * 512 + ch] = (bf16_t)f2bf(hc);
;                 else MIX[row * DM + ch] = (bf16_t)f2bf(grv[ti] * (hfv[ti] + hc)); }
;         }
;     }
;     if (!FINAL) { RGA[sidx] = Ap; RGH[sidx] = hc; }
	v_rcp_f32_e32 v4, v4
	v_rcp_f32_e32 v5, v5
	v_rcp_f32_e32 v6, v6
	v_rcp_f32_e32 v7, v7
	v_rcp_f32_e32 v8, v8
	v_rcp_f32_e32 v9, v9
	v_rcp_f32_e32 v10, v10
	v_rcp_f32_e32 v11, v11
	v_rcp_f32_e32 v12, v12
	v_rcp_f32_e32 v13, v13
	v_rcp_f32_e32 v14, v14
	v_rcp_f32_e32 v15, v15
	v_rcp_f32_e32 v16, v16
	v_rcp_f32_e32 v17, v17
	v_rcp_f32_e32 v18, v18
	v_rcp_f32_e32 v19, v19
	v_rcp_f32_e32 v20, v20
	v_rcp_f32_e32 v21, v21
	v_rcp_f32_e32 v22, v22
	v_rcp_f32_e32 v23, v23
	v_rcp_f32_e32 v24, v24
	v_rcp_f32_e32 v25, v25
	v_rcp_f32_e32 v26, v26
	v_rcp_f32_e32 v27, v27
	v_rcp_f32_e32 v28, v28
	v_rcp_f32_e32 v29, v29
	v_rcp_f32_e32 v30, v30
	v_rcp_f32_e32 v31, v31
	v_pk_mul_f32 v[0:1], v[246:247], v[0:1]
	v_pk_mul_f32 v[2:3], v[246:247], v[2:3]
	v_pk_mul_f32 v[4:5], v[246:247], v[4:5]
	v_pk_mul_f32 v[6:7], v[246:247], v[6:7]
	v_pk_mul_f32 v[8:9], v[246:247], v[8:9]
	v_pk_mul_f32 v[10:11], v[246:247], v[10:11]
	v_pk_mul_f32 v[12:13], v[246:247], v[12:13]
	v_pk_mul_f32 v[14:15], v[246:247], v[14:15]
	v_lshlrev_b32_e32 v48, 16, v48
	v_lshlrev_b32_e32 v49, 16, v49
	v_lshlrev_b32_e32 v50, 16, v50
	v_lshlrev_b32_e32 v51, 16, v51
	v_lshlrev_b32_e32 v52, 16, v52
	v_lshlrev_b32_e32 v53, 16, v53
	v_lshlrev_b32_e32 v54, 16, v54
	v_lshlrev_b32_e32 v55, 16, v55
	v_lshlrev_b32_e32 v56, 16, v56
	v_lshlrev_b32_e32 v57, 16, v57
	v_lshlrev_b32_e32 v58, 16, v58
	v_lshlrev_b32_e32 v59, 16, v59
	v_lshlrev_b32_e32 v60, 16, v60
	v_lshlrev_b32_e32 v61, 16, v61
	v_lshlrev_b32_e32 v62, 16, v62
	v_lshlrev_b32_e32 v63, 16, v63
	v_exp_f32_e32 v0, v0
	v_exp_f32_e32 v1, v1
	v_exp_f32_e32 v2, v2
	v_exp_f32_e32 v3, v3
	v_exp_f32_e32 v4, v4
	v_exp_f32_e32 v5, v5
	v_exp_f32_e32 v6, v6
	v_exp_f32_e32 v7, v7
	v_exp_f32_e32 v8, v8
	v_exp_f32_e32 v9, v9
	v_exp_f32_e32 v10, v10
	v_exp_f32_e32 v11, v11
	v_exp_f32_e32 v12, v12
	v_exp_f32_e32 v13, v13
	v_exp_f32_e32 v14, v14
	v_exp_f32_e32 v15, v15
	v_fma_f32 v32, -v0, v0, 1.0
	v_fma_f32 v33, -v1, v1, 1.0
	v_fma_f32 v34, -v2, v2, 1.0
	v_fma_f32 v35, -v3, v3, 1.0
	v_fma_f32 v36, -v4, v4, 1.0
	v_fma_f32 v37, -v5, v5, 1.0
	v_fma_f32 v38, -v6, v6, 1.0
	v_fma_f32 v39, -v7, v7, 1.0
	v_fma_f32 v40, -v8, v8, 1.0
	v_fma_f32 v41, -v9, v9, 1.0
	v_fma_f32 v42, -v10, v10, 1.0
	v_fma_f32 v43, -v11, v11, 1.0
	v_fma_f32 v44, -v12, v12, 1.0
	v_fma_f32 v45, -v13, v13, 1.0
	v_fma_f32 v46, -v14, v14, 1.0
	v_fma_f32 v47, -v15, v15, 1.0
	v_max_f32_e32 v32, 0, v32
	v_max_f32_e32 v33, 0, v33
	v_max_f32_e32 v34, 0, v34
	v_max_f32_e32 v35, 0, v35
	v_max_f32_e32 v36, 0, v36
	v_max_f32_e32 v37, 0, v37
	v_max_f32_e32 v38, 0, v38
	v_max_f32_e32 v39, 0, v39
	v_max_f32_e32 v40, 0, v40
	v_max_f32_e32 v41, 0, v41
	v_max_f32_e32 v42, 0, v42
	v_max_f32_e32 v43, 0, v43
	v_max_f32_e32 v44, 0, v44
	v_max_f32_e32 v45, 0, v45
	v_max_f32_e32 v46, 0, v46
	v_max_f32_e32 v47, 0, v47
	v_sqrt_f32_e32 v32, v32
	v_sqrt_f32_e32 v33, v33
	v_sqrt_f32_e32 v34, v34
	v_sqrt_f32_e32 v35, v35
	v_sqrt_f32_e32 v36, v36
	v_sqrt_f32_e32 v37, v37
	v_sqrt_f32_e32 v38, v38
	v_sqrt_f32_e32 v39, v39
	v_sqrt_f32_e32 v40, v40
	v_sqrt_f32_e32 v41, v41
	v_sqrt_f32_e32 v42, v42
	v_sqrt_f32_e32 v43, v43
	v_sqrt_f32_e32 v44, v44
	v_sqrt_f32_e32 v45, v45
	v_sqrt_f32_e32 v46, v46
	v_sqrt_f32_e32 v47, v47
	s_nop 0
	v_pk_mul_f32 v[16:17], v[16:17], v[32:33]
	v_pk_mul_f32 v[18:19], v[18:19], v[34:35]
	v_pk_mul_f32 v[20:21], v[20:21], v[36:37]
	v_pk_mul_f32 v[22:23], v[22:23], v[38:39]
	v_pk_mul_f32 v[24:25], v[24:25], v[40:41]
	v_pk_mul_f32 v[26:27], v[26:27], v[42:43]
	v_pk_mul_f32 v[28:29], v[28:29], v[44:45]
	v_pk_mul_f32 v[30:31], v[30:31], v[46:47]
	v_pk_mul_f32 v[16:17], v[16:17], v[48:49]
	v_pk_mul_f32 v[18:19], v[18:19], v[50:51]
	v_pk_mul_f32 v[20:21], v[20:21], v[52:53]
	v_pk_mul_f32 v[22:23], v[22:23], v[54:55]
	v_pk_mul_f32 v[24:25], v[24:25], v[56:57]
	v_pk_mul_f32 v[26:27], v[26:27], v[58:59]
	v_pk_mul_f32 v[28:29], v[28:29], v[60:61]
	v_pk_mul_f32 v[30:31], v[30:31], v[62:63]
	v_fma_f32 v32, v0, v250, v16
	v_mul_f32_e32 v232, v232, v0
	v_fma_f32 v250, v1, v32, v17
	v_mul_f32_e32 v232, v232, v1
	v_fma_f32 v32, v2, v250, v18
	v_mul_f32_e32 v232, v232, v2
	v_fma_f32 v250, v3, v32, v19
	v_mul_f32_e32 v232, v232, v3
	v_fma_f32 v32, v4, v250, v20
	v_mul_f32_e32 v232, v232, v4
	v_fma_f32 v250, v5, v32, v21
	v_mul_f32_e32 v232, v232, v5
	v_fma_f32 v32, v6, v250, v22
	v_mul_f32_e32 v232, v232, v6
	v_fma_f32 v250, v7, v32, v23
	v_mul_f32_e32 v232, v232, v7
	v_fma_f32 v32, v8, v250, v24
	v_mul_f32_e32 v232, v232, v8
	v_fma_f32 v250, v9, v32, v25
	v_mul_f32_e32 v232, v232, v9
	v_fma_f32 v32, v10, v250, v26
	v_mul_f32_e32 v232, v232, v10
	v_fma_f32 v250, v11, v32, v27
	v_mul_f32_e32 v232, v232, v11
	v_fma_f32 v32, v12, v250, v28
	v_mul_f32_e32 v232, v232, v12
	v_fma_f32 v250, v13, v32, v29
	v_mul_f32_e32 v232, v232, v13
	v_fma_f32 v32, v14, v250, v30
	v_mul_f32_e32 v232, v232, v14
	v_fma_f32 v250, v15, v32, v31
	v_mul_f32_e32 v232, v232, v15
	s_add_u32 s96, s0, 0x400000
	s_addc_u32 s97, s1, 0
	s_add_u32 s96, s96, s36
	s_addc_u32 s97, s97, 0
	global_store_dword v235, v232, s[96:97]
	s_add_u32 s96, s96, 0x300000
	s_addc_u32 s97, s97, 0
	global_store_dword v235, v250, s[96:97]
	global_load_dword v45, v235, s[76:77] offset:2048
	global_load_dword v46, v235, s[78:79] offset:2048
	global_load_dword v47, v235, s[80:81] offset:2048
	s_waitcnt vmcnt(0)
; template <bool FINAL, int D>
; __device__ __forceinline__ void rg_dir(PREF p, int l, int h, int ch, int sidx, int rowbase  , LAS bf16_t* sXc, LAS float* stg, int lane) {
;     ...
;     const float ba = p.rg_ba[(l * 2 + D) * 512 + ch], bi = p.rg_bi[(l * 2 + D) * 512 + ch], lam = p.rg_lam[(l * 2 + D) * 512 + ch];
;     const float e_ = __expf(-lam), u_ = 1.f + e_;
;     const float l1p = (u_ == 1.f) ? e_ : __logf(u_) * e_ * rcpf_(u_ - 1.f);
;     const float sp8 = -8.f * 1.4426950408889634f * l1p;
;     float hc = FINAL ? RGC[sidx] : 0.f, Ap = 1.f;
;     bf16x8 Br[4][2], Bi[4][2];
; #pragma unroll
;     for (int nt = 0; nt < 4; ++nt) { const int o0 = (nt * 16 + (lane & 15)) * 64 + (lane >> 4) * 8;
;         Br[nt][0] = *(const bf16x8*)(wr_ + o0); Br[nt][1] = *(const bf16x8*)(wr_ + o0 + 32); Bi[nt][0] = *(const bf16x8*)(wi_ + o0); Bi[nt][1] = *(const bf16x8*)(wi_ + o0 + 32); }
;     if (FINAL && D == 1) asm volatile("s_waitcnt vmcnt(0)" ::: "memory");
; #pragma unroll 1
;     for (int mi = 0; mi < 4; ++mi) { const int mt = D ? 3 - mi : mi;
;         float grv[16], hfv[16];
;         if (FINAL && D == 1) {
; #pragma unroll
;             for (int ti = 0; ti < 16; ++ti) { const size_t row = (size_t)(rowbase + mt * 16 + 15 - ti); grv[ti] = __builtin_bit_cast(float, (unsigned)P[row * PW + 512 + ch]); hfv[ti] = __builtin_bit_cast(float, (unsigned)TMP[row * 512 + ch]); }
;             __builtin_amdgcn_sched_barrier(0);
; #pragma unroll
;             for (int ti = 0; ti < 16; ++ti) { grv[ti] = bf2f(__builtin_bit_cast(unsigned, grv[ti])); hfv[ti] = bf2f(__builtin_bit_cast(unsigned, hfv[ti])); }
;         }
;         const bf16x8 A0 = *(const LAS bf16x8*)(sXc + (mt * 16 + (lane & 15)) * 72 + (lane >> 4) * 8), A1 = *(const LAS bf16x8*)(sXc + (mt * 16 + (lane & 15)) * 72 + 32 + (lane >> 4) * 8);
;         f32x4 ar[4], ai[4];
; #pragma unroll
;         for (int nt = 0; nt < 4; ++nt) { const f32x4 z = {0.f, 0.f, 0.f, 0.f};
;             ar[nt] = mfma16(A0, Br[nt][0], z); ar[nt] = mfma16(A1, Br[nt][1], ar[nt]); ai[nt] = mfma16(A0, Bi[nt][0], z); ai[nt] = mfma16(A1, Bi[nt][1], ai[nt]); }
;         WAVE_SYNC();
; #pragma unroll
;         for (int nt = 0; nt < 4; ++nt)
; #pragma unroll
;             for (int j = 0; j < 4; ++j) { const int o = ((lane >> 4) * 4 + j) * 64 + nt * 16 + (lane & 15); stg[o] = ar[nt][j]; stg[1024 + o] = ai[nt][j]; }
;         WAVE_SYNC();
	s_mov_b32 s8, 0x800000
	s_mov_b32 s9, 0x3f317217
	s_mov_b32 s14, 0x7f800000
	v_mul_f32_e32 v32, 0xbfb8aa3b, v45
	v_exp_f32_e32 v32, v32
	s_nop 0
	v_add_f32_e32 v33, 1.0, v32
	v_cmp_gt_f32_e32 vcc, s8, v33
	s_nop 1
	v_cndmask_b32_e64 v34, 0, 32, vcc
	v_ldexp_f32 v34, v33, v34
	v_log_f32_e32 v34, v34
	v_cndmask_b32_e32 v36, 0, v226, vcc
	v_cmp_eq_f32_e32 vcc, 1.0, v33
	v_mul_f32_e32 v35, 0x3f317217, v34
	v_fma_f32 v35, v34, s9, -v35
	v_fmac_f32_e32 v35, 0x3377d1cf, v34
	v_fmac_f32_e32 v35, 0x3f317217, v34
	v_cmp_lt_f32_e64 s[10:11], |v34|, s14
	s_nop 1
	v_cndmask_b32_e64 v34, v34, v35, s[10:11]
	v_add_f32_e32 v35, -1.0, v33
	v_rcp_f32_e32 v35, v35
	v_sub_f32_e32 v34, v34, v36
	v_mul_f32_e32 v34, v32, v34
	v_mul_f32_e32 v34, v34, v35
	v_cndmask_b32_e32 v32, v34, v32, vcc
	v_mul_f32_e32 v246, 0xc138aa3b, v32
	v_mov_b32_e32 v247, v246
	v_mov_b32_e32 v242, v46
	v_mov_b32_e32 v243, v46
	v_mov_b32_e32 v244, v47
	v_mov_b32_e32 v245, v47
	v_mov_b32_e32 v250, 0
	v_mov_b32_e32 v232, 1.0
	ds_read_b128 v[32:35], v236 offset:6912
	ds_read_b128 v[36:39], v236 offset:6976
	s_waitcnt lgkmcnt(0)
	v_mfma_f32_16x16x32_bf16 v[0:3], v[32:35], v[80:83], 0
	v_mfma_f32_16x16x32_bf16 v[4:7], v[32:35], v[88:91], 0
	v_mfma_f32_16x16x32_bf16 v[8:11], v[32:35], v[96:99], 0
	v_mfma_f32_16x16x32_bf16 v[12:15], v[32:35], v[104:107], 0
	v_mfma_f32_16x16x32_bf16 v[16:19], v[32:35], v[112:115], 0
	v_mfma_f32_16x16x32_bf16 v[20:23], v[32:35], v[120:123], 0
	v_mfma_f32_16x16x32_bf16 v[24:27], v[32:35], v[128:131], 0
	v_mfma_f32_16x16x32_bf16 v[28:31], v[32:35], v[136:139], 0
	v_mfma_f32_16x16x32_bf16 v[0:3], v[36:39], v[84:87], v[0:3]
	v_mfma_f32_16x16x32_bf16 v[4:7], v[36:39], v[92:95], v[4:7]
	v_mfma_f32_16x16x32_bf16 v[8:11], v[36:39], v[100:103], v[8:11]
	v_mfma_f32_16x16x32_bf16 v[12:15], v[36:39], v[108:111], v[12:15]
	v_mfma_f32_16x16x32_bf16 v[16:19], v[36:39], v[148:151], v[16:19]
	v_mfma_f32_16x16x32_bf16 v[20:23], v[36:39], v[124:127], v[20:23]
	v_mfma_f32_16x16x32_bf16 v[24:27], v[36:39], v[132:135], v[24:27]
	v_mfma_f32_16x16x32_bf16 v[28:31], v[36:39], v[228:231], v[28:31]
	s_nop 3
	ds_write2_b32 v237, v0, v4 offset0:0 offset1:16
	ds_write2_b32 v237, v8, v12 offset0:32 offset1:48
	ds_write2_b32 v237, v1, v5 offset0:64 offset1:80
	ds_write2_b32 v237, v9, v13 offset0:96 offset1:112
	ds_write2_b32 v237, v2, v6 offset0:128 offset1:144
	ds_write2_b32 v237, v10, v14 offset0:160 offset1:176
	ds_write2_b32 v237, v3, v7 offset0:192 offset1:208
	ds_write2_b32 v237, v11, v15 offset0:224 offset1:240
	ds_write2_b32 v238, v16, v20 offset0:0 offset1:16
	ds_write2_b32 v238, v24, v28 offset0:32 offset1:48
	ds_write2_b32 v238, v17, v21 offset0:64 offset1:80
	ds_write2_b32 v238, v25, v29 offset0:96 offset1:112
	ds_write2_b32 v238, v18, v22 offset0:128 offset1:144
	ds_write2_b32 v238, v26, v30 offset0:160 offset1:176
	ds_write2_b32 v238, v19, v23 offset0:192 offset1:208
	ds_write2_b32 v238, v27, v31 offset0:224 offset1:240
	s_waitcnt lgkmcnt(0)
	ds_read2st64_b32 v[0:1], v239 offset0:36 offset1:37
	ds_read2st64_b32 v[2:3], v239 offset0:38 offset1:39
	ds_read2st64_b32 v[4:5], v239 offset0:40 offset1:41
	ds_read2st64_b32 v[6:7], v239 offset0:42 offset1:43
	ds_read2st64_b32 v[8:9], v239 offset0:44 offset1:45
	ds_read2st64_b32 v[10:11], v239 offset0:46 offset1:47
	ds_read2st64_b32 v[12:13], v239 offset0:48 offset1:49
	ds_read2st64_b32 v[14:15], v239 offset0:50 offset1:51
	ds_read2st64_b32 v[16:17], v239 offset0:52 offset1:53
	ds_read2st64_b32 v[18:19], v239 offset0:54 offset1:55
	ds_read2st64_b32 v[20:21], v239 offset0:56 offset1:57
	ds_read2st64_b32 v[22:23], v239 offset0:58 offset1:59
	ds_read2st64_b32 v[24:25], v239 offset0:60 offset1:61
	ds_read2st64_b32 v[26:27], v239 offset0:62 offset1:63
	ds_read2st64_b32 v[28:29], v239 offset0:64 offset1:65
	ds_read2st64_b32 v[30:31], v239 offset0:66 offset1:67
	ds_read_u16 v48, v240 offset:6912
	ds_read_u16 v49, v240 offset:7056
	ds_read_u16 v50, v240 offset:7200
	ds_read_u16 v51, v240 offset:7344
	ds_read_u16 v52, v240 offset:7488
	ds_read_u16 v53, v240 offset:7632
	ds_read_u16 v54, v240 offset:7776
	ds_read_u16 v55, v240 offset:7920
	ds_read_u16 v56, v240 offset:8064
	ds_read_u16 v57, v240 offset:8208
	ds_read_u16 v58, v240 offset:8352
	ds_read_u16 v59, v240 offset:8496
	ds_read_u16 v60, v240 offset:8640
	ds_read_u16 v61, v240 offset:8784
	ds_read_u16 v62, v240 offset:8928
	ds_read_u16 v63, v240 offset:9072
	s_waitcnt lgkmcnt(0)
; __device__ __forceinline__ float sigmoid_f(float x) { return rcpf_(1.f + __expf(-x)); }
; template <bool FINAL, int D>
; __device__ __forceinline__ void rg_dir(PREF p, int l, int h, int ch, int sidx, int rowbase  , LAS bf16_t* sXc, LAS float* stg, int lane) {
;     ...
;         float av[16], iv[16];
; #pragma unroll
;         for (int ti = 0; ti < 16; ++ti) { const int tk = D ? 15 - ti : ti;
;             const float zr = stg[tk * 64 + lane] + ba, zi = stg[1024 + tk * 64 + lane] + bi;
;             const float r = sigmoid_f(zr), ig = sigmoid_f(zi);
;             const float a = __builtin_amdgcn_exp2f(r * sp8);
;             const float xc = bf2f(sXc[(mt * 16 + tk) * 72 + lane]);
;             av[ti] = a; iv[ti] = __builtin_amdgcn_sqrtf(fmaxf(1.f - a * a, 0.f)) * ig * xc;
	v_pk_add_f32 v[0:1], v[242:243], v[0:1]
	v_pk_add_f32 v[2:3], v[242:243], v[2:3]
	v_pk_add_f32 v[4:5], v[242:243], v[4:5]
	v_pk_add_f32 v[6:7], v[242:243], v[6:7]
	v_pk_add_f32 v[8:9], v[242:243], v[8:9]
	v_pk_add_f32 v[10:11], v[242:243], v[10:11]
	v_pk_add_f32 v[12:13], v[242:243], v[12:13]
	v_pk_add_f32 v[14:15], v[242:243], v[14:15]
	v_pk_add_f32 v[16:17], v[244:245], v[16:17]
	v_pk_add_f32 v[18:19], v[244:245], v[18:19]
	v_pk_add_f32 v[20:21], v[244:245], v[20:21]
	v_pk_add_f32 v[22:23], v[244:245], v[22:23]
	v_pk_add_f32 v[24:25], v[244:245], v[24:25]
	v_pk_add_f32 v[26:27], v[244:245], v[26:27]
	v_pk_add_f32 v[28:29], v[244:245], v[28:29]
	v_pk_add_f32 v[30:31], v[244:245], v[30:31]
	v_pk_mul_f32 v[0:1], v[248:249], v[0:1]
	v_pk_mul_f32 v[2:3], v[248:249], v[2:3]
	v_pk_mul_f32 v[4:5], v[248:249], v[4:5]
	v_pk_mul_f32 v[6:7], v[248:249], v[6:7]
	v_pk_mul_f32 v[8:9], v[248:249], v[8:9]
	v_pk_mul_f32 v[10:11], v[248:249], v[10:11]
	v_pk_mul_f32 v[12:13], v[248:249], v[12:13]
	v_pk_mul_f32 v[14:15], v[248:249], v[14:15]
	v_pk_mul_f32 v[16:17], v[248:249], v[16:17]
	v_pk_mul_f32 v[18:19], v[248:249], v[18:19]
	v_pk_mul_f32 v[20:21], v[248:249], v[20:21]
	v_pk_mul_f32 v[22:23], v[248:249], v[22:23]
	v_pk_mul_f32 v[24:25], v[248:249], v[24:25]
	v_pk_mul_f32 v[26:27], v[248:249], v[26:27]
	v_pk_mul_f32 v[28:29], v[248:249], v[28:29]
	v_pk_mul_f32 v[30:31], v[248:249], v[30:31]
	v_exp_f32_e32 v0, v0
	v_exp_f32_e32 v1, v1
	v_exp_f32_e32 v2, v2
	v_exp_f32_e32 v3, v3
	v_exp_f32_e32 v4, v4
	v_exp_f32_e32 v5, v5
	v_exp_f32_e32 v6, v6
	v_exp_f32_e32 v7, v7
	v_exp_f32_e32 v8, v8
	v_exp_f32_e32 v9, v9
	v_exp_f32_e32 v10, v10
	v_exp_f32_e32 v11, v11
	v_exp_f32_e32 v12, v12
	v_exp_f32_e32 v13, v13
	v_exp_f32_e32 v14, v14
	v_exp_f32_e32 v15, v15
	v_exp_f32_e32 v16, v16
	v_exp_f32_e32 v17, v17
	v_exp_f32_e32 v18, v18
	v_exp_f32_e32 v19, v19
	v_exp_f32_e32 v20, v20
	v_exp_f32_e32 v21, v21
	v_exp_f32_e32 v22, v22
	v_exp_f32_e32 v23, v23
	v_exp_f32_e32 v24, v24
	v_exp_f32_e32 v25, v25
	v_exp_f32_e32 v26, v26
	v_exp_f32_e32 v27, v27
	v_exp_f32_e32 v28, v28
	v_exp_f32_e32 v29, v29
	v_exp_f32_e32 v30, v30
	v_exp_f32_e32 v31, v31
	v_pk_add_f32 v[0:1], v[0:1], 1.0 op_sel_hi:[1,0]
	v_pk_add_f32 v[2:3], v[2:3], 1.0 op_sel_hi:[1,0]
	v_pk_add_f32 v[4:5], v[4:5], 1.0 op_sel_hi:[1,0]
	v_pk_add_f32 v[6:7], v[6:7], 1.0 op_sel_hi:[1,0]
	v_pk_add_f32 v[8:9], v[8:9], 1.0 op_sel_hi:[1,0]
	v_pk_add_f32 v[10:11], v[10:11], 1.0 op_sel_hi:[1,0]
	v_pk_add_f32 v[12:13], v[12:13], 1.0 op_sel_hi:[1,0]
	v_pk_add_f32 v[14:15], v[14:15], 1.0 op_sel_hi:[1,0]
	v_pk_add_f32 v[16:17], v[16:17], 1.0 op_sel_hi:[1,0]
	v_pk_add_f32 v[18:19], v[18:19], 1.0 op_sel_hi:[1,0]
	v_pk_add_f32 v[20:21], v[20:21], 1.0 op_sel_hi:[1,0]
	v_pk_add_f32 v[22:23], v[22:23], 1.0 op_sel_hi:[1,0]
	v_pk_add_f32 v[24:25], v[24:25], 1.0 op_sel_hi:[1,0]
	v_pk_add_f32 v[26:27], v[26:27], 1.0 op_sel_hi:[1,0]
	v_pk_add_f32 v[28:29], v[28:29], 1.0 op_sel_hi:[1,0]
	v_pk_add_f32 v[30:31], v[30:31], 1.0 op_sel_hi:[1,0]
	v_rcp_f32_e32 v0, v0
	v_rcp_f32_e32 v1, v1
	v_rcp_f32_e32 v2, v2
	v_rcp_f32_e32 v3, v3
	v_rcp_f32_e32 v4, v4
	v_rcp_f32_e32 v5, v5
	v_rcp_f32_e32 v6, v6
	v_rcp_f32_e32 v7, v7
	v_rcp_f32_e32 v8, v8
	v_rcp_f32_e32 v9, v9
	v_rcp_f32_e32 v10, v10
	v_rcp_f32_e32 v11, v11
	v_rcp_f32_e32 v12, v12
	v_rcp_f32_e32 v13, v13
	v_rcp_f32_e32 v14, v14
	v_rcp_f32_e32 v15, v15
	v_rcp_f32_e32 v16, v16
	v_rcp_f32_e32 v17, v17
	v_rcp_f32_e32 v18, v18
	v_rcp_f32_e32 v19, v19
	v_rcp_f32_e32 v20, v20
	v_rcp_f32_e32 v21, v21
	v_rcp_f32_e32 v22, v22
	v_rcp_f32_e32 v23, v23
	v_rcp_f32_e32 v24, v24
	v_rcp_f32_e32 v25, v25
	v_rcp_f32_e32 v26, v26
	v_rcp_f32_e32 v27, v27
	v_rcp_f32_e32 v28, v28
	v_rcp_f32_e32 v29, v29
	v_rcp_f32_e32 v30, v30
	v_rcp_f32_e32 v31, v31
	v_pk_mul_f32 v[0:1], v[246:247], v[0:1]
	v_pk_mul_f32 v[2:3], v[246:247], v[2:3]
	v_pk_mul_f32 v[4:5], v[246:247], v[4:5]
	v_pk_mul_f32 v[6:7], v[246:247], v[6:7]
	v_pk_mul_f32 v[8:9], v[246:247], v[8:9]
	v_pk_mul_f32 v[10:11], v[246:247], v[10:11]
	v_pk_mul_f32 v[12:13], v[246:247], v[12:13]
	v_pk_mul_f32 v[14:15], v[246:247], v[14:15]
	v_lshlrev_b32_e32 v48, 16, v48
	v_lshlrev_b32_e32 v49, 16, v49
	v_lshlrev_b32_e32 v50, 16, v50
	v_lshlrev_b32_e32 v51, 16, v51
	v_lshlrev_b32_e32 v52, 16, v52
	v_lshlrev_b32_e32 v53, 16, v53
	v_lshlrev_b32_e32 v54, 16, v54
	v_lshlrev_b32_e32 v55, 16, v55
	v_lshlrev_b32_e32 v56, 16, v56
	v_lshlrev_b32_e32 v57, 16, v57
	v_lshlrev_b32_e32 v58, 16, v58
	v_lshlrev_b32_e32 v59, 16, v59
	v_lshlrev_b32_e32 v60, 16, v60
	v_lshlrev_b32_e32 v61, 16, v61
	v_lshlrev_b32_e32 v62, 16, v62
	v_lshlrev_b32_e32 v63, 16, v63
	v_exp_f32_e32 v0, v0
	v_exp_f32_e32 v1, v1
	v_exp_f32_e32 v2, v2
	v_exp_f32_e32 v3, v3
	v_exp_f32_e32 v4, v4
	v_exp_f32_e32 v5, v5
	v_exp_f32_e32 v6, v6
	v_exp_f32_e32 v7, v7
	v_exp_f32_e32 v8, v8
	v_exp_f32_e32 v9, v9
	v_exp_f32_e32 v10, v10
	v_exp_f32_e32 v11, v11
	v_exp_f32_e32 v12, v12
	v_exp_f32_e32 v13, v13
	v_exp_f32_e32 v14, v14
	v_exp_f32_e32 v15, v15
	v_fma_f32 v32, -v0, v0, 1.0
	v_fma_f32 v33, -v1, v1, 1.0
	v_fma_f32 v34, -v2, v2, 1.0
	v_fma_f32 v35, -v3, v3, 1.0
	v_fma_f32 v36, -v4, v4, 1.0
	v_fma_f32 v37, -v5, v5, 1.0
	v_fma_f32 v38, -v6, v6, 1.0
	v_fma_f32 v39, -v7, v7, 1.0
	v_fma_f32 v40, -v8, v8, 1.0
	v_fma_f32 v41, -v9, v9, 1.0
	v_fma_f32 v42, -v10, v10, 1.0
	v_fma_f32 v43, -v11, v11, 1.0
	v_fma_f32 v44, -v12, v12, 1.0
	v_fma_f32 v45, -v13, v13, 1.0
	v_fma_f32 v46, -v14, v14, 1.0
	v_fma_f32 v47, -v15, v15, 1.0
	v_max_f32_e32 v32, 0, v32
	v_max_f32_e32 v33, 0, v33
	v_max_f32_e32 v34, 0, v34
	v_max_f32_e32 v35, 0, v35
	v_max_f32_e32 v36, 0, v36
	v_max_f32_e32 v37, 0, v37
	v_max_f32_e32 v38, 0, v38
	v_max_f32_e32 v39, 0, v39
; #define LAS __attribute__((address_space(3)))
; #define WAVE_SYNC() asm volatile("s_waitcnt lgkmcnt(0)" ::: "memory")
; __device__ __forceinline__ float sigmoid_f(float x) { return rcpf_(1.f + __expf(-x)); }
; __device__ __forceinline__ float gelu_tanh_f(float x) { const float y = 0.7978845608028654f * (x + 0.044715f * x * x * x); return x * sigmoid_f(2.f * y); }
; __device__ __forceinline__ f32x4 mfma16(bf16x8 a, bf16x8 b, f32x4 c) { return __builtin_amdgcn_mfma_f32_16x16x32_bf16(a, b, c, 0, 0, 0); }
; template <bool FINAL, int D>
; __device__ __forceinline__ void rg_dir(PREF p, int l, int h, int ch, int sidx, int rowbase  , LAS bf16_t* sXc, LAS float* stg, int lane) {
;     ...
;         const bf16x8 A0 = *(const LAS bf16x8*)(sXc + (mt * 16 + (lane & 15)) * 72 + (lane >> 4) * 8), A1 = *(const LAS bf16x8*)(sXc + (mt * 16 + (lane & 15)) * 72 + 32 + (lane >> 4) * 8);
;         f32x4 ar[4], ai[4];
; #pragma unroll
;         for (int nt = 0; nt < 4; ++nt) { const f32x4 z = {0.f, 0.f, 0.f, 0.f};
;             ar[nt] = mfma16(A0, Br[nt][0], z); ar[nt] = mfma16(A1, Br[nt][1], ar[nt]); ai[nt] = mfma16(A0, Bi[nt][0], z); ai[nt] = mfma16(A1, Bi[nt][1], ai[nt]); }
;         WAVE_SYNC();
; #pragma unroll
;         for (int nt = 0; nt < 4; ++nt)
; #pragma unroll
;             for (int j = 0; j < 4; ++j) { const int o = ((lane >> 4) * 4 + j) * 64 + nt * 16 + (lane & 15); stg[o] = ar[nt][j]; stg[1024 + o] = ai[nt][j]; }
;         WAVE_SYNC();
;         float av[16], iv[16];
; #pragma unroll
;         for (int ti = 0; ti < 16; ++ti) { const int tk = D ? 15 - ti : ti;
;             const float zr = stg[tk * 64 + lane] + ba, zi = stg[1024 + tk * 64 + lane] + bi;
;             const float r = sigmoid_f(zr), ig = sigmoid_f(zi);
;             const float a = __builtin_amdgcn_exp2f(r * sp8);
;             const float xc = bf2f(sXc[(mt * 16 + tk) * 72 + lane]);
;             av[ti] = a; iv[ti] = __builtin_amdgcn_sqrtf(fmaxf(1.f - a * a, 0.f)) * ig * xc;
;             if (FINAL && D == 1) grv[ti] = gelu_tanh_f(grv[ti]);
;         }
; #pragma unroll
;         for (int ti = 0; ti < 16; ++ti) { const int tk = D ? 15 - ti : ti;
;             hc = av[ti] * hc + iv[ti]; Ap *= av[ti];
	v_max_f32_e32 v40, 0, v40
	v_max_f32_e32 v41, 0, v41
	v_max_f32_e32 v42, 0, v42
	v_max_f32_e32 v43, 0, v43
	v_max_f32_e32 v44, 0, v44
	v_max_f32_e32 v45, 0, v45
	v_max_f32_e32 v46, 0, v46
	v_max_f32_e32 v47, 0, v47
	v_sqrt_f32_e32 v32, v32
	v_sqrt_f32_e32 v33, v33
	v_sqrt_f32_e32 v34, v34
	v_sqrt_f32_e32 v35, v35
	v_sqrt_f32_e32 v36, v36
	v_sqrt_f32_e32 v37, v37
	v_sqrt_f32_e32 v38, v38
	v_sqrt_f32_e32 v39, v39
	v_sqrt_f32_e32 v40, v40
	v_sqrt_f32_e32 v41, v41
	v_sqrt_f32_e32 v42, v42
	v_sqrt_f32_e32 v43, v43
	v_sqrt_f32_e32 v44, v44
	v_sqrt_f32_e32 v45, v45
	v_sqrt_f32_e32 v46, v46
	v_sqrt_f32_e32 v47, v47
	s_nop 0
	v_pk_mul_f32 v[16:17], v[16:17], v[32:33]
	v_pk_mul_f32 v[18:19], v[18:19], v[34:35]
	v_pk_mul_f32 v[20:21], v[20:21], v[36:37]
	v_pk_mul_f32 v[22:23], v[22:23], v[38:39]
	v_pk_mul_f32 v[24:25], v[24:25], v[40:41]
	v_pk_mul_f32 v[26:27], v[26:27], v[42:43]
	v_pk_mul_f32 v[28:29], v[28:29], v[44:45]
	v_pk_mul_f32 v[30:31], v[30:31], v[46:47]
	v_pk_mul_f32 v[16:17], v[16:17], v[48:49]
	v_pk_mul_f32 v[18:19], v[18:19], v[50:51]
	v_pk_mul_f32 v[20:21], v[20:21], v[52:53]
	v_pk_mul_f32 v[22:23], v[22:23], v[54:55]
	v_pk_mul_f32 v[24:25], v[24:25], v[56:57]
	v_pk_mul_f32 v[26:27], v[26:27], v[58:59]
	v_pk_mul_f32 v[28:29], v[28:29], v[60:61]
	v_pk_mul_f32 v[30:31], v[30:31], v[62:63]
	v_fma_f32 v250, v15, v250, v31
	v_mul_f32_e32 v232, v232, v15
	v_fma_f32 v250, v14, v250, v30
	v_mul_f32_e32 v232, v232, v14
	v_fma_f32 v250, v13, v250, v29
	v_mul_f32_e32 v232, v232, v13
	v_fma_f32 v250, v12, v250, v28
	v_mul_f32_e32 v232, v232, v12
	v_fma_f32 v250, v11, v250, v27
	v_mul_f32_e32 v232, v232, v11
	v_fma_f32 v250, v10, v250, v26
	v_mul_f32_e32 v232, v232, v10
	v_fma_f32 v250, v9, v250, v25
	v_mul_f32_e32 v232, v232, v9
	v_fma_f32 v250, v8, v250, v24
	v_mul_f32_e32 v232, v232, v8
	v_fma_f32 v250, v7, v250, v23
	v_mul_f32_e32 v232, v232, v7
	v_fma_f32 v250, v6, v250, v22
	v_mul_f32_e32 v232, v232, v6
	v_fma_f32 v250, v5, v250, v21
	v_mul_f32_e32 v232, v232, v5
	v_fma_f32 v250, v4, v250, v20
	v_mul_f32_e32 v232, v232, v4
	v_fma_f32 v250, v3, v250, v19
	v_mul_f32_e32 v232, v232, v3
	v_fma_f32 v250, v2, v250, v18
	v_mul_f32_e32 v232, v232, v2
	v_fma_f32 v250, v1, v250, v17
	v_mul_f32_e32 v232, v232, v1
	v_fma_f32 v250, v0, v250, v16
	v_mul_f32_e32 v232, v232, v0
	ds_read_b128 v[32:35], v236 offset:4608
	ds_read_b128 v[36:39], v236 offset:4672
	s_waitcnt lgkmcnt(0)
	v_mfma_f32_16x16x32_bf16 v[0:3], v[32:35], v[80:83], 0
	v_mfma_f32_16x16x32_bf16 v[4:7], v[32:35], v[88:91], 0
	v_mfma_f32_16x16x32_bf16 v[8:11], v[32:35], v[96:99], 0
	v_mfma_f32_16x16x32_bf16 v[12:15], v[32:35], v[104:107], 0
	v_mfma_f32_16x16x32_bf16 v[16:19], v[32:35], v[112:115], 0
	v_mfma_f32_16x16x32_bf16 v[20:23], v[32:35], v[120:123], 0
	v_mfma_f32_16x16x32_bf16 v[24:27], v[32:35], v[128:131], 0
	v_mfma_f32_16x16x32_bf16 v[28:31], v[32:35], v[136:139], 0
	v_mfma_f32_16x16x32_bf16 v[0:3], v[36:39], v[84:87], v[0:3]
	v_mfma_f32_16x16x32_bf16 v[4:7], v[36:39], v[92:95], v[4:7]
	v_mfma_f32_16x16x32_bf16 v[8:11], v[36:39], v[100:103], v[8:11]
	v_mfma_f32_16x16x32_bf16 v[12:15], v[36:39], v[108:111], v[12:15]
	v_mfma_f32_16x16x32_bf16 v[16:19], v[36:39], v[148:151], v[16:19]
	v_mfma_f32_16x16x32_bf16 v[20:23], v[36:39], v[124:127], v[20:23]
	v_mfma_f32_16x16x32_bf16 v[24:27], v[36:39], v[132:135], v[24:27]
	v_mfma_f32_16x16x32_bf16 v[28:31], v[36:39], v[228:231], v[28:31]
	s_nop 3
	ds_write2_b32 v237, v0, v4 offset0:0 offset1:16
	ds_write2_b32 v237, v8, v12 offset0:32 offset1:48
	ds_write2_b32 v237, v1, v5 offset0:64 offset1:80
	ds_write2_b32 v237, v9, v13 offset0:96 offset1:112
	ds_write2_b32 v237, v2, v6 offset0:128 offset1:144
	ds_write2_b32 v237, v10, v14 offset0:160 offset1:176
	ds_write2_b32 v237, v3, v7 offset0:192 offset1:208
	ds_write2_b32 v237, v11, v15 offset0:224 offset1:240
	ds_write2_b32 v238, v16, v20 offset0:0 offset1:16
	ds_write2_b32 v238, v24, v28 offset0:32 offset1:48
	ds_write2_b32 v238, v17, v21 offset0:64 offset1:80
	ds_write2_b32 v238, v25, v29 offset0:96 offset1:112
	ds_write2_b32 v238, v18, v22 offset0:128 offset1:144
	ds_write2_b32 v238, v26, v30 offset0:160 offset1:176
	ds_write2_b32 v238, v19, v23 offset0:192 offset1:208
	ds_write2_b32 v238, v27, v31 offset0:224 offset1:240
	s_waitcnt lgkmcnt(0)
	ds_read2st64_b32 v[0:1], v239 offset0:36 offset1:37
	ds_read2st64_b32 v[2:3], v239 offset0:38 offset1:39
	ds_read2st64_b32 v[4:5], v239 offset0:40 offset1:41
	ds_read2st64_b32 v[6:7], v239 offset0:42 offset1:43
	ds_read2st64_b32 v[8:9], v239 offset0:44 offset1:45
	ds_read2st64_b32 v[10:11], v239 offset0:46 offset1:47
	ds_read2st64_b32 v[12:13], v239 offset0:48 offset1:49
	ds_read2st64_b32 v[14:15], v239 offset0:50 offset1:51
	ds_read2st64_b32 v[16:17], v239 offset0:52 offset1:53
	ds_read2st64_b32 v[18:19], v239 offset0:54 offset1:55
	ds_read2st64_b32 v[20:21], v239 offset0:56 offset1:57
	ds_read2st64_b32 v[22:23], v239 offset0:58 offset1:59
	ds_read2st64_b32 v[24:25], v239 offset0:60 offset1:61
	ds_read2st64_b32 v[26:27], v239 offset0:62 offset1:63
	ds_read2st64_b32 v[28:29], v239 offset0:64 offset1:65
	ds_read2st64_b32 v[30:31], v239 offset0:66 offset1:67
	ds_read_u16 v48, v240 offset:4608
	ds_read_u16 v49, v240 offset:4752
	ds_read_u16 v50, v240 offset:4896
	ds_read_u16 v51, v240 offset:5040
	ds_read_u16 v52, v240 offset:5184
	ds_read_u16 v53, v240 offset:5328
	ds_read_u16 v54, v240 offset:5472
	ds_read_u16 v55, v240 offset:5616
	ds_read_u16 v56, v240 offset:5760
	ds_read_u16 v57, v240 offset:5904
	ds_read_u16 v58, v240 offset:6048
	ds_read_u16 v59, v240 offset:6192
	ds_read_u16 v60, v240 offset:6336
	ds_read_u16 v61, v240 offset:6480
	ds_read_u16 v62, v240 offset:6624
	ds_read_u16 v63, v240 offset:6768
	s_waitcnt lgkmcnt(0)
; __device__ __forceinline__ float sigmoid_f(float x) { return rcpf_(1.f + __expf(-x)); }
; template <bool FINAL, int D>
; __device__ __forceinline__ void rg_dir(PREF p, int l, int h, int ch, int sidx, int rowbase  , LAS bf16_t* sXc, LAS float* stg, int lane) {
;     ...
;         float av[16], iv[16];
; #pragma unroll
;         for (int ti = 0; ti < 16; ++ti) { const int tk = D ? 15 - ti : ti;
;             const float zr = stg[tk * 64 + lane] + ba, zi = stg[1024 + tk * 64 + lane] + bi;
;             const float r = sigmoid_f(zr), ig = sigmoid_f(zi);
;             const float a = __builtin_amdgcn_exp2f(r * sp8);
;             const float xc = bf2f(sXc[(mt * 16 + tk) * 72 + lane]);
;             av[ti] = a; iv[ti] = __builtin_amdgcn_sqrtf(fmaxf(1.f - a * a, 0.f)) * ig * xc;
	v_pk_add_f32 v[0:1], v[242:243], v[0:1]
	v_pk_add_f32 v[2:3], v[242:243], v[2:3]
	v_pk_add_f32 v[4:5], v[242:243], v[4:5]
	v_pk_add_f32 v[6:7], v[242:243], v[6:7]
	v_pk_add_f32 v[8:9], v[242:243], v[8:9]
	v_pk_add_f32 v[10:11], v[242:243], v[10:11]
	v_pk_add_f32 v[12:13], v[242:243], v[12:13]
	v_pk_add_f32 v[14:15], v[242:243], v[14:15]
	v_pk_add_f32 v[16:17], v[244:245], v[16:17]
	v_pk_add_f32 v[18:19], v[244:245], v[18:19]
	v_pk_add_f32 v[20:21], v[244:245], v[20:21]
	v_pk_add_f32 v[22:23], v[244:245], v[22:23]
	v_pk_add_f32 v[24:25], v[244:245], v[24:25]
	v_pk_add_f32 v[26:27], v[244:245], v[26:27]
	v_pk_add_f32 v[28:29], v[244:245], v[28:29]
	v_pk_add_f32 v[30:31], v[244:245], v[30:31]
	v_pk_mul_f32 v[0:1], v[248:249], v[0:1]
	v_pk_mul_f32 v[2:3], v[248:249], v[2:3]
	v_pk_mul_f32 v[4:5], v[248:249], v[4:5]
	v_pk_mul_f32 v[6:7], v[248:249], v[6:7]
	v_pk_mul_f32 v[8:9], v[248:249], v[8:9]
	v_pk_mul_f32 v[10:11], v[248:249], v[10:11]
	v_pk_mul_f32 v[12:13], v[248:249], v[12:13]
	v_pk_mul_f32 v[14:15], v[248:249], v[14:15]
	v_pk_mul_f32 v[16:17], v[248:249], v[16:17]
	v_pk_mul_f32 v[18:19], v[248:249], v[18:19]
	v_pk_mul_f32 v[20:21], v[248:249], v[20:21]
	v_pk_mul_f32 v[22:23], v[248:249], v[22:23]
	v_pk_mul_f32 v[24:25], v[248:249], v[24:25]
	v_pk_mul_f32 v[26:27], v[248:249], v[26:27]
	v_pk_mul_f32 v[28:29], v[248:249], v[28:29]
	v_pk_mul_f32 v[30:31], v[248:249], v[30:31]
	v_exp_f32_e32 v0, v0
	v_exp_f32_e32 v1, v1
	v_exp_f32_e32 v2, v2
	v_exp_f32_e32 v3, v3
	v_exp_f32_e32 v4, v4
	v_exp_f32_e32 v5, v5
	v_exp_f32_e32 v6, v6
	v_exp_f32_e32 v7, v7
	v_exp_f32_e32 v8, v8
	v_exp_f32_e32 v9, v9
	v_exp_f32_e32 v10, v10
	v_exp_f32_e32 v11, v11
	v_exp_f32_e32 v12, v12
	v_exp_f32_e32 v13, v13
	v_exp_f32_e32 v14, v14
	v_exp_f32_e32 v15, v15
	v_exp_f32_e32 v16, v16
	v_exp_f32_e32 v17, v17
	v_exp_f32_e32 v18, v18
	v_exp_f32_e32 v19, v19
	v_exp_f32_e32 v20, v20
	v_exp_f32_e32 v21, v21
	v_exp_f32_e32 v22, v22
	v_exp_f32_e32 v23, v23
	v_exp_f32_e32 v24, v24
	v_exp_f32_e32 v25, v25
	v_exp_f32_e32 v26, v26
	v_exp_f32_e32 v27, v27
	v_exp_f32_e32 v28, v28
	v_exp_f32_e32 v29, v29
	v_exp_f32_e32 v30, v30
	v_exp_f32_e32 v31, v31
	v_pk_add_f32 v[0:1], v[0:1], 1.0 op_sel_hi:[1,0]
	v_pk_add_f32 v[2:3], v[2:3], 1.0 op_sel_hi:[1,0]
	v_pk_add_f32 v[4:5], v[4:5], 1.0 op_sel_hi:[1,0]
	v_pk_add_f32 v[6:7], v[6:7], 1.0 op_sel_hi:[1,0]
	v_pk_add_f32 v[8:9], v[8:9], 1.0 op_sel_hi:[1,0]
	v_pk_add_f32 v[10:11], v[10:11], 1.0 op_sel_hi:[1,0]
	v_pk_add_f32 v[12:13], v[12:13], 1.0 op_sel_hi:[1,0]
	v_pk_add_f32 v[14:15], v[14:15], 1.0 op_sel_hi:[1,0]
	v_pk_add_f32 v[16:17], v[16:17], 1.0 op_sel_hi:[1,0]
	v_pk_add_f32 v[18:19], v[18:19], 1.0 op_sel_hi:[1,0]
	v_pk_add_f32 v[20:21], v[20:21], 1.0 op_sel_hi:[1,0]
	v_pk_add_f32 v[22:23], v[22:23], 1.0 op_sel_hi:[1,0]
	v_pk_add_f32 v[24:25], v[24:25], 1.0 op_sel_hi:[1,0]
	v_pk_add_f32 v[26:27], v[26:27], 1.0 op_sel_hi:[1,0]
	v_pk_add_f32 v[28:29], v[28:29], 1.0 op_sel_hi:[1,0]
	v_pk_add_f32 v[30:31], v[30:31], 1.0 op_sel_hi:[1,0]
	v_rcp_f32_e32 v0, v0
	v_rcp_f32_e32 v1, v1
	v_rcp_f32_e32 v2, v2
	v_rcp_f32_e32 v3, v3
	v_rcp_f32_e32 v4, v4
	v_rcp_f32_e32 v5, v5
	v_rcp_f32_e32 v6, v6
	v_rcp_f32_e32 v7, v7
	v_rcp_f32_e32 v8, v8
	v_rcp_f32_e32 v9, v9
	v_rcp_f32_e32 v10, v10
	v_rcp_f32_e32 v11, v11
	v_rcp_f32_e32 v12, v12
	v_rcp_f32_e32 v13, v13
	v_rcp_f32_e32 v14, v14
	v_rcp_f32_e32 v15, v15
	v_rcp_f32_e32 v16, v16
	v_rcp_f32_e32 v17, v17
	v_rcp_f32_e32 v18, v18
	v_rcp_f32_e32 v19, v19
	v_rcp_f32_e32 v20, v20
	v_rcp_f32_e32 v21, v21
	v_rcp_f32_e32 v22, v22
	v_rcp_f32_e32 v23, v23
	v_rcp_f32_e32 v24, v24
	v_rcp_f32_e32 v25, v25
	v_rcp_f32_e32 v26, v26
	v_rcp_f32_e32 v27, v27
	v_rcp_f32_e32 v28, v28
	v_rcp_f32_e32 v29, v29
	v_rcp_f32_e32 v30, v30
	v_rcp_f32_e32 v31, v31
	v_pk_mul_f32 v[0:1], v[246:247], v[0:1]
	v_pk_mul_f32 v[2:3], v[246:247], v[2:3]
	v_pk_mul_f32 v[4:5], v[246:247], v[4:5]
	v_pk_mul_f32 v[6:7], v[246:247], v[6:7]
	v_pk_mul_f32 v[8:9], v[246:247], v[8:9]
	v_pk_mul_f32 v[10:11], v[246:247], v[10:11]
	v_pk_mul_f32 v[12:13], v[246:247], v[12:13]
	v_pk_mul_f32 v[14:15], v[246:247], v[14:15]
	v_lshlrev_b32_e32 v48, 16, v48
	v_lshlrev_b32_e32 v49, 16, v49
	v_lshlrev_b32_e32 v50, 16, v50
	v_lshlrev_b32_e32 v51, 16, v51
	v_lshlrev_b32_e32 v52, 16, v52
	v_lshlrev_b32_e32 v53, 16, v53
	v_lshlrev_b32_e32 v54, 16, v54
	v_lshlrev_b32_e32 v55, 16, v55
	v_lshlrev_b32_e32 v56, 16, v56
	v_lshlrev_b32_e32 v57, 16, v57
	v_lshlrev_b32_e32 v58, 16, v58
	v_lshlrev_b32_e32 v59, 16, v59
	v_lshlrev_b32_e32 v60, 16, v60
	v_lshlrev_b32_e32 v61, 16, v61
	v_lshlrev_b32_e32 v62, 16, v62
	v_lshlrev_b32_e32 v63, 16, v63
	v_exp_f32_e32 v0, v0
	v_exp_f32_e32 v1, v1
	v_exp_f32_e32 v2, v2
	v_exp_f32_e32 v3, v3
	v_exp_f32_e32 v4, v4
	v_exp_f32_e32 v5, v5
	v_exp_f32_e32 v6, v6
	v_exp_f32_e32 v7, v7
	v_exp_f32_e32 v8, v8
	v_exp_f32_e32 v9, v9
	v_exp_f32_e32 v10, v10
	v_exp_f32_e32 v11, v11
	v_exp_f32_e32 v12, v12
	v_exp_f32_e32 v13, v13
	v_exp_f32_e32 v14, v14
	v_exp_f32_e32 v15, v15
	v_fma_f32 v32, -v0, v0, 1.0
	v_fma_f32 v33, -v1, v1, 1.0
	v_fma_f32 v34, -v2, v2, 1.0
	v_fma_f32 v35, -v3, v3, 1.0
	v_fma_f32 v36, -v4, v4, 1.0
	v_fma_f32 v37, -v5, v5, 1.0
	v_fma_f32 v38, -v6, v6, 1.0
	v_fma_f32 v39, -v7, v7, 1.0
	v_fma_f32 v40, -v8, v8, 1.0
	v_fma_f32 v41, -v9, v9, 1.0
	v_fma_f32 v42, -v10, v10, 1.0
	v_fma_f32 v43, -v11, v11, 1.0
	v_fma_f32 v44, -v12, v12, 1.0
	v_fma_f32 v45, -v13, v13, 1.0
	v_fma_f32 v46, -v14, v14, 1.0
	v_fma_f32 v47, -v15, v15, 1.0
	v_max_f32_e32 v32, 0, v32
	v_max_f32_e32 v33, 0, v33
	v_max_f32_e32 v34, 0, v34
	v_max_f32_e32 v35, 0, v35
	v_max_f32_e32 v36, 0, v36
	v_max_f32_e32 v37, 0, v37
	v_max_f32_e32 v38, 0, v38
	v_max_f32_e32 v39, 0, v39
; #define LAS __attribute__((address_space(3)))
; #define WAVE_SYNC() asm volatile("s_waitcnt lgkmcnt(0)" ::: "memory")
; __device__ __forceinline__ float sigmoid_f(float x) { return rcpf_(1.f + __expf(-x)); }
; __device__ __forceinline__ float gelu_tanh_f(float x) { const float y = 0.7978845608028654f * (x + 0.044715f * x * x * x); return x * sigmoid_f(2.f * y); }
; __device__ __forceinline__ f32x4 mfma16(bf16x8 a, bf16x8 b, f32x4 c) { return __builtin_amdgcn_mfma_f32_16x16x32_bf16(a, b, c, 0, 0, 0); }
; template <bool FINAL, int D>
; __device__ __forceinline__ void rg_dir(PREF p, int l, int h, int ch, int sidx, int rowbase  , LAS bf16_t* sXc, LAS float* stg, int lane) {
;     ...
;         const bf16x8 A0 = *(const LAS bf16x8*)(sXc + (mt * 16 + (lane & 15)) * 72 + (lane >> 4) * 8), A1 = *(const LAS bf16x8*)(sXc + (mt * 16 + (lane & 15)) * 72 + 32 + (lane >> 4) * 8);
;         f32x4 ar[4], ai[4];
; #pragma unroll
;         for (int nt = 0; nt < 4; ++nt) { const f32x4 z = {0.f, 0.f, 0.f, 0.f};
;             ar[nt] = mfma16(A0, Br[nt][0], z); ar[nt] = mfma16(A1, Br[nt][1], ar[nt]); ai[nt] = mfma16(A0, Bi[nt][0], z); ai[nt] = mfma16(A1, Bi[nt][1], ai[nt]); }
;         WAVE_SYNC();
; #pragma unroll
;         for (int nt = 0; nt < 4; ++nt)
; #pragma unroll
;             for (int j = 0; j < 4; ++j) { const int o = ((lane >> 4) * 4 + j) * 64 + nt * 16 + (lane & 15); stg[o] = ar[nt][j]; stg[1024 + o] = ai[nt][j]; }
;         WAVE_SYNC();
;         float av[16], iv[16];
; #pragma unroll
;         for (int ti = 0; ti < 16; ++ti) { const int tk = D ? 15 - ti : ti;
;             const float zr = stg[tk * 64 + lane] + ba, zi = stg[1024 + tk * 64 + lane] + bi;
;             const float r = sigmoid_f(zr), ig = sigmoid_f(zi);
;             const float a = __builtin_amdgcn_exp2f(r * sp8);
;             const float xc = bf2f(sXc[(mt * 16 + tk) * 72 + lane]);
;             av[ti] = a; iv[ti] = __builtin_amdgcn_sqrtf(fmaxf(1.f - a * a, 0.f)) * ig * xc;
;             if (FINAL && D == 1) grv[ti] = gelu_tanh_f(grv[ti]);
;         }
; #pragma unroll
;         for (int ti = 0; ti < 16; ++ti) { const int tk = D ? 15 - ti : ti;
;             hc = av[ti] * hc + iv[ti]; Ap *= av[ti];
	v_max_f32_e32 v40, 0, v40
	v_max_f32_e32 v41, 0, v41
	v_max_f32_e32 v42, 0, v42
	v_max_f32_e32 v43, 0, v43
	v_max_f32_e32 v44, 0, v44
	v_max_f32_e32 v45, 0, v45
	v_max_f32_e32 v46, 0, v46
	v_max_f32_e32 v47, 0, v47
	v_sqrt_f32_e32 v32, v32
	v_sqrt_f32_e32 v33, v33
	v_sqrt_f32_e32 v34, v34
	v_sqrt_f32_e32 v35, v35
	v_sqrt_f32_e32 v36, v36
	v_sqrt_f32_e32 v37, v37
	v_sqrt_f32_e32 v38, v38
	v_sqrt_f32_e32 v39, v39
	v_sqrt_f32_e32 v40, v40
	v_sqrt_f32_e32 v41, v41
	v_sqrt_f32_e32 v42, v42
	v_sqrt_f32_e32 v43, v43
	v_sqrt_f32_e32 v44, v44
	v_sqrt_f32_e32 v45, v45
	v_sqrt_f32_e32 v46, v46
	v_sqrt_f32_e32 v47, v47
	s_nop 0
	v_pk_mul_f32 v[16:17], v[16:17], v[32:33]
	v_pk_mul_f32 v[18:19], v[18:19], v[34:35]
	v_pk_mul_f32 v[20:21], v[20:21], v[36:37]
	v_pk_mul_f32 v[22:23], v[22:23], v[38:39]
	v_pk_mul_f32 v[24:25], v[24:25], v[40:41]
	v_pk_mul_f32 v[26:27], v[26:27], v[42:43]
	v_pk_mul_f32 v[28:29], v[28:29], v[44:45]
	v_pk_mul_f32 v[30:31], v[30:31], v[46:47]
	v_pk_mul_f32 v[16:17], v[16:17], v[48:49]
	v_pk_mul_f32 v[18:19], v[18:19], v[50:51]
	v_pk_mul_f32 v[20:21], v[20:21], v[52:53]
	v_pk_mul_f32 v[22:23], v[22:23], v[54:55]
	v_pk_mul_f32 v[24:25], v[24:25], v[56:57]
	v_pk_mul_f32 v[26:27], v[26:27], v[58:59]
	v_pk_mul_f32 v[28:29], v[28:29], v[60:61]
	v_pk_mul_f32 v[30:31], v[30:31], v[62:63]
	v_fma_f32 v250, v15, v250, v31
	v_mul_f32_e32 v232, v232, v15
	v_fma_f32 v250, v14, v250, v30
	v_mul_f32_e32 v232, v232, v14
	v_fma_f32 v250, v13, v250, v29
	v_mul_f32_e32 v232, v232, v13
	v_fma_f32 v250, v12, v250, v28
	v_mul_f32_e32 v232, v232, v12
	v_fma_f32 v250, v11, v250, v27
	v_mul_f32_e32 v232, v232, v11
	v_fma_f32 v250, v10, v250, v26
	v_mul_f32_e32 v232, v232, v10
	v_fma_f32 v250, v9, v250, v25
	v_mul_f32_e32 v232, v232, v9
	v_fma_f32 v250, v8, v250, v24
	v_mul_f32_e32 v232, v232, v8
	v_fma_f32 v250, v7, v250, v23
	v_mul_f32_e32 v232, v232, v7
	v_fma_f32 v250, v6, v250, v22
	v_mul_f32_e32 v232, v232, v6
	v_fma_f32 v250, v5, v250, v21
	v_mul_f32_e32 v232, v232, v5
	v_fma_f32 v250, v4, v250, v20
	v_mul_f32_e32 v232, v232, v4
	v_fma_f32 v250, v3, v250, v19
	v_mul_f32_e32 v232, v232, v3
	v_fma_f32 v250, v2, v250, v18
	v_mul_f32_e32 v232, v232, v2
	v_fma_f32 v250, v1, v250, v17
	v_mul_f32_e32 v232, v232, v1
	v_fma_f32 v250, v0, v250, v16
	v_mul_f32_e32 v232, v232, v0
	ds_read_b128 v[32:35], v236 offset:2304
	ds_read_b128 v[36:39], v236 offset:2368
	s_waitcnt lgkmcnt(0)
	v_mfma_f32_16x16x32_bf16 v[0:3], v[32:35], v[80:83], 0
	v_mfma_f32_16x16x32_bf16 v[4:7], v[32:35], v[88:91], 0
	v_mfma_f32_16x16x32_bf16 v[8:11], v[32:35], v[96:99], 0
	v_mfma_f32_16x16x32_bf16 v[12:15], v[32:35], v[104:107], 0
	v_mfma_f32_16x16x32_bf16 v[16:19], v[32:35], v[112:115], 0
	v_mfma_f32_16x16x32_bf16 v[20:23], v[32:35], v[120:123], 0
	v_mfma_f32_16x16x32_bf16 v[24:27], v[32:35], v[128:131], 0
	v_mfma_f32_16x16x32_bf16 v[28:31], v[32:35], v[136:139], 0
	v_mfma_f32_16x16x32_bf16 v[0:3], v[36:39], v[84:87], v[0:3]
	v_mfma_f32_16x16x32_bf16 v[4:7], v[36:39], v[92:95], v[4:7]
	v_mfma_f32_16x16x32_bf16 v[8:11], v[36:39], v[100:103], v[8:11]
	v_mfma_f32_16x16x32_bf16 v[12:15], v[36:39], v[108:111], v[12:15]
	v_mfma_f32_16x16x32_bf16 v[16:19], v[36:39], v[148:151], v[16:19]
	v_mfma_f32_16x16x32_bf16 v[20:23], v[36:39], v[124:127], v[20:23]
	v_mfma_f32_16x16x32_bf16 v[24:27], v[36:39], v[132:135], v[24:27]
	v_mfma_f32_16x16x32_bf16 v[28:31], v[36:39], v[228:231], v[28:31]
	s_nop 3
	ds_write2_b32 v237, v0, v4 offset0:0 offset1:16
	ds_write2_b32 v237, v8, v12 offset0:32 offset1:48
	ds_write2_b32 v237, v1, v5 offset0:64 offset1:80
	ds_write2_b32 v237, v9, v13 offset0:96 offset1:112
	ds_write2_b32 v237, v2, v6 offset0:128 offset1:144
	ds_write2_b32 v237, v10, v14 offset0:160 offset1:176
	ds_write2_b32 v237, v3, v7 offset0:192 offset1:208
	ds_write2_b32 v237, v11, v15 offset0:224 offset1:240
	ds_write2_b32 v238, v16, v20 offset0:0 offset1:16
	ds_write2_b32 v238, v24, v28 offset0:32 offset1:48
	ds_write2_b32 v238, v17, v21 offset0:64 offset1:80
	ds_write2_b32 v238, v25, v29 offset0:96 offset1:112
	ds_write2_b32 v238, v18, v22 offset0:128 offset1:144
	ds_write2_b32 v238, v26, v30 offset0:160 offset1:176
	ds_write2_b32 v238, v19, v23 offset0:192 offset1:208
	ds_write2_b32 v238, v27, v31 offset0:224 offset1:240
	s_waitcnt lgkmcnt(0)
	ds_read2st64_b32 v[0:1], v239 offset0:36 offset1:37
	ds_read2st64_b32 v[2:3], v239 offset0:38 offset1:39
	ds_read2st64_b32 v[4:5], v239 offset0:40 offset1:41
	ds_read2st64_b32 v[6:7], v239 offset0:42 offset1:43
	ds_read2st64_b32 v[8:9], v239 offset0:44 offset1:45
	ds_read2st64_b32 v[10:11], v239 offset0:46 offset1:47
	ds_read2st64_b32 v[12:13], v239 offset0:48 offset1:49
	ds_read2st64_b32 v[14:15], v239 offset0:50 offset1:51
	ds_read2st64_b32 v[16:17], v239 offset0:52 offset1:53
	ds_read2st64_b32 v[18:19], v239 offset0:54 offset1:55
	ds_read2st64_b32 v[20:21], v239 offset0:56 offset1:57
	ds_read2st64_b32 v[22:23], v239 offset0:58 offset1:59
	ds_read2st64_b32 v[24:25], v239 offset0:60 offset1:61
	ds_read2st64_b32 v[26:27], v239 offset0:62 offset1:63
	ds_read2st64_b32 v[28:29], v239 offset0:64 offset1:65
	ds_read2st64_b32 v[30:31], v239 offset0:66 offset1:67
	ds_read_u16 v48, v240 offset:2304
	ds_read_u16 v49, v240 offset:2448
	ds_read_u16 v50, v240 offset:2592
	ds_read_u16 v51, v240 offset:2736
	ds_read_u16 v52, v240 offset:2880
	ds_read_u16 v53, v240 offset:3024
	ds_read_u16 v54, v240 offset:3168
	ds_read_u16 v55, v240 offset:3312
	ds_read_u16 v56, v240 offset:3456
	ds_read_u16 v57, v240 offset:3600
	ds_read_u16 v58, v240 offset:3744
	ds_read_u16 v59, v240 offset:3888
	ds_read_u16 v60, v240 offset:4032
	ds_read_u16 v61, v240 offset:4176
	ds_read_u16 v62, v240 offset:4320
	ds_read_u16 v63, v240 offset:4464
	s_waitcnt lgkmcnt(0)
; __device__ __forceinline__ float sigmoid_f(float x) { return rcpf_(1.f + __expf(-x)); }
; template <bool FINAL, int D>
; __device__ __forceinline__ void rg_dir(PREF p, int l, int h, int ch, int sidx, int rowbase  , LAS bf16_t* sXc, LAS float* stg, int lane) {
;     ...
;         float av[16], iv[16];
; #pragma unroll
;         for (int ti = 0; ti < 16; ++ti) { const int tk = D ? 15 - ti : ti;
;             const float zr = stg[tk * 64 + lane] + ba, zi = stg[1024 + tk * 64 + lane] + bi;
;             const float r = sigmoid_f(zr), ig = sigmoid_f(zi);
;             const float a = __builtin_amdgcn_exp2f(r * sp8);
;             const float xc = bf2f(sXc[(mt * 16 + tk) * 72 + lane]);
;             av[ti] = a; iv[ti] = __builtin_amdgcn_sqrtf(fmaxf(1.f - a * a, 0.f)) * ig * xc;
	v_pk_add_f32 v[0:1], v[242:243], v[0:1]
	v_pk_add_f32 v[2:3], v[242:243], v[2:3]
	v_pk_add_f32 v[4:5], v[242:243], v[4:5]
	v_pk_add_f32 v[6:7], v[242:243], v[6:7]
	v_pk_add_f32 v[8:9], v[242:243], v[8:9]
	v_pk_add_f32 v[10:11], v[242:243], v[10:11]
	v_pk_add_f32 v[12:13], v[242:243], v[12:13]
	v_pk_add_f32 v[14:15], v[242:243], v[14:15]
	v_pk_add_f32 v[16:17], v[244:245], v[16:17]
	v_pk_add_f32 v[18:19], v[244:245], v[18:19]
	v_pk_add_f32 v[20:21], v[244:245], v[20:21]
	v_pk_add_f32 v[22:23], v[244:245], v[22:23]
	v_pk_add_f32 v[24:25], v[244:245], v[24:25]
	v_pk_add_f32 v[26:27], v[244:245], v[26:27]
	v_pk_add_f32 v[28:29], v[244:245], v[28:29]
	v_pk_add_f32 v[30:31], v[244:245], v[30:31]
	v_pk_mul_f32 v[0:1], v[248:249], v[0:1]
	v_pk_mul_f32 v[2:3], v[248:249], v[2:3]
	v_pk_mul_f32 v[4:5], v[248:249], v[4:5]
	v_pk_mul_f32 v[6:7], v[248:249], v[6:7]
	v_pk_mul_f32 v[8:9], v[248:249], v[8:9]
	v_pk_mul_f32 v[10:11], v[248:249], v[10:11]
	v_pk_mul_f32 v[12:13], v[248:249], v[12:13]
	v_pk_mul_f32 v[14:15], v[248:249], v[14:15]
	v_pk_mul_f32 v[16:17], v[248:249], v[16:17]
	v_pk_mul_f32 v[18:19], v[248:249], v[18:19]
	v_pk_mul_f32 v[20:21], v[248:249], v[20:21]
	v_pk_mul_f32 v[22:23], v[248:249], v[22:23]
	v_pk_mul_f32 v[24:25], v[248:249], v[24:25]
	v_pk_mul_f32 v[26:27], v[248:249], v[26:27]
	v_pk_mul_f32 v[28:29], v[248:249], v[28:29]
	v_pk_mul_f32 v[30:31], v[248:249], v[30:31]
	v_exp_f32_e32 v0, v0
	v_exp_f32_e32 v1, v1
	v_exp_f32_e32 v2, v2
	v_exp_f32_e32 v3, v3
	v_exp_f32_e32 v4, v4
	v_exp_f32_e32 v5, v5
	v_exp_f32_e32 v6, v6
	v_exp_f32_e32 v7, v7
	v_exp_f32_e32 v8, v8
	v_exp_f32_e32 v9, v9
	v_exp_f32_e32 v10, v10
	v_exp_f32_e32 v11, v11
	v_exp_f32_e32 v12, v12
	v_exp_f32_e32 v13, v13
	v_exp_f32_e32 v14, v14
	v_exp_f32_e32 v15, v15
	v_exp_f32_e32 v16, v16
	v_exp_f32_e32 v17, v17
	v_exp_f32_e32 v18, v18
	v_exp_f32_e32 v19, v19
	v_exp_f32_e32 v20, v20
	v_exp_f32_e32 v21, v21
	v_exp_f32_e32 v22, v22
	v_exp_f32_e32 v23, v23
	v_exp_f32_e32 v24, v24
	v_exp_f32_e32 v25, v25
	v_exp_f32_e32 v26, v26
	v_exp_f32_e32 v27, v27
	v_exp_f32_e32 v28, v28
	v_exp_f32_e32 v29, v29
	v_exp_f32_e32 v30, v30
	v_exp_f32_e32 v31, v31
	v_pk_add_f32 v[0:1], v[0:1], 1.0 op_sel_hi:[1,0]
	v_pk_add_f32 v[2:3], v[2:3], 1.0 op_sel_hi:[1,0]
	v_pk_add_f32 v[4:5], v[4:5], 1.0 op_sel_hi:[1,0]
	v_pk_add_f32 v[6:7], v[6:7], 1.0 op_sel_hi:[1,0]
	v_pk_add_f32 v[8:9], v[8:9], 1.0 op_sel_hi:[1,0]
	v_pk_add_f32 v[10:11], v[10:11], 1.0 op_sel_hi:[1,0]
	v_pk_add_f32 v[12:13], v[12:13], 1.0 op_sel_hi:[1,0]
	v_pk_add_f32 v[14:15], v[14:15], 1.0 op_sel_hi:[1,0]
	v_pk_add_f32 v[16:17], v[16:17], 1.0 op_sel_hi:[1,0]
	v_pk_add_f32 v[18:19], v[18:19], 1.0 op_sel_hi:[1,0]
	v_pk_add_f32 v[20:21], v[20:21], 1.0 op_sel_hi:[1,0]
	v_pk_add_f32 v[22:23], v[22:23], 1.0 op_sel_hi:[1,0]
	v_pk_add_f32 v[24:25], v[24:25], 1.0 op_sel_hi:[1,0]
	v_pk_add_f32 v[26:27], v[26:27], 1.0 op_sel_hi:[1,0]
	v_pk_add_f32 v[28:29], v[28:29], 1.0 op_sel_hi:[1,0]
	v_pk_add_f32 v[30:31], v[30:31], 1.0 op_sel_hi:[1,0]
	v_rcp_f32_e32 v0, v0
	v_rcp_f32_e32 v1, v1
	v_rcp_f32_e32 v2, v2
	v_rcp_f32_e32 v3, v3
	v_rcp_f32_e32 v4, v4
	v_rcp_f32_e32 v5, v5
	v_rcp_f32_e32 v6, v6
	v_rcp_f32_e32 v7, v7
	v_rcp_f32_e32 v8, v8
	v_rcp_f32_e32 v9, v9
	v_rcp_f32_e32 v10, v10
	v_rcp_f32_e32 v11, v11
	v_rcp_f32_e32 v12, v12
	v_rcp_f32_e32 v13, v13
	v_rcp_f32_e32 v14, v14
	v_rcp_f32_e32 v15, v15
	v_rcp_f32_e32 v16, v16
	v_rcp_f32_e32 v17, v17
	v_rcp_f32_e32 v18, v18
	v_rcp_f32_e32 v19, v19
	v_rcp_f32_e32 v20, v20
	v_rcp_f32_e32 v21, v21
	v_rcp_f32_e32 v22, v22
	v_rcp_f32_e32 v23, v23
	v_rcp_f32_e32 v24, v24
	v_rcp_f32_e32 v25, v25
	v_rcp_f32_e32 v26, v26
	v_rcp_f32_e32 v27, v27
	v_rcp_f32_e32 v28, v28
	v_rcp_f32_e32 v29, v29
	v_rcp_f32_e32 v30, v30
	v_rcp_f32_e32 v31, v31
	v_pk_mul_f32 v[0:1], v[246:247], v[0:1]
	v_pk_mul_f32 v[2:3], v[246:247], v[2:3]
	v_pk_mul_f32 v[4:5], v[246:247], v[4:5]
	v_pk_mul_f32 v[6:7], v[246:247], v[6:7]
	v_pk_mul_f32 v[8:9], v[246:247], v[8:9]
	v_pk_mul_f32 v[10:11], v[246:247], v[10:11]
	v_pk_mul_f32 v[12:13], v[246:247], v[12:13]
	v_pk_mul_f32 v[14:15], v[246:247], v[14:15]
	v_lshlrev_b32_e32 v48, 16, v48
	v_lshlrev_b32_e32 v49, 16, v49
	v_lshlrev_b32_e32 v50, 16, v50
	v_lshlrev_b32_e32 v51, 16, v51
	v_lshlrev_b32_e32 v52, 16, v52
	v_lshlrev_b32_e32 v53, 16, v53
	v_lshlrev_b32_e32 v54, 16, v54
	v_lshlrev_b32_e32 v55, 16, v55
	v_lshlrev_b32_e32 v56, 16, v56
	v_lshlrev_b32_e32 v57, 16, v57
	v_lshlrev_b32_e32 v58, 16, v58
	v_lshlrev_b32_e32 v59, 16, v59
	v_lshlrev_b32_e32 v60, 16, v60
	v_lshlrev_b32_e32 v61, 16, v61
	v_lshlrev_b32_e32 v62, 16, v62
	v_lshlrev_b32_e32 v63, 16, v63
	v_exp_f32_e32 v0, v0
	v_exp_f32_e32 v1, v1
	v_exp_f32_e32 v2, v2
	v_exp_f32_e32 v3, v3
	v_exp_f32_e32 v4, v4
	v_exp_f32_e32 v5, v5
	v_exp_f32_e32 v6, v6
	v_exp_f32_e32 v7, v7
	v_exp_f32_e32 v8, v8
	v_exp_f32_e32 v9, v9
	v_exp_f32_e32 v10, v10
	v_exp_f32_e32 v11, v11
	v_exp_f32_e32 v12, v12
	v_exp_f32_e32 v13, v13
	v_exp_f32_e32 v14, v14
	v_exp_f32_e32 v15, v15
	v_fma_f32 v32, -v0, v0, 1.0
	v_fma_f32 v33, -v1, v1, 1.0
	v_fma_f32 v34, -v2, v2, 1.0
	v_fma_f32 v35, -v3, v3, 1.0
	v_fma_f32 v36, -v4, v4, 1.0
	v_fma_f32 v37, -v5, v5, 1.0
	v_fma_f32 v38, -v6, v6, 1.0
	v_fma_f32 v39, -v7, v7, 1.0
	v_fma_f32 v40, -v8, v8, 1.0
	v_fma_f32 v41, -v9, v9, 1.0
	v_fma_f32 v42, -v10, v10, 1.0
	v_fma_f32 v43, -v11, v11, 1.0
	v_fma_f32 v44, -v12, v12, 1.0
	v_fma_f32 v45, -v13, v13, 1.0
	v_fma_f32 v46, -v14, v14, 1.0
	v_fma_f32 v47, -v15, v15, 1.0
	v_max_f32_e32 v32, 0, v32
	v_max_f32_e32 v33, 0, v33
	v_max_f32_e32 v34, 0, v34
	v_max_f32_e32 v35, 0, v35
	v_max_f32_e32 v36, 0, v36
	v_max_f32_e32 v37, 0, v37
	v_max_f32_e32 v38, 0, v38
	v_max_f32_e32 v39, 0, v39
; #define LAS __attribute__((address_space(3)))
; #define WAVE_SYNC() asm volatile("s_waitcnt lgkmcnt(0)" ::: "memory")
; __device__ __forceinline__ float sigmoid_f(float x) { return rcpf_(1.f + __expf(-x)); }
; __device__ __forceinline__ float gelu_tanh_f(float x) { const float y = 0.7978845608028654f * (x + 0.044715f * x * x * x); return x * sigmoid_f(2.f * y); }
; __device__ __forceinline__ f32x4 mfma16(bf16x8 a, bf16x8 b, f32x4 c) { return __builtin_amdgcn_mfma_f32_16x16x32_bf16(a, b, c, 0, 0, 0); }
; template <bool FINAL, int D>
; __device__ __forceinline__ void rg_dir(PREF p, int l, int h, int ch, int sidx, int rowbase  , LAS bf16_t* sXc, LAS float* stg, int lane) {
;     ...
;         const bf16x8 A0 = *(const LAS bf16x8*)(sXc + (mt * 16 + (lane & 15)) * 72 + (lane >> 4) * 8), A1 = *(const LAS bf16x8*)(sXc + (mt * 16 + (lane & 15)) * 72 + 32 + (lane >> 4) * 8);
;         f32x4 ar[4], ai[4];
; #pragma unroll
;         for (int nt = 0; nt < 4; ++nt) { const f32x4 z = {0.f, 0.f, 0.f, 0.f};
;             ar[nt] = mfma16(A0, Br[nt][0], z); ar[nt] = mfma16(A1, Br[nt][1], ar[nt]); ai[nt] = mfma16(A0, Bi[nt][0], z); ai[nt] = mfma16(A1, Bi[nt][1], ai[nt]); }
;         WAVE_SYNC();
; #pragma unroll
;         for (int nt = 0; nt < 4; ++nt)
; #pragma unroll
;             for (int j = 0; j < 4; ++j) { const int o = ((lane >> 4) * 4 + j) * 64 + nt * 16 + (lane & 15); stg[o] = ar[nt][j]; stg[1024 + o] = ai[nt][j]; }
;         WAVE_SYNC();
;         float av[16], iv[16];
; #pragma unroll
;         for (int ti = 0; ti < 16; ++ti) { const int tk = D ? 15 - ti : ti;
;             const float zr = stg[tk * 64 + lane] + ba, zi = stg[1024 + tk * 64 + lane] + bi;
;             const float r = sigmoid_f(zr), ig = sigmoid_f(zi);
;             const float a = __builtin_amdgcn_exp2f(r * sp8);
;             const float xc = bf2f(sXc[(mt * 16 + tk) * 72 + lane]);
;             av[ti] = a; iv[ti] = __builtin_amdgcn_sqrtf(fmaxf(1.f - a * a, 0.f)) * ig * xc;
;             if (FINAL && D == 1) grv[ti] = gelu_tanh_f(grv[ti]);
;         }
; #pragma unroll
;         for (int ti = 0; ti < 16; ++ti) { const int tk = D ? 15 - ti : ti;
;             hc = av[ti] * hc + iv[ti]; Ap *= av[ti];
	v_max_f32_e32 v40, 0, v40
	v_max_f32_e32 v41, 0, v41
	v_max_f32_e32 v42, 0, v42
	v_max_f32_e32 v43, 0, v43
	v_max_f32_e32 v44, 0, v44
	v_max_f32_e32 v45, 0, v45
	v_max_f32_e32 v46, 0, v46
	v_max_f32_e32 v47, 0, v47
	v_sqrt_f32_e32 v32, v32
	v_sqrt_f32_e32 v33, v33
	v_sqrt_f32_e32 v34, v34
	v_sqrt_f32_e32 v35, v35
	v_sqrt_f32_e32 v36, v36
	v_sqrt_f32_e32 v37, v37
	v_sqrt_f32_e32 v38, v38
	v_sqrt_f32_e32 v39, v39
	v_sqrt_f32_e32 v40, v40
	v_sqrt_f32_e32 v41, v41
	v_sqrt_f32_e32 v42, v42
	v_sqrt_f32_e32 v43, v43
	v_sqrt_f32_e32 v44, v44
	v_sqrt_f32_e32 v45, v45
	v_sqrt_f32_e32 v46, v46
	v_sqrt_f32_e32 v47, v47
	s_nop 0
	v_pk_mul_f32 v[16:17], v[16:17], v[32:33]
	v_pk_mul_f32 v[18:19], v[18:19], v[34:35]
	v_pk_mul_f32 v[20:21], v[20:21], v[36:37]
	v_pk_mul_f32 v[22:23], v[22:23], v[38:39]
	v_pk_mul_f32 v[24:25], v[24:25], v[40:41]
	v_pk_mul_f32 v[26:27], v[26:27], v[42:43]
	v_pk_mul_f32 v[28:29], v[28:29], v[44:45]
	v_pk_mul_f32 v[30:31], v[30:31], v[46:47]
	v_pk_mul_f32 v[16:17], v[16:17], v[48:49]
	v_pk_mul_f32 v[18:19], v[18:19], v[50:51]
	v_pk_mul_f32 v[20:21], v[20:21], v[52:53]
	v_pk_mul_f32 v[22:23], v[22:23], v[54:55]
	v_pk_mul_f32 v[24:25], v[24:25], v[56:57]
	v_pk_mul_f32 v[26:27], v[26:27], v[58:59]
	v_pk_mul_f32 v[28:29], v[28:29], v[60:61]
	v_pk_mul_f32 v[30:31], v[30:31], v[62:63]
	v_fma_f32 v250, v15, v250, v31
	v_mul_f32_e32 v232, v232, v15
	v_fma_f32 v250, v14, v250, v30
	v_mul_f32_e32 v232, v232, v14
	v_fma_f32 v250, v13, v250, v29
	v_mul_f32_e32 v232, v232, v13
	v_fma_f32 v250, v12, v250, v28
	v_mul_f32_e32 v232, v232, v12
	v_fma_f32 v250, v11, v250, v27
	v_mul_f32_e32 v232, v232, v11
	v_fma_f32 v250, v10, v250, v26
	v_mul_f32_e32 v232, v232, v10
	v_fma_f32 v250, v9, v250, v25
	v_mul_f32_e32 v232, v232, v9
	v_fma_f32 v250, v8, v250, v24
	v_mul_f32_e32 v232, v232, v8
	v_fma_f32 v250, v7, v250, v23
	v_mul_f32_e32 v232, v232, v7
	v_fma_f32 v250, v6, v250, v22
	v_mul_f32_e32 v232, v232, v6
	v_fma_f32 v250, v5, v250, v21
	v_mul_f32_e32 v232, v232, v5
	v_fma_f32 v250, v4, v250, v20
	v_mul_f32_e32 v232, v232, v4
	v_fma_f32 v250, v3, v250, v19
	v_mul_f32_e32 v232, v232, v3
	v_fma_f32 v250, v2, v250, v18
	v_mul_f32_e32 v232, v232, v2
	v_fma_f32 v250, v1, v250, v17
	v_mul_f32_e32 v232, v232, v1
	v_fma_f32 v250, v0, v250, v16
	v_mul_f32_e32 v232, v232, v0
	ds_read_b128 v[32:35], v236 offset:0
	ds_read_b128 v[36:39], v236 offset:64
	s_waitcnt lgkmcnt(0)
	v_mfma_f32_16x16x32_bf16 v[0:3], v[32:35], v[80:83], 0
	v_mfma_f32_16x16x32_bf16 v[4:7], v[32:35], v[88:91], 0
	v_mfma_f32_16x16x32_bf16 v[8:11], v[32:35], v[96:99], 0
	v_mfma_f32_16x16x32_bf16 v[12:15], v[32:35], v[104:107], 0
	v_mfma_f32_16x16x32_bf16 v[16:19], v[32:35], v[112:115], 0
	v_mfma_f32_16x16x32_bf16 v[20:23], v[32:35], v[120:123], 0
	v_mfma_f32_16x16x32_bf16 v[24:27], v[32:35], v[128:131], 0
	v_mfma_f32_16x16x32_bf16 v[28:31], v[32:35], v[136:139], 0
	v_mfma_f32_16x16x32_bf16 v[0:3], v[36:39], v[84:87], v[0:3]
	v_mfma_f32_16x16x32_bf16 v[4:7], v[36:39], v[92:95], v[4:7]
	v_mfma_f32_16x16x32_bf16 v[8:11], v[36:39], v[100:103], v[8:11]
	v_mfma_f32_16x16x32_bf16 v[12:15], v[36:39], v[108:111], v[12:15]
	v_mfma_f32_16x16x32_bf16 v[16:19], v[36:39], v[148:151], v[16:19]
	v_mfma_f32_16x16x32_bf16 v[20:23], v[36:39], v[124:127], v[20:23]
	v_mfma_f32_16x16x32_bf16 v[24:27], v[36:39], v[132:135], v[24:27]
	v_mfma_f32_16x16x32_bf16 v[28:31], v[36:39], v[228:231], v[28:31]
	s_nop 3
	ds_write2_b32 v237, v0, v4 offset0:0 offset1:16
	ds_write2_b32 v237, v8, v12 offset0:32 offset1:48
	ds_write2_b32 v237, v1, v5 offset0:64 offset1:80
	ds_write2_b32 v237, v9, v13 offset0:96 offset1:112
	ds_write2_b32 v237, v2, v6 offset0:128 offset1:144
	ds_write2_b32 v237, v10, v14 offset0:160 offset1:176
	ds_write2_b32 v237, v3, v7 offset0:192 offset1:208
	ds_write2_b32 v237, v11, v15 offset0:224 offset1:240
	ds_write2_b32 v238, v16, v20 offset0:0 offset1:16
	ds_write2_b32 v238, v24, v28 offset0:32 offset1:48
	ds_write2_b32 v238, v17, v21 offset0:64 offset1:80
	ds_write2_b32 v238, v25, v29 offset0:96 offset1:112
	ds_write2_b32 v238, v18, v22 offset0:128 offset1:144
	ds_write2_b32 v238, v26, v30 offset0:160 offset1:176
	ds_write2_b32 v238, v19, v23 offset0:192 offset1:208
	ds_write2_b32 v238, v27, v31 offset0:224 offset1:240
	s_waitcnt lgkmcnt(0)
	ds_read2st64_b32 v[0:1], v239 offset0:36 offset1:37
	ds_read2st64_b32 v[2:3], v239 offset0:38 offset1:39
	ds_read2st64_b32 v[4:5], v239 offset0:40 offset1:41
	ds_read2st64_b32 v[6:7], v239 offset0:42 offset1:43
	ds_read2st64_b32 v[8:9], v239 offset0:44 offset1:45
	ds_read2st64_b32 v[10:11], v239 offset0:46 offset1:47
	ds_read2st64_b32 v[12:13], v239 offset0:48 offset1:49
	ds_read2st64_b32 v[14:15], v239 offset0:50 offset1:51
	ds_read2st64_b32 v[16:17], v239 offset0:52 offset1:53
	ds_read2st64_b32 v[18:19], v239 offset0:54 offset1:55
	ds_read2st64_b32 v[20:21], v239 offset0:56 offset1:57
	ds_read2st64_b32 v[22:23], v239 offset0:58 offset1:59
	ds_read2st64_b32 v[24:25], v239 offset0:60 offset1:61
	ds_read2st64_b32 v[26:27], v239 offset0:62 offset1:63
	ds_read2st64_b32 v[28:29], v239 offset0:64 offset1:65
	ds_read2st64_b32 v[30:31], v239 offset0:66 offset1:67
	ds_read_u16 v48, v240 offset:0
	ds_read_u16 v49, v240 offset:144
	ds_read_u16 v50, v240 offset:288
	ds_read_u16 v51, v240 offset:432
	ds_read_u16 v52, v240 offset:576
	ds_read_u16 v53, v240 offset:720
	ds_read_u16 v54, v240 offset:864
	ds_read_u16 v55, v240 offset:1008
	ds_read_u16 v56, v240 offset:1152
	ds_read_u16 v57, v240 offset:1296
	ds_read_u16 v58, v240 offset:1440
	ds_read_u16 v59, v240 offset:1584
	ds_read_u16 v60, v240 offset:1728
	ds_read_u16 v61, v240 offset:1872
	ds_read_u16 v62, v240 offset:2016
	ds_read_u16 v63, v240 offset:2160
	s_waitcnt lgkmcnt(0)
; __device__ __forceinline__ float sigmoid_f(float x) { return rcpf_(1.f + __expf(-x)); }
; template <bool FINAL, int D>
; __device__ __forceinline__ void rg_dir(PREF p, int l, int h, int ch, int sidx, int rowbase  , LAS bf16_t* sXc, LAS float* stg, int lane) {
;     ...
;         float av[16], iv[16];
; #pragma unroll
;         for (int ti = 0; ti < 16; ++ti) { const int tk = D ? 15 - ti : ti;
;             const float zr = stg[tk * 64 + lane] + ba, zi = stg[1024 + tk * 64 + lane] + bi;
;             const float r = sigmoid_f(zr), ig = sigmoid_f(zi);
;             const float a = __builtin_amdgcn_exp2f(r * sp8);
;             const float xc = bf2f(sXc[(mt * 16 + tk) * 72 + lane]);
;             av[ti] = a; iv[ti] = __builtin_amdgcn_sqrtf(fmaxf(1.f - a * a, 0.f)) * ig * xc;
	v_pk_add_f32 v[0:1], v[242:243], v[0:1]
	v_pk_add_f32 v[2:3], v[242:243], v[2:3]
	v_pk_add_f32 v[4:5], v[242:243], v[4:5]
	v_pk_add_f32 v[6:7], v[242:243], v[6:7]
	v_pk_add_f32 v[8:9], v[242:243], v[8:9]
	v_pk_add_f32 v[10:11], v[242:243], v[10:11]
	v_pk_add_f32 v[12:13], v[242:243], v[12:13]
	v_pk_add_f32 v[14:15], v[242:243], v[14:15]
	v_pk_add_f32 v[16:17], v[244:245], v[16:17]
	v_pk_add_f32 v[18:19], v[244:245], v[18:19]
	v_pk_add_f32 v[20:21], v[244:245], v[20:21]
	v_pk_add_f32 v[22:23], v[244:245], v[22:23]
	v_pk_add_f32 v[24:25], v[244:245], v[24:25]
	v_pk_add_f32 v[26:27], v[244:245], v[26:27]
	v_pk_add_f32 v[28:29], v[244:245], v[28:29]
	v_pk_add_f32 v[30:31], v[244:245], v[30:31]
	v_pk_mul_f32 v[0:1], v[248:249], v[0:1]
	v_pk_mul_f32 v[2:3], v[248:249], v[2:3]
	v_pk_mul_f32 v[4:5], v[248:249], v[4:5]
	v_pk_mul_f32 v[6:7], v[248:249], v[6:7]
	v_pk_mul_f32 v[8:9], v[248:249], v[8:9]
	v_pk_mul_f32 v[10:11], v[248:249], v[10:11]
	v_pk_mul_f32 v[12:13], v[248:249], v[12:13]
	v_pk_mul_f32 v[14:15], v[248:249], v[14:15]
	v_pk_mul_f32 v[16:17], v[248:249], v[16:17]
	v_pk_mul_f32 v[18:19], v[248:249], v[18:19]
	v_pk_mul_f32 v[20:21], v[248:249], v[20:21]
	v_pk_mul_f32 v[22:23], v[248:249], v[22:23]
	v_pk_mul_f32 v[24:25], v[248:249], v[24:25]
	v_pk_mul_f32 v[26:27], v[248:249], v[26:27]
	v_pk_mul_f32 v[28:29], v[248:249], v[28:29]
	v_pk_mul_f32 v[30:31], v[248:249], v[30:31]
	v_exp_f32_e32 v0, v0
	v_exp_f32_e32 v1, v1
	v_exp_f32_e32 v2, v2
	v_exp_f32_e32 v3, v3
	v_exp_f32_e32 v4, v4
	v_exp_f32_e32 v5, v5
	v_exp_f32_e32 v6, v6
	v_exp_f32_e32 v7, v7
	v_exp_f32_e32 v8, v8
	v_exp_f32_e32 v9, v9
	v_exp_f32_e32 v10, v10
	v_exp_f32_e32 v11, v11
	v_exp_f32_e32 v12, v12
	v_exp_f32_e32 v13, v13
	v_exp_f32_e32 v14, v14
	v_exp_f32_e32 v15, v15
	v_exp_f32_e32 v16, v16
	v_exp_f32_e32 v17, v17
	v_exp_f32_e32 v18, v18
	v_exp_f32_e32 v19, v19
	v_exp_f32_e32 v20, v20
	v_exp_f32_e32 v21, v21
	v_exp_f32_e32 v22, v22
	v_exp_f32_e32 v23, v23
	v_exp_f32_e32 v24, v24
	v_exp_f32_e32 v25, v25
	v_exp_f32_e32 v26, v26
	v_exp_f32_e32 v27, v27
	v_exp_f32_e32 v28, v28
	v_exp_f32_e32 v29, v29
	v_exp_f32_e32 v30, v30
	v_exp_f32_e32 v31, v31
	v_pk_add_f32 v[0:1], v[0:1], 1.0 op_sel_hi:[1,0]
	v_pk_add_f32 v[2:3], v[2:3], 1.0 op_sel_hi:[1,0]
	v_pk_add_f32 v[4:5], v[4:5], 1.0 op_sel_hi:[1,0]
	v_pk_add_f32 v[6:7], v[6:7], 1.0 op_sel_hi:[1,0]
	v_pk_add_f32 v[8:9], v[8:9], 1.0 op_sel_hi:[1,0]
	v_pk_add_f32 v[10:11], v[10:11], 1.0 op_sel_hi:[1,0]
	v_pk_add_f32 v[12:13], v[12:13], 1.0 op_sel_hi:[1,0]
	v_pk_add_f32 v[14:15], v[14:15], 1.0 op_sel_hi:[1,0]
	v_pk_add_f32 v[16:17], v[16:17], 1.0 op_sel_hi:[1,0]
	v_pk_add_f32 v[18:19], v[18:19], 1.0 op_sel_hi:[1,0]
	v_pk_add_f32 v[20:21], v[20:21], 1.0 op_sel_hi:[1,0]
	v_pk_add_f32 v[22:23], v[22:23], 1.0 op_sel_hi:[1,0]
	v_pk_add_f32 v[24:25], v[24:25], 1.0 op_sel_hi:[1,0]
	v_pk_add_f32 v[26:27], v[26:27], 1.0 op_sel_hi:[1,0]
	v_pk_add_f32 v[28:29], v[28:29], 1.0 op_sel_hi:[1,0]
	v_pk_add_f32 v[30:31], v[30:31], 1.0 op_sel_hi:[1,0]
	v_rcp_f32_e32 v0, v0
	v_rcp_f32_e32 v1, v1
	v_rcp_f32_e32 v2, v2
	v_rcp_f32_e32 v3, v3
	v_rcp_f32_e32 v4, v4
	v_rcp_f32_e32 v5, v5
	v_rcp_f32_e32 v6, v6
	v_rcp_f32_e32 v7, v7
	v_rcp_f32_e32 v8, v8
	v_rcp_f32_e32 v9, v9
	v_rcp_f32_e32 v10, v10
	v_rcp_f32_e32 v11, v11
	v_rcp_f32_e32 v12, v12
	v_rcp_f32_e32 v13, v13
	v_rcp_f32_e32 v14, v14
	v_rcp_f32_e32 v15, v15
	v_rcp_f32_e32 v16, v16
	v_rcp_f32_e32 v17, v17
	v_rcp_f32_e32 v18, v18
	v_rcp_f32_e32 v19, v19
	v_rcp_f32_e32 v20, v20
	v_rcp_f32_e32 v21, v21
	v_rcp_f32_e32 v22, v22
	v_rcp_f32_e32 v23, v23
	v_rcp_f32_e32 v24, v24
	v_rcp_f32_e32 v25, v25
	v_rcp_f32_e32 v26, v26
	v_rcp_f32_e32 v27, v27
	v_rcp_f32_e32 v28, v28
	v_rcp_f32_e32 v29, v29
	v_rcp_f32_e32 v30, v30
	v_rcp_f32_e32 v31, v31
	v_pk_mul_f32 v[0:1], v[246:247], v[0:1]
	v_pk_mul_f32 v[2:3], v[246:247], v[2:3]
	v_pk_mul_f32 v[4:5], v[246:247], v[4:5]
	v_pk_mul_f32 v[6:7], v[246:247], v[6:7]
	v_pk_mul_f32 v[8:9], v[246:247], v[8:9]
	v_pk_mul_f32 v[10:11], v[246:247], v[10:11]
	v_pk_mul_f32 v[12:13], v[246:247], v[12:13]
	v_pk_mul_f32 v[14:15], v[246:247], v[14:15]
	v_lshlrev_b32_e32 v48, 16, v48
	v_lshlrev_b32_e32 v49, 16, v49
	v_lshlrev_b32_e32 v50, 16, v50
	v_lshlrev_b32_e32 v51, 16, v51
	v_lshlrev_b32_e32 v52, 16, v52
	v_lshlrev_b32_e32 v53, 16, v53
	v_lshlrev_b32_e32 v54, 16, v54
	v_lshlrev_b32_e32 v55, 16, v55
	v_lshlrev_b32_e32 v56, 16, v56
	v_lshlrev_b32_e32 v57, 16, v57
	v_lshlrev_b32_e32 v58, 16, v58
	v_lshlrev_b32_e32 v59, 16, v59
	v_lshlrev_b32_e32 v60, 16, v60
	v_lshlrev_b32_e32 v61, 16, v61
	v_lshlrev_b32_e32 v62, 16, v62
	v_lshlrev_b32_e32 v63, 16, v63
	v_exp_f32_e32 v0, v0
	v_exp_f32_e32 v1, v1
	v_exp_f32_e32 v2, v2
	v_exp_f32_e32 v3, v3
	v_exp_f32_e32 v4, v4
	v_exp_f32_e32 v5, v5
	v_exp_f32_e32 v6, v6
	v_exp_f32_e32 v7, v7
	v_exp_f32_e32 v8, v8
	v_exp_f32_e32 v9, v9
	v_exp_f32_e32 v10, v10
	v_exp_f32_e32 v11, v11
	v_exp_f32_e32 v12, v12
	v_exp_f32_e32 v13, v13
	v_exp_f32_e32 v14, v14
	v_exp_f32_e32 v15, v15
	v_fma_f32 v32, -v0, v0, 1.0
; __device__ __forceinline__ unsigned f2bf(float f) { unsigned r; asm("v_cvt_pk_bf16_f32 %0, %1, %1" : "=v"(r) : "v"(f)); return r & 0xffffu; }
; __device__ __forceinline__ float gelu_tanh_f(float x) { const float y = 0.7978845608028654f * (x + 0.044715f * x * x * x); return x * sigmoid_f(2.f * y); }
; template <bool FINAL, int D>
; __device__ __forceinline__ void rg_dir(PREF p, int l, int h, int ch, int sidx, int rowbase  , LAS bf16_t* sXc, LAS float* stg, int lane) {
;     ...
;             av[ti] = a; iv[ti] = __builtin_amdgcn_sqrtf(fmaxf(1.f - a * a, 0.f)) * ig * xc;
;             if (FINAL && D == 1) grv[ti] = gelu_tanh_f(grv[ti]);
;         }
; #pragma unroll
;         for (int ti = 0; ti < 16; ++ti) { const int tk = D ? 15 - ti : ti;
;             hc = av[ti] * hc + iv[ti]; Ap *= av[ti];
;             if (FINAL) { const size_t row = (size_t)(rowbase + mt * 16 + tk);
;                 if (D == 0) TMP[row * 512 + ch] = (bf16_t)f2bf(hc);
;                 else MIX[row * DM + ch] = (bf16_t)f2bf(grv[ti] * (hfv[ti] + hc)); }
;         }
;     }
;     if (!FINAL) { RGA[sidx] = Ap; RGH[sidx] = hc; }
; __global__ void __launch_bounds__(NTHREADS, 2) mega_fwd(Params p_arg) {
;     ...
;             for (int item = gw; item < 2 * NCH * 8; item += NGW) rg_item<false>(p, l, item, lds + wave * 18432, lane);
	v_fma_f32 v33, -v1, v1, 1.0
	v_fma_f32 v34, -v2, v2, 1.0
	v_fma_f32 v35, -v3, v3, 1.0
	v_fma_f32 v36, -v4, v4, 1.0
	v_fma_f32 v37, -v5, v5, 1.0
	v_fma_f32 v38, -v6, v6, 1.0
	v_fma_f32 v39, -v7, v7, 1.0
	v_fma_f32 v40, -v8, v8, 1.0
	v_fma_f32 v41, -v9, v9, 1.0
	v_fma_f32 v42, -v10, v10, 1.0
	v_fma_f32 v43, -v11, v11, 1.0
	v_fma_f32 v44, -v12, v12, 1.0
	v_fma_f32 v45, -v13, v13, 1.0
	v_fma_f32 v46, -v14, v14, 1.0
	v_fma_f32 v47, -v15, v15, 1.0
	v_max_f32_e32 v32, 0, v32
	v_max_f32_e32 v33, 0, v33
	v_max_f32_e32 v34, 0, v34
	v_max_f32_e32 v35, 0, v35
	v_max_f32_e32 v36, 0, v36
	v_max_f32_e32 v37, 0, v37
	v_max_f32_e32 v38, 0, v38
	v_max_f32_e32 v39, 0, v39
	v_max_f32_e32 v40, 0, v40
	v_max_f32_e32 v41, 0, v41
	v_max_f32_e32 v42, 0, v42
	v_max_f32_e32 v43, 0, v43
	v_max_f32_e32 v44, 0, v44
	v_max_f32_e32 v45, 0, v45
	v_max_f32_e32 v46, 0, v46
	v_max_f32_e32 v47, 0, v47
	v_sqrt_f32_e32 v32, v32
	v_sqrt_f32_e32 v33, v33
	v_sqrt_f32_e32 v34, v34
	v_sqrt_f32_e32 v35, v35
	v_sqrt_f32_e32 v36, v36
	v_sqrt_f32_e32 v37, v37
	v_sqrt_f32_e32 v38, v38
	v_sqrt_f32_e32 v39, v39
	v_sqrt_f32_e32 v40, v40
	v_sqrt_f32_e32 v41, v41
	v_sqrt_f32_e32 v42, v42
	v_sqrt_f32_e32 v43, v43
	v_sqrt_f32_e32 v44, v44
	v_sqrt_f32_e32 v45, v45
	v_sqrt_f32_e32 v46, v46
	v_sqrt_f32_e32 v47, v47
	s_nop 0
	v_pk_mul_f32 v[16:17], v[16:17], v[32:33]
	v_pk_mul_f32 v[18:19], v[18:19], v[34:35]
	v_pk_mul_f32 v[20:21], v[20:21], v[36:37]
	v_pk_mul_f32 v[22:23], v[22:23], v[38:39]
	v_pk_mul_f32 v[24:25], v[24:25], v[40:41]
	v_pk_mul_f32 v[26:27], v[26:27], v[42:43]
	v_pk_mul_f32 v[28:29], v[28:29], v[44:45]
	v_pk_mul_f32 v[30:31], v[30:31], v[46:47]
	v_pk_mul_f32 v[16:17], v[16:17], v[48:49]
	v_pk_mul_f32 v[18:19], v[18:19], v[50:51]
	v_pk_mul_f32 v[20:21], v[20:21], v[52:53]
	v_pk_mul_f32 v[22:23], v[22:23], v[54:55]
	v_pk_mul_f32 v[24:25], v[24:25], v[56:57]
	v_pk_mul_f32 v[26:27], v[26:27], v[58:59]
	v_pk_mul_f32 v[28:29], v[28:29], v[60:61]
	v_pk_mul_f32 v[30:31], v[30:31], v[62:63]
	v_fma_f32 v250, v15, v250, v31
	v_mul_f32_e32 v232, v232, v15
	v_fma_f32 v250, v14, v250, v30
	v_mul_f32_e32 v232, v232, v14
	v_fma_f32 v250, v13, v250, v29
	v_mul_f32_e32 v232, v232, v13
	v_fma_f32 v250, v12, v250, v28
	v_mul_f32_e32 v232, v232, v12
	v_fma_f32 v250, v11, v250, v27
	v_mul_f32_e32 v232, v232, v11
	v_fma_f32 v250, v10, v250, v26
	v_mul_f32_e32 v232, v232, v10
	v_fma_f32 v250, v9, v250, v25
	v_mul_f32_e32 v232, v232, v9
	v_fma_f32 v250, v8, v250, v24
	v_mul_f32_e32 v232, v232, v8
	v_fma_f32 v250, v7, v250, v23
	v_mul_f32_e32 v232, v232, v7
	v_fma_f32 v250, v6, v250, v22
	v_mul_f32_e32 v232, v232, v6
	v_fma_f32 v250, v5, v250, v21
	v_mul_f32_e32 v232, v232, v5
	v_fma_f32 v250, v4, v250, v20
	v_mul_f32_e32 v232, v232, v4
	v_fma_f32 v250, v3, v250, v19
	v_mul_f32_e32 v232, v232, v3
	v_fma_f32 v250, v2, v250, v18
	v_mul_f32_e32 v232, v232, v2
	v_fma_f32 v250, v1, v250, v17
	v_mul_f32_e32 v232, v232, v1
	v_fma_f32 v250, v0, v250, v16
	v_mul_f32_e32 v232, v232, v0
	s_add_u32 s96, s0, 0x400800
	s_addc_u32 s97, s1, 0
	s_add_u32 s96, s96, s36
	s_addc_u32 s97, s97, 0
	global_store_dword v235, v232, s[96:97]
	s_add_u32 s96, s96, 0x300000
	s_addc_u32 s97, s97, 0
	global_store_dword v235, v250, s[96:97]
	s_waitcnt lgkmcnt(0)
	v_readlane_b32 s84, v253, 29
	s_add_i32 s12, s12, s84
	s_cmpk_lt_i32 s12, 0x1000
	s_cbranch_scc1 .Lrg5_keep
	s_sub_i32 s0, s12, 0x1000
	s_lshr_b32 s1, s0, 5
	s_and_b32 s0, s0, 31
	s_and_b32 s12, s1, 7
	s_add_i32 s1, s1, 0x1000
	s_cmp_eq_u32 s0, s12
	s_cselect_b32 s12, s1, 0x2000
.Lrg5_keep:
	s_movk_i32 s0, 0x1040
	s_movk_i32 s94, 0x90
	v_readlane_b32 s38, v253, 55
	v_readlane_b32 s39, v253, 56
	s_cmp_ge_i32 s12, s0
	s_cbranch_scc0 .LBB0_176
	v_readlane_b32 s76, v253, 22
	v_readlane_b32 s82, v253, 27
	v_readlane_b32 s74, v253, 20
	v_readlane_b32 s77, v253, 23
	v_readlane_b32 s79, v253, 25
	v_readlane_b32 s83, v253, 28
	v_readlane_b32 s90, v254, 15
	v_readlane_b32 s92, v253, 35
	v_readlane_b32 s70, v253, 53
	v_readlane_b32 s72, v253, 61
	v_mov_b32_e32 v0, v65
	v_mov_b32_e32 v1, v119
	v_readlane_b32 s75, v253, 21
	v_readlane_b32 s78, v253, 24
	v_readlane_b32 s95, v253, 26
	v_readlane_b32 s81, v253, 31
	v_readlane_b32 s91, v254, 16
	v_readlane_b32 s76, v253, 32
	v_readlane_b32 s77, v253, 33
	v_readlane_b32 s79, v253, 34
	v_readlane_b32 s93, v253, 36
	v_readlane_b32 s85, v253, 37
	v_readlane_b32 s96, v253, 40
	v_readlane_b32 s83, v253, 41
	v_readlane_b32 s57, v253, 42
	v_readlane_b32 s58, v253, 43
	s_movk_i32 s86, 0x1600
	s_mov_b32 s59, 0xbfb8aa3b
	s_mov_b32 s60, 0x800000
	s_mov_b32 s61, 0x3f317217
	s_mov_b32 s62, 0x7f800000
	s_mov_b32 s66, 0x5040100
	s_mov_b64 s[88:89], 0x1000
	s_mov_b64 s[68:69], 0x80
	v_readlane_b32 s71, v253, 54
	v_readlane_b32 s80, v254, 8
	v_readlane_b32 s97, v254, 7
	v_readlane_b32 s65, v254, 6
	v_readlane_b32 s64, v254, 5
	v_readlane_b32 s73, v253, 62
	v_readlane_b32 s36, v254, 12
	v_readlane_b32 s44, v254, 14
	v_readlane_b32 s63, v254, 4
	v_readlane_b32 s87, v254, 3
	v_readlane_b32 s10, v254, 11
	v_readlane_b32 s37, v254, 13

; __device__ __forceinline__ void gl1_item(PREF p, int l, int item, bool valid, LAS unsigned char* pl, int sw, int lane) {
;     ...
;     const int h = item & 3, rest = item >> 2;
;     const int cj = rest < 512 ? 4 + (rest & 255) : ((rest - 512) & 3), b = rest < 512 ? (rest >> 8) : ((rest - 512) >> 2);
;     int row0, rstride; gla_rows(b, cj, row0, rstride);
; __global__ void __launch_bounds__(NTHREADS, 2) mega_fwd(Params p_arg) {
;     ...
;             for (int it = 0; it * NP < 2 * NCH * 4; ++it) { const int item = it * NP + pgid; gl1_item(p, l, item, item < 2 * NCH * 4, lds + (wave >> 1) * 37376, wave & 1, lane); }
.LBB0_184:
	s_add_i32 s0, s14, s0
	s_cmpk_lt_i32 s0, 0x800
	s_cbranch_scc1 .Lbal_gl1_keep
	s_sub_i32 s1, 0xbff, s0
	s_lshr_b32 s2, s1, 5
	s_and_b32 s1, s1, 31
	s_and_b32 s0, s2, 3
	s_add_i32 s1, s1, s0
	s_add_i32 s2, s2, 0x800
	s_cmp_eq_u32 s1, 11
	s_cselect_b32 s0, s2, 0xbff
.Lbal_gl1_keep:
	s_ashr_i32 s12, s0, 2
	s_cmpk_gt_i32 s12, 0x1ff
	s_cselect_b64 s[4:5], -1, 0
	s_and_b32 s3, s12, 0xff
	s_add_i32 s1, s3, 4
	s_ashr_i32 s2, s0, 10
	s_cmpk_lt_i32 s12, 0x200
	s_mov_b64 s[6:7], -1
	s_cbranch_scc0 .LBB0_186
	s_lshl_b32 s7, s1, 12
	s_lshl_b32 s6, s2, 14
	s_and_b32 s7, s7, 0x3000
	s_or_b32 s6, s7, s6
	s_lshr_b32 s3, s3, 2
	s_or_b32 s43, s6, s3
	s_mov_b64 s[6:7], 0
